# write-through (sc1) stores for the fc1 activation, the phase-0 outputs and the FFT-phase outputs so the grid barrier's L2 write-back finds less dirty data
# speedup vs baseline: 1.2137x; 1.0062x over previous
.LBB0_139:
	s_waitcnt lgkmcnt(0)
	v_mul_f32_e32 v120, v120, v168
	v_max_f32_e32 v120, 0, v120
	v_mul_f32_e32 v121, v121, v168
	v_mul_f32_e32 v122, v122, v168
	v_lshl_or_b32 v130, s55, 8, v207
	v_mul_f32_e32 v134, v120, v120
	v_mul_f32_e32 v120, v125, v168
	v_max_f32_e32 v121, 0, v121
	v_max_f32_e32 v122, 0, v122
	v_ashrrev_i32_e32 v131, 31, v130
	v_lshlrev_b64 v[132:133], 13, v[170:171]
	v_mul_f32_e32 v124, v124, v168
	v_max_f32_e32 v120, 0, v120
	v_mul_f32_e32 v125, v121, v121
	v_mul_f32_e32 v121, v126, v168
	v_mul_f32_e32 v126, v122, v122
	v_mul_f32_e32 v122, v127, v168
	v_mul_f32_e32 v123, v123, v168
	v_lshl_add_u64 v[132:133], s[70:71], 0, v[132:133]
	v_lshlrev_b64 v[130:131], 1, v[130:131]
	v_max_f32_e32 v124, 0, v124
	v_mul_f32_e32 v120, v120, v120
	v_max_f32_e32 v121, 0, v121
	v_max_f32_e32 v122, 0, v122
	v_max_f32_e32 v123, 0, v123
	v_mul_f32_e32 v112, v112, v168
	v_mul_f32_e32 v113, v113, v168
	v_mul_f32_e32 v114, v114, v168
	v_lshl_add_u64 v[132:133], v[132:133], 0, v[130:131]
	v_mul_f32_e32 v124, v124, v124
	v_mul_f32_e32 v121, v121, v121
	v_mul_f32_e32 v122, v122, v122
	v_mul_f32_e32 v123, v123, v123
	v_cvt_pk_bf16_f32 v120, v124, v120
	v_max_f32_e32 v112, 0, v112
	v_max_f32_e32 v113, 0, v113
	v_max_f32_e32 v114, 0, v114
	v_cvt_pk_bf16_f32 v121, v121, v122
	v_cvt_pk_bf16_f32 v122, v134, v125
	v_cvt_pk_bf16_f32 v123, v126, v123
	global_store_dwordx4 v[132:133], v[120:123], off sc1
	v_mul_f32_e32 v116, v116, v168
	v_mul_f32_e32 v115, v115, v168
	v_mul_f32_e32 v120, v112, v112
	v_mul_f32_e32 v112, v117, v168
	v_mul_f32_e32 v117, v113, v113
	v_mul_f32_e32 v113, v118, v168
	v_mul_f32_e32 v118, v114, v114
	v_mul_f32_e32 v114, v119, v168
	v_max_f32_e32 v112, 0, v112
	v_max_f32_e32 v113, 0, v113
	v_max_f32_e32 v114, 0, v114
	v_max_f32_e32 v116, 0, v116
	v_mul_f32_e32 v112, v112, v112
	v_mul_f32_e32 v113, v113, v113
	v_max_f32_e32 v115, 0, v115
	v_mul_f32_e32 v114, v114, v114
	v_mul_f32_e32 v104, v104, v169
	v_mul_f32_e32 v116, v116, v116
	v_mul_f32_e32 v115, v115, v115
	v_cvt_pk_bf16_f32 v112, v116, v112
	v_cvt_pk_bf16_f32 v113, v113, v114
	v_cvt_pk_bf16_f32 v114, v120, v117
	v_max_f32_e32 v104, 0, v104
	v_mul_f32_e32 v105, v105, v169
	v_mul_f32_e32 v106, v106, v169
	v_cvt_pk_bf16_f32 v115, v118, v115
	global_store_dwordx4 v[132:133], v[112:115], off offset:256 sc1
	v_max_f32_e32 v105, 0, v105
	v_max_f32_e32 v106, 0, v106
	v_mul_f32_e32 v114, v104, v104
	v_mul_f32_e32 v104, v109, v169
	v_lshlrev_b64 v[112:113], 13, v[166:167]
	v_mul_f32_e32 v108, v108, v169
	v_max_f32_e32 v104, 0, v104
	v_mul_f32_e32 v109, v105, v105
	v_mul_f32_e32 v105, v110, v169
	v_mul_f32_e32 v110, v106, v106
	v_mul_f32_e32 v106, v111, v169
	v_mul_f32_e32 v107, v107, v169
	v_lshl_add_u64 v[112:113], s[70:71], 0, v[112:113]
	v_max_f32_e32 v108, 0, v108
	v_mul_f32_e32 v104, v104, v104
	v_max_f32_e32 v105, 0, v105
	v_max_f32_e32 v106, 0, v106
	v_max_f32_e32 v107, 0, v107
	v_mul_f32_e32 v96, v96, v169
	v_mul_f32_e32 v97, v97, v169
	v_mul_f32_e32 v98, v98, v169
	v_lshl_add_u64 v[112:113], v[112:113], 0, v[130:131]
	v_mul_f32_e32 v108, v108, v108
	v_mul_f32_e32 v105, v105, v105
	v_mul_f32_e32 v106, v106, v106
	v_mul_f32_e32 v107, v107, v107
	v_cvt_pk_bf16_f32 v104, v108, v104
	v_max_f32_e32 v96, 0, v96
	v_max_f32_e32 v97, 0, v97
	v_max_f32_e32 v98, 0, v98
	v_cvt_pk_bf16_f32 v105, v105, v106
	v_cvt_pk_bf16_f32 v106, v114, v109
	v_cvt_pk_bf16_f32 v107, v110, v107
	global_store_dwordx4 v[112:113], v[104:107], off sc1
	v_mul_f32_e32 v100, v100, v169
	v_mul_f32_e32 v99, v99, v169
	v_mul_f32_e32 v104, v96, v96
	v_mul_f32_e32 v96, v101, v169
	v_mul_f32_e32 v101, v97, v97
	v_mul_f32_e32 v97, v102, v169
	v_mul_f32_e32 v102, v98, v98
	v_mul_f32_e32 v98, v103, v169
	v_max_f32_e32 v96, 0, v96
	v_max_f32_e32 v97, 0, v97
	v_max_f32_e32 v98, 0, v98
	v_max_f32_e32 v100, 0, v100
	v_mul_f32_e32 v96, v96, v96
	v_mul_f32_e32 v97, v97, v97
	v_max_f32_e32 v99, 0, v99
	v_mul_f32_e32 v98, v98, v98
	v_mul_f32_e32 v88, v88, v172
	v_mul_f32_e32 v100, v100, v100
	v_mul_f32_e32 v99, v99, v99
	v_cvt_pk_bf16_f32 v96, v100, v96
	v_cvt_pk_bf16_f32 v97, v97, v98
	v_cvt_pk_bf16_f32 v98, v104, v101
	v_max_f32_e32 v88, 0, v88
	v_mul_f32_e32 v89, v89, v172
	v_mul_f32_e32 v90, v90, v172
	v_cvt_pk_bf16_f32 v99, v102, v99
	global_store_dwordx4 v[112:113], v[96:99], off offset:256 sc1
	v_max_f32_e32 v89, 0, v89
	v_max_f32_e32 v90, 0, v90
	v_mul_f32_e32 v98, v88, v88
	v_mul_f32_e32 v88, v93, v172
	v_lshlrev_b64 v[96:97], 13, v[164:165]
	v_mul_f32_e32 v92, v92, v172
	v_max_f32_e32 v88, 0, v88
	v_mul_f32_e32 v93, v89, v89
	v_mul_f32_e32 v89, v94, v172
	v_mul_f32_e32 v94, v90, v90
	v_mul_f32_e32 v90, v95, v172
	v_mul_f32_e32 v91, v91, v172
	v_lshl_add_u64 v[96:97], s[70:71], 0, v[96:97]
	v_max_f32_e32 v92, 0, v92
	v_mul_f32_e32 v88, v88, v88
	v_max_f32_e32 v89, 0, v89
	v_max_f32_e32 v90, 0, v90
	v_max_f32_e32 v91, 0, v91
	v_mul_f32_e32 v80, v80, v172
	v_mul_f32_e32 v81, v81, v172
	v_mul_f32_e32 v82, v82, v172
	v_lshl_add_u64 v[96:97], v[96:97], 0, v[130:131]
	v_mul_f32_e32 v92, v92, v92
	v_mul_f32_e32 v89, v89, v89
	v_mul_f32_e32 v90, v90, v90
	v_mul_f32_e32 v91, v91, v91
	v_cvt_pk_bf16_f32 v88, v92, v88
	v_max_f32_e32 v80, 0, v80
	v_max_f32_e32 v81, 0, v81
	v_max_f32_e32 v82, 0, v82
	v_cvt_pk_bf16_f32 v89, v89, v90
	v_cvt_pk_bf16_f32 v90, v98, v93
	v_cvt_pk_bf16_f32 v91, v94, v91
	global_store_dwordx4 v[96:97], v[88:91], off sc1
	v_mul_f32_e32 v84, v84, v172
	v_mul_f32_e32 v83, v83, v172
	v_mul_f32_e32 v88, v80, v80
	v_mul_f32_e32 v80, v85, v172
	v_mul_f32_e32 v85, v81, v81
	v_mul_f32_e32 v81, v86, v172
	v_mul_f32_e32 v86, v82, v82
	v_mul_f32_e32 v82, v87, v172
	v_max_f32_e32 v80, 0, v80
	v_max_f32_e32 v81, 0, v81
	v_max_f32_e32 v82, 0, v82
	v_max_f32_e32 v84, 0, v84
	v_mul_f32_e32 v80, v80, v80
	v_mul_f32_e32 v81, v81, v81
	v_max_f32_e32 v83, 0, v83
	v_mul_f32_e32 v82, v82, v82
	v_mul_f32_e32 v72, v72, v173
	v_mul_f32_e32 v84, v84, v84
	v_mul_f32_e32 v83, v83, v83
	v_cvt_pk_bf16_f32 v80, v84, v80
	v_cvt_pk_bf16_f32 v81, v81, v82
	v_cvt_pk_bf16_f32 v82, v88, v85
	v_max_f32_e32 v72, 0, v72
	v_mul_f32_e32 v73, v73, v173
	v_mul_f32_e32 v74, v74, v173
	v_cvt_pk_bf16_f32 v83, v86, v83
	global_store_dwordx4 v[96:97], v[80:83], off offset:256 sc1
	v_max_f32_e32 v73, 0, v73
	v_max_f32_e32 v74, 0, v74
	v_mul_f32_e32 v82, v72, v72
	v_mul_f32_e32 v72, v77, v173
	v_lshlrev_b64 v[80:81], 13, v[162:163]
	v_mul_f32_e32 v76, v76, v173
	v_max_f32_e32 v72, 0, v72
	v_mul_f32_e32 v77, v73, v73
	v_mul_f32_e32 v73, v78, v173
	v_mul_f32_e32 v78, v74, v74
	v_mul_f32_e32 v74, v79, v173
	v_mul_f32_e32 v75, v75, v173
	v_lshl_add_u64 v[80:81], s[70:71], 0, v[80:81]
	v_max_f32_e32 v76, 0, v76
	v_mul_f32_e32 v72, v72, v72
	v_max_f32_e32 v73, 0, v73
	v_max_f32_e32 v74, 0, v74
	v_max_f32_e32 v75, 0, v75
	v_mul_f32_e32 v64, v64, v173
	v_mul_f32_e32 v65, v65, v173
	v_mul_f32_e32 v66, v66, v173
	v_lshl_add_u64 v[80:81], v[80:81], 0, v[130:131]
	v_mul_f32_e32 v76, v76, v76
	v_mul_f32_e32 v73, v73, v73
	v_mul_f32_e32 v74, v74, v74
	v_mul_f32_e32 v75, v75, v75
	v_cvt_pk_bf16_f32 v72, v76, v72
	v_max_f32_e32 v64, 0, v64
	v_max_f32_e32 v65, 0, v65
	v_max_f32_e32 v66, 0, v66
	v_cvt_pk_bf16_f32 v73, v73, v74
	v_cvt_pk_bf16_f32 v74, v82, v77
	v_cvt_pk_bf16_f32 v75, v78, v75
	global_store_dwordx4 v[80:81], v[72:75], off sc1
	v_mul_f32_e32 v68, v68, v173
	v_mul_f32_e32 v67, v67, v173
	v_mul_f32_e32 v72, v64, v64
	v_mul_f32_e32 v64, v69, v173
	v_mul_f32_e32 v69, v65, v65
	v_mul_f32_e32 v65, v70, v173
	v_mul_f32_e32 v70, v66, v66
	v_mul_f32_e32 v66, v71, v173
	v_max_f32_e32 v64, 0, v64
	v_max_f32_e32 v65, 0, v65
	v_max_f32_e32 v66, 0, v66
	v_max_f32_e32 v68, 0, v68
	v_mul_f32_e32 v64, v64, v64
	v_mul_f32_e32 v65, v65, v65
	v_max_f32_e32 v67, 0, v67
	v_mul_f32_e32 v66, v66, v66
	v_mul_f32_e32 v56, v56, v174
	v_mul_f32_e32 v68, v68, v68
	v_mul_f32_e32 v67, v67, v67
	v_cvt_pk_bf16_f32 v64, v68, v64
	v_cvt_pk_bf16_f32 v65, v65, v66
	v_cvt_pk_bf16_f32 v66, v72, v69
	v_max_f32_e32 v56, 0, v56
	v_mul_f32_e32 v57, v57, v174
	v_mul_f32_e32 v58, v58, v174
	v_cvt_pk_bf16_f32 v67, v70, v67
	global_store_dwordx4 v[80:81], v[64:67], off offset:256 sc1
	v_max_f32_e32 v57, 0, v57
	v_max_f32_e32 v58, 0, v58
	v_mul_f32_e32 v66, v56, v56
	v_mul_f32_e32 v56, v61, v174
	v_lshlrev_b64 v[64:65], 13, v[160:161]
	v_mul_f32_e32 v60, v60, v174
	v_max_f32_e32 v56, 0, v56
	v_mul_f32_e32 v61, v57, v57
	v_mul_f32_e32 v57, v62, v174
	v_mul_f32_e32 v62, v58, v58
	v_mul_f32_e32 v58, v63, v174
	v_mul_f32_e32 v59, v59, v174
	v_lshl_add_u64 v[64:65], s[70:71], 0, v[64:65]
	v_max_f32_e32 v60, 0, v60
	v_mul_f32_e32 v56, v56, v56
	v_max_f32_e32 v57, 0, v57
	v_max_f32_e32 v58, 0, v58
	v_max_f32_e32 v59, 0, v59
	v_mul_f32_e32 v48, v48, v174
	v_mul_f32_e32 v49, v49, v174
	v_mul_f32_e32 v50, v50, v174
	v_lshl_add_u64 v[64:65], v[64:65], 0, v[130:131]
	v_mul_f32_e32 v60, v60, v60
	v_mul_f32_e32 v57, v57, v57
	v_mul_f32_e32 v58, v58, v58
	v_mul_f32_e32 v59, v59, v59
	v_cvt_pk_bf16_f32 v56, v60, v56
	v_max_f32_e32 v48, 0, v48
	v_max_f32_e32 v49, 0, v49
	v_max_f32_e32 v50, 0, v50
	v_cvt_pk_bf16_f32 v57, v57, v58
	v_cvt_pk_bf16_f32 v58, v66, v61
	v_cvt_pk_bf16_f32 v59, v62, v59
	global_store_dwordx4 v[64:65], v[56:59], off sc1
	v_mul_f32_e32 v52, v52, v174
	v_mul_f32_e32 v51, v51, v174
	v_mul_f32_e32 v56, v48, v48
	v_mul_f32_e32 v48, v53, v174
	v_mul_f32_e32 v53, v49, v49
	v_mul_f32_e32 v49, v54, v174
	v_mul_f32_e32 v54, v50, v50
	v_mul_f32_e32 v50, v55, v174
	v_max_f32_e32 v48, 0, v48
	v_max_f32_e32 v49, 0, v49
	v_max_f32_e32 v50, 0, v50
	v_max_f32_e32 v52, 0, v52
	v_mul_f32_e32 v48, v48, v48
	v_mul_f32_e32 v49, v49, v49
	v_max_f32_e32 v51, 0, v51
	v_mul_f32_e32 v50, v50, v50
	v_mul_f32_e32 v40, v40, v175
	v_mul_f32_e32 v52, v52, v52
	v_mul_f32_e32 v51, v51, v51
	v_cvt_pk_bf16_f32 v48, v52, v48
	v_cvt_pk_bf16_f32 v49, v49, v50
	v_cvt_pk_bf16_f32 v50, v56, v53
	v_max_f32_e32 v40, 0, v40
	v_mul_f32_e32 v41, v41, v175
	v_mul_f32_e32 v42, v42, v175
	v_cvt_pk_bf16_f32 v51, v54, v51
	global_store_dwordx4 v[64:65], v[48:51], off offset:256 sc1
	v_max_f32_e32 v41, 0, v41
	v_max_f32_e32 v42, 0, v42
	v_mul_f32_e32 v50, v40, v40
	v_mul_f32_e32 v40, v45, v175
	v_lshlrev_b64 v[48:49], 13, v[158:159]
	v_mul_f32_e32 v44, v44, v175
	v_max_f32_e32 v40, 0, v40
	v_mul_f32_e32 v45, v41, v41
	v_mul_f32_e32 v41, v46, v175
	v_mul_f32_e32 v46, v42, v42
	v_mul_f32_e32 v42, v47, v175
	v_mul_f32_e32 v43, v43, v175
	v_lshl_add_u64 v[48:49], s[70:71], 0, v[48:49]
	v_max_f32_e32 v44, 0, v44
	v_mul_f32_e32 v40, v40, v40
	v_max_f32_e32 v41, 0, v41
	v_max_f32_e32 v42, 0, v42
	v_max_f32_e32 v43, 0, v43
	v_mul_f32_e32 v32, v32, v175
	v_mul_f32_e32 v33, v33, v175
	v_mul_f32_e32 v34, v34, v175
	v_lshl_add_u64 v[48:49], v[48:49], 0, v[130:131]
	v_mul_f32_e32 v44, v44, v44
	v_mul_f32_e32 v41, v41, v41
	v_mul_f32_e32 v42, v42, v42
	v_mul_f32_e32 v43, v43, v43
	v_cvt_pk_bf16_f32 v40, v44, v40
	v_max_f32_e32 v32, 0, v32
	v_max_f32_e32 v33, 0, v33
	v_max_f32_e32 v34, 0, v34
	v_cvt_pk_bf16_f32 v41, v41, v42
	v_cvt_pk_bf16_f32 v42, v50, v45
	v_cvt_pk_bf16_f32 v43, v46, v43
	global_store_dwordx4 v[48:49], v[40:43], off sc1
	v_mul_f32_e32 v36, v36, v175
	v_mul_f32_e32 v35, v35, v175
	v_mul_f32_e32 v40, v32, v32
	v_mul_f32_e32 v32, v37, v175
	v_mul_f32_e32 v37, v33, v33
	v_mul_f32_e32 v33, v38, v175
	v_mul_f32_e32 v38, v34, v34
	v_mul_f32_e32 v34, v39, v175
	v_max_f32_e32 v32, 0, v32
	v_max_f32_e32 v33, 0, v33
	v_max_f32_e32 v34, 0, v34
	v_max_f32_e32 v36, 0, v36
	v_mul_f32_e32 v32, v32, v32
	v_mul_f32_e32 v33, v33, v33
	v_max_f32_e32 v35, 0, v35
	v_mul_f32_e32 v34, v34, v34
	v_mul_f32_e32 v24, v24, v128
	v_mul_f32_e32 v36, v36, v36
	v_mul_f32_e32 v35, v35, v35
	v_cvt_pk_bf16_f32 v32, v36, v32
	v_cvt_pk_bf16_f32 v33, v33, v34
	v_cvt_pk_bf16_f32 v34, v40, v37
	v_max_f32_e32 v24, 0, v24
	v_mul_f32_e32 v25, v25, v128
	v_mul_f32_e32 v26, v26, v128
	v_cvt_pk_bf16_f32 v35, v38, v35
	global_store_dwordx4 v[48:49], v[32:35], off offset:256 sc1
	v_max_f32_e32 v25, 0, v25
	v_max_f32_e32 v26, 0, v26
	v_mul_f32_e32 v34, v24, v24
	v_mul_f32_e32 v24, v29, v128
	v_lshlrev_b64 v[32:33], 13, v[156:157]
	v_mul_f32_e32 v28, v28, v128
	v_max_f32_e32 v24, 0, v24
	v_mul_f32_e32 v29, v25, v25
	v_mul_f32_e32 v25, v30, v128
	v_mul_f32_e32 v30, v26, v26
	v_mul_f32_e32 v26, v31, v128
	v_mul_f32_e32 v27, v27, v128
	v_lshl_add_u64 v[32:33], s[70:71], 0, v[32:33]
	v_max_f32_e32 v28, 0, v28
	v_mul_f32_e32 v24, v24, v24
	v_max_f32_e32 v25, 0, v25
	v_max_f32_e32 v26, 0, v26
	v_max_f32_e32 v27, 0, v27
	v_mul_f32_e32 v16, v16, v128
	v_mul_f32_e32 v17, v17, v128
	v_mul_f32_e32 v18, v18, v128
	v_lshl_add_u64 v[32:33], v[32:33], 0, v[130:131]
	v_mul_f32_e32 v28, v28, v28
	v_mul_f32_e32 v25, v25, v25
	v_mul_f32_e32 v26, v26, v26
	v_mul_f32_e32 v27, v27, v27
	v_cvt_pk_bf16_f32 v24, v28, v24
	v_max_f32_e32 v16, 0, v16
	v_max_f32_e32 v17, 0, v17
	v_max_f32_e32 v18, 0, v18
	v_cvt_pk_bf16_f32 v25, v25, v26
	v_cvt_pk_bf16_f32 v26, v34, v29
	v_cvt_pk_bf16_f32 v27, v30, v27
	global_store_dwordx4 v[32:33], v[24:27], off sc1
	v_mul_f32_e32 v20, v20, v128
	v_mul_f32_e32 v19, v19, v128
	v_mul_f32_e32 v24, v16, v16
	v_mul_f32_e32 v16, v21, v128
	v_mul_f32_e32 v21, v17, v17
	v_mul_f32_e32 v17, v22, v128
	v_mul_f32_e32 v22, v18, v18
	v_mul_f32_e32 v18, v23, v128
	v_max_f32_e32 v16, 0, v16
	v_max_f32_e32 v17, 0, v17
	v_max_f32_e32 v18, 0, v18
	v_max_f32_e32 v20, 0, v20
	v_mul_f32_e32 v16, v16, v16
	v_mul_f32_e32 v17, v17, v17
	v_max_f32_e32 v19, 0, v19
	v_mul_f32_e32 v18, v18, v18
	v_mul_f32_e32 v8, v8, v129
	v_mul_f32_e32 v20, v20, v20
	v_mul_f32_e32 v19, v19, v19
	v_cvt_pk_bf16_f32 v16, v20, v16
	v_cvt_pk_bf16_f32 v17, v17, v18
	v_cvt_pk_bf16_f32 v18, v24, v21
	v_max_f32_e32 v8, 0, v8
	v_mul_f32_e32 v9, v9, v129
	v_mul_f32_e32 v10, v10, v129
	v_cvt_pk_bf16_f32 v19, v22, v19
	global_store_dwordx4 v[32:33], v[16:19], off offset:256 sc1
	v_max_f32_e32 v9, 0, v9
	v_max_f32_e32 v10, 0, v10
	v_mul_f32_e32 v18, v8, v8
	v_mul_f32_e32 v8, v13, v129
	v_lshlrev_b64 v[16:17], 13, v[154:155]
	v_mul_f32_e32 v12, v12, v129
	v_max_f32_e32 v8, 0, v8
	v_mul_f32_e32 v13, v9, v9
	v_mul_f32_e32 v9, v14, v129
	v_mul_f32_e32 v14, v10, v10
	v_mul_f32_e32 v10, v15, v129
	v_mul_f32_e32 v11, v11, v129
	v_lshl_add_u64 v[16:17], s[70:71], 0, v[16:17]
	v_max_f32_e32 v12, 0, v12
	v_mul_f32_e32 v8, v8, v8
	v_max_f32_e32 v9, 0, v9
	v_max_f32_e32 v10, 0, v10
	v_max_f32_e32 v11, 0, v11
	v_mul_f32_e32 v0, v0, v129
	v_mul_f32_e32 v1, v1, v129
	v_mul_f32_e32 v2, v2, v129
	v_lshl_add_u64 v[16:17], v[16:17], 0, v[130:131]
	v_mul_f32_e32 v12, v12, v12
	v_mul_f32_e32 v9, v9, v9
	v_mul_f32_e32 v10, v10, v10
	v_mul_f32_e32 v11, v11, v11
	v_cvt_pk_bf16_f32 v8, v12, v8
	v_max_f32_e32 v0, 0, v0
	v_max_f32_e32 v1, 0, v1
	v_max_f32_e32 v2, 0, v2
	v_cvt_pk_bf16_f32 v9, v9, v10
	v_cvt_pk_bf16_f32 v10, v18, v13
	v_cvt_pk_bf16_f32 v11, v14, v11
	global_store_dwordx4 v[16:17], v[8:11], off sc1
	v_mul_f32_e32 v3, v3, v129
	v_mul_f32_e32 v4, v4, v129
	v_mul_f32_e32 v8, v0, v0
	v_mul_f32_e32 v0, v5, v129
	v_mul_f32_e32 v5, v1, v1
	v_mul_f32_e32 v1, v6, v129
	v_mul_f32_e32 v6, v2, v2
	v_mul_f32_e32 v2, v7, v129
	v_max_f32_e32 v0, 0, v0
	v_max_f32_e32 v1, 0, v1
	v_max_f32_e32 v2, 0, v2
	v_max_f32_e32 v3, 0, v3
	v_max_f32_e32 v4, 0, v4
	v_mul_f32_e32 v0, v0, v0
	v_mul_f32_e32 v1, v1, v1
	v_mul_f32_e32 v2, v2, v2
	v_mul_f32_e32 v3, v3, v3
	s_and_b64 vcc, exec, s[38:39]
	s_mov_b32 s55, s40
	s_mov_b32 s2, s42
	s_mov_b64 s[28:29], s[46:47]
	s_mov_b64 s[0:1], s[44:45]
	v_mul_f32_e32 v4, v4, v4
	v_cvt_pk_bf16_f32 v0, v4, v0
	v_cvt_pk_bf16_f32 v1, v1, v2
	v_cvt_pk_bf16_f32 v2, v8, v5
	v_cvt_pk_bf16_f32 v3, v6, v3
	global_store_dwordx4 v[16:17], v[0:3], off offset:256 sc1
	s_cbranch_vccnz .LBB0_152

.LBB0_209:
	s_waitcnt vmcnt(5)
	v_lshlrev_b32_e32 v10, 16, v143
	v_and_b32_e32 v121, 0x1ff, v212
	v_cmp_eq_u32_e32 vcc, 0, v121
	v_and_b32_e32 v12, 0xffff0000, v4
	v_lshlrev_b32_e32 v13, 16, v4
	v_cndmask_b32_e64 v10, v10, 0, vcc
	v_pk_mul_f32 v[14:15], v[32:33], v[12:13]
	v_mov_b32_e32 v105, v13
	v_fma_f32 v4, v41, v10, v15
	v_add_f32_e32 v4, v14, v4
	v_add_f32_e32 v14, v219, v4
	v_and_b32_e32 v4, 0xffff0000, v5
	v_lshlrev_b32_e32 v5, 16, v5
	v_mov_b32_e32 v104, v5
	v_pk_mul_f32 v[104:105], v[40:41], v[104:105]
	v_pk_mul_f32 v[106:107], v[32:33], v[4:5]
	v_fma_f32 v10, v33, v12, v105
	v_add_f32_e32 v10, v104, v10
	v_add_f32_e32 v104, v219, v10
	v_fma_f32 v10, v41, v12, v107
	v_lshlrev_b32_e32 v107, 16, v6
	v_mov_b32_e32 v108, v107
	v_mov_b32_e32 v109, v5
	v_add_f32_e32 v10, v106, v10
	v_and_b32_e32 v106, 0xffff0000, v6
	v_pk_mul_f32 v[108:109], v[40:41], v[108:109]
	v_pk_mul_f32 v[110:111], v[32:33], v[106:107]
	v_fma_f32 v5, v33, v4, v109
	v_add_f32_e32 v5, v108, v5
	v_fma_f32 v4, v41, v4, v111
	v_add_f32_e32 v108, v219, v5
	v_add_f32_e32 v4, v110, v4
	v_lshlrev_b32_e32 v5, 16, v7
	v_add_f32_e32 v110, v219, v4
	v_and_b32_e32 v4, 0xffff0000, v7
	v_mov_b32_e32 v6, v5
	v_mov_b32_e32 v7, v107
	v_pk_mul_f32 v[6:7], v[40:41], v[6:7]
	s_waitcnt vmcnt(4)
	v_lshlrev_b32_e32 v11, 16, v142
	v_fma_f32 v7, v33, v106, v7
	v_add_f32_e32 v6, v6, v7
	v_add_f32_e32 v112, v219, v6
	v_pk_mul_f32 v[6:7], v[32:33], v[4:5]
	v_cmp_eq_u32_e64 s[0:1], s37, v121
	v_fma_f32 v7, v41, v106, v7
	v_add_f32_e32 v12, v219, v10
	v_cndmask_b32_e64 v11, v11, 0, s[0:1]
	v_add_f32_e32 v6, v6, v7
	v_mov_b32_e32 v10, v5
	v_add_f32_e32 v106, v219, v6
	v_pk_mul_f32 v[6:7], v[98:99], v[10:11]
	s_waitcnt vmcnt(2)
	v_lshlrev_b32_e32 v5, 16, v140
	v_fma_f32 v4, v33, v4, v6
	v_add_f32_e32 v4, v4, v7
	v_add_f32_e32 v10, v219, v4
	v_lshlrev_b32_e32 v4, 16, v141
	v_and_b32_e32 v6, 0xffff0000, v0
	v_lshlrev_b32_e32 v7, 16, v0
	v_cndmask_b32_e64 v4, v4, 0, vcc
	v_pk_mul_f32 v[114:115], v[32:33], v[6:7]
	v_mov_b32_e32 v117, v7
	v_fma_f32 v0, v41, v4, v115
	v_add_f32_e32 v0, v114, v0
	v_add_f32_e32 v114, v219, v0
	v_and_b32_e32 v0, 0xffff0000, v1
	v_lshlrev_b32_e32 v1, 16, v1
	v_mov_b32_e32 v116, v1
	v_pk_mul_f32 v[116:117], v[40:41], v[116:117]
	v_lshlrev_b32_e32 v7, 16, v2
	v_fma_f32 v4, v33, v6, v117
	v_mov_b32_e32 v118, v7
	v_mov_b32_e32 v119, v1
	v_add_f32_e32 v4, v116, v4
	v_pk_mul_f32 v[116:117], v[32:33], v[0:1]
	v_pk_mul_f32 v[118:119], v[40:41], v[118:119]
	v_add_f32_e32 v105, v219, v4
	v_fma_f32 v4, v41, v6, v117
	v_and_b32_e32 v6, 0xffff0000, v2
	v_fma_f32 v1, v33, v0, v119
	v_add_f32_e32 v1, v118, v1
	v_pk_mul_f32 v[118:119], v[32:33], v[6:7]
	v_add_f32_e32 v109, v219, v1
	v_fma_f32 v0, v41, v0, v119
	v_add_f32_e32 v0, v118, v0
	v_lshlrev_b32_e32 v1, 16, v3
	v_add_f32_e32 v118, v219, v0
	v_and_b32_e32 v0, 0xffff0000, v3
	v_mov_b32_e32 v2, v1
	v_mov_b32_e32 v3, v7
	v_pk_mul_f32 v[2:3], v[40:41], v[2:3]
	v_add_f32_e32 v4, v116, v4
	v_fma_f32 v3, v33, v6, v3
	v_add_f32_e32 v2, v2, v3
	v_add_f32_e32 v113, v219, v2
	v_pk_mul_f32 v[2:3], v[32:33], v[0:1]
	v_cndmask_b32_e64 v5, v5, 0, s[0:1]
	v_fma_f32 v3, v41, v6, v3
	v_add_f32_e32 v116, v219, v4
	v_add_f32_e32 v2, v2, v3
	v_mov_b32_e32 v4, v1
	v_add_f32_e32 v120, v219, v2
	v_pk_mul_f32 v[2:3], v[98:99], v[4:5]
	v_lshlrev_b32_e32 v122, 3, v121
	v_fma_f32 v0, v33, v0, v2
	v_add_f32_e32 v0, v0, v3
	v_add_f32_e32 v11, v219, v0
	v_add_u32_e32 v0, -1, v122
	v_cndmask_b32_e64 v176, v0, 0, vcc
	v_add_u32_e32 v0, 8, v122
	s_add_u32 s44, s28, s42
	v_cndmask_b32_e64 v13, v0, v229, s[0:1]
	v_lshlrev_b32_e32 v0, 4, v121
	v_mov_b32_e32 v1, v177
	s_addc_u32 s45, s29, s43
	v_bfe_u32 v8, v212, 1, 8
	v_lshl_add_u64 v[0:1], s[44:45], 0, v[0:1]
	v_add_u32_e32 v126, v122, v8
	v_mov_b32_e32 v9, v214
	v_mov_b32_e32 v8, v213
	v_add_co_u32_e32 v2, vcc, s5, v0
	v_lshl_add_u32 v117, v126, 3, 0
	s_nop 0
	v_addc_co_u32_e32 v3, vcc, 0, v1, vcc
	v_xor_b32_e32 v126, 0x80000000, v9
	v_mov_b32_e32 v127, v8
	s_mov_b32 s9, s30
	v_add_co_u32_e32 v4, vcc, s27, v0
	v_pk_mul_f32 v[126:127], v[126:127], v[114:115] op_sel_hi:[1,0]
	v_pk_mul_f32 v[128:129], v[214:215], s[8:9] op_sel_hi:[0,1]
	v_addc_co_u32_e32 v5, vcc, 0, v1, vcc
	v_pk_fma_f32 v[126:127], v[8:9], v[14:15], v[126:127] op_sel_hi:[1,0,1]
	v_pk_fma_f32 v[8:9], v[212:213], s[30:31], v[128:129] op_sel:[1,0,0]
	v_mov_b32_e32 v15, v114
	global_load_dwordx4 v[0:3], v[2:3], off
	s_nop 0
	global_load_dwordx4 v[4:7], v[4:5], off
	ds_write2_b64 v117, v[14:15], v[104:105] offset1:1
	v_pk_mul_f32 v[14:15], v[104:105], v[8:9] op_sel:[1,1] op_sel_hi:[1,0] neg_lo:[0,1]
	v_lshl_add_u64 v[122:123], v[176:177], 1, s[44:45]
	v_lshlrev_b32_e32 v176, 1, v13
	v_add_u32_e32 v13, 0x8800, v117
	v_pk_fma_f32 v[14:15], v[8:9], v[104:105], v[14:15] op_sel_hi:[1,0,1]
	ds_write2_b64 v13, v[126:127], v[14:15] offset1:1
	v_pk_mul_f32 v[14:15], v[8:9], s[8:9] op_sel:[1,0]
	v_add_u32_e32 v107, 0x8810, v117
	v_pk_fma_f32 v[8:9], v[8:9], s[30:31], v[14:15] op_sel_hi:[0,1,1]
	v_pk_mul_f32 v[14:15], v[116:117], v[8:9] op_sel:[0,1] op_sel_hi:[0,0] neg_lo:[0,1]
	v_pk_mul_f32 v[104:105], v[8:9], s[8:9] op_sel:[1,0]
	v_pk_fma_f32 v[14:15], v[12:13], v[8:9], v[14:15] op_sel_hi:[0,1,1]
	v_pk_fma_f32 v[8:9], v[8:9], s[30:31], v[104:105] op_sel_hi:[0,1,1]
	v_mov_b32_e32 v13, v116
	ds_write2_b64 v117, v[12:13], v[108:109] offset0:2 offset1:3
	v_pk_mul_f32 v[12:13], v[108:109], v[8:9] op_sel:[1,1] op_sel_hi:[1,0] neg_lo:[0,1]
	s_nop 0
	v_pk_fma_f32 v[12:13], v[108:109], v[8:9], v[12:13] op_sel_hi:[0,1,1]
	ds_write2_b64 v107, v[14:15], v[12:13] offset1:1
	v_pk_mul_f32 v[12:13], v[8:9], s[8:9] op_sel:[1,0]
	v_add_u32_e32 v107, 0x8820, v117
	v_pk_fma_f32 v[8:9], v[8:9], s[30:31], v[12:13] op_sel_hi:[0,1,1]
	v_pk_mul_f32 v[12:13], v[118:119], v[8:9] op_sel:[0,1] op_sel_hi:[0,0] neg_lo:[0,1]
	v_pk_mul_f32 v[14:15], v[8:9], s[8:9] op_sel:[1,0]
	v_pk_fma_f32 v[12:13], v[110:111], v[8:9], v[12:13] op_sel_hi:[0,1,1]
	v_pk_fma_f32 v[8:9], v[8:9], s[30:31], v[14:15] op_sel_hi:[0,1,1]
	v_pk_mul_f32 v[14:15], v[112:113], v[8:9] op_sel:[1,1] op_sel_hi:[1,0] neg_lo:[0,1]
	s_nop 0
	v_pk_fma_f32 v[14:15], v[112:113], v[8:9], v[14:15] op_sel_hi:[0,1,1]
	ds_write2_b64 v107, v[12:13], v[14:15] offset1:1
	v_pk_mul_f32 v[12:13], v[8:9], s[8:9] op_sel:[1,0]
	v_add_u32_e32 v108, 0x8830, v117
	v_pk_fma_f32 v[8:9], v[8:9], s[30:31], v[12:13] op_sel_hi:[0,1,1]
	v_pk_mul_f32 v[12:13], v[120:121], v[8:9] op_sel:[0,1] op_sel_hi:[0,0] neg_lo:[0,1]
	v_pk_mul_f32 v[14:15], v[8:9], s[8:9] op_sel:[1,0]
	v_pk_fma_f32 v[12:13], v[106:107], v[8:9], v[12:13] op_sel_hi:[0,1,1]
	v_pk_fma_f32 v[8:9], v[8:9], s[30:31], v[14:15] op_sel_hi:[0,1,1]
	v_pk_mul_f32 v[14:15], v[10:11], v[8:9] op_sel:[1,1] op_sel_hi:[1,0] neg_lo:[0,1]
	s_nop 0
	v_pk_fma_f32 v[8:9], v[10:11], v[8:9], v[14:15] op_sel_hi:[0,1,1]
	ds_write2_b64 v108, v[12:13], v[8:9] offset1:1
	v_add_co_u32_e32 v8, vcc, s27, v122
	v_mov_b32_e32 v107, v120
	s_nop 0
	v_addc_co_u32_e32 v9, vcc, 0, v123, vcc
	ds_write2_b64 v117, v[106:107], v[10:11] offset0:6 offset1:7
	v_add_co_u32_e32 v10, vcc, s5, v122
	v_lshl_add_u64 v[124:125], s[44:45], 0, v[176:177]
	s_nop 0
	v_addc_co_u32_e32 v11, vcc, 0, v123, vcc
	v_add_co_u32_e32 v12, vcc, s27, v124
	v_mov_b32_e32 v111, v118
	s_nop 0
	v_addc_co_u32_e32 v13, vcc, 0, v125, vcc
	ds_write2_b64 v117, v[110:111], v[112:113] offset0:4 offset1:5
	v_add_co_u32_e32 v14, vcc, s5, v124
	v_mov_b32_e32 v110, 1.0
	s_nop 0
	v_addc_co_u32_e32 v15, vcc, 0, v125, vcc
	global_load_ushort v162, v[8:9], off
	global_load_ushort v163, v[10:11], off
	global_load_ushort v160, v[12:13], off
	global_load_ushort v161, v[14:15], off
	v_mov_b32_e32 v111, v177
	v_pk_mul_f32 v[10:11], v[208:209], v[208:209] op_sel:[1,1] op_sel_hi:[0,1] neg_lo:[1,0]
	s_waitcnt lgkmcnt(0)
	v_pk_fma_f32 v[10:11], v[208:209], v[208:209], v[10:11] op_sel_hi:[0,1,1]
	v_pk_mul_f32 v[104:105], v[10:11], v[10:11] op_sel:[1,1] op_sel_hi:[1,0] neg_lo:[0,1]
	v_pk_mul_f32 v[12:13], v[208:209], v[176:177] op_sel:[1,1] op_sel_hi:[0,1] neg_lo:[1,0]
	v_pk_fma_f32 v[104:105], v[10:11], v[10:11], v[104:105] op_sel_hi:[1,0,1]
	v_pk_fma_f32 v[114:115], v[208:209], v[110:111], v[12:13] op_sel_hi:[1,0,1]
	v_pk_mul_f32 v[8:9], v[176:177], v[10:11] op_sel:[1,1] op_sel_hi:[1,0] neg_lo:[0,1]
	s_nop 0
	v_pk_fma_f32 v[116:117], v[110:111], v[10:11], v[8:9] op_sel_hi:[0,1,1]
	v_pk_mul_f32 v[8:9], v[114:115], v[10:11] op_sel:[1,1] op_sel_hi:[1,0] neg_lo:[0,1]
	v_pk_mul_f32 v[108:109], v[104:105], v[104:105] op_sel:[1,1] op_sel_hi:[1,0] neg_lo:[0,1]
	v_pk_fma_f32 v[118:119], v[10:11], v[114:115], v[8:9] op_sel_hi:[1,0,1]
	v_pk_mul_f32 v[8:9], v[176:177], v[104:105] op_sel:[1,1] op_sel_hi:[1,0] neg_lo:[0,1]
	s_nop 0
	v_pk_fma_f32 v[120:121], v[110:111], v[104:105], v[8:9] op_sel_hi:[0,1,1]
	v_pk_mul_f32 v[8:9], v[114:115], v[104:105] op_sel:[1,1] op_sel_hi:[1,0] neg_lo:[0,1]
	s_barrier
	v_pk_fma_f32 v[122:123], v[114:115], v[104:105], v[8:9] op_sel_hi:[0,1,1]
	v_pk_mul_f32 v[8:9], v[116:117], v[104:105] op_sel:[1,1] op_sel_hi:[1,0] neg_lo:[0,1]
	s_nop 0
	v_pk_fma_f32 v[124:125], v[104:105], v[116:117], v[8:9] op_sel_hi:[1,0,1]
	v_pk_mul_f32 v[8:9], v[118:119], v[104:105] op_sel:[1,1] op_sel_hi:[1,0] neg_lo:[0,1]
	s_nop 0
	v_pk_fma_f32 v[126:127], v[104:105], v[118:119], v[8:9] op_sel_hi:[1,0,1]
	v_pk_fma_f32 v[8:9], v[104:105], v[104:105], v[108:109] op_sel_hi:[1,0,1]
	s_nop 0
	v_pk_mul_f32 v[10:11], v[176:177], v[8:9] op_sel:[1,1] op_sel_hi:[1,0] neg_lo:[0,1]
	s_nop 0
	v_pk_fma_f32 v[112:113], v[110:111], v[8:9], v[10:11] op_sel_hi:[0,1,1]
	v_pk_mul_f32 v[10:11], v[114:115], v[8:9] op_sel:[1,1] op_sel_hi:[1,0] neg_lo:[0,1]
	s_nop 0
	v_pk_fma_f32 v[108:109], v[114:115], v[8:9], v[10:11] op_sel_hi:[0,1,1]
	v_pk_mul_f32 v[10:11], v[116:117], v[8:9] op_sel:[1,1] op_sel_hi:[1,0] neg_lo:[0,1]
	s_nop 0
	v_pk_fma_f32 v[106:107], v[116:117], v[8:9], v[10:11] op_sel_hi:[0,1,1]
	v_pk_mul_f32 v[10:11], v[118:119], v[8:9] op_sel:[1,1] op_sel_hi:[1,0] neg_lo:[0,1]
	s_nop 0
	v_pk_fma_f32 v[104:105], v[118:119], v[8:9], v[10:11] op_sel_hi:[0,1,1]
	v_pk_mul_f32 v[10:11], v[120:121], v[8:9] op_sel:[1,1] op_sel_hi:[1,0] neg_lo:[0,1]
	s_nop 0
	v_pk_fma_f32 v[14:15], v[8:9], v[120:121], v[10:11] op_sel_hi:[1,0,1]
	v_pk_mul_f32 v[10:11], v[122:123], v[8:9] op_sel:[1,1] op_sel_hi:[1,0] neg_lo:[0,1]
	s_nop 0
	v_pk_fma_f32 v[12:13], v[8:9], v[122:123], v[10:11] op_sel_hi:[1,0,1]
	v_pk_mul_f32 v[10:11], v[124:125], v[8:9] op_sel:[1,1] op_sel_hi:[1,0] neg_lo:[0,1]
	v_pk_mul_f32 v[128:129], v[126:127], v[8:9] op_sel:[1,1] op_sel_hi:[1,0] neg_lo:[0,1]
	v_pk_fma_f32 v[10:11], v[8:9], v[124:125], v[10:11] op_sel_hi:[1,0,1]
	v_pk_fma_f32 v[8:9], v[8:9], v[126:127], v[128:129] op_sel_hi:[1,0,1]
	v_mov_b32_e32 v128, v206
	s_nop 0
	v_lshlrev_b32_sdwa v129, v228, v128 dst_sel:DWORD dst_unused:UNUSED_PAD src0_sel:DWORD src1_sel:BYTE_0
	v_lshrrev_b32_e32 v128, 1, v206
	v_and_b32_e32 v128, 0x78, v128
	v_add3_u32 v168, v207, v129, v128
	ds_read_b64 v[128:129], v168
	ds_read_b64 v[130:131], v168 offset:2176
	ds_read_b64 v[132:133], v168 offset:4352
	ds_read_b64 v[134:135], v168 offset:6528
	ds_read_b64 v[136:137], v168 offset:8704
	ds_read_b64 v[138:139], v168 offset:10880
	ds_read_b64 v[140:141], v168 offset:13056
	ds_read_b64 v[142:143], v168 offset:15232
	ds_read_b64 v[144:145], v168 offset:17408
	ds_read_b64 v[146:147], v168 offset:19584
	ds_read_b64 v[148:149], v168 offset:21760
	ds_read_b64 v[150:151], v168 offset:23936
	ds_read_b64 v[152:153], v168 offset:26112
	ds_read_b64 v[154:155], v168 offset:28288
	ds_read_b64 v[156:157], v168 offset:30464
	ds_read_b64 v[158:159], v168 offset:32640
	s_waitcnt lgkmcnt(7)
	v_pk_add_f32 v[164:165], v[128:129], v[144:145]
	v_pk_add_f32 v[128:129], v[128:129], v[144:145] neg_lo:[0,1] neg_hi:[0,1]
	s_waitcnt lgkmcnt(3)
	v_pk_add_f32 v[144:145], v[136:137], v[152:153]
	v_pk_add_f32 v[136:137], v[136:137], v[152:153] neg_lo:[0,1] neg_hi:[0,1]
	s_nop 0
	v_pk_add_f32 v[166:167], v[128:129], v[136:137] op_sel:[0,1] op_sel_hi:[1,0] neg_hi:[0,1]
	v_pk_add_f32 v[128:129], v[128:129], v[136:137] op_sel:[0,1] op_sel_hi:[1,0] neg_lo:[0,1]
	v_pk_add_f32 v[152:153], v[130:131], v[146:147]
	v_pk_add_f32 v[130:131], v[130:131], v[146:147] neg_lo:[0,1] neg_hi:[0,1]
	s_waitcnt lgkmcnt(2)
	v_pk_add_f32 v[146:147], v[138:139], v[154:155]
	v_pk_add_f32 v[138:139], v[138:139], v[154:155] neg_lo:[0,1] neg_hi:[0,1]
	v_pk_add_f32 v[136:137], v[164:165], v[144:145]
	v_xor_b32_e32 v155, 0x80000000, v138
	v_mov_b32_e32 v154, v139
	v_pk_add_f32 v[138:139], v[152:153], v[146:147]
	v_pk_add_f32 v[146:147], v[152:153], v[146:147] neg_lo:[0,1] neg_hi:[0,1]
	v_pk_add_f32 v[152:153], v[132:133], v[148:149]
	v_pk_add_f32 v[132:133], v[132:133], v[148:149] neg_lo:[0,1] neg_hi:[0,1]
	s_waitcnt lgkmcnt(1)
	v_pk_add_f32 v[148:149], v[140:141], v[156:157]
	v_pk_add_f32 v[140:141], v[140:141], v[156:157] neg_lo:[0,1] neg_hi:[0,1]
	v_pk_add_f32 v[144:145], v[164:165], v[144:145] neg_lo:[0,1] neg_hi:[0,1]
	v_pk_add_f32 v[164:165], v[130:131], v[154:155]
	v_pk_add_f32 v[130:131], v[130:131], v[154:155] neg_lo:[0,1] neg_hi:[0,1]
	v_xor_b32_e32 v155, 0x80000000, v140
	v_mov_b32_e32 v154, v141
	v_pk_add_f32 v[140:141], v[152:153], v[148:149]
	v_pk_add_f32 v[148:149], v[152:153], v[148:149] neg_lo:[0,1] neg_hi:[0,1]
	v_pk_add_f32 v[152:153], v[134:135], v[150:151]
	v_pk_add_f32 v[134:135], v[134:135], v[150:151] neg_lo:[0,1] neg_hi:[0,1]
	s_waitcnt lgkmcnt(0)
	v_pk_add_f32 v[150:151], v[142:143], v[158:159]
	v_pk_add_f32 v[142:143], v[142:143], v[158:159] neg_lo:[0,1] neg_hi:[0,1]
	v_pk_add_f32 v[156:157], v[132:133], v[154:155]
	v_pk_add_f32 v[132:133], v[132:133], v[154:155] neg_lo:[0,1] neg_hi:[0,1]
	v_pk_add_f32 v[158:159], v[134:135], v[142:143] op_sel:[0,1] op_sel_hi:[1,0] neg_hi:[0,1]
	v_pk_add_f32 v[134:135], v[134:135], v[142:143] op_sel:[0,1] op_sel_hi:[1,0] neg_lo:[0,1]
	v_pk_mul_f32 v[154:155], v[146:147], s[12:13] op_sel:[1,0] op_sel_hi:[0,0] neg_lo:[1,0]
	v_pk_add_f32 v[142:143], v[152:153], v[150:151]
	v_pk_fma_f32 v[146:147], v[146:147], s[12:13], v[154:155] op_sel_hi:[1,0,1] neg_lo:[0,0,1] neg_hi:[0,0,1]
	v_pk_mul_f32 v[154:155], v[130:131], s[36:37] op_sel:[1,0] op_sel_hi:[0,0] neg_lo:[1,0]
	v_pk_add_f32 v[150:151], v[152:153], v[150:151] neg_lo:[0,1] neg_hi:[0,1]
	v_pk_fma_f32 v[130:131], v[130:131], s[22:23], v[154:155] op_sel_hi:[1,0,1] neg_lo:[0,0,1] neg_hi:[0,0,1]
	v_pk_mul_f32 v[154:155], v[156:157], s[12:13] op_sel:[1,0] op_sel_hi:[0,0] neg_lo:[1,0]
	v_pk_fma_f32 v[154:155], v[156:157], s[12:13], v[154:155] op_sel_hi:[1,0,1] neg_lo:[0,0,1] neg_hi:[0,0,1]
	v_pk_fma_f32 v[148:149], v[148:149], 0, v[148:149] op_sel:[0,0,1] op_sel_hi:[1,0,0] neg_hi:[0,0,1]
	v_pk_mul_f32 v[156:157], v[132:133], s[12:13] op_sel:[1,0] op_sel_hi:[0,0] neg_lo:[1,0]
	v_pk_fma_f32 v[132:133], v[132:133], s[18:19], v[156:157] op_sel_hi:[1,0,1] neg_lo:[0,0,1] neg_hi:[0,0,1]
	v_pk_mul_f32 v[156:157], v[158:159], s[36:37] op_sel:[1,0] op_sel_hi:[0,0] neg_lo:[1,0]
	v_pk_mul_f32 v[152:153], v[164:165], s[22:23] op_sel:[1,0] op_sel_hi:[0,0] neg_lo:[1,0]
	v_pk_fma_f32 v[156:157], v[158:159], s[22:23], v[156:157] op_sel_hi:[1,0,1] neg_lo:[0,0,1] neg_hi:[0,0,1]
	v_pk_mul_f32 v[158:159], v[150:151], s[12:13] op_sel:[1,0] op_sel_hi:[0,0] neg_lo:[1,0]
	v_pk_fma_f32 v[152:153], v[164:165], s[36:37], v[152:153] op_sel_hi:[1,0,1] neg_lo:[0,0,1] neg_hi:[0,0,1]
	v_pk_fma_f32 v[150:151], v[150:151], s[18:19], v[158:159] op_sel_hi:[1,0,1] neg_lo:[0,0,1] neg_hi:[0,0,1]
	v_xor_b32_e32 v158, 0x80000000, v135
	v_mov_b32_e32 v159, v134
	v_pk_mul_f32 v[134:135], v[134:135], s[36:37] op_sel_hi:[1,0]
	s_nop 0
	v_pk_fma_f32 v[134:135], v[158:159], s[22:23], v[134:135] op_sel_hi:[1,0,1] neg_lo:[0,0,1] neg_hi:[0,0,1]
	v_pk_add_f32 v[158:159], v[136:137], v[140:141]
	v_pk_add_f32 v[136:137], v[136:137], v[140:141] neg_lo:[0,1] neg_hi:[0,1]
	v_pk_add_f32 v[140:141], v[138:139], v[142:143]
	v_pk_add_f32 v[138:139], v[138:139], v[142:143] neg_lo:[0,1] neg_hi:[0,1]
	s_nop 0
	v_xor_b32_e32 v143, 0x80000000, v138
	v_mov_b32_e32 v142, v139
	v_pk_add_f32 v[138:139], v[158:159], v[140:141]
	v_pk_add_f32 v[140:141], v[158:159], v[140:141] neg_lo:[0,1] neg_hi:[0,1]
	v_pk_add_f32 v[158:159], v[152:153], v[156:157]
	v_pk_add_f32 v[152:153], v[152:153], v[156:157] neg_lo:[0,1] neg_hi:[0,1]
	v_pk_add_f32 v[164:165], v[136:137], v[142:143]
	v_pk_add_f32 v[136:137], v[136:137], v[142:143] neg_lo:[0,1] neg_hi:[0,1]
	v_pk_add_f32 v[142:143], v[166:167], v[154:155]
	v_pk_add_f32 v[154:155], v[166:167], v[154:155] neg_lo:[0,1] neg_hi:[0,1]
	s_nop 0
	v_pk_add_f32 v[166:167], v[154:155], v[152:153] op_sel:[0,1] op_sel_hi:[1,0] neg_hi:[0,1]
	v_pk_add_f32 v[154:155], v[154:155], v[152:153] op_sel:[0,1] op_sel_hi:[1,0] neg_lo:[0,1]
	v_pk_add_f32 v[156:157], v[144:145], v[148:149]
	v_pk_add_f32 v[144:145], v[144:145], v[148:149] neg_lo:[0,1] neg_hi:[0,1]
	v_pk_add_f32 v[148:149], v[146:147], v[150:151]
	v_pk_add_f32 v[146:147], v[146:147], v[150:151] neg_lo:[0,1] neg_hi:[0,1]
	v_pk_add_f32 v[152:153], v[142:143], v[158:159]
	v_pk_add_f32 v[142:143], v[142:143], v[158:159] neg_lo:[0,1] neg_hi:[0,1]
	v_pk_add_f32 v[158:159], v[144:145], v[146:147] op_sel:[0,1] op_sel_hi:[1,0] neg_hi:[0,1]
	v_pk_add_f32 v[144:145], v[144:145], v[146:147] op_sel:[0,1] op_sel_hi:[1,0] neg_lo:[0,1]
	v_pk_add_f32 v[150:151], v[128:129], v[132:133]
	v_pk_add_f32 v[128:129], v[128:129], v[132:133] neg_lo:[0,1] neg_hi:[0,1]
	v_pk_add_f32 v[132:133], v[130:131], v[134:135]
	v_pk_add_f32 v[130:131], v[130:131], v[134:135] neg_lo:[0,1] neg_hi:[0,1]
	v_pk_add_f32 v[146:147], v[156:157], v[148:149]
	v_pk_add_f32 v[148:149], v[156:157], v[148:149] neg_lo:[0,1] neg_hi:[0,1]
	v_pk_add_f32 v[156:157], v[128:129], v[130:131] op_sel:[0,1] op_sel_hi:[1,0] neg_hi:[0,1]
	v_pk_add_f32 v[128:129], v[128:129], v[130:131] op_sel:[0,1] op_sel_hi:[1,0] neg_lo:[0,1]
	v_xor_b32_e32 v134, 0x80000000, v111
	v_mov_b32_e32 v135, v110
	v_pk_mul_f32 v[134:135], v[134:135], v[138:139] op_sel:[0,1]
	v_pk_add_f32 v[130:131], v[150:151], v[132:133]
	v_pk_fma_f32 v[110:111], v[110:111], v[138:139], v[134:135] op_sel_hi:[1,0,1]
	ds_write_b64 v168, v[110:111]
	v_pk_mul_f32 v[110:111], v[114:115], v[152:153] op_sel:[1,1] op_sel_hi:[0,1] neg_lo:[1,0]
	v_pk_add_f32 v[132:133], v[150:151], v[132:133] neg_lo:[0,1] neg_hi:[0,1]
	v_pk_fma_f32 v[110:111], v[114:115], v[152:153], v[110:111] op_sel_hi:[1,0,1]
	ds_write_b64 v168, v[110:111] offset:2176
	v_pk_mul_f32 v[110:111], v[116:117], v[146:147] op_sel:[1,1] op_sel_hi:[0,1] neg_lo:[1,0]
	v_pk_fma_f32 v[110:111], v[116:117], v[146:147], v[110:111] op_sel_hi:[1,0,1]
	ds_write_b64 v168, v[110:111] offset:4352
	v_pk_mul_f32 v[110:111], v[118:119], v[130:131] op_sel:[1,1] op_sel_hi:[0,1] neg_lo:[1,0]
	v_pk_fma_f32 v[110:111], v[118:119], v[130:131], v[110:111] op_sel_hi:[1,0,1]
	ds_write_b64 v168, v[110:111] offset:6528
	v_pk_mul_f32 v[110:111], v[120:121], v[164:165] op_sel:[1,1] op_sel_hi:[0,1] neg_lo:[1,0]
	v_pk_fma_f32 v[110:111], v[120:121], v[164:165], v[110:111] op_sel_hi:[1,0,1]
	ds_write_b64 v168, v[110:111] offset:8704
	v_pk_mul_f32 v[110:111], v[122:123], v[166:167] op_sel:[1,1] op_sel_hi:[0,1] neg_lo:[1,0]
	v_pk_fma_f32 v[110:111], v[122:123], v[166:167], v[110:111] op_sel_hi:[1,0,1]
	ds_write_b64 v168, v[110:111] offset:10880
	v_pk_mul_f32 v[110:111], v[124:125], v[158:159] op_sel:[1,1] op_sel_hi:[0,1] neg_lo:[1,0]
	v_pk_fma_f32 v[110:111], v[124:125], v[158:159], v[110:111] op_sel_hi:[1,0,1]
	ds_write_b64 v168, v[110:111] offset:13056
	v_pk_mul_f32 v[110:111], v[126:127], v[156:157] op_sel:[1,1] op_sel_hi:[0,1] neg_lo:[1,0]
	v_pk_fma_f32 v[110:111], v[126:127], v[156:157], v[110:111] op_sel_hi:[1,0,1]
	ds_write_b64 v168, v[110:111] offset:15232
	v_pk_mul_f32 v[110:111], v[112:113], v[140:141] op_sel:[1,1] op_sel_hi:[0,1] neg_lo:[1,0]
	v_pk_fma_f32 v[110:111], v[112:113], v[140:141], v[110:111] op_sel_hi:[1,0,1]
	ds_write_b64 v168, v[110:111] offset:17408
	v_pk_mul_f32 v[110:111], v[108:109], v[142:143] op_sel:[1,1] op_sel_hi:[0,1] neg_lo:[1,0]
	v_pk_fma_f32 v[108:109], v[108:109], v[142:143], v[110:111] op_sel_hi:[1,0,1]
	ds_write_b64 v168, v[108:109] offset:19584
	v_pk_mul_f32 v[108:109], v[106:107], v[148:149] op_sel:[1,1] op_sel_hi:[0,1] neg_lo:[1,0]
	v_pk_fma_f32 v[106:107], v[106:107], v[148:149], v[108:109] op_sel_hi:[1,0,1]
	ds_write_b64 v168, v[106:107] offset:21760
	v_pk_mul_f32 v[106:107], v[104:105], v[132:133] op_sel:[1,1] op_sel_hi:[0,1] neg_lo:[1,0]
	v_pk_fma_f32 v[104:105], v[104:105], v[132:133], v[106:107] op_sel_hi:[1,0,1]
	ds_write_b64 v168, v[104:105] offset:23936
	v_pk_mul_f32 v[104:105], v[14:15], v[136:137] op_sel:[1,1] op_sel_hi:[0,1] neg_lo:[1,0]
	v_pk_fma_f32 v[14:15], v[14:15], v[136:137], v[104:105] op_sel_hi:[1,0,1]
	ds_write_b64 v168, v[14:15] offset:26112
	v_pk_mul_f32 v[14:15], v[12:13], v[154:155] op_sel:[1,1] op_sel_hi:[0,1] neg_lo:[1,0]
	v_pk_fma_f32 v[12:13], v[12:13], v[154:155], v[14:15] op_sel_hi:[1,0,1]
	ds_write_b64 v168, v[12:13] offset:28288
	v_pk_mul_f32 v[12:13], v[10:11], v[144:145] op_sel:[1,1] op_sel_hi:[0,1] neg_lo:[1,0]
	v_pk_fma_f32 v[10:11], v[10:11], v[144:145], v[12:13] op_sel_hi:[1,0,1]
	ds_write_b64 v168, v[10:11] offset:30464
	v_pk_mul_f32 v[10:11], v[8:9], v[128:129] op_sel:[1,1] op_sel_hi:[0,1] neg_lo:[1,0]
	v_pk_fma_f32 v[8:9], v[8:9], v[128:129], v[10:11] op_sel_hi:[1,0,1]
	ds_write_b64 v168, v[8:9] offset:32640
	v_mov_b32_e32 v116, 1.0
	v_pk_mul_f32 v[10:11], v[210:211], v[210:211] op_sel:[1,1] op_sel_hi:[0,1] neg_lo:[1,0]
	v_mov_b32_e32 v117, v177
	v_pk_fma_f32 v[10:11], v[210:211], v[210:211], v[10:11] op_sel_hi:[0,1,1]
	v_pk_mul_f32 v[104:105], v[10:11], v[10:11] op_sel:[1,1] op_sel_hi:[1,0] neg_lo:[0,1]
	v_pk_mul_f32 v[12:13], v[210:211], v[176:177] op_sel:[1,1] op_sel_hi:[0,1] neg_lo:[1,0]
	v_pk_fma_f32 v[104:105], v[10:11], v[10:11], v[104:105] op_sel_hi:[1,0,1]
	v_pk_fma_f32 v[126:127], v[210:211], v[116:117], v[12:13] op_sel_hi:[1,0,1]
	v_pk_mul_f32 v[8:9], v[176:177], v[10:11] op_sel:[1,1] op_sel_hi:[1,0] neg_lo:[0,1]
	s_nop 0
	v_pk_fma_f32 v[124:125], v[116:117], v[10:11], v[8:9] op_sel_hi:[0,1,1]
	v_pk_mul_f32 v[8:9], v[126:127], v[10:11] op_sel:[1,1] op_sel_hi:[1,0] neg_lo:[0,1]
	v_pk_mul_f32 v[108:109], v[104:105], v[104:105] op_sel:[1,1] op_sel_hi:[1,0] neg_lo:[0,1]
	v_pk_fma_f32 v[122:123], v[10:11], v[126:127], v[8:9] op_sel_hi:[1,0,1]
	v_pk_mul_f32 v[8:9], v[176:177], v[104:105] op_sel:[1,1] op_sel_hi:[1,0] neg_lo:[0,1]
	s_nop 0
	v_pk_fma_f32 v[120:121], v[116:117], v[104:105], v[8:9] op_sel_hi:[0,1,1]
	v_pk_mul_f32 v[8:9], v[126:127], v[104:105] op_sel:[1,1] op_sel_hi:[1,0] neg_lo:[0,1]
	s_waitcnt lgkmcnt(0)
	v_pk_fma_f32 v[118:119], v[126:127], v[104:105], v[8:9] op_sel_hi:[0,1,1]
	v_pk_mul_f32 v[8:9], v[124:125], v[104:105] op_sel:[1,1] op_sel_hi:[1,0] neg_lo:[0,1]
	s_barrier
	v_pk_fma_f32 v[114:115], v[104:105], v[124:125], v[8:9] op_sel_hi:[1,0,1]
	v_pk_mul_f32 v[8:9], v[122:123], v[104:105] op_sel:[1,1] op_sel_hi:[1,0] neg_lo:[0,1]
	s_nop 0
	v_pk_fma_f32 v[112:113], v[104:105], v[122:123], v[8:9] op_sel_hi:[1,0,1]
	v_pk_fma_f32 v[8:9], v[104:105], v[104:105], v[108:109] op_sel_hi:[1,0,1]
	s_nop 0
	v_pk_mul_f32 v[10:11], v[176:177], v[8:9] op_sel:[1,1] op_sel_hi:[1,0] neg_lo:[0,1]
	s_nop 0
	v_pk_fma_f32 v[110:111], v[116:117], v[8:9], v[10:11] op_sel_hi:[0,1,1]
	v_pk_mul_f32 v[10:11], v[126:127], v[8:9] op_sel:[1,1] op_sel_hi:[1,0] neg_lo:[0,1]
	s_nop 0
	v_pk_fma_f32 v[108:109], v[126:127], v[8:9], v[10:11] op_sel_hi:[0,1,1]
	v_pk_mul_f32 v[10:11], v[124:125], v[8:9] op_sel:[1,1] op_sel_hi:[1,0] neg_lo:[0,1]
	s_nop 0
	v_pk_fma_f32 v[106:107], v[124:125], v[8:9], v[10:11] op_sel_hi:[0,1,1]
	v_pk_mul_f32 v[10:11], v[122:123], v[8:9] op_sel:[1,1] op_sel_hi:[1,0] neg_lo:[0,1]
	s_nop 0
	v_pk_fma_f32 v[104:105], v[122:123], v[8:9], v[10:11] op_sel_hi:[0,1,1]
	v_pk_mul_f32 v[10:11], v[120:121], v[8:9] op_sel:[1,1] op_sel_hi:[1,0] neg_lo:[0,1]
	s_nop 0
	v_pk_fma_f32 v[14:15], v[8:9], v[120:121], v[10:11] op_sel_hi:[1,0,1]
	v_pk_mul_f32 v[10:11], v[118:119], v[8:9] op_sel:[1,1] op_sel_hi:[1,0] neg_lo:[0,1]
	s_nop 0
	v_pk_fma_f32 v[12:13], v[8:9], v[118:119], v[10:11] op_sel_hi:[1,0,1]
	v_pk_mul_f32 v[10:11], v[114:115], v[8:9] op_sel:[1,1] op_sel_hi:[1,0] neg_lo:[0,1]
	v_pk_mul_f32 v[128:129], v[112:113], v[8:9] op_sel:[1,1] op_sel_hi:[1,0] neg_lo:[0,1]
	v_pk_fma_f32 v[10:11], v[8:9], v[114:115], v[10:11] op_sel_hi:[1,0,1]
	v_pk_fma_f32 v[8:9], v[8:9], v[112:113], v[128:129] op_sel_hi:[1,0,1]
	s_nop 0
	v_bfe_u32 v129, v206, 4, 4
	v_and_b32_e32 v128, 15, v206
	v_mul_u32_u24_e32 v129, 0x880, v129
	v_lshlrev_b32_e32 v128, 3, v128
	v_add3_u32 v176, v207, v129, v128
	ds_read2_b64 v[128:131], v176 offset1:17
	ds_read2_b64 v[132:135], v176 offset0:34 offset1:51
	ds_read2_b64 v[136:139], v176 offset0:68 offset1:85
	ds_read2_b64 v[140:143], v176 offset0:136 offset1:153
	ds_read2_b64 v[144:147], v176 offset0:102 offset1:119
	ds_read2_b64 v[148:151], v176 offset0:204 offset1:221
	ds_read2_b64 v[152:155], v176 offset0:170 offset1:187
	ds_read2_b64 v[156:159], v176 offset0:238 offset1:255
	s_waitcnt lgkmcnt(4)
	v_pk_add_f32 v[164:165], v[128:129], v[140:141]
	v_pk_add_f32 v[128:129], v[128:129], v[140:141] neg_lo:[0,1] neg_hi:[0,1]
	s_waitcnt lgkmcnt(2)
	v_pk_add_f32 v[140:141], v[136:137], v[148:149]
	v_pk_add_f32 v[136:137], v[136:137], v[148:149] neg_lo:[0,1] neg_hi:[0,1]
	s_nop 0
	v_pk_add_f32 v[166:167], v[128:129], v[136:137] op_sel:[0,1] op_sel_hi:[1,0] neg_hi:[0,1]
	v_pk_add_f32 v[128:129], v[128:129], v[136:137] op_sel:[0,1] op_sel_hi:[1,0] neg_lo:[0,1]
	v_pk_add_f32 v[148:149], v[130:131], v[142:143]
	v_pk_add_f32 v[130:131], v[130:131], v[142:143] neg_lo:[0,1] neg_hi:[0,1]
	v_pk_add_f32 v[142:143], v[138:139], v[150:151]
	v_pk_add_f32 v[138:139], v[138:139], v[150:151] neg_lo:[0,1] neg_hi:[0,1]
	v_pk_add_f32 v[136:137], v[164:165], v[140:141]
	v_pk_add_f32 v[140:141], v[164:165], v[140:141] neg_lo:[0,1] neg_hi:[0,1]
	v_pk_add_f32 v[164:165], v[130:131], v[138:139] op_sel:[0,1] op_sel_hi:[1,0] neg_hi:[0,1]
	v_pk_add_f32 v[130:131], v[130:131], v[138:139] op_sel:[0,1] op_sel_hi:[1,0] neg_lo:[0,1]
	s_waitcnt lgkmcnt(0)
	v_pk_add_f32 v[150:151], v[144:145], v[156:157]
	v_pk_add_f32 v[144:145], v[144:145], v[156:157] neg_lo:[0,1] neg_hi:[0,1]
	v_pk_add_f32 v[138:139], v[148:149], v[142:143]
	v_pk_add_f32 v[142:143], v[148:149], v[142:143] neg_lo:[0,1] neg_hi:[0,1]
	v_pk_add_f32 v[148:149], v[132:133], v[152:153]
	v_pk_add_f32 v[132:133], v[132:133], v[152:153] neg_lo:[0,1] neg_hi:[0,1]
	s_nop 0
	v_pk_add_f32 v[156:157], v[132:133], v[144:145] op_sel:[0,1] op_sel_hi:[1,0] neg_hi:[0,1]
	v_pk_add_f32 v[132:133], v[132:133], v[144:145] op_sel:[0,1] op_sel_hi:[1,0] neg_lo:[0,1]
	v_pk_add_f32 v[152:153], v[146:147], v[158:159]
	v_pk_add_f32 v[146:147], v[146:147], v[158:159] neg_lo:[0,1] neg_hi:[0,1]
	v_pk_add_f32 v[144:145], v[148:149], v[150:151]
	v_pk_add_f32 v[148:149], v[148:149], v[150:151] neg_lo:[0,1] neg_hi:[0,1]
	v_pk_add_f32 v[150:151], v[134:135], v[154:155]
	v_pk_add_f32 v[134:135], v[134:135], v[154:155] neg_lo:[0,1] neg_hi:[0,1]
	s_nop 0
	v_pk_add_f32 v[158:159], v[134:135], v[146:147] op_sel:[0,1] op_sel_hi:[1,0] neg_hi:[0,1]
	v_pk_add_f32 v[134:135], v[134:135], v[146:147] op_sel:[0,1] op_sel_hi:[1,0] neg_lo:[0,1]
	v_pk_mul_f32 v[154:155], v[142:143], s[12:13] op_sel:[1,0] op_sel_hi:[0,0] neg_lo:[1,0]
	v_pk_add_f32 v[146:147], v[150:151], v[152:153]
	v_pk_fma_f32 v[142:143], v[142:143], s[12:13], v[154:155] op_sel_hi:[1,0,1] neg_lo:[0,0,1] neg_hi:[0,0,1]
	v_pk_mul_f32 v[154:155], v[130:131], s[36:37] op_sel:[1,0] op_sel_hi:[0,0] neg_lo:[1,0]
	v_pk_add_f32 v[150:151], v[150:151], v[152:153] neg_lo:[0,1] neg_hi:[0,1]
	v_pk_fma_f32 v[130:131], v[130:131], s[22:23], v[154:155] op_sel_hi:[1,0,1] neg_lo:[0,0,1] neg_hi:[0,0,1]
	v_pk_mul_f32 v[154:155], v[156:157], s[12:13] op_sel:[1,0] op_sel_hi:[0,0] neg_lo:[1,0]
	v_pk_fma_f32 v[154:155], v[156:157], s[12:13], v[154:155] op_sel_hi:[1,0,1] neg_lo:[0,0,1] neg_hi:[0,0,1]
	v_pk_fma_f32 v[148:149], v[148:149], 0, v[148:149] op_sel:[0,0,1] op_sel_hi:[1,0,0] neg_hi:[0,0,1]
	v_pk_mul_f32 v[156:157], v[132:133], s[12:13] op_sel:[1,0] op_sel_hi:[0,0] neg_lo:[1,0]
	v_pk_fma_f32 v[132:133], v[132:133], s[18:19], v[156:157] op_sel_hi:[1,0,1] neg_lo:[0,0,1] neg_hi:[0,0,1]
	v_pk_mul_f32 v[156:157], v[158:159], s[36:37] op_sel:[1,0] op_sel_hi:[0,0] neg_lo:[1,0]
	v_pk_mul_f32 v[152:153], v[164:165], s[22:23] op_sel:[1,0] op_sel_hi:[0,0] neg_lo:[1,0]
	v_pk_fma_f32 v[156:157], v[158:159], s[22:23], v[156:157] op_sel_hi:[1,0,1] neg_lo:[0,0,1] neg_hi:[0,0,1]
	v_pk_mul_f32 v[158:159], v[150:151], s[12:13] op_sel:[1,0] op_sel_hi:[0,0] neg_lo:[1,0]
	v_pk_fma_f32 v[152:153], v[164:165], s[36:37], v[152:153] op_sel_hi:[1,0,1] neg_lo:[0,0,1] neg_hi:[0,0,1]
	v_pk_fma_f32 v[150:151], v[150:151], s[18:19], v[158:159] op_sel_hi:[1,0,1] neg_lo:[0,0,1] neg_hi:[0,0,1]
	v_xor_b32_e32 v158, 0x80000000, v135
	v_mov_b32_e32 v159, v134
	v_pk_mul_f32 v[134:135], v[134:135], s[36:37] op_sel_hi:[1,0]
	s_nop 0
	v_pk_fma_f32 v[134:135], v[158:159], s[22:23], v[134:135] op_sel_hi:[1,0,1] neg_lo:[0,0,1] neg_hi:[0,0,1]
	v_pk_add_f32 v[158:159], v[136:137], v[144:145]
	v_pk_add_f32 v[136:137], v[136:137], v[144:145] neg_lo:[0,1] neg_hi:[0,1]
	v_pk_add_f32 v[144:145], v[138:139], v[146:147]
	v_pk_add_f32 v[138:139], v[138:139], v[146:147] neg_lo:[0,1] neg_hi:[0,1]
	s_nop 0
	v_xor_b32_e32 v147, 0x80000000, v138
	v_mov_b32_e32 v146, v139
	v_pk_add_f32 v[138:139], v[158:159], v[144:145]
	v_pk_add_f32 v[164:165], v[136:137], v[146:147]
	v_pk_add_f32 v[144:145], v[158:159], v[144:145] neg_lo:[0,1] neg_hi:[0,1]
	v_pk_add_f32 v[146:147], v[136:137], v[146:147] neg_lo:[0,1] neg_hi:[0,1]
	v_pk_add_f32 v[136:137], v[166:167], v[154:155]
	v_pk_add_f32 v[158:159], v[152:153], v[156:157]
	v_pk_add_f32 v[152:153], v[152:153], v[156:157] neg_lo:[0,1] neg_hi:[0,1]
	v_pk_add_f32 v[154:155], v[166:167], v[154:155] neg_lo:[0,1] neg_hi:[0,1]
	v_xor_b32_e32 v157, 0x80000000, v152
	v_mov_b32_e32 v156, v153
	v_pk_add_f32 v[152:153], v[136:137], v[158:159]
	v_pk_add_f32 v[168:169], v[136:137], v[158:159] neg_lo:[0,1] neg_hi:[0,1]
	v_pk_add_f32 v[136:137], v[140:141], v[148:149]
	v_pk_add_f32 v[140:141], v[140:141], v[148:149] neg_lo:[0,1] neg_hi:[0,1]
	v_pk_add_f32 v[148:149], v[142:143], v[150:151]
	v_pk_add_f32 v[166:167], v[154:155], v[156:157]
	v_pk_add_f32 v[170:171], v[154:155], v[156:157] neg_lo:[0,1] neg_hi:[0,1]
	v_pk_add_f32 v[142:143], v[142:143], v[150:151] neg_lo:[0,1] neg_hi:[0,1]
	v_pk_add_f32 v[154:155], v[136:137], v[148:149]
	v_pk_add_f32 v[148:149], v[136:137], v[148:149] neg_lo:[0,1] neg_hi:[0,1]
	v_pk_add_f32 v[136:137], v[128:129], v[132:133]
	v_pk_add_f32 v[128:129], v[128:129], v[132:133] neg_lo:[0,1] neg_hi:[0,1]
	v_pk_add_f32 v[132:133], v[130:131], v[134:135]
	v_pk_add_f32 v[130:131], v[130:131], v[134:135] neg_lo:[0,1] neg_hi:[0,1]
	v_xor_b32_e32 v151, 0x80000000, v142
	v_mov_b32_e32 v150, v143
	v_xor_b32_e32 v135, 0x80000000, v130
	v_mov_b32_e32 v134, v131
	v_xor_b32_e32 v142, 0x80000000, v117
	v_mov_b32_e32 v143, v116
	v_pk_add_f32 v[172:173], v[140:141], v[150:151]
	v_pk_add_f32 v[174:175], v[140:141], v[150:151] neg_lo:[0,1] neg_hi:[0,1]
	v_pk_add_f32 v[130:131], v[136:137], v[132:133]
	v_pk_add_f32 v[150:151], v[128:129], v[134:135]
	v_pk_add_f32 v[198:199], v[136:137], v[132:133] neg_lo:[0,1] neg_hi:[0,1]
	v_pk_add_f32 v[200:201], v[128:129], v[134:135] neg_lo:[0,1] neg_hi:[0,1]
	v_pk_mul_f32 v[128:129], v[142:143], v[138:139] op_sel:[0,1]
	v_pk_mul_f32 v[132:133], v[126:127], v[152:153] op_sel:[1,1] op_sel_hi:[0,1] neg_lo:[1,0]
	v_pk_fma_f32 v[128:129], v[116:117], v[138:139], v[128:129] op_sel_hi:[1,0,1]
	v_pk_fma_f32 v[132:133], v[126:127], v[152:153], v[132:133] op_sel_hi:[1,0,1]
	ds_write2_b64 v176, v[128:129], v[132:133] offset1:17
	v_pk_mul_f32 v[128:129], v[124:125], v[154:155] op_sel:[1,1] op_sel_hi:[0,1] neg_lo:[1,0]
	v_pk_mul_f32 v[132:133], v[122:123], v[130:131] op_sel:[1,1] op_sel_hi:[0,1] neg_lo:[1,0]
	v_pk_fma_f32 v[128:129], v[124:125], v[154:155], v[128:129] op_sel_hi:[1,0,1]
	v_pk_fma_f32 v[130:131], v[122:123], v[130:131], v[132:133] op_sel_hi:[1,0,1]
	ds_write2_b64 v176, v[128:129], v[130:131] offset0:34 offset1:51
	v_pk_mul_f32 v[128:129], v[120:121], v[164:165] op_sel:[1,1] op_sel_hi:[0,1] neg_lo:[1,0]
	v_pk_mul_f32 v[130:131], v[118:119], v[166:167] op_sel:[1,1] op_sel_hi:[0,1] neg_lo:[1,0]
	v_pk_fma_f32 v[128:129], v[120:121], v[164:165], v[128:129] op_sel_hi:[1,0,1]
	v_pk_fma_f32 v[130:131], v[118:119], v[166:167], v[130:131] op_sel_hi:[1,0,1]
	ds_write2_b64 v176, v[128:129], v[130:131] offset0:68 offset1:85
	v_pk_mul_f32 v[128:129], v[114:115], v[172:173] op_sel:[1,1] op_sel_hi:[0,1] neg_lo:[1,0]
	v_pk_mul_f32 v[130:131], v[112:113], v[150:151] op_sel:[1,1] op_sel_hi:[0,1] neg_lo:[1,0]
	v_pk_fma_f32 v[128:129], v[114:115], v[172:173], v[128:129] op_sel_hi:[1,0,1]
	v_pk_fma_f32 v[130:131], v[112:113], v[150:151], v[130:131] op_sel_hi:[1,0,1]
	ds_write2_b64 v176, v[128:129], v[130:131] offset0:102 offset1:119
	v_pk_mul_f32 v[128:129], v[110:111], v[144:145] op_sel:[1,1] op_sel_hi:[0,1] neg_lo:[1,0]
	v_pk_mul_f32 v[130:131], v[108:109], v[168:169] op_sel:[1,1] op_sel_hi:[0,1] neg_lo:[1,0]
	v_pk_fma_f32 v[128:129], v[110:111], v[144:145], v[128:129] op_sel_hi:[1,0,1]
	v_pk_fma_f32 v[130:131], v[108:109], v[168:169], v[130:131] op_sel_hi:[1,0,1]
	ds_write2_b64 v176, v[128:129], v[130:131] offset0:136 offset1:153
	v_pk_mul_f32 v[128:129], v[106:107], v[148:149] op_sel:[1,1] op_sel_hi:[0,1] neg_lo:[1,0]
	v_pk_fma_f32 v[128:129], v[106:107], v[148:149], v[128:129] op_sel_hi:[1,0,1]
	v_pk_mul_f32 v[130:131], v[104:105], v[198:199] op_sel:[1,1] op_sel_hi:[0,1] neg_lo:[1,0]
	v_pk_fma_f32 v[130:131], v[104:105], v[198:199], v[130:131] op_sel_hi:[1,0,1]
	ds_write2_b64 v176, v[128:129], v[130:131] offset0:170 offset1:187
	v_pk_mul_f32 v[128:129], v[14:15], v[146:147] op_sel:[1,1] op_sel_hi:[0,1] neg_lo:[1,0]
	v_pk_fma_f32 v[128:129], v[14:15], v[146:147], v[128:129] op_sel_hi:[1,0,1]
	v_pk_mul_f32 v[144:145], v[12:13], v[170:171] op_sel:[1,1] op_sel_hi:[0,1] neg_lo:[1,0]
	v_pk_fma_f32 v[144:145], v[12:13], v[170:171], v[144:145] op_sel_hi:[1,0,1]
	ds_write2_b64 v176, v[128:129], v[144:145] offset0:204 offset1:221
	v_pk_mul_f32 v[144:145], v[10:11], v[174:175] op_sel:[1,1] op_sel_hi:[0,1] neg_lo:[1,0]
	v_pk_fma_f32 v[164:165], v[10:11], v[174:175], v[144:145] op_sel_hi:[1,0,1]
	v_pk_mul_f32 v[166:167], v[8:9], v[200:201] op_sel:[1,1] op_sel_hi:[0,1] neg_lo:[1,0]
	v_pk_fma_f32 v[166:167], v[8:9], v[200:201], v[166:167] op_sel_hi:[1,0,1]
	ds_write2_b64 v176, v[164:165], v[166:167] offset0:238 offset1:255
	s_waitcnt lgkmcnt(0)
	s_barrier
	s_nop 0
	v_and_b32_e32 v129, 0xff, v206
	v_mad_u32_u24 v129, v129, s19, v207
	ds_read2_b64 v[164:167], v129 offset1:1
	ds_read2_b64 v[168:171], v129 offset0:2 offset1:3
	ds_read2_b64 v[172:175], v129 offset0:8 offset1:9
	ds_read2_b64 v[198:201], v129 offset0:4 offset1:5
	ds_read2_b64 v[202:205], v129 offset0:6 offset1:7
	ds_read2_b64 v[232:235], v129 offset0:12 offset1:13
	ds_read2_b64 v[236:239], v129 offset0:10 offset1:11
	ds_read2_b64 v[240:243], v129 offset0:14 offset1:15
	s_waitcnt lgkmcnt(5)
	v_pk_add_f32 v[244:245], v[164:165], v[172:173]
	v_pk_add_f32 v[164:165], v[164:165], v[172:173] neg_lo:[0,1] neg_hi:[0,1]
	s_waitcnt lgkmcnt(2)
	v_pk_add_f32 v[172:173], v[198:199], v[232:233]
	v_pk_add_f32 v[198:199], v[198:199], v[232:233] neg_lo:[0,1] neg_hi:[0,1]
	s_nop 0
	v_pk_add_f32 v[246:247], v[164:165], v[198:199] op_sel:[0,1] op_sel_hi:[1,0] neg_hi:[0,1]
	v_pk_add_f32 v[164:165], v[164:165], v[198:199] op_sel:[0,1] op_sel_hi:[1,0] neg_lo:[0,1]
	v_pk_add_f32 v[232:233], v[166:167], v[174:175]
	v_pk_add_f32 v[166:167], v[166:167], v[174:175] neg_lo:[0,1] neg_hi:[0,1]
	v_pk_add_f32 v[174:175], v[200:201], v[234:235]
	v_pk_add_f32 v[200:201], v[200:201], v[234:235] neg_lo:[0,1] neg_hi:[0,1]
	v_pk_add_f32 v[198:199], v[244:245], v[172:173]
	v_pk_add_f32 v[172:173], v[244:245], v[172:173] neg_lo:[0,1] neg_hi:[0,1]
	v_pk_add_f32 v[244:245], v[166:167], v[200:201] op_sel:[0,1] op_sel_hi:[1,0] neg_hi:[0,1]
	v_pk_add_f32 v[166:167], v[166:167], v[200:201] op_sel:[0,1] op_sel_hi:[1,0] neg_lo:[0,1]
	s_waitcnt lgkmcnt(0)
	v_pk_add_f32 v[234:235], v[202:203], v[240:241]
	v_pk_add_f32 v[202:203], v[202:203], v[240:241] neg_lo:[0,1] neg_hi:[0,1]
	v_pk_add_f32 v[200:201], v[232:233], v[174:175]
	v_pk_add_f32 v[174:175], v[232:233], v[174:175] neg_lo:[0,1] neg_hi:[0,1]
	v_pk_add_f32 v[232:233], v[168:169], v[236:237]
	v_pk_add_f32 v[168:169], v[168:169], v[236:237] neg_lo:[0,1] neg_hi:[0,1]
	s_nop 0
	v_pk_add_f32 v[240:241], v[168:169], v[202:203] op_sel:[0,1] op_sel_hi:[1,0] neg_hi:[0,1]
	v_pk_add_f32 v[168:169], v[168:169], v[202:203] op_sel:[0,1] op_sel_hi:[1,0] neg_lo:[0,1]
	v_pk_add_f32 v[236:237], v[204:205], v[242:243]
	v_pk_add_f32 v[204:205], v[204:205], v[242:243] neg_lo:[0,1] neg_hi:[0,1]
	v_pk_add_f32 v[202:203], v[232:233], v[234:235]
	v_pk_add_f32 v[232:233], v[232:233], v[234:235] neg_lo:[0,1] neg_hi:[0,1]
	v_pk_add_f32 v[234:235], v[170:171], v[238:239]
	v_pk_add_f32 v[170:171], v[170:171], v[238:239] neg_lo:[0,1] neg_hi:[0,1]
	s_nop 0
	v_pk_add_f32 v[242:243], v[170:171], v[204:205] op_sel:[0,1] op_sel_hi:[1,0] neg_hi:[0,1]
	v_pk_add_f32 v[170:171], v[170:171], v[204:205] op_sel:[0,1] op_sel_hi:[1,0] neg_lo:[0,1]
	v_pk_mul_f32 v[238:239], v[174:175], s[12:13] op_sel:[1,0] op_sel_hi:[0,0] neg_lo:[1,0]
	v_pk_add_f32 v[204:205], v[234:235], v[236:237]
	v_pk_fma_f32 v[174:175], v[174:175], s[12:13], v[238:239] op_sel_hi:[1,0,1] neg_lo:[0,0,1] neg_hi:[0,0,1]
	v_pk_mul_f32 v[238:239], v[166:167], s[36:37] op_sel:[1,0] op_sel_hi:[0,0] neg_lo:[1,0]
	v_pk_add_f32 v[234:235], v[234:235], v[236:237] neg_lo:[0,1] neg_hi:[0,1]
	v_pk_fma_f32 v[166:167], v[166:167], s[22:23], v[238:239] op_sel_hi:[1,0,1] neg_lo:[0,0,1] neg_hi:[0,0,1]
	v_pk_mul_f32 v[238:239], v[240:241], s[12:13] op_sel:[1,0] op_sel_hi:[0,0] neg_lo:[1,0]
	v_pk_fma_f32 v[238:239], v[240:241], s[12:13], v[238:239] op_sel_hi:[1,0,1] neg_lo:[0,0,1] neg_hi:[0,0,1]
	v_pk_fma_f32 v[232:233], v[232:233], 0, v[232:233] op_sel:[0,0,1] op_sel_hi:[1,0,0] neg_hi:[0,0,1]
	v_pk_mul_f32 v[240:241], v[168:169], s[12:13] op_sel:[1,0] op_sel_hi:[0,0] neg_lo:[1,0]
	v_pk_fma_f32 v[168:169], v[168:169], s[18:19], v[240:241] op_sel_hi:[1,0,1] neg_lo:[0,0,1] neg_hi:[0,0,1]
	v_pk_mul_f32 v[240:241], v[242:243], s[36:37] op_sel:[1,0] op_sel_hi:[0,0] neg_lo:[1,0]
	v_pk_mul_f32 v[236:237], v[244:245], s[22:23] op_sel:[1,0] op_sel_hi:[0,0] neg_lo:[1,0]
	v_pk_fma_f32 v[240:241], v[242:243], s[22:23], v[240:241] op_sel_hi:[1,0,1] neg_lo:[0,0,1] neg_hi:[0,0,1]
	v_pk_mul_f32 v[242:243], v[234:235], s[12:13] op_sel:[1,0] op_sel_hi:[0,0] neg_lo:[1,0]
	v_pk_fma_f32 v[236:237], v[244:245], s[36:37], v[236:237] op_sel_hi:[1,0,1] neg_lo:[0,0,1] neg_hi:[0,0,1]
	v_pk_fma_f32 v[234:235], v[234:235], s[18:19], v[242:243] op_sel_hi:[1,0,1] neg_lo:[0,0,1] neg_hi:[0,0,1]
	v_xor_b32_e32 v242, 0x80000000, v171
	v_mov_b32_e32 v243, v170
	v_pk_mul_f32 v[170:171], v[170:171], s[36:37] op_sel_hi:[1,0]
	s_nop 0
	v_pk_fma_f32 v[170:171], v[242:243], s[22:23], v[170:171] op_sel_hi:[1,0,1] neg_lo:[0,0,1] neg_hi:[0,0,1]
	v_pk_add_f32 v[242:243], v[198:199], v[202:203]
	v_pk_add_f32 v[198:199], v[198:199], v[202:203] neg_lo:[0,1] neg_hi:[0,1]
	v_pk_add_f32 v[202:203], v[200:201], v[204:205]
	v_pk_add_f32 v[200:201], v[200:201], v[204:205] neg_lo:[0,1] neg_hi:[0,1]
	s_nop 0
	v_xor_b32_e32 v205, 0x80000000, v200
	v_mov_b32_e32 v204, v201
	v_pk_add_f32 v[200:201], v[242:243], v[202:203]
	v_pk_add_f32 v[202:203], v[242:243], v[202:203] neg_lo:[0,1] neg_hi:[0,1]
	v_pk_add_f32 v[242:243], v[236:237], v[240:241]
	v_pk_add_f32 v[236:237], v[236:237], v[240:241] neg_lo:[0,1] neg_hi:[0,1]
	v_pk_add_f32 v[244:245], v[198:199], v[204:205]
	v_pk_add_f32 v[198:199], v[198:199], v[204:205] neg_lo:[0,1] neg_hi:[0,1]
	v_pk_add_f32 v[204:205], v[246:247], v[238:239]
	v_pk_add_f32 v[238:239], v[246:247], v[238:239] neg_lo:[0,1] neg_hi:[0,1]
	s_nop 0
	v_pk_add_f32 v[246:247], v[238:239], v[236:237] op_sel:[0,1] op_sel_hi:[1,0] neg_hi:[0,1]
	v_pk_add_f32 v[238:239], v[238:239], v[236:237] op_sel:[0,1] op_sel_hi:[1,0] neg_lo:[0,1]
	v_pk_add_f32 v[240:241], v[172:173], v[232:233]
	v_pk_add_f32 v[172:173], v[172:173], v[232:233] neg_lo:[0,1] neg_hi:[0,1]
	v_pk_add_f32 v[232:233], v[174:175], v[234:235]
	v_pk_add_f32 v[174:175], v[174:175], v[234:235] neg_lo:[0,1] neg_hi:[0,1]
	v_pk_add_f32 v[236:237], v[204:205], v[242:243]
	v_pk_add_f32 v[204:205], v[204:205], v[242:243] neg_lo:[0,1] neg_hi:[0,1]
	v_pk_add_f32 v[242:243], v[172:173], v[174:175] op_sel:[0,1] op_sel_hi:[1,0] neg_hi:[0,1]
	v_pk_add_f32 v[172:173], v[172:173], v[174:175] op_sel:[0,1] op_sel_hi:[1,0] neg_lo:[0,1]
	v_pk_add_f32 v[234:235], v[164:165], v[168:169]
	v_pk_add_f32 v[164:165], v[164:165], v[168:169] neg_lo:[0,1] neg_hi:[0,1]
	v_pk_add_f32 v[168:169], v[166:167], v[170:171]
	v_pk_add_f32 v[166:167], v[166:167], v[170:171] neg_lo:[0,1] neg_hi:[0,1]
	v_pk_add_f32 v[174:175], v[240:241], v[232:233]
	v_pk_add_f32 v[232:233], v[240:241], v[232:233] neg_lo:[0,1] neg_hi:[0,1]
	v_pk_add_f32 v[240:241], v[164:165], v[166:167] op_sel:[0,1] op_sel_hi:[1,0] neg_hi:[0,1]
	v_pk_add_f32 v[164:165], v[164:165], v[166:167] op_sel:[0,1] op_sel_hi:[1,0] neg_lo:[0,1]
	v_pk_mul_f32 v[170:171], v[66:67], v[200:201] op_sel:[0,1]
	v_pk_add_f32 v[166:167], v[234:235], v[168:169]
	v_pk_fma_f32 v[170:171], v[16:17], v[200:201], v[170:171] op_sel_hi:[1,0,1]
	v_pk_mul_f32 v[200:201], v[68:69], v[244:245] op_sel:[0,1]
	v_pk_add_f32 v[168:169], v[234:235], v[168:169] neg_lo:[0,1] neg_hi:[0,1]
	v_pk_fma_f32 v[200:201], v[18:19], v[244:245], v[200:201] op_sel_hi:[1,0,1]
	v_pk_mul_f32 v[244:245], v[78:79], v[204:205] op_sel:[0,1]
	v_pk_mul_f32 v[234:235], v[70:71], v[202:203] op_sel:[0,1]
	v_pk_fma_f32 v[204:205], v[46:47], v[204:205], v[244:245] op_sel_hi:[1,0,1]
	v_pk_mul_f32 v[244:245], v[80:81], v[238:239] op_sel:[0,1]
	v_pk_fma_f32 v[202:203], v[20:21], v[202:203], v[234:235] op_sel_hi:[1,0,1]
	v_pk_fma_f32 v[238:239], v[48:49], v[238:239], v[244:245] op_sel_hi:[1,0,1]
	v_pk_mul_f32 v[244:245], v[82:83], v[174:175] op_sel:[0,1]
	v_pk_mul_f32 v[234:235], v[72:73], v[198:199] op_sel:[0,1]
	v_pk_fma_f32 v[174:175], v[50:51], v[174:175], v[244:245] op_sel_hi:[1,0,1]
	v_pk_mul_f32 v[244:245], v[84:85], v[242:243] op_sel:[0,1]
	v_pk_fma_f32 v[198:199], v[22:23], v[198:199], v[234:235] op_sel_hi:[1,0,1]
	v_pk_fma_f32 v[242:243], v[52:53], v[242:243], v[244:245] op_sel_hi:[1,0,1]
	v_pk_mul_f32 v[244:245], v[86:87], v[232:233] op_sel:[0,1]
	v_pk_mul_f32 v[234:235], v[74:75], v[236:237] op_sel:[0,1]
	v_pk_fma_f32 v[232:233], v[54:55], v[232:233], v[244:245] op_sel_hi:[1,0,1]
	v_pk_mul_f32 v[244:245], v[88:89], v[172:173] op_sel:[0,1]
	v_pk_fma_f32 v[234:235], v[42:43], v[236:237], v[234:235] op_sel_hi:[1,0,1]
	v_pk_fma_f32 v[172:173], v[56:57], v[172:173], v[244:245] op_sel_hi:[1,0,1]
	v_pk_mul_f32 v[244:245], v[90:91], v[166:167] op_sel:[0,1]
	v_pk_mul_f32 v[236:237], v[76:77], v[246:247] op_sel:[0,1]
	v_pk_fma_f32 v[166:167], v[58:59], v[166:167], v[244:245] op_sel_hi:[1,0,1]
	v_pk_mul_f32 v[244:245], v[92:93], v[240:241] op_sel:[0,1]
	v_pk_fma_f32 v[236:237], v[44:45], v[246:247], v[236:237] op_sel_hi:[1,0,1]
	v_pk_fma_f32 v[240:241], v[60:61], v[240:241], v[244:245] op_sel_hi:[1,0,1]
	v_pk_mul_f32 v[244:245], v[94:95], v[168:169] op_sel:[0,1]
	s_nop 0
	v_pk_fma_f32 v[168:169], v[62:63], v[168:169], v[244:245] op_sel_hi:[1,0,1]
	v_pk_mul_f32 v[244:245], v[96:97], v[164:165] op_sel:[0,1]
	s_nop 0
	v_pk_fma_f32 v[164:165], v[64:65], v[164:165], v[244:245] op_sel_hi:[1,0,1]
	v_pk_add_f32 v[244:245], v[170:171], v[202:203]
	v_pk_add_f32 v[170:171], v[170:171], v[202:203] neg_lo:[0,1] neg_hi:[0,1]
	v_pk_add_f32 v[202:203], v[200:201], v[198:199]
	v_pk_add_f32 v[198:199], v[200:201], v[198:199] neg_lo:[0,1] neg_hi:[0,1]
	s_nop 0
	v_pk_add_f32 v[246:247], v[170:171], v[198:199] op_sel:[0,1] op_sel_hi:[1,0] neg_lo:[0,1]
	v_pk_add_f32 v[170:171], v[170:171], v[198:199] op_sel:[0,1] op_sel_hi:[1,0] neg_hi:[0,1]
	v_pk_add_f32 v[200:201], v[234:235], v[204:205]
	v_pk_add_f32 v[204:205], v[234:235], v[204:205] neg_lo:[0,1] neg_hi:[0,1]
	v_pk_add_f32 v[234:235], v[236:237], v[238:239]
	v_pk_add_f32 v[236:237], v[236:237], v[238:239] neg_lo:[0,1] neg_hi:[0,1]
	v_pk_add_f32 v[198:199], v[244:245], v[202:203]
	v_xor_b32_e32 v238, 0x80000000, v237
	v_mov_b32_e32 v239, v236
	v_pk_add_f32 v[236:237], v[200:201], v[234:235]
	v_pk_add_f32 v[200:201], v[200:201], v[234:235] neg_lo:[0,1] neg_hi:[0,1]
	v_pk_add_f32 v[234:235], v[174:175], v[232:233]
	v_pk_add_f32 v[174:175], v[174:175], v[232:233] neg_lo:[0,1] neg_hi:[0,1]
	v_pk_add_f32 v[232:233], v[242:243], v[172:173]
	v_pk_add_f32 v[172:173], v[242:243], v[172:173] neg_lo:[0,1] neg_hi:[0,1]
	v_pk_add_f32 v[202:203], v[244:245], v[202:203] neg_lo:[0,1] neg_hi:[0,1]
	v_pk_add_f32 v[244:245], v[204:205], v[238:239]
	v_pk_add_f32 v[204:205], v[204:205], v[238:239] neg_lo:[0,1] neg_hi:[0,1]
	v_xor_b32_e32 v238, 0x80000000, v173
	v_mov_b32_e32 v239, v172
	v_pk_add_f32 v[172:173], v[234:235], v[232:233]
	v_pk_add_f32 v[232:233], v[234:235], v[232:233] neg_lo:[0,1] neg_hi:[0,1]
	v_pk_add_f32 v[234:235], v[166:167], v[168:169]
	v_pk_add_f32 v[166:167], v[166:167], v[168:169] neg_lo:[0,1] neg_hi:[0,1]
	v_pk_add_f32 v[168:169], v[240:241], v[164:165]
	v_pk_add_f32 v[164:165], v[240:241], v[164:165] neg_lo:[0,1] neg_hi:[0,1]
	v_pk_add_f32 v[242:243], v[174:175], v[238:239]
	v_pk_add_f32 v[174:175], v[174:175], v[238:239] neg_lo:[0,1] neg_hi:[0,1]
	v_pk_add_f32 v[240:241], v[166:167], v[164:165] op_sel:[0,1] op_sel_hi:[1,0] neg_lo:[0,1]
	v_pk_add_f32 v[166:167], v[166:167], v[164:165] op_sel:[0,1] op_sel_hi:[1,0] neg_hi:[0,1]
	v_pk_mul_f32 v[238:239], v[200:201], s[12:13] op_sel:[1,0] op_sel_hi:[0,0] neg_lo:[1,0]
	v_pk_add_f32 v[164:165], v[234:235], v[168:169]
	v_pk_fma_f32 v[200:201], v[200:201], s[12:13], v[238:239] op_sel_hi:[1,0,1]
	v_pk_mul_f32 v[238:239], v[204:205], s[36:37] op_sel:[1,0] op_sel_hi:[0,0] neg_lo:[1,0]
	v_pk_add_f32 v[168:169], v[234:235], v[168:169] neg_lo:[0,1] neg_hi:[0,1]
	v_pk_fma_f32 v[204:205], v[204:205], s[22:23], v[238:239] op_sel_hi:[1,0,1]
	v_pk_mul_f32 v[238:239], v[242:243], s[12:13] op_sel:[1,0] op_sel_hi:[0,0] neg_lo:[1,0]
	v_pk_fma_f32 v[238:239], v[242:243], s[12:13], v[238:239] op_sel_hi:[1,0,1]
	v_pk_fma_f32 v[232:233], v[232:233], 0, v[232:233] op_sel:[0,0,1] op_sel_hi:[1,0,0] neg_lo:[0,0,1]
	v_xor_b32_e32 v242, 0x80000000, v175
	v_mov_b32_e32 v243, v174
	v_pk_mul_f32 v[174:175], v[174:175], s[12:13] op_sel_hi:[1,0]
	s_nop 0
	v_pk_fma_f32 v[174:175], v[242:243], s[12:13], v[174:175] op_sel_hi:[1,0,1] neg_lo:[0,0,1] neg_hi:[0,0,1]
	v_pk_mul_f32 v[242:243], v[240:241], s[36:37] op_sel:[1,0] op_sel_hi:[0,0] neg_lo:[1,0]
	v_pk_mul_f32 v[234:235], v[244:245], s[22:23] op_sel:[1,0] op_sel_hi:[0,0] neg_lo:[1,0]
	v_pk_fma_f32 v[240:241], v[240:241], s[22:23], v[242:243] op_sel_hi:[1,0,1]
	v_xor_b32_e32 v242, 0x80000000, v169
	v_mov_b32_e32 v243, v168
	v_pk_mul_f32 v[168:169], v[168:169], s[12:13] op_sel_hi:[1,0]
	v_pk_fma_f32 v[234:235], v[244:245], s[36:37], v[234:235] op_sel_hi:[1,0,1]
	v_pk_fma_f32 v[168:169], v[242:243], s[12:13], v[168:169] op_sel_hi:[1,0,1] neg_lo:[0,0,1] neg_hi:[0,0,1]
	v_pk_mul_f32 v[242:243], v[166:167], s[22:23] op_sel:[1,0] op_sel_hi:[0,0] neg_lo:[1,0]
	v_pk_fma_f32 v[166:167], v[166:167], s[26:27], v[242:243] op_sel_hi:[1,0,1] neg_lo:[0,0,1] neg_hi:[0,0,1]
	v_pk_add_f32 v[242:243], v[198:199], v[172:173]
	v_pk_add_f32 v[172:173], v[198:199], v[172:173] neg_lo:[0,1] neg_hi:[0,1]
	v_pk_add_f32 v[198:199], v[236:237], v[164:165]
	v_pk_add_f32 v[164:165], v[236:237], v[164:165] neg_lo:[0,1] neg_hi:[0,1]
	s_nop 0
	v_xor_b32_e32 v236, 0x80000000, v165
	v_mov_b32_e32 v237, v164
	v_pk_add_f32 v[164:165], v[242:243], v[198:199]
	v_pk_add_f32 v[198:199], v[242:243], v[198:199] neg_lo:[0,1] neg_hi:[0,1]
	v_pk_add_f32 v[242:243], v[234:235], v[240:241]
	v_pk_add_f32 v[234:235], v[234:235], v[240:241] neg_lo:[0,1] neg_hi:[0,1]
	v_pk_add_f32 v[244:245], v[172:173], v[236:237]
	v_pk_add_f32 v[172:173], v[172:173], v[236:237] neg_lo:[0,1] neg_hi:[0,1]
	v_pk_add_f32 v[236:237], v[246:247], v[238:239]
	v_pk_add_f32 v[238:239], v[246:247], v[238:239] neg_lo:[0,1] neg_hi:[0,1]
	s_nop 0
	v_pk_add_f32 v[246:247], v[238:239], v[234:235] op_sel:[0,1] op_sel_hi:[1,0] neg_lo:[0,1]
	v_pk_add_f32 v[238:239], v[238:239], v[234:235] op_sel:[0,1] op_sel_hi:[1,0] neg_hi:[0,1]
	v_pk_add_f32 v[240:241], v[202:203], v[232:233]
	v_pk_add_f32 v[202:203], v[202:203], v[232:233] neg_lo:[0,1] neg_hi:[0,1]
	v_pk_add_f32 v[232:233], v[200:201], v[168:169]
	v_pk_add_f32 v[168:169], v[200:201], v[168:169] neg_lo:[0,1] neg_hi:[0,1]
	v_pk_add_f32 v[234:235], v[236:237], v[242:243]
	v_pk_add_f32 v[236:237], v[236:237], v[242:243] neg_lo:[0,1] neg_hi:[0,1]
	v_pk_add_f32 v[242:243], v[202:203], v[168:169] op_sel:[0,1] op_sel_hi:[1,0] neg_lo:[0,1]
	v_pk_add_f32 v[200:201], v[202:203], v[168:169] op_sel:[0,1] op_sel_hi:[1,0] neg_hi:[0,1]
	v_pk_add_f32 v[202:203], v[170:171], v[174:175]
	v_pk_add_f32 v[170:171], v[170:171], v[174:175] neg_lo:[0,1] neg_hi:[0,1]
	v_pk_add_f32 v[174:175], v[204:205], v[166:167]
	v_pk_add_f32 v[166:167], v[204:205], v[166:167] neg_lo:[0,1] neg_hi:[0,1]
	v_pk_add_f32 v[168:169], v[240:241], v[232:233]
	v_xor_b32_e32 v204, 0x80000000, v167
	v_mov_b32_e32 v205, v166
	v_pk_add_f32 v[166:167], v[202:203], v[174:175]
	v_pk_add_f32 v[174:175], v[202:203], v[174:175] neg_lo:[0,1] neg_hi:[0,1]
	v_mov_b32_e32 v202, v116
	v_mov_b32_e32 v203, v142
	v_pk_mul_f32 v[142:143], v[202:203], v[164:165] op_sel_hi:[1,0]
	v_pk_add_f32 v[232:233], v[240:241], v[232:233] neg_lo:[0,1] neg_hi:[0,1]
	v_pk_fma_f32 v[116:117], v[116:117], v[164:165], v[142:143] op_sel:[1,1,0] op_sel_hi:[0,1,1]
	v_pk_mul_f32 v[142:143], v[126:127], v[234:235] op_sel_hi:[1,0] neg_hi:[1,0]
	v_pk_add_f32 v[240:241], v[170:171], v[204:205]
	v_pk_fma_f32 v[126:127], v[126:127], v[234:235], v[142:143] op_sel:[1,1,0] op_sel_hi:[0,1,1]
	ds_write2_b64 v129, v[116:117], v[126:127] offset1:1
	v_pk_mul_f32 v[116:117], v[124:125], v[168:169] op_sel_hi:[1,0] neg_hi:[1,0]
	v_pk_add_f32 v[170:171], v[170:171], v[204:205] neg_lo:[0,1] neg_hi:[0,1]
	v_pk_fma_f32 v[116:117], v[124:125], v[168:169], v[116:117] op_sel:[1,1,0] op_sel_hi:[0,1,1]
	v_pk_mul_f32 v[124:125], v[122:123], v[166:167] op_sel_hi:[1,0] neg_hi:[1,0]
	s_nop 0
	v_pk_fma_f32 v[122:123], v[122:123], v[166:167], v[124:125] op_sel:[1,1,0] op_sel_hi:[0,1,1]
	ds_write2_b64 v129, v[116:117], v[122:123] offset0:2 offset1:3
	v_pk_mul_f32 v[116:117], v[120:121], v[244:245] op_sel_hi:[1,0] neg_hi:[1,0]
	s_nop 0
	v_pk_fma_f32 v[116:117], v[120:121], v[244:245], v[116:117] op_sel:[1,1,0] op_sel_hi:[0,1,1]
	v_pk_mul_f32 v[120:121], v[118:119], v[246:247] op_sel_hi:[1,0] neg_hi:[1,0]
	s_nop 0
	v_pk_fma_f32 v[118:119], v[118:119], v[246:247], v[120:121] op_sel:[1,1,0] op_sel_hi:[0,1,1]
	ds_write2_b64 v129, v[116:117], v[118:119] offset0:4 offset1:5
	v_pk_mul_f32 v[116:117], v[114:115], v[242:243] op_sel_hi:[1,0] neg_hi:[1,0]
	s_nop 0
	v_pk_fma_f32 v[114:115], v[114:115], v[242:243], v[116:117] op_sel:[1,1,0] op_sel_hi:[0,1,1]
	v_pk_mul_f32 v[116:117], v[112:113], v[240:241] op_sel_hi:[1,0] neg_hi:[1,0]
	s_nop 0
	v_pk_fma_f32 v[112:113], v[112:113], v[240:241], v[116:117] op_sel:[1,1,0] op_sel_hi:[0,1,1]
	ds_write2_b64 v129, v[114:115], v[112:113] offset0:6 offset1:7
	v_pk_mul_f32 v[112:113], v[110:111], v[198:199] op_sel_hi:[1,0] neg_hi:[1,0]
	s_nop 0
	v_pk_fma_f32 v[110:111], v[110:111], v[198:199], v[112:113] op_sel:[1,1,0] op_sel_hi:[0,1,1]
	v_pk_mul_f32 v[112:113], v[108:109], v[236:237] op_sel_hi:[1,0] neg_hi:[1,0]
	s_nop 0
	v_pk_fma_f32 v[108:109], v[108:109], v[236:237], v[112:113] op_sel:[1,1,0] op_sel_hi:[0,1,1]
	ds_write2_b64 v129, v[110:111], v[108:109] offset0:8 offset1:9
	v_pk_mul_f32 v[108:109], v[106:107], v[232:233] op_sel_hi:[1,0] neg_hi:[1,0]
	s_nop 0
	v_pk_fma_f32 v[106:107], v[106:107], v[232:233], v[108:109] op_sel:[1,1,0] op_sel_hi:[0,1,1]
	v_pk_mul_f32 v[108:109], v[104:105], v[174:175] op_sel_hi:[1,0] neg_hi:[1,0]
	s_nop 0
	v_pk_fma_f32 v[104:105], v[104:105], v[174:175], v[108:109] op_sel:[1,1,0] op_sel_hi:[0,1,1]
	ds_write2_b64 v129, v[106:107], v[104:105] offset0:10 offset1:11
	v_pk_mul_f32 v[104:105], v[14:15], v[172:173] op_sel_hi:[1,0] neg_hi:[1,0]
	s_nop 0
	v_pk_fma_f32 v[14:15], v[14:15], v[172:173], v[104:105] op_sel:[1,1,0] op_sel_hi:[0,1,1]
	v_pk_mul_f32 v[104:105], v[12:13], v[238:239] op_sel_hi:[1,0] neg_hi:[1,0]
	s_nop 0
	v_pk_fma_f32 v[12:13], v[12:13], v[238:239], v[104:105] op_sel:[1,1,0] op_sel_hi:[0,1,1]
	ds_write2_b64 v129, v[14:15], v[12:13] offset0:12 offset1:13
	v_pk_mul_f32 v[12:13], v[10:11], v[200:201] op_sel_hi:[1,0] neg_hi:[1,0]
	s_nop 0
	v_pk_fma_f32 v[10:11], v[10:11], v[200:201], v[12:13] op_sel:[1,1,0] op_sel_hi:[0,1,1]
	v_pk_mul_f32 v[12:13], v[8:9], v[170:171] op_sel_hi:[1,0] neg_hi:[1,0]
	s_nop 0
	v_pk_fma_f32 v[8:9], v[8:9], v[170:171], v[12:13] op_sel:[1,1,0] op_sel_hi:[0,1,1]
	ds_write2_b64 v129, v[10:11], v[8:9] offset0:14 offset1:15
	v_mov_b32_e32 v8, v217
	v_mov_b32_e32 v9, v218
	v_mov_b32_e32 v138, v215
	v_xor_b32_e32 v12, 0x80000000, v9
	v_mov_b32_e32 v13, v8
	v_pk_mul_f32 v[10:11], v[12:13], v[218:219] op_sel_hi:[1,0]
	v_mov_b32_e32 v139, v216
	v_pk_fma_f32 v[10:11], v[216:217], v[8:9], v[10:11] op_sel:[1,0,0]
	s_nop 0
	v_pk_mul_f32 v[104:105], v[10:11], v[10:11] op_sel:[1,1] op_sel_hi:[1,0] neg_lo:[0,1]
	v_pk_mul_f32 v[12:13], v[12:13], v[216:217] op_sel_hi:[1,0]
	v_pk_fma_f32 v[104:105], v[10:11], v[10:11], v[104:105] op_sel_hi:[1,0,1]
	v_pk_fma_f32 v[140:141], v[8:9], v[214:215], v[12:13] op_sel:[0,1,0]
	v_pk_mul_f32 v[8:9], v[216:217], v[10:11] op_sel:[0,1] op_sel_hi:[0,0] neg_lo:[0,1]
	v_pk_fma_f32 v[142:143], v[214:215], v[10:11], v[8:9] op_sel:[1,0,0]
	v_pk_mul_f32 v[8:9], v[140:141], v[10:11] op_sel:[1,1] op_sel_hi:[1,0] neg_lo:[0,1]
	v_pk_mul_f32 v[108:109], v[104:105], v[104:105] op_sel:[1,1] op_sel_hi:[1,0] neg_lo:[0,1]
	v_pk_fma_f32 v[144:145], v[10:11], v[140:141], v[8:9] op_sel_hi:[1,0,1]
	v_pk_mul_f32 v[8:9], v[216:217], v[104:105] op_sel:[0,1] op_sel_hi:[0,0] neg_lo:[0,1]
	v_pk_fma_f32 v[146:147], v[214:215], v[104:105], v[8:9] op_sel:[1,0,0]
	v_pk_mul_f32 v[8:9], v[140:141], v[104:105] op_sel:[1,1] op_sel_hi:[1,0] neg_lo:[0,1]
	s_waitcnt lgkmcnt(0)
	v_pk_fma_f32 v[148:149], v[140:141], v[104:105], v[8:9] op_sel_hi:[0,1,1]
	v_pk_mul_f32 v[8:9], v[142:143], v[104:105] op_sel:[1,1] op_sel_hi:[1,0] neg_lo:[0,1]
	s_barrier
	v_pk_fma_f32 v[150:151], v[104:105], v[142:143], v[8:9] op_sel_hi:[1,0,1]
	v_pk_mul_f32 v[8:9], v[144:145], v[104:105] op_sel:[1,1] op_sel_hi:[1,0] neg_lo:[0,1]
	s_nop 0
	v_pk_fma_f32 v[152:153], v[104:105], v[144:145], v[8:9] op_sel_hi:[1,0,1]
	v_pk_fma_f32 v[8:9], v[104:105], v[104:105], v[108:109] op_sel_hi:[1,0,1]
	s_nop 0
	v_pk_mul_f32 v[10:11], v[216:217], v[8:9] op_sel:[0,1] op_sel_hi:[0,0] neg_lo:[0,1]
	v_pk_fma_f32 v[154:155], v[214:215], v[8:9], v[10:11] op_sel:[1,0,0]
	v_pk_mul_f32 v[10:11], v[140:141], v[8:9] op_sel:[1,1] op_sel_hi:[1,0] neg_lo:[0,1]
	s_nop 0
	v_pk_fma_f32 v[156:157], v[140:141], v[8:9], v[10:11] op_sel_hi:[0,1,1]
	v_pk_mul_f32 v[10:11], v[142:143], v[8:9] op_sel:[1,1] op_sel_hi:[1,0] neg_lo:[0,1]
	s_nop 0
	v_pk_fma_f32 v[158:159], v[142:143], v[8:9], v[10:11] op_sel_hi:[0,1,1]
	v_pk_mul_f32 v[10:11], v[144:145], v[8:9] op_sel:[1,1] op_sel_hi:[1,0] neg_lo:[0,1]
	s_nop 0
	v_pk_fma_f32 v[104:105], v[144:145], v[8:9], v[10:11] op_sel_hi:[0,1,1]
	v_pk_mul_f32 v[10:11], v[146:147], v[8:9] op_sel:[1,1] op_sel_hi:[1,0] neg_lo:[0,1]
	s_nop 0
	v_pk_fma_f32 v[14:15], v[8:9], v[146:147], v[10:11] op_sel_hi:[1,0,1]
	v_pk_mul_f32 v[10:11], v[148:149], v[8:9] op_sel:[1,1] op_sel_hi:[1,0] neg_lo:[0,1]
	s_nop 0
	v_pk_fma_f32 v[12:13], v[8:9], v[148:149], v[10:11] op_sel_hi:[1,0,1]
	v_pk_mul_f32 v[10:11], v[150:151], v[8:9] op_sel:[1,1] op_sel_hi:[1,0] neg_lo:[0,1]
	v_pk_mul_f32 v[106:107], v[152:153], v[8:9] op_sel:[1,1] op_sel_hi:[1,0] neg_lo:[0,1]
	v_pk_fma_f32 v[10:11], v[8:9], v[150:151], v[10:11] op_sel_hi:[1,0,1]
	v_pk_fma_f32 v[8:9], v[8:9], v[152:153], v[106:107] op_sel_hi:[1,0,1]
	s_nop 0
	v_bfe_u32 v107, v206, 4, 4
	v_and_b32_e32 v106, 15, v206
	v_mul_u32_u24_e32 v107, 0x880, v107
	v_lshlrev_b32_e32 v106, 3, v106
	v_add3_u32 v168, v207, v107, v106
	ds_read2_b64 v[106:109], v168 offset1:17
	ds_read2_b64 v[110:113], v168 offset0:34 offset1:51
	ds_read2_b64 v[114:117], v168 offset0:68 offset1:85
	ds_read2_b64 v[118:121], v168 offset0:136 offset1:153
	ds_read2_b64 v[122:125], v168 offset0:102 offset1:119
	ds_read2_b64 v[126:129], v168 offset0:204 offset1:221
	ds_read2_b64 v[130:133], v168 offset0:170 offset1:187
	ds_read2_b64 v[134:137], v168 offset0:238 offset1:255
	s_waitcnt lgkmcnt(4)
	v_pk_add_f32 v[164:165], v[106:107], v[118:119]
	v_pk_add_f32 v[106:107], v[106:107], v[118:119] neg_lo:[0,1] neg_hi:[0,1]
	s_waitcnt lgkmcnt(2)
	v_pk_add_f32 v[118:119], v[114:115], v[126:127]
	v_pk_add_f32 v[114:115], v[114:115], v[126:127] neg_lo:[0,1] neg_hi:[0,1]
	s_nop 0
	v_pk_add_f32 v[166:167], v[106:107], v[114:115] op_sel:[0,1] op_sel_hi:[1,0] neg_lo:[0,1]
	v_pk_add_f32 v[106:107], v[106:107], v[114:115] op_sel:[0,1] op_sel_hi:[1,0] neg_hi:[0,1]
	v_pk_add_f32 v[126:127], v[108:109], v[120:121]
	v_pk_add_f32 v[108:109], v[108:109], v[120:121] neg_lo:[0,1] neg_hi:[0,1]
	v_pk_add_f32 v[120:121], v[116:117], v[128:129]
	v_pk_add_f32 v[116:117], v[116:117], v[128:129] neg_lo:[0,1] neg_hi:[0,1]
	v_pk_add_f32 v[114:115], v[164:165], v[118:119]
	v_pk_add_f32 v[118:119], v[164:165], v[118:119] neg_lo:[0,1] neg_hi:[0,1]
	v_pk_add_f32 v[164:165], v[108:109], v[116:117] op_sel:[0,1] op_sel_hi:[1,0] neg_lo:[0,1]
	v_pk_add_f32 v[108:109], v[108:109], v[116:117] op_sel:[0,1] op_sel_hi:[1,0] neg_hi:[0,1]
	s_waitcnt lgkmcnt(0)
	v_pk_add_f32 v[128:129], v[122:123], v[134:135]
	v_pk_add_f32 v[122:123], v[122:123], v[134:135] neg_lo:[0,1] neg_hi:[0,1]
	v_pk_add_f32 v[116:117], v[126:127], v[120:121]
	v_pk_add_f32 v[120:121], v[126:127], v[120:121] neg_lo:[0,1] neg_hi:[0,1]
	v_pk_add_f32 v[126:127], v[110:111], v[130:131]
	v_pk_add_f32 v[110:111], v[110:111], v[130:131] neg_lo:[0,1] neg_hi:[0,1]
	s_nop 0
	v_pk_add_f32 v[134:135], v[110:111], v[122:123] op_sel:[0,1] op_sel_hi:[1,0] neg_lo:[0,1]
	v_pk_add_f32 v[110:111], v[110:111], v[122:123] op_sel:[0,1] op_sel_hi:[1,0] neg_hi:[0,1]
	v_pk_add_f32 v[130:131], v[124:125], v[136:137]
	v_pk_add_f32 v[124:125], v[124:125], v[136:137] neg_lo:[0,1] neg_hi:[0,1]
	v_pk_add_f32 v[122:123], v[126:127], v[128:129]
	v_pk_add_f32 v[126:127], v[126:127], v[128:129] neg_lo:[0,1] neg_hi:[0,1]
	v_pk_add_f32 v[128:129], v[112:113], v[132:133]
	v_pk_add_f32 v[112:113], v[112:113], v[132:133] neg_lo:[0,1] neg_hi:[0,1]
	s_nop 0
	v_pk_add_f32 v[136:137], v[112:113], v[124:125] op_sel:[0,1] op_sel_hi:[1,0] neg_lo:[0,1]
	v_pk_add_f32 v[112:113], v[112:113], v[124:125] op_sel:[0,1] op_sel_hi:[1,0] neg_hi:[0,1]
	v_pk_mul_f32 v[132:133], v[120:121], s[12:13] op_sel:[1,0] op_sel_hi:[0,0] neg_lo:[1,0]
	v_pk_add_f32 v[124:125], v[128:129], v[130:131]
	v_pk_fma_f32 v[120:121], v[120:121], s[12:13], v[132:133] op_sel_hi:[1,0,1]
	v_pk_mul_f32 v[132:133], v[108:109], s[36:37] op_sel:[1,0] op_sel_hi:[0,0] neg_lo:[1,0]
	v_pk_add_f32 v[128:129], v[128:129], v[130:131] neg_lo:[0,1] neg_hi:[0,1]
	v_pk_fma_f32 v[108:109], v[108:109], s[22:23], v[132:133] op_sel_hi:[1,0,1]
	v_pk_mul_f32 v[132:133], v[134:135], s[12:13] op_sel:[1,0] op_sel_hi:[0,0] neg_lo:[1,0]
	v_pk_fma_f32 v[132:133], v[134:135], s[12:13], v[132:133] op_sel_hi:[1,0,1]
	v_pk_fma_f32 v[126:127], v[126:127], 0, v[126:127] op_sel:[0,0,1] op_sel_hi:[1,0,0] neg_lo:[0,0,1]
	v_xor_b32_e32 v134, 0x80000000, v111
	v_mov_b32_e32 v135, v110
	v_pk_mul_f32 v[110:111], v[110:111], s[12:13] op_sel_hi:[1,0]
	s_nop 0
	v_pk_fma_f32 v[110:111], v[134:135], s[12:13], v[110:111] op_sel_hi:[1,0,1] neg_lo:[0,0,1] neg_hi:[0,0,1]
	v_pk_mul_f32 v[134:135], v[136:137], s[36:37] op_sel:[1,0] op_sel_hi:[0,0] neg_lo:[1,0]
	v_pk_mul_f32 v[130:131], v[164:165], s[22:23] op_sel:[1,0] op_sel_hi:[0,0] neg_lo:[1,0]
	v_pk_fma_f32 v[134:135], v[136:137], s[22:23], v[134:135] op_sel_hi:[1,0,1]
	v_xor_b32_e32 v136, 0x80000000, v129
	v_mov_b32_e32 v137, v128
	v_pk_mul_f32 v[128:129], v[128:129], s[12:13] op_sel_hi:[1,0]
	v_pk_fma_f32 v[130:131], v[164:165], s[36:37], v[130:131] op_sel_hi:[1,0,1]
	v_pk_fma_f32 v[128:129], v[136:137], s[12:13], v[128:129] op_sel_hi:[1,0,1] neg_lo:[0,0,1] neg_hi:[0,0,1]
	v_pk_mul_f32 v[136:137], v[112:113], s[22:23] op_sel:[1,0] op_sel_hi:[0,0] neg_lo:[1,0]
	v_pk_fma_f32 v[112:113], v[112:113], s[26:27], v[136:137] op_sel_hi:[1,0,1] neg_lo:[0,0,1] neg_hi:[0,0,1]
	v_pk_add_f32 v[136:137], v[114:115], v[122:123]
	v_pk_add_f32 v[114:115], v[114:115], v[122:123] neg_lo:[0,1] neg_hi:[0,1]
	v_pk_add_f32 v[122:123], v[116:117], v[124:125]
	v_pk_add_f32 v[116:117], v[116:117], v[124:125] neg_lo:[0,1] neg_hi:[0,1]
	s_nop 0
	v_xor_b32_e32 v124, 0x80000000, v117
	v_mov_b32_e32 v125, v116
	v_pk_add_f32 v[116:117], v[136:137], v[122:123]
	v_pk_add_f32 v[122:123], v[136:137], v[122:123] neg_lo:[0,1] neg_hi:[0,1]
	v_pk_add_f32 v[136:137], v[130:131], v[134:135]
	v_pk_add_f32 v[130:131], v[130:131], v[134:135] neg_lo:[0,1] neg_hi:[0,1]
	v_pk_add_f32 v[164:165], v[114:115], v[124:125]
	v_pk_add_f32 v[114:115], v[114:115], v[124:125] neg_lo:[0,1] neg_hi:[0,1]
	v_pk_add_f32 v[124:125], v[166:167], v[132:133]
	v_pk_add_f32 v[132:133], v[166:167], v[132:133] neg_lo:[0,1] neg_hi:[0,1]
	s_nop 0
	v_pk_add_f32 v[166:167], v[132:133], v[130:131] op_sel:[0,1] op_sel_hi:[1,0] neg_lo:[0,1]
	v_pk_add_f32 v[132:133], v[132:133], v[130:131] op_sel:[0,1] op_sel_hi:[1,0] neg_hi:[0,1]
	v_pk_add_f32 v[134:135], v[118:119], v[126:127]
	v_pk_add_f32 v[118:119], v[118:119], v[126:127] neg_lo:[0,1] neg_hi:[0,1]
	v_pk_add_f32 v[126:127], v[120:121], v[128:129]
	v_pk_add_f32 v[120:121], v[120:121], v[128:129] neg_lo:[0,1] neg_hi:[0,1]
	v_pk_add_f32 v[130:131], v[124:125], v[136:137]
	v_pk_add_f32 v[124:125], v[124:125], v[136:137] neg_lo:[0,1] neg_hi:[0,1]
	v_pk_add_f32 v[136:137], v[118:119], v[120:121] op_sel:[0,1] op_sel_hi:[1,0] neg_lo:[0,1]
	v_pk_add_f32 v[118:119], v[118:119], v[120:121] op_sel:[0,1] op_sel_hi:[1,0] neg_hi:[0,1]
	v_pk_add_f32 v[128:129], v[106:107], v[110:111]
	v_pk_add_f32 v[106:107], v[106:107], v[110:111] neg_lo:[0,1] neg_hi:[0,1]
	v_pk_add_f32 v[110:111], v[108:109], v[112:113]
	v_pk_add_f32 v[108:109], v[108:109], v[112:113] neg_lo:[0,1] neg_hi:[0,1]
	v_pk_add_f32 v[120:121], v[134:135], v[126:127]
	v_pk_add_f32 v[126:127], v[134:135], v[126:127] neg_lo:[0,1] neg_hi:[0,1]
	v_pk_add_f32 v[134:135], v[106:107], v[108:109] op_sel:[0,1] op_sel_hi:[1,0] neg_lo:[0,1]
	v_pk_add_f32 v[106:107], v[106:107], v[108:109] op_sel:[0,1] op_sel_hi:[1,0] neg_hi:[0,1]
	v_xor_b32_e32 v112, 0x80000000, v139
	v_mov_b32_e32 v113, v138
	v_pk_mul_f32 v[112:113], v[112:113], v[116:117] op_sel:[0,1]
	v_pk_add_f32 v[108:109], v[128:129], v[110:111]
	v_pk_fma_f32 v[112:113], v[138:139], v[116:117], v[112:113] op_sel_hi:[1,0,1]
	v_pk_mul_f32 v[116:117], v[140:141], v[130:131] op_sel:[1,1] op_sel_hi:[0,1] neg_lo:[1,0]
	v_pk_add_f32 v[110:111], v[128:129], v[110:111] neg_lo:[0,1] neg_hi:[0,1]
	v_pk_fma_f32 v[116:117], v[140:141], v[130:131], v[116:117] op_sel_hi:[1,0,1]
	ds_write2_b64 v168, v[112:113], v[116:117] offset1:17
	v_pk_mul_f32 v[112:113], v[142:143], v[120:121] op_sel:[1,1] op_sel_hi:[0,1] neg_lo:[1,0]
	v_pk_mul_f32 v[116:117], v[144:145], v[108:109] op_sel:[1,1] op_sel_hi:[0,1] neg_lo:[1,0]
	v_pk_fma_f32 v[112:113], v[142:143], v[120:121], v[112:113] op_sel_hi:[1,0,1]
	v_pk_fma_f32 v[108:109], v[144:145], v[108:109], v[116:117] op_sel_hi:[1,0,1]
	ds_write2_b64 v168, v[112:113], v[108:109] offset0:34 offset1:51
	v_pk_mul_f32 v[108:109], v[146:147], v[164:165] op_sel:[1,1] op_sel_hi:[0,1] neg_lo:[1,0]
	v_pk_mul_f32 v[112:113], v[148:149], v[166:167] op_sel:[1,1] op_sel_hi:[0,1] neg_lo:[1,0]
	v_pk_fma_f32 v[108:109], v[146:147], v[164:165], v[108:109] op_sel_hi:[1,0,1]
	v_pk_fma_f32 v[112:113], v[148:149], v[166:167], v[112:113] op_sel_hi:[1,0,1]
	ds_write2_b64 v168, v[108:109], v[112:113] offset0:68 offset1:85
	v_pk_mul_f32 v[108:109], v[150:151], v[136:137] op_sel:[1,1] op_sel_hi:[0,1] neg_lo:[1,0]
	v_pk_mul_f32 v[112:113], v[152:153], v[134:135] op_sel:[1,1] op_sel_hi:[0,1] neg_lo:[1,0]
	v_pk_fma_f32 v[108:109], v[150:151], v[136:137], v[108:109] op_sel_hi:[1,0,1]
	v_pk_fma_f32 v[112:113], v[152:153], v[134:135], v[112:113] op_sel_hi:[1,0,1]
	ds_write2_b64 v168, v[108:109], v[112:113] offset0:102 offset1:119
	v_pk_mul_f32 v[108:109], v[154:155], v[122:123] op_sel:[1,1] op_sel_hi:[0,1] neg_lo:[1,0]
	v_pk_mul_f32 v[112:113], v[156:157], v[124:125] op_sel:[1,1] op_sel_hi:[0,1] neg_lo:[1,0]
	v_pk_fma_f32 v[108:109], v[154:155], v[122:123], v[108:109] op_sel_hi:[1,0,1]
	v_pk_fma_f32 v[112:113], v[156:157], v[124:125], v[112:113] op_sel_hi:[1,0,1]
	ds_write2_b64 v168, v[108:109], v[112:113] offset0:136 offset1:153
	v_pk_mul_f32 v[108:109], v[158:159], v[126:127] op_sel:[1,1] op_sel_hi:[0,1] neg_lo:[1,0]
	v_pk_mul_f32 v[112:113], v[104:105], v[110:111] op_sel:[1,1] op_sel_hi:[0,1] neg_lo:[1,0]
	v_pk_fma_f32 v[108:109], v[158:159], v[126:127], v[108:109] op_sel_hi:[1,0,1]
	v_pk_fma_f32 v[104:105], v[104:105], v[110:111], v[112:113] op_sel_hi:[1,0,1]
	ds_write2_b64 v168, v[108:109], v[104:105] offset0:170 offset1:187
	v_pk_mul_f32 v[104:105], v[14:15], v[114:115] op_sel:[1,1] op_sel_hi:[0,1] neg_lo:[1,0]
	v_pk_fma_f32 v[14:15], v[14:15], v[114:115], v[104:105] op_sel_hi:[1,0,1]
	v_pk_mul_f32 v[104:105], v[12:13], v[132:133] op_sel:[1,1] op_sel_hi:[0,1] neg_lo:[1,0]
	v_pk_fma_f32 v[12:13], v[12:13], v[132:133], v[104:105] op_sel_hi:[1,0,1]
	ds_write2_b64 v168, v[14:15], v[12:13] offset0:204 offset1:221
	v_pk_mul_f32 v[12:13], v[10:11], v[118:119] op_sel:[1,1] op_sel_hi:[0,1] neg_lo:[1,0]
	v_pk_fma_f32 v[10:11], v[10:11], v[118:119], v[12:13] op_sel_hi:[1,0,1]
	v_pk_mul_f32 v[12:13], v[8:9], v[106:107] op_sel:[1,1] op_sel_hi:[0,1] neg_lo:[1,0]
	v_pk_fma_f32 v[8:9], v[8:9], v[106:107], v[12:13] op_sel_hi:[1,0,1]
	ds_write2_b64 v168, v[10:11], v[8:9] offset0:238 offset1:255
	v_mov_b32_e32 v8, v206
	s_waitcnt lgkmcnt(0)
	s_barrier
	s_nop 0
	v_lshlrev_b32_sdwa v9, v228, v8 dst_sel:DWORD dst_unused:UNUSED_PAD src0_sel:DWORD src1_sel:BYTE_0
	v_lshrrev_b32_e32 v8, 1, v206
	v_and_b32_e32 v8, 0x78, v8
	v_add3_u32 v132, v207, v9, v8
	ds_read_b64 v[8:9], v132
	ds_read_b64 v[10:11], v132 offset:2176
	ds_read_b64 v[12:13], v132 offset:4352
	ds_read_b64 v[14:15], v132 offset:6528
	ds_read_b64 v[104:105], v132 offset:8704
	ds_read_b64 v[106:107], v132 offset:10880
	ds_read_b64 v[108:109], v132 offset:13056
	ds_read_b64 v[110:111], v132 offset:15232
	ds_read_b64 v[112:113], v132 offset:17408
	ds_read_b64 v[114:115], v132 offset:19584
	ds_read_b64 v[116:117], v132 offset:21760
	ds_read_b64 v[118:119], v132 offset:23936
	ds_read_b64 v[120:121], v132 offset:26112
	ds_read_b64 v[122:123], v132 offset:28288
	ds_read_b64 v[124:125], v132 offset:30464
	ds_read_b64 v[126:127], v132 offset:32640
	s_waitcnt lgkmcnt(7)
	v_pk_add_f32 v[128:129], v[8:9], v[112:113]
	v_pk_add_f32 v[8:9], v[8:9], v[112:113] neg_lo:[0,1] neg_hi:[0,1]
	s_waitcnt lgkmcnt(3)
	v_pk_add_f32 v[112:113], v[104:105], v[120:121]
	v_pk_add_f32 v[104:105], v[104:105], v[120:121] neg_lo:[0,1] neg_hi:[0,1]
	s_nop 0
	v_pk_add_f32 v[130:131], v[8:9], v[104:105] op_sel:[0,1] op_sel_hi:[1,0] neg_lo:[0,1]
	v_pk_add_f32 v[8:9], v[8:9], v[104:105] op_sel:[0,1] op_sel_hi:[1,0] neg_hi:[0,1]
	v_pk_add_f32 v[120:121], v[10:11], v[114:115]
	v_pk_add_f32 v[10:11], v[10:11], v[114:115] neg_lo:[0,1] neg_hi:[0,1]
	s_waitcnt lgkmcnt(2)
	v_pk_add_f32 v[114:115], v[106:107], v[122:123]
	v_pk_add_f32 v[106:107], v[106:107], v[122:123] neg_lo:[0,1] neg_hi:[0,1]
	v_pk_add_f32 v[104:105], v[128:129], v[112:113]
	v_xor_b32_e32 v122, 0x80000000, v107
	v_mov_b32_e32 v123, v106
	v_pk_add_f32 v[106:107], v[120:121], v[114:115]
	v_pk_add_f32 v[114:115], v[120:121], v[114:115] neg_lo:[0,1] neg_hi:[0,1]
	v_pk_add_f32 v[120:121], v[12:13], v[116:117]
	v_pk_add_f32 v[12:13], v[12:13], v[116:117] neg_lo:[0,1] neg_hi:[0,1]
	s_waitcnt lgkmcnt(1)
	v_pk_add_f32 v[116:117], v[108:109], v[124:125]
	v_pk_add_f32 v[108:109], v[108:109], v[124:125] neg_lo:[0,1] neg_hi:[0,1]
	v_pk_add_f32 v[112:113], v[128:129], v[112:113] neg_lo:[0,1] neg_hi:[0,1]
	v_pk_add_f32 v[128:129], v[10:11], v[122:123]
	v_pk_add_f32 v[10:11], v[10:11], v[122:123] neg_lo:[0,1] neg_hi:[0,1]
	v_xor_b32_e32 v122, 0x80000000, v109
	v_mov_b32_e32 v123, v108
	v_pk_add_f32 v[108:109], v[120:121], v[116:117]
	v_pk_add_f32 v[116:117], v[120:121], v[116:117] neg_lo:[0,1] neg_hi:[0,1]
	v_pk_add_f32 v[120:121], v[14:15], v[118:119]
	v_pk_add_f32 v[14:15], v[14:15], v[118:119] neg_lo:[0,1] neg_hi:[0,1]
	s_waitcnt lgkmcnt(0)
	v_pk_add_f32 v[118:119], v[110:111], v[126:127]
	v_pk_add_f32 v[110:111], v[110:111], v[126:127] neg_lo:[0,1] neg_hi:[0,1]
	v_pk_add_f32 v[124:125], v[12:13], v[122:123]
	v_pk_add_f32 v[12:13], v[12:13], v[122:123] neg_lo:[0,1] neg_hi:[0,1]
	v_pk_add_f32 v[126:127], v[14:15], v[110:111] op_sel:[0,1] op_sel_hi:[1,0] neg_lo:[0,1]
	v_pk_add_f32 v[14:15], v[14:15], v[110:111] op_sel:[0,1] op_sel_hi:[1,0] neg_hi:[0,1]
	v_pk_mul_f32 v[122:123], v[114:115], s[12:13] op_sel:[1,0] op_sel_hi:[0,0] neg_lo:[1,0]
	v_pk_add_f32 v[110:111], v[120:121], v[118:119]
	v_pk_fma_f32 v[114:115], v[114:115], s[12:13], v[122:123] op_sel_hi:[1,0,1]
	v_pk_mul_f32 v[122:123], v[10:11], s[36:37] op_sel:[1,0] op_sel_hi:[0,0] neg_lo:[1,0]
	v_pk_add_f32 v[118:119], v[120:121], v[118:119] neg_lo:[0,1] neg_hi:[0,1]
	v_pk_fma_f32 v[10:11], v[10:11], s[22:23], v[122:123] op_sel_hi:[1,0,1]
	v_pk_mul_f32 v[122:123], v[124:125], s[12:13] op_sel:[1,0] op_sel_hi:[0,0] neg_lo:[1,0]
	v_pk_fma_f32 v[122:123], v[124:125], s[12:13], v[122:123] op_sel_hi:[1,0,1]
	v_pk_fma_f32 v[116:117], v[116:117], 0, v[116:117] op_sel:[0,0,1] op_sel_hi:[1,0,0] neg_lo:[0,0,1]
	v_xor_b32_e32 v124, 0x80000000, v13
	v_mov_b32_e32 v125, v12
	v_pk_mul_f32 v[12:13], v[12:13], s[12:13] op_sel_hi:[1,0]
	s_nop 0
	v_pk_fma_f32 v[12:13], v[124:125], s[12:13], v[12:13] op_sel_hi:[1,0,1] neg_lo:[0,0,1] neg_hi:[0,0,1]
	v_pk_mul_f32 v[124:125], v[126:127], s[36:37] op_sel:[1,0] op_sel_hi:[0,0] neg_lo:[1,0]
	v_pk_mul_f32 v[120:121], v[128:129], s[22:23] op_sel:[1,0] op_sel_hi:[0,0] neg_lo:[1,0]
	v_pk_fma_f32 v[124:125], v[126:127], s[22:23], v[124:125] op_sel_hi:[1,0,1]
	v_xor_b32_e32 v126, 0x80000000, v119
	v_mov_b32_e32 v127, v118
	v_pk_mul_f32 v[118:119], v[118:119], s[12:13] op_sel_hi:[1,0]
	v_pk_fma_f32 v[120:121], v[128:129], s[36:37], v[120:121] op_sel_hi:[1,0,1]
	v_pk_fma_f32 v[118:119], v[126:127], s[12:13], v[118:119] op_sel_hi:[1,0,1] neg_lo:[0,0,1] neg_hi:[0,0,1]
	v_pk_mul_f32 v[126:127], v[14:15], s[22:23] op_sel:[1,0] op_sel_hi:[0,0] neg_lo:[1,0]
	v_pk_fma_f32 v[14:15], v[14:15], s[26:27], v[126:127] op_sel_hi:[1,0,1] neg_lo:[0,0,1] neg_hi:[0,0,1]
	v_pk_add_f32 v[126:127], v[104:105], v[108:109]
	v_pk_add_f32 v[104:105], v[104:105], v[108:109] neg_lo:[0,1] neg_hi:[0,1]
	v_pk_add_f32 v[108:109], v[106:107], v[110:111]
	v_pk_add_f32 v[106:107], v[106:107], v[110:111] neg_lo:[0,1] neg_hi:[0,1]
	s_nop 0
	v_xor_b32_e32 v110, 0x80000000, v107
	v_mov_b32_e32 v111, v106
	v_pk_add_f32 v[106:107], v[126:127], v[108:109]
	v_pk_add_f32 v[108:109], v[126:127], v[108:109] neg_lo:[0,1] neg_hi:[0,1]
	v_pk_add_f32 v[126:127], v[120:121], v[124:125]
	v_pk_add_f32 v[120:121], v[120:121], v[124:125] neg_lo:[0,1] neg_hi:[0,1]
	v_pk_add_f32 v[128:129], v[104:105], v[110:111]
	v_pk_add_f32 v[104:105], v[104:105], v[110:111] neg_lo:[0,1] neg_hi:[0,1]
	v_pk_add_f32 v[110:111], v[130:131], v[122:123]
	v_pk_add_f32 v[122:123], v[130:131], v[122:123] neg_lo:[0,1] neg_hi:[0,1]
	s_nop 0
	v_pk_add_f32 v[130:131], v[122:123], v[120:121] op_sel:[0,1] op_sel_hi:[1,0] neg_lo:[0,1]
	v_pk_add_f32 v[122:123], v[122:123], v[120:121] op_sel:[0,1] op_sel_hi:[1,0] neg_hi:[0,1]
	v_pk_add_f32 v[124:125], v[112:113], v[116:117]
	v_pk_add_f32 v[112:113], v[112:113], v[116:117] neg_lo:[0,1] neg_hi:[0,1]
	v_pk_add_f32 v[116:117], v[114:115], v[118:119]
	v_pk_add_f32 v[114:115], v[114:115], v[118:119] neg_lo:[0,1] neg_hi:[0,1]
	v_pk_add_f32 v[120:121], v[110:111], v[126:127]
	v_pk_add_f32 v[110:111], v[110:111], v[126:127] neg_lo:[0,1] neg_hi:[0,1]
	v_pk_add_f32 v[126:127], v[112:113], v[114:115] op_sel:[0,1] op_sel_hi:[1,0] neg_lo:[0,1]
	v_pk_add_f32 v[112:113], v[112:113], v[114:115] op_sel:[0,1] op_sel_hi:[1,0] neg_hi:[0,1]
	v_pk_add_f32 v[118:119], v[8:9], v[12:13]
	v_pk_add_f32 v[8:9], v[8:9], v[12:13] neg_lo:[0,1] neg_hi:[0,1]
	v_pk_add_f32 v[12:13], v[10:11], v[14:15]
	v_pk_add_f32 v[10:11], v[10:11], v[14:15] neg_lo:[0,1] neg_hi:[0,1]
	v_pk_add_f32 v[114:115], v[124:125], v[116:117]
	v_pk_add_f32 v[116:117], v[124:125], v[116:117] neg_lo:[0,1] neg_hi:[0,1]
	v_pk_add_f32 v[124:125], v[8:9], v[10:11] op_sel:[0,1] op_sel_hi:[1,0] neg_lo:[0,1]
	v_pk_add_f32 v[8:9], v[8:9], v[10:11] op_sel:[0,1] op_sel_hi:[1,0] neg_hi:[0,1]
	v_pk_add_f32 v[10:11], v[118:119], v[12:13]
	v_pk_add_f32 v[12:13], v[118:119], v[12:13] neg_lo:[0,1] neg_hi:[0,1]
	ds_write_b64 v132, v[106:107]
	ds_write_b64 v132, v[128:129] offset:8704
	ds_write_b64 v132, v[108:109] offset:17408
	ds_write_b64 v132, v[104:105] offset:26112
	ds_write_b64 v132, v[120:121] offset:2176
	ds_write_b64 v132, v[130:131] offset:10880
	ds_write_b64 v132, v[110:111] offset:19584
	ds_write_b64 v132, v[122:123] offset:28288
	ds_write_b64 v132, v[114:115] offset:4352
	ds_write_b64 v132, v[126:127] offset:13056
	ds_write_b64 v132, v[116:117] offset:21760
	ds_write_b64 v132, v[112:113] offset:30464
	ds_write_b64 v132, v[10:11] offset:6528
	ds_write_b64 v132, v[124:125] offset:15232
	ds_write_b64 v132, v[12:13] offset:23936
	ds_write_b64 v132, v[8:9] offset:32640
	s_waitcnt lgkmcnt(0)
	s_barrier
	s_waitcnt vmcnt(4)
	v_lshlrev_b32_e32 v9, 16, v4
	v_and_b32_e32 v104, 0x1ff, v212
	v_lshlrev_b32_e32 v105, 3, v104
	v_bfe_u32 v8, v212, 1, 8
	v_add_u32_e32 v106, v105, v8
	v_lshlrev_b32_e32 v8, 16, v0
	v_and_b32_e32 v11, 0xffff0000, v4
	v_and_b32_e32 v10, 0xffff0000, v0
	s_waitcnt vmcnt(2)
	v_lshlrev_b32_e32 v0, 16, v163
	v_lshlrev_b32_e32 v4, 16, v162
	v_cmp_eq_u32_e32 vcc, 0, v104
	v_pk_mul_f32 v[14:15], v[38:39], v[10:11]
	v_cmp_eq_u32_e64 s[0:1], s37, v104
	v_cndmask_b32_e64 v13, v4, 0, vcc
	v_cndmask_b32_e64 v12, v0, 0, vcc
	v_pk_mul_f32 v[12:13], v[24:25], v[12:13]
	v_and_b32_e32 v4, 0xffff0000, v1
	v_pk_fma_f32 v[12:13], v[38:39], v[8:9], v[12:13]
	v_pk_fma_f32 v[8:9], v[24:25], v[8:9], v[14:15]
	v_pk_fma_f32 v[12:13], v[26:27], v[10:11], v[12:13]
	v_lshl_add_u32 v136, v106, 3, 0
	v_pk_add_f32 v[122:123], v[28:29], v[12:13]
	v_lshlrev_b32_e32 v13, 16, v5
	v_lshlrev_b32_e32 v12, 16, v1
	v_pk_mul_f32 v[0:1], v[38:39], v[12:13]
	v_pk_fma_f32 v[8:9], v[26:27], v[12:13], v[8:9]
	v_and_b32_e32 v5, 0xffff0000, v5
	v_pk_fma_f32 v[0:1], v[24:25], v[10:11], v[0:1]
	v_pk_add_f32 v[124:125], v[28:29], v[8:9]
	v_pk_fma_f32 v[0:1], v[26:27], v[4:5], v[0:1]
	v_pk_mul_f32 v[8:9], v[38:39], v[4:5]
	v_pk_add_f32 v[126:127], v[28:29], v[0:1]
	v_lshlrev_b32_e32 v1, 16, v6
	v_lshlrev_b32_e32 v0, 16, v2
	v_pk_fma_f32 v[8:9], v[24:25], v[12:13], v[8:9]
	v_pk_mul_f32 v[10:11], v[38:39], v[0:1]
	v_pk_fma_f32 v[8:9], v[26:27], v[0:1], v[8:9]
	v_pk_fma_f32 v[4:5], v[24:25], v[4:5], v[10:11]
	v_pk_add_f32 v[128:129], v[28:29], v[8:9]
	v_and_b32_e32 v9, 0xffff0000, v6
	v_and_b32_e32 v8, 0xffff0000, v2
	v_pk_fma_f32 v[4:5], v[26:27], v[8:9], v[4:5]
	v_lshlrev_b32_e32 v11, 16, v7
	v_pk_add_f32 v[130:131], v[28:29], v[4:5]
	v_pk_mul_f32 v[4:5], v[38:39], v[8:9]
	v_lshlrev_b32_e32 v10, 16, v3
	v_pk_fma_f32 v[0:1], v[24:25], v[0:1], v[4:5]
	s_waitcnt vmcnt(0)
	v_lshlrev_b32_e32 v6, 16, v161
	v_pk_fma_f32 v[0:1], v[26:27], v[10:11], v[0:1]
	v_cndmask_b32_e64 v6, v6, 0, s[0:1]
	v_pk_add_f32 v[4:5], v[28:29], v[0:1]
	v_and_b32_e32 v0, 0xffff0000, v3
	v_pk_mul_f32 v[2:3], v[38:39], v[10:11]
	v_and_b32_e32 v1, 0xffff0000, v7
	v_pk_fma_f32 v[2:3], v[24:25], v[8:9], v[2:3]
	v_lshlrev_b32_e32 v7, 16, v160
	v_pk_fma_f32 v[2:3], v[26:27], v[0:1], v[2:3]
	v_pk_mul_f32 v[0:1], v[38:39], v[0:1]
	v_cndmask_b32_e64 v7, v7, 0, s[0:1]
	v_pk_fma_f32 v[0:1], v[24:25], v[10:11], v[0:1]
	v_mov_b32_e32 v121, v214
	v_pk_fma_f32 v[0:1], v[26:27], v[6:7], v[0:1]
	v_add_u32_e32 v6, -1, v105
	v_cndmask_b32_e64 v176, v6, 0, vcc
	v_add_u32_e32 v6, 8, v105
	v_cndmask_b32_e64 v105, v6, v229, s[0:1]
	s_add_u32 s0, s39, s42
	v_lshlrev_b32_e32 v6, 4, v104
	v_mov_b32_e32 v7, v177
	s_addc_u32 s1, s46, s43
	v_lshl_add_u64 v[6:7], s[0:1], 0, v[6:7]
	v_add_co_u32_e32 v8, vcc, s5, v6
	v_mov_b32_e32 v120, v213
	s_nop 0
	v_addc_co_u32_e32 v9, vcc, 0, v7, vcc
	v_add_co_u32_e32 v6, vcc, s27, v6
	v_add_u32_e32 v137, 0x8800, v136
	s_nop 0
	v_addc_co_u32_e32 v7, vcc, 0, v7, vcc
	global_load_dwordx4 v[12:15], v[8:9], off
	s_nop 0
	global_load_dwordx4 v[8:11], v[6:7], off
	ds_read2_b64 v[108:111], v137 offset1:1
	v_lshl_add_u64 v[6:7], v[176:177], 1, s[0:1]
	v_lshlrev_b32_e32 v176, 1, v105
	ds_read2_b64 v[104:107], v136 offset1:1
	v_xor_b32_e32 v135, 0x80000000, v121
	v_mov_b32_e32 v134, v120
	v_add_u32_e32 v138, 0x8810, v136
	ds_read2_b64 v[112:115], v138 offset1:1
	s_waitcnt lgkmcnt(2)
	v_pk_mul_f32 v[116:117], v[134:135], v[108:109] op_sel_hi:[1,0]
	v_lshl_add_u64 v[132:133], s[0:1], 0, v[176:177]
	v_pk_fma_f32 v[108:109], v[120:121], v[108:109], v[116:117] op_sel:[1,1,0] op_sel_hi:[0,1,1]
	ds_read2_b64 v[116:119], v136 offset0:2 offset1:3
	s_waitcnt lgkmcnt(2)
	v_pk_add_f32 v[104:105], v[104:105], v[108:109]
	v_mov_b32_e32 v108, v135
	v_pk_mul_f32 v[104:105], v[122:123], v[104:105]
	v_mov_b32_e32 v109, v120
	v_pk_mul_f32 v[108:109], v[108:109], v[104:105] op_sel:[0,1]
	v_pk_mul_f32 v[122:123], v[214:215], s[8:9] op_sel_hi:[0,1]
	v_pk_fma_f32 v[108:109], v[120:121], v[104:105], v[108:109] op_sel_hi:[1,0,1]
	v_pk_fma_f32 v[120:121], v[212:213], s[30:31], v[122:123] op_sel:[1,0,0]
	s_nop 0
	v_pk_mul_f32 v[134:135], v[120:121], v[110:111] op_sel_hi:[1,0] neg_hi:[1,0]
	v_mov_b32_e32 v110, v111
	v_pk_fma_f32 v[110:111], v[120:121], v[110:111], v[134:135] op_sel:[1,1,0] op_sel_hi:[0,1,1]
	v_pk_add_f32 v[106:107], v[106:107], v[110:111]
	v_add_u32_e32 v122, 0x8820, v136
	v_pk_mul_f32 v[106:107], v[124:125], v[106:107]
	ds_write2_b64 v136, v[104:105], v[106:107] offset1:1
	v_pk_mul_f32 v[104:105], v[120:121], v[106:107] op_sel:[1,1] op_sel_hi:[0,1] neg_lo:[1,0]
	v_pk_add_f32 v[2:3], v[28:29], v[2:3]
	v_pk_fma_f32 v[104:105], v[120:121], v[106:107], v[104:105] op_sel_hi:[1,0,1]
	ds_write2_b64 v137, v[108:109], v[104:105] offset1:1
	v_pk_mul_f32 v[104:105], v[120:121], s[8:9] op_sel:[1,0]
	v_pk_add_f32 v[0:1], v[28:29], v[0:1]
	v_pk_fma_f32 v[104:105], v[120:121], s[30:31], v[104:105] op_sel_hi:[0,1,1]
	s_waitcnt lgkmcnt(3)
	v_pk_mul_f32 v[108:109], v[104:105], v[112:113] op_sel_hi:[1,0] neg_hi:[1,0]
	s_nop 0
	v_pk_fma_f32 v[108:109], v[104:105], v[112:113], v[108:109] op_sel:[1,1,0] op_sel_hi:[0,1,1]
	s_waitcnt lgkmcnt(2)
	v_pk_add_f32 v[108:109], v[116:117], v[108:109]
	s_nop 0
	v_pk_mul_f32 v[108:109], v[126:127], v[108:109]
	v_pk_mul_f32 v[110:111], v[104:105], s[8:9] op_sel:[1,0]
	v_pk_mul_f32 v[106:107], v[104:105], v[108:109] op_sel:[1,1] op_sel_hi:[0,1] neg_lo:[1,0]
	v_pk_fma_f32 v[110:111], v[104:105], s[30:31], v[110:111] op_sel_hi:[0,1,1]
	v_pk_fma_f32 v[106:107], v[104:105], v[108:109], v[106:107] op_sel_hi:[1,0,1]
	v_pk_mul_f32 v[112:113], v[110:111], v[114:115] op_sel_hi:[1,0] neg_hi:[1,0]
	s_nop 0
	v_pk_fma_f32 v[112:113], v[110:111], v[114:115], v[112:113] op_sel:[1,1,0] op_sel_hi:[0,1,1]
	v_pk_add_f32 v[112:113], v[118:119], v[112:113]
	s_nop 0
	v_pk_mul_f32 v[112:113], v[128:129], v[112:113]
	s_nop 0
	v_pk_mul_f32 v[104:105], v[110:111], v[112:113] op_sel:[1,1] op_sel_hi:[0,1] neg_lo:[1,0]
	ds_write2_b64 v136, v[108:109], v[112:113] offset0:2 offset1:3
	v_pk_fma_f32 v[104:105], v[110:111], v[112:113], v[104:105] op_sel_hi:[1,0,1]
	ds_write2_b64 v138, v[106:107], v[104:105] offset1:1
	ds_read2_b64 v[104:107], v122 offset1:1
	v_pk_mul_f32 v[108:109], v[110:111], s[8:9] op_sel:[1,0]
	s_nop 0
	v_pk_fma_f32 v[116:117], v[110:111], s[30:31], v[108:109] op_sel_hi:[0,1,1]
	ds_read2_b64 v[108:111], v136 offset0:4 offset1:5
	s_waitcnt lgkmcnt(1)
	v_pk_mul_f32 v[112:113], v[116:117], v[104:105] op_sel_hi:[1,0] neg_hi:[1,0]
	s_nop 0
	v_pk_fma_f32 v[104:105], v[116:117], v[104:105], v[112:113] op_sel:[1,1,0] op_sel_hi:[0,1,1]
	s_waitcnt lgkmcnt(0)
	v_pk_add_f32 v[104:105], v[108:109], v[104:105]
	s_nop 0
	v_pk_mul_f32 v[104:105], v[130:131], v[104:105]
	s_nop 0
	v_pk_mul_f32 v[108:109], v[116:117], v[104:105] op_sel:[1,1] op_sel_hi:[0,1] neg_lo:[1,0]
	v_pk_mul_f32 v[118:119], v[116:117], s[8:9] op_sel:[1,0]
	v_pk_fma_f32 v[108:109], v[116:117], v[104:105], v[108:109] op_sel_hi:[1,0,1]
	v_pk_fma_f32 v[116:117], v[116:117], s[30:31], v[118:119] op_sel_hi:[0,1,1]
	v_pk_mul_f32 v[120:121], v[116:117], v[106:107] op_sel_hi:[1,0] neg_hi:[1,0]
	v_mov_b32_e32 v106, v107
	v_pk_fma_f32 v[106:107], v[116:117], v[106:107], v[120:121] op_sel:[1,1,0] op_sel_hi:[0,1,1]
	v_pk_add_f32 v[106:107], v[110:111], v[106:107]
	ds_read2_b64 v[112:115], v136 offset0:6 offset1:7
	v_pk_mul_f32 v[4:5], v[4:5], v[106:107]
	v_add_co_u32_e32 v106, vcc, s5, v6
	s_nop 1
	v_addc_co_u32_e32 v107, vcc, 0, v7, vcc
	v_add_co_u32_e32 v110, vcc, s5, v132
	s_nop 1
	v_addc_co_u32_e32 v111, vcc, 0, v133, vcc
	v_add_co_u32_e32 v6, vcc, s27, v6
	s_nop 1
	v_addc_co_u32_e32 v7, vcc, 0, v7, vcc
	v_add_co_u32_e32 v120, vcc, s27, v132
	s_nop 1
	v_addc_co_u32_e32 v121, vcc, 0, v133, vcc
	global_load_ushort v233, v[106:107], off
	global_load_ushort v232, v[110:111], off
	global_load_ushort v231, v[6:7], off
	global_load_ushort v176, v[120:121], off
	v_pk_mul_f32 v[6:7], v[116:117], v[4:5] op_sel:[1,1] op_sel_hi:[0,1] neg_lo:[1,0]
	ds_write2_b64 v136, v[104:105], v[4:5] offset0:4 offset1:5
	v_pk_fma_f32 v[4:5], v[116:117], v[4:5], v[6:7] op_sel_hi:[1,0,1]
	v_add_u32_e32 v110, 0x8830, v136
	ds_write2_b64 v122, v[108:109], v[4:5] offset1:1
	ds_read2_b64 v[4:7], v110 offset1:1
	v_pk_mul_f32 v[104:105], v[116:117], s[8:9] op_sel:[1,0]
	v_mov_b32_e32 v111, v177
	v_pk_fma_f32 v[104:105], v[116:117], s[30:31], v[104:105] op_sel_hi:[0,1,1]
	s_waitcnt lgkmcnt(0)
	v_pk_mul_f32 v[108:109], v[104:105], v[4:5] op_sel_hi:[1,0] neg_hi:[1,0]
	s_nop 0
	v_pk_fma_f32 v[4:5], v[104:105], v[4:5], v[108:109] op_sel:[1,1,0] op_sel_hi:[0,1,1]
	v_pk_add_f32 v[4:5], v[112:113], v[4:5]
	s_nop 0
	v_pk_mul_f32 v[2:3], v[2:3], v[4:5]
	s_nop 0
	v_pk_mul_f32 v[4:5], v[104:105], v[2:3] op_sel:[1,1] op_sel_hi:[0,1] neg_lo:[1,0]
	v_pk_mul_f32 v[106:107], v[104:105], s[8:9] op_sel:[1,0]
	v_pk_fma_f32 v[4:5], v[104:105], v[2:3], v[4:5] op_sel_hi:[1,0,1]
	v_pk_fma_f32 v[104:105], v[104:105], s[30:31], v[106:107] op_sel_hi:[0,1,1]
	v_pk_mul_f32 v[108:109], v[104:105], v[6:7] op_sel_hi:[1,0] neg_hi:[1,0]
	v_mov_b32_e32 v6, v7
	v_pk_fma_f32 v[6:7], v[104:105], v[6:7], v[108:109] op_sel:[1,1,0] op_sel_hi:[0,1,1]
	v_pk_add_f32 v[6:7], v[114:115], v[6:7]
	s_nop 0
	v_pk_mul_f32 v[0:1], v[0:1], v[6:7]
	ds_write2_b64 v136, v[2:3], v[0:1] offset0:6 offset1:7
	v_pk_mul_f32 v[2:3], v[104:105], v[0:1] op_sel:[1,1] op_sel_hi:[0,1] neg_lo:[1,0]
	v_pk_fma_f32 v[0:1], v[104:105], v[0:1], v[2:3] op_sel_hi:[1,0,1]
	ds_write2_b64 v110, v[4:5], v[0:1] offset1:1
	v_and_b32_e32 v0, 0x1ff, v212
	v_lshl_add_u32 v0, v0, 3, 0
	v_add_u32_e32 v234, 0x11040, v0
	v_mov_b32_e32 v110, 1.0
	v_pk_mul_f32 v[2:3], v[208:209], v[208:209] op_sel:[1,1] op_sel_hi:[0,1] neg_lo:[1,0]
	s_waitcnt lgkmcnt(0)
	v_pk_fma_f32 v[2:3], v[208:209], v[208:209], v[2:3] op_sel_hi:[0,1,1]
	v_pk_mul_f32 v[104:105], v[2:3], v[2:3] op_sel:[1,1] op_sel_hi:[1,0] neg_lo:[0,1]
	v_pk_mul_f32 v[4:5], v[208:209], v[176:177] op_sel:[1,1] op_sel_hi:[0,1] neg_lo:[1,0]
	v_pk_fma_f32 v[104:105], v[2:3], v[2:3], v[104:105] op_sel_hi:[1,0,1]
	v_pk_fma_f32 v[114:115], v[208:209], v[110:111], v[4:5] op_sel_hi:[1,0,1]
	v_pk_mul_f32 v[0:1], v[176:177], v[2:3] op_sel:[1,1] op_sel_hi:[1,0] neg_lo:[0,1]
	s_nop 0
	v_pk_fma_f32 v[116:117], v[110:111], v[2:3], v[0:1] op_sel_hi:[0,1,1]
	v_pk_mul_f32 v[0:1], v[114:115], v[2:3] op_sel:[1,1] op_sel_hi:[1,0] neg_lo:[0,1]
	v_pk_mul_f32 v[108:109], v[104:105], v[104:105] op_sel:[1,1] op_sel_hi:[1,0] neg_lo:[0,1]
	v_pk_fma_f32 v[118:119], v[2:3], v[114:115], v[0:1] op_sel_hi:[1,0,1]
	v_pk_mul_f32 v[0:1], v[176:177], v[104:105] op_sel:[1,1] op_sel_hi:[1,0] neg_lo:[0,1]
	s_nop 0
	v_pk_fma_f32 v[120:121], v[110:111], v[104:105], v[0:1] op_sel_hi:[0,1,1]
	v_pk_mul_f32 v[0:1], v[114:115], v[104:105] op_sel:[1,1] op_sel_hi:[1,0] neg_lo:[0,1]
	s_barrier
	v_pk_fma_f32 v[122:123], v[114:115], v[104:105], v[0:1] op_sel_hi:[0,1,1]
	v_pk_mul_f32 v[0:1], v[116:117], v[104:105] op_sel:[1,1] op_sel_hi:[1,0] neg_lo:[0,1]
	s_nop 0
	v_pk_fma_f32 v[124:125], v[104:105], v[116:117], v[0:1] op_sel_hi:[1,0,1]
	v_pk_mul_f32 v[0:1], v[118:119], v[104:105] op_sel:[1,1] op_sel_hi:[1,0] neg_lo:[0,1]
	s_nop 0
	v_pk_fma_f32 v[126:127], v[104:105], v[118:119], v[0:1] op_sel_hi:[1,0,1]
	v_pk_fma_f32 v[0:1], v[104:105], v[104:105], v[108:109] op_sel_hi:[1,0,1]
	s_nop 0
	v_pk_mul_f32 v[2:3], v[176:177], v[0:1] op_sel:[1,1] op_sel_hi:[1,0] neg_lo:[0,1]
	s_nop 0
	v_pk_fma_f32 v[112:113], v[110:111], v[0:1], v[2:3] op_sel_hi:[0,1,1]
	v_pk_mul_f32 v[2:3], v[114:115], v[0:1] op_sel:[1,1] op_sel_hi:[1,0] neg_lo:[0,1]
	s_nop 0
	v_pk_fma_f32 v[108:109], v[114:115], v[0:1], v[2:3] op_sel_hi:[0,1,1]
	v_pk_mul_f32 v[2:3], v[116:117], v[0:1] op_sel:[1,1] op_sel_hi:[1,0] neg_lo:[0,1]
	s_nop 0
	v_pk_fma_f32 v[106:107], v[116:117], v[0:1], v[2:3] op_sel_hi:[0,1,1]
	v_pk_mul_f32 v[2:3], v[118:119], v[0:1] op_sel:[1,1] op_sel_hi:[1,0] neg_lo:[0,1]
	s_nop 0
	v_pk_fma_f32 v[104:105], v[118:119], v[0:1], v[2:3] op_sel_hi:[0,1,1]
	v_pk_mul_f32 v[2:3], v[120:121], v[0:1] op_sel:[1,1] op_sel_hi:[1,0] neg_lo:[0,1]
	s_nop 0
	v_pk_fma_f32 v[6:7], v[0:1], v[120:121], v[2:3] op_sel_hi:[1,0,1]
	v_pk_mul_f32 v[2:3], v[122:123], v[0:1] op_sel:[1,1] op_sel_hi:[1,0] neg_lo:[0,1]
	s_nop 0
	v_pk_fma_f32 v[4:5], v[0:1], v[122:123], v[2:3] op_sel_hi:[1,0,1]
	v_pk_mul_f32 v[2:3], v[124:125], v[0:1] op_sel:[1,1] op_sel_hi:[1,0] neg_lo:[0,1]
	v_pk_mul_f32 v[128:129], v[126:127], v[0:1] op_sel:[1,1] op_sel_hi:[1,0] neg_lo:[0,1]
	v_pk_fma_f32 v[2:3], v[0:1], v[124:125], v[2:3] op_sel_hi:[1,0,1]
	v_pk_fma_f32 v[0:1], v[0:1], v[126:127], v[128:129] op_sel_hi:[1,0,1]
	v_mov_b32_e32 v128, v206
	s_nop 0
	v_lshlrev_b32_sdwa v129, v228, v128 dst_sel:DWORD dst_unused:UNUSED_PAD src0_sel:DWORD src1_sel:BYTE_0
	v_lshrrev_b32_e32 v128, 1, v206
	v_and_b32_e32 v128, 0x78, v128
	v_add3_u32 v164, v207, v129, v128
	ds_read_b64 v[128:129], v164
	ds_read_b64 v[130:131], v164 offset:2176
	ds_read_b64 v[132:133], v164 offset:4352
	ds_read_b64 v[134:135], v164 offset:6528
	ds_read_b64 v[136:137], v164 offset:8704
	ds_read_b64 v[138:139], v164 offset:10880
	ds_read_b64 v[140:141], v164 offset:13056
	ds_read_b64 v[142:143], v164 offset:15232
	ds_read_b64 v[144:145], v164 offset:17408
	ds_read_b64 v[146:147], v164 offset:19584
	ds_read_b64 v[148:149], v164 offset:21760
	ds_read_b64 v[150:151], v164 offset:23936
	ds_read_b64 v[152:153], v164 offset:26112
	ds_read_b64 v[154:155], v164 offset:28288
	ds_read_b64 v[156:157], v164 offset:30464
	ds_read_b64 v[158:159], v164 offset:32640
	s_waitcnt lgkmcnt(7)
	v_pk_add_f32 v[160:161], v[128:129], v[144:145]
	v_pk_add_f32 v[128:129], v[128:129], v[144:145] neg_lo:[0,1] neg_hi:[0,1]
	s_waitcnt lgkmcnt(3)
	v_pk_add_f32 v[144:145], v[136:137], v[152:153]
	v_pk_add_f32 v[136:137], v[136:137], v[152:153] neg_lo:[0,1] neg_hi:[0,1]
	s_nop 0
	v_pk_add_f32 v[162:163], v[128:129], v[136:137] op_sel:[0,1] op_sel_hi:[1,0] neg_hi:[0,1]
	v_pk_add_f32 v[128:129], v[128:129], v[136:137] op_sel:[0,1] op_sel_hi:[1,0] neg_lo:[0,1]
	v_pk_add_f32 v[152:153], v[130:131], v[146:147]
	v_pk_add_f32 v[130:131], v[130:131], v[146:147] neg_lo:[0,1] neg_hi:[0,1]
	s_waitcnt lgkmcnt(2)
	v_pk_add_f32 v[146:147], v[138:139], v[154:155]
	v_pk_add_f32 v[138:139], v[138:139], v[154:155] neg_lo:[0,1] neg_hi:[0,1]
	v_pk_add_f32 v[136:137], v[160:161], v[144:145]
	v_xor_b32_e32 v155, 0x80000000, v138
	v_mov_b32_e32 v154, v139
	v_pk_add_f32 v[138:139], v[152:153], v[146:147]
	v_pk_add_f32 v[146:147], v[152:153], v[146:147] neg_lo:[0,1] neg_hi:[0,1]
	v_pk_add_f32 v[152:153], v[132:133], v[148:149]
	v_pk_add_f32 v[132:133], v[132:133], v[148:149] neg_lo:[0,1] neg_hi:[0,1]
	s_waitcnt lgkmcnt(1)
	v_pk_add_f32 v[148:149], v[140:141], v[156:157]
	v_pk_add_f32 v[140:141], v[140:141], v[156:157] neg_lo:[0,1] neg_hi:[0,1]
	v_pk_add_f32 v[144:145], v[160:161], v[144:145] neg_lo:[0,1] neg_hi:[0,1]
	v_pk_add_f32 v[160:161], v[130:131], v[154:155]
	v_pk_add_f32 v[130:131], v[130:131], v[154:155] neg_lo:[0,1] neg_hi:[0,1]
	v_xor_b32_e32 v155, 0x80000000, v140
	v_mov_b32_e32 v154, v141
	v_pk_add_f32 v[140:141], v[152:153], v[148:149]
	v_pk_add_f32 v[148:149], v[152:153], v[148:149] neg_lo:[0,1] neg_hi:[0,1]
	v_pk_add_f32 v[152:153], v[134:135], v[150:151]
	v_pk_add_f32 v[134:135], v[134:135], v[150:151] neg_lo:[0,1] neg_hi:[0,1]
	s_waitcnt lgkmcnt(0)
	v_pk_add_f32 v[150:151], v[142:143], v[158:159]
	v_pk_add_f32 v[142:143], v[142:143], v[158:159] neg_lo:[0,1] neg_hi:[0,1]
	v_pk_add_f32 v[156:157], v[132:133], v[154:155]
	v_pk_add_f32 v[132:133], v[132:133], v[154:155] neg_lo:[0,1] neg_hi:[0,1]
	v_pk_add_f32 v[158:159], v[134:135], v[142:143] op_sel:[0,1] op_sel_hi:[1,0] neg_hi:[0,1]
	v_pk_add_f32 v[134:135], v[134:135], v[142:143] op_sel:[0,1] op_sel_hi:[1,0] neg_lo:[0,1]
	v_pk_mul_f32 v[154:155], v[146:147], s[12:13] op_sel:[1,0] op_sel_hi:[0,0] neg_lo:[1,0]
	v_pk_add_f32 v[142:143], v[152:153], v[150:151]
	v_pk_fma_f32 v[146:147], v[146:147], s[12:13], v[154:155] op_sel_hi:[1,0,1] neg_lo:[0,0,1] neg_hi:[0,0,1]
	v_pk_mul_f32 v[154:155], v[130:131], s[36:37] op_sel:[1,0] op_sel_hi:[0,0] neg_lo:[1,0]
	v_pk_add_f32 v[150:151], v[152:153], v[150:151] neg_lo:[0,1] neg_hi:[0,1]
	v_pk_fma_f32 v[130:131], v[130:131], s[22:23], v[154:155] op_sel_hi:[1,0,1] neg_lo:[0,0,1] neg_hi:[0,0,1]
	v_pk_mul_f32 v[154:155], v[156:157], s[12:13] op_sel:[1,0] op_sel_hi:[0,0] neg_lo:[1,0]
	v_pk_fma_f32 v[154:155], v[156:157], s[12:13], v[154:155] op_sel_hi:[1,0,1] neg_lo:[0,0,1] neg_hi:[0,0,1]
	v_pk_fma_f32 v[148:149], v[148:149], 0, v[148:149] op_sel:[0,0,1] op_sel_hi:[1,0,0] neg_hi:[0,0,1]
	v_pk_mul_f32 v[156:157], v[132:133], s[12:13] op_sel:[1,0] op_sel_hi:[0,0] neg_lo:[1,0]
	v_pk_fma_f32 v[132:133], v[132:133], s[18:19], v[156:157] op_sel_hi:[1,0,1] neg_lo:[0,0,1] neg_hi:[0,0,1]
	v_pk_mul_f32 v[156:157], v[158:159], s[36:37] op_sel:[1,0] op_sel_hi:[0,0] neg_lo:[1,0]
	v_pk_mul_f32 v[152:153], v[160:161], s[22:23] op_sel:[1,0] op_sel_hi:[0,0] neg_lo:[1,0]
	v_pk_fma_f32 v[156:157], v[158:159], s[22:23], v[156:157] op_sel_hi:[1,0,1] neg_lo:[0,0,1] neg_hi:[0,0,1]
	v_pk_mul_f32 v[158:159], v[150:151], s[12:13] op_sel:[1,0] op_sel_hi:[0,0] neg_lo:[1,0]
	v_pk_fma_f32 v[152:153], v[160:161], s[36:37], v[152:153] op_sel_hi:[1,0,1] neg_lo:[0,0,1] neg_hi:[0,0,1]
	v_pk_fma_f32 v[150:151], v[150:151], s[18:19], v[158:159] op_sel_hi:[1,0,1] neg_lo:[0,0,1] neg_hi:[0,0,1]
	v_xor_b32_e32 v158, 0x80000000, v135
	v_mov_b32_e32 v159, v134
	v_pk_mul_f32 v[134:135], v[134:135], s[36:37] op_sel_hi:[1,0]
	s_nop 0
	v_pk_fma_f32 v[134:135], v[158:159], s[22:23], v[134:135] op_sel_hi:[1,0,1] neg_lo:[0,0,1] neg_hi:[0,0,1]
	v_pk_add_f32 v[158:159], v[136:137], v[140:141]
	v_pk_add_f32 v[136:137], v[136:137], v[140:141] neg_lo:[0,1] neg_hi:[0,1]
	v_pk_add_f32 v[140:141], v[138:139], v[142:143]
	v_pk_add_f32 v[138:139], v[138:139], v[142:143] neg_lo:[0,1] neg_hi:[0,1]
	s_nop 0
	v_xor_b32_e32 v143, 0x80000000, v138
	v_mov_b32_e32 v142, v139
	v_pk_add_f32 v[138:139], v[158:159], v[140:141]
	v_pk_add_f32 v[140:141], v[158:159], v[140:141] neg_lo:[0,1] neg_hi:[0,1]
	v_pk_add_f32 v[158:159], v[152:153], v[156:157]
	v_pk_add_f32 v[152:153], v[152:153], v[156:157] neg_lo:[0,1] neg_hi:[0,1]
	v_pk_add_f32 v[160:161], v[136:137], v[142:143]
	v_pk_add_f32 v[136:137], v[136:137], v[142:143] neg_lo:[0,1] neg_hi:[0,1]
	v_pk_add_f32 v[142:143], v[162:163], v[154:155]
	v_pk_add_f32 v[154:155], v[162:163], v[154:155] neg_lo:[0,1] neg_hi:[0,1]
	s_nop 0
	v_pk_add_f32 v[162:163], v[154:155], v[152:153] op_sel:[0,1] op_sel_hi:[1,0] neg_hi:[0,1]
	v_pk_add_f32 v[154:155], v[154:155], v[152:153] op_sel:[0,1] op_sel_hi:[1,0] neg_lo:[0,1]
	v_pk_add_f32 v[156:157], v[144:145], v[148:149]
	v_pk_add_f32 v[144:145], v[144:145], v[148:149] neg_lo:[0,1] neg_hi:[0,1]
	v_pk_add_f32 v[148:149], v[146:147], v[150:151]
	v_pk_add_f32 v[146:147], v[146:147], v[150:151] neg_lo:[0,1] neg_hi:[0,1]
	v_pk_add_f32 v[152:153], v[142:143], v[158:159]
	v_pk_add_f32 v[142:143], v[142:143], v[158:159] neg_lo:[0,1] neg_hi:[0,1]
	v_pk_add_f32 v[158:159], v[144:145], v[146:147] op_sel:[0,1] op_sel_hi:[1,0] neg_hi:[0,1]
	v_pk_add_f32 v[144:145], v[144:145], v[146:147] op_sel:[0,1] op_sel_hi:[1,0] neg_lo:[0,1]
	v_pk_add_f32 v[150:151], v[128:129], v[132:133]
	v_pk_add_f32 v[128:129], v[128:129], v[132:133] neg_lo:[0,1] neg_hi:[0,1]
	v_pk_add_f32 v[132:133], v[130:131], v[134:135]
	v_pk_add_f32 v[130:131], v[130:131], v[134:135] neg_lo:[0,1] neg_hi:[0,1]
	v_pk_add_f32 v[146:147], v[156:157], v[148:149]
	v_pk_add_f32 v[148:149], v[156:157], v[148:149] neg_lo:[0,1] neg_hi:[0,1]
	v_pk_add_f32 v[156:157], v[128:129], v[130:131] op_sel:[0,1] op_sel_hi:[1,0] neg_hi:[0,1]
	v_pk_add_f32 v[128:129], v[128:129], v[130:131] op_sel:[0,1] op_sel_hi:[1,0] neg_lo:[0,1]
	v_xor_b32_e32 v134, 0x80000000, v111
	v_mov_b32_e32 v135, v110
	v_pk_mul_f32 v[134:135], v[134:135], v[138:139] op_sel:[0,1]
	v_pk_add_f32 v[130:131], v[150:151], v[132:133]
	v_pk_fma_f32 v[110:111], v[110:111], v[138:139], v[134:135] op_sel_hi:[1,0,1]
	ds_write_b64 v164, v[110:111]
	v_pk_mul_f32 v[110:111], v[114:115], v[152:153] op_sel:[1,1] op_sel_hi:[0,1] neg_lo:[1,0]
	v_pk_add_f32 v[132:133], v[150:151], v[132:133] neg_lo:[0,1] neg_hi:[0,1]
	v_pk_fma_f32 v[110:111], v[114:115], v[152:153], v[110:111] op_sel_hi:[1,0,1]
	ds_write_b64 v164, v[110:111] offset:2176
	v_pk_mul_f32 v[110:111], v[116:117], v[146:147] op_sel:[1,1] op_sel_hi:[0,1] neg_lo:[1,0]
	v_pk_fma_f32 v[110:111], v[116:117], v[146:147], v[110:111] op_sel_hi:[1,0,1]
	ds_write_b64 v164, v[110:111] offset:4352
	v_pk_mul_f32 v[110:111], v[118:119], v[130:131] op_sel:[1,1] op_sel_hi:[0,1] neg_lo:[1,0]
	v_pk_fma_f32 v[110:111], v[118:119], v[130:131], v[110:111] op_sel_hi:[1,0,1]
	ds_write_b64 v164, v[110:111] offset:6528
	v_pk_mul_f32 v[110:111], v[120:121], v[160:161] op_sel:[1,1] op_sel_hi:[0,1] neg_lo:[1,0]
	v_pk_fma_f32 v[110:111], v[120:121], v[160:161], v[110:111] op_sel_hi:[1,0,1]
	ds_write_b64 v164, v[110:111] offset:8704
	v_pk_mul_f32 v[110:111], v[122:123], v[162:163] op_sel:[1,1] op_sel_hi:[0,1] neg_lo:[1,0]
	v_pk_fma_f32 v[110:111], v[122:123], v[162:163], v[110:111] op_sel_hi:[1,0,1]
	ds_write_b64 v164, v[110:111] offset:10880
	v_pk_mul_f32 v[110:111], v[124:125], v[158:159] op_sel:[1,1] op_sel_hi:[0,1] neg_lo:[1,0]
	v_pk_fma_f32 v[110:111], v[124:125], v[158:159], v[110:111] op_sel_hi:[1,0,1]
	ds_write_b64 v164, v[110:111] offset:13056
	v_pk_mul_f32 v[110:111], v[126:127], v[156:157] op_sel:[1,1] op_sel_hi:[0,1] neg_lo:[1,0]
	v_pk_fma_f32 v[110:111], v[126:127], v[156:157], v[110:111] op_sel_hi:[1,0,1]
	ds_write_b64 v164, v[110:111] offset:15232
	v_pk_mul_f32 v[110:111], v[112:113], v[140:141] op_sel:[1,1] op_sel_hi:[0,1] neg_lo:[1,0]
	v_pk_fma_f32 v[110:111], v[112:113], v[140:141], v[110:111] op_sel_hi:[1,0,1]
	ds_write_b64 v164, v[110:111] offset:17408
	v_pk_mul_f32 v[110:111], v[108:109], v[142:143] op_sel:[1,1] op_sel_hi:[0,1] neg_lo:[1,0]
	v_pk_fma_f32 v[108:109], v[108:109], v[142:143], v[110:111] op_sel_hi:[1,0,1]
	ds_write_b64 v164, v[108:109] offset:19584
	v_pk_mul_f32 v[108:109], v[106:107], v[148:149] op_sel:[1,1] op_sel_hi:[0,1] neg_lo:[1,0]
	v_pk_fma_f32 v[106:107], v[106:107], v[148:149], v[108:109] op_sel_hi:[1,0,1]
	ds_write_b64 v164, v[106:107] offset:21760
	v_pk_mul_f32 v[106:107], v[104:105], v[132:133] op_sel:[1,1] op_sel_hi:[0,1] neg_lo:[1,0]
	v_pk_fma_f32 v[104:105], v[104:105], v[132:133], v[106:107] op_sel_hi:[1,0,1]
	ds_write_b64 v164, v[104:105] offset:23936
	v_pk_mul_f32 v[104:105], v[6:7], v[136:137] op_sel:[1,1] op_sel_hi:[0,1] neg_lo:[1,0]
	v_pk_fma_f32 v[6:7], v[6:7], v[136:137], v[104:105] op_sel_hi:[1,0,1]
	ds_write_b64 v164, v[6:7] offset:26112
	v_pk_mul_f32 v[6:7], v[4:5], v[154:155] op_sel:[1,1] op_sel_hi:[0,1] neg_lo:[1,0]
	v_pk_fma_f32 v[4:5], v[4:5], v[154:155], v[6:7] op_sel_hi:[1,0,1]
	ds_write_b64 v164, v[4:5] offset:28288
	v_pk_mul_f32 v[4:5], v[2:3], v[144:145] op_sel:[1,1] op_sel_hi:[0,1] neg_lo:[1,0]
	v_pk_fma_f32 v[2:3], v[2:3], v[144:145], v[4:5] op_sel_hi:[1,0,1]
	ds_write_b64 v164, v[2:3] offset:30464
	v_pk_mul_f32 v[2:3], v[0:1], v[128:129] op_sel:[1,1] op_sel_hi:[0,1] neg_lo:[1,0]
	v_pk_fma_f32 v[0:1], v[0:1], v[128:129], v[2:3] op_sel_hi:[1,0,1]
	ds_write_b64 v164, v[0:1] offset:32640
	v_mov_b32_e32 v116, 1.0
	v_pk_mul_f32 v[2:3], v[210:211], v[210:211] op_sel:[1,1] op_sel_hi:[0,1] neg_lo:[1,0]
	v_mov_b32_e32 v117, v177
	v_pk_fma_f32 v[2:3], v[210:211], v[210:211], v[2:3] op_sel_hi:[0,1,1]
	v_pk_mul_f32 v[104:105], v[2:3], v[2:3] op_sel:[1,1] op_sel_hi:[1,0] neg_lo:[0,1]
	v_pk_mul_f32 v[4:5], v[210:211], v[176:177] op_sel:[1,1] op_sel_hi:[0,1] neg_lo:[1,0]
	v_pk_fma_f32 v[104:105], v[2:3], v[2:3], v[104:105] op_sel_hi:[1,0,1]
	v_pk_fma_f32 v[126:127], v[210:211], v[116:117], v[4:5] op_sel_hi:[1,0,1]
	v_pk_mul_f32 v[0:1], v[176:177], v[2:3] op_sel:[1,1] op_sel_hi:[1,0] neg_lo:[0,1]
	s_nop 0
	v_pk_fma_f32 v[124:125], v[116:117], v[2:3], v[0:1] op_sel_hi:[0,1,1]
	v_pk_mul_f32 v[0:1], v[126:127], v[2:3] op_sel:[1,1] op_sel_hi:[1,0] neg_lo:[0,1]
	v_pk_mul_f32 v[108:109], v[104:105], v[104:105] op_sel:[1,1] op_sel_hi:[1,0] neg_lo:[0,1]
	v_pk_fma_f32 v[122:123], v[2:3], v[126:127], v[0:1] op_sel_hi:[1,0,1]
	v_pk_mul_f32 v[0:1], v[176:177], v[104:105] op_sel:[1,1] op_sel_hi:[1,0] neg_lo:[0,1]
	s_nop 0
	v_pk_fma_f32 v[120:121], v[116:117], v[104:105], v[0:1] op_sel_hi:[0,1,1]
	v_pk_mul_f32 v[0:1], v[126:127], v[104:105] op_sel:[1,1] op_sel_hi:[1,0] neg_lo:[0,1]
	s_waitcnt lgkmcnt(0)
	v_pk_fma_f32 v[118:119], v[126:127], v[104:105], v[0:1] op_sel_hi:[0,1,1]
	v_pk_mul_f32 v[0:1], v[124:125], v[104:105] op_sel:[1,1] op_sel_hi:[1,0] neg_lo:[0,1]
	s_barrier
	v_pk_fma_f32 v[114:115], v[104:105], v[124:125], v[0:1] op_sel_hi:[1,0,1]
	v_pk_mul_f32 v[0:1], v[122:123], v[104:105] op_sel:[1,1] op_sel_hi:[1,0] neg_lo:[0,1]
	s_nop 0
	v_pk_fma_f32 v[112:113], v[104:105], v[122:123], v[0:1] op_sel_hi:[1,0,1]
	v_pk_fma_f32 v[0:1], v[104:105], v[104:105], v[108:109] op_sel_hi:[1,0,1]
	s_nop 0
	v_pk_mul_f32 v[2:3], v[176:177], v[0:1] op_sel:[1,1] op_sel_hi:[1,0] neg_lo:[0,1]
	s_nop 0
	v_pk_fma_f32 v[110:111], v[116:117], v[0:1], v[2:3] op_sel_hi:[0,1,1]
	v_pk_mul_f32 v[2:3], v[126:127], v[0:1] op_sel:[1,1] op_sel_hi:[1,0] neg_lo:[0,1]
	s_nop 0
	v_pk_fma_f32 v[108:109], v[126:127], v[0:1], v[2:3] op_sel_hi:[0,1,1]
	v_pk_mul_f32 v[2:3], v[124:125], v[0:1] op_sel:[1,1] op_sel_hi:[1,0] neg_lo:[0,1]
	s_nop 0
	v_pk_fma_f32 v[106:107], v[124:125], v[0:1], v[2:3] op_sel_hi:[0,1,1]
	v_pk_mul_f32 v[2:3], v[122:123], v[0:1] op_sel:[1,1] op_sel_hi:[1,0] neg_lo:[0,1]
	s_nop 0
	v_pk_fma_f32 v[104:105], v[122:123], v[0:1], v[2:3] op_sel_hi:[0,1,1]
	v_pk_mul_f32 v[2:3], v[120:121], v[0:1] op_sel:[1,1] op_sel_hi:[1,0] neg_lo:[0,1]
	s_nop 0
	v_pk_fma_f32 v[6:7], v[0:1], v[120:121], v[2:3] op_sel_hi:[1,0,1]
	v_pk_mul_f32 v[2:3], v[118:119], v[0:1] op_sel:[1,1] op_sel_hi:[1,0] neg_lo:[0,1]
	s_nop 0
	v_pk_fma_f32 v[4:5], v[0:1], v[118:119], v[2:3] op_sel_hi:[1,0,1]
	v_pk_mul_f32 v[2:3], v[114:115], v[0:1] op_sel:[1,1] op_sel_hi:[1,0] neg_lo:[0,1]
	v_pk_mul_f32 v[128:129], v[112:113], v[0:1] op_sel:[1,1] op_sel_hi:[1,0] neg_lo:[0,1]
	v_pk_fma_f32 v[2:3], v[0:1], v[114:115], v[2:3] op_sel_hi:[1,0,1]
	v_pk_fma_f32 v[0:1], v[0:1], v[112:113], v[128:129] op_sel_hi:[1,0,1]
	s_nop 0
	v_bfe_u32 v129, v206, 4, 4
	v_and_b32_e32 v128, 15, v206
	v_mul_u32_u24_e32 v129, 0x880, v129
	v_lshlrev_b32_e32 v128, 3, v128
	v_add3_u32 v184, v207, v129, v128
	ds_read2_b64 v[128:131], v184 offset1:17
	ds_read2_b64 v[132:135], v184 offset0:34 offset1:51
	ds_read2_b64 v[136:139], v184 offset0:68 offset1:85
	ds_read2_b64 v[140:143], v184 offset0:102 offset1:119
	ds_read2_b64 v[144:147], v184 offset0:136 offset1:153
	ds_read2_b64 v[148:151], v184 offset0:170 offset1:187
	ds_read2_b64 v[152:155], v184 offset0:204 offset1:221
	ds_read2_b64 v[156:159], v184 offset0:238 offset1:255
	s_waitcnt lgkmcnt(3)
	v_pk_add_f32 v[160:161], v[128:129], v[144:145]
	v_pk_add_f32 v[128:129], v[128:129], v[144:145] neg_lo:[0,1] neg_hi:[0,1]
	s_waitcnt lgkmcnt(1)
	v_pk_add_f32 v[144:145], v[136:137], v[152:153]
	v_pk_add_f32 v[136:137], v[136:137], v[152:153] neg_lo:[0,1] neg_hi:[0,1]
	s_nop 0
	v_pk_add_f32 v[162:163], v[128:129], v[136:137] op_sel:[0,1] op_sel_hi:[1,0] neg_hi:[0,1]
	v_pk_add_f32 v[128:129], v[128:129], v[136:137] op_sel:[0,1] op_sel_hi:[1,0] neg_lo:[0,1]
	v_pk_add_f32 v[152:153], v[130:131], v[146:147]
	v_pk_add_f32 v[130:131], v[130:131], v[146:147] neg_lo:[0,1] neg_hi:[0,1]
	v_pk_add_f32 v[146:147], v[138:139], v[154:155]
	v_pk_add_f32 v[138:139], v[138:139], v[154:155] neg_lo:[0,1] neg_hi:[0,1]
	v_pk_add_f32 v[136:137], v[160:161], v[144:145]
	v_xor_b32_e32 v155, 0x80000000, v138
	v_mov_b32_e32 v154, v139
	v_pk_add_f32 v[138:139], v[152:153], v[146:147]
	v_pk_add_f32 v[146:147], v[152:153], v[146:147] neg_lo:[0,1] neg_hi:[0,1]
	v_pk_add_f32 v[152:153], v[132:133], v[148:149]
	v_pk_add_f32 v[132:133], v[132:133], v[148:149] neg_lo:[0,1] neg_hi:[0,1]
	s_waitcnt lgkmcnt(0)
	v_pk_add_f32 v[148:149], v[140:141], v[156:157]
	v_pk_add_f32 v[140:141], v[140:141], v[156:157] neg_lo:[0,1] neg_hi:[0,1]
	v_pk_add_f32 v[144:145], v[160:161], v[144:145] neg_lo:[0,1] neg_hi:[0,1]
	v_pk_add_f32 v[160:161], v[130:131], v[154:155]
	v_pk_add_f32 v[130:131], v[130:131], v[154:155] neg_lo:[0,1] neg_hi:[0,1]
	v_xor_b32_e32 v155, 0x80000000, v140
	v_mov_b32_e32 v154, v141
	v_pk_add_f32 v[140:141], v[152:153], v[148:149]
	v_pk_add_f32 v[148:149], v[152:153], v[148:149] neg_lo:[0,1] neg_hi:[0,1]
	v_pk_add_f32 v[152:153], v[134:135], v[150:151]
	v_pk_add_f32 v[134:135], v[134:135], v[150:151] neg_lo:[0,1] neg_hi:[0,1]
	v_pk_add_f32 v[150:151], v[142:143], v[158:159]
	v_pk_add_f32 v[142:143], v[142:143], v[158:159] neg_lo:[0,1] neg_hi:[0,1]
	v_pk_add_f32 v[156:157], v[132:133], v[154:155]
	v_pk_add_f32 v[132:133], v[132:133], v[154:155] neg_lo:[0,1] neg_hi:[0,1]
	v_pk_add_f32 v[158:159], v[134:135], v[142:143] op_sel:[0,1] op_sel_hi:[1,0] neg_hi:[0,1]
	v_pk_add_f32 v[134:135], v[134:135], v[142:143] op_sel:[0,1] op_sel_hi:[1,0] neg_lo:[0,1]
	v_pk_mul_f32 v[154:155], v[146:147], s[12:13] op_sel:[1,0] op_sel_hi:[0,0] neg_lo:[1,0]
	v_pk_add_f32 v[142:143], v[152:153], v[150:151]
	v_pk_fma_f32 v[146:147], v[146:147], s[12:13], v[154:155] op_sel_hi:[1,0,1] neg_lo:[0,0,1] neg_hi:[0,0,1]
	v_pk_mul_f32 v[154:155], v[130:131], s[36:37] op_sel:[1,0] op_sel_hi:[0,0] neg_lo:[1,0]
	v_pk_add_f32 v[150:151], v[152:153], v[150:151] neg_lo:[0,1] neg_hi:[0,1]
	v_pk_fma_f32 v[130:131], v[130:131], s[22:23], v[154:155] op_sel_hi:[1,0,1] neg_lo:[0,0,1] neg_hi:[0,0,1]
	v_pk_mul_f32 v[154:155], v[156:157], s[12:13] op_sel:[1,0] op_sel_hi:[0,0] neg_lo:[1,0]
	v_pk_fma_f32 v[154:155], v[156:157], s[12:13], v[154:155] op_sel_hi:[1,0,1] neg_lo:[0,0,1] neg_hi:[0,0,1]
	v_pk_fma_f32 v[148:149], v[148:149], 0, v[148:149] op_sel:[0,0,1] op_sel_hi:[1,0,0] neg_hi:[0,0,1]
	v_pk_mul_f32 v[156:157], v[132:133], s[12:13] op_sel:[1,0] op_sel_hi:[0,0] neg_lo:[1,0]
	v_pk_fma_f32 v[132:133], v[132:133], s[18:19], v[156:157] op_sel_hi:[1,0,1] neg_lo:[0,0,1] neg_hi:[0,0,1]
	v_pk_mul_f32 v[156:157], v[158:159], s[36:37] op_sel:[1,0] op_sel_hi:[0,0] neg_lo:[1,0]
	v_pk_mul_f32 v[152:153], v[160:161], s[22:23] op_sel:[1,0] op_sel_hi:[0,0] neg_lo:[1,0]
	v_pk_fma_f32 v[156:157], v[158:159], s[22:23], v[156:157] op_sel_hi:[1,0,1] neg_lo:[0,0,1] neg_hi:[0,0,1]
	v_pk_mul_f32 v[158:159], v[150:151], s[12:13] op_sel:[1,0] op_sel_hi:[0,0] neg_lo:[1,0]
	v_pk_fma_f32 v[152:153], v[160:161], s[36:37], v[152:153] op_sel_hi:[1,0,1] neg_lo:[0,0,1] neg_hi:[0,0,1]
	v_pk_fma_f32 v[150:151], v[150:151], s[18:19], v[158:159] op_sel_hi:[1,0,1] neg_lo:[0,0,1] neg_hi:[0,0,1]
	v_xor_b32_e32 v158, 0x80000000, v135
	v_mov_b32_e32 v159, v134
	v_pk_mul_f32 v[134:135], v[134:135], s[36:37] op_sel_hi:[1,0]
	s_nop 0
	v_pk_fma_f32 v[134:135], v[158:159], s[22:23], v[134:135] op_sel_hi:[1,0,1] neg_lo:[0,0,1] neg_hi:[0,0,1]
	v_pk_add_f32 v[158:159], v[136:137], v[140:141]
	v_pk_add_f32 v[136:137], v[136:137], v[140:141] neg_lo:[0,1] neg_hi:[0,1]
	v_pk_add_f32 v[140:141], v[138:139], v[142:143]
	v_pk_add_f32 v[138:139], v[138:139], v[142:143] neg_lo:[0,1] neg_hi:[0,1]
	v_pk_add_f32 v[164:165], v[158:159], v[140:141] neg_lo:[0,1] neg_hi:[0,1]
	v_pk_add_f32 v[160:161], v[136:137], v[138:139] op_sel:[0,1] op_sel_hi:[1,0] neg_hi:[0,1]
	v_pk_add_f32 v[166:167], v[136:137], v[138:139] op_sel:[0,1] op_sel_hi:[1,0] neg_lo:[0,1]
	v_pk_add_f32 v[142:143], v[152:153], v[156:157]
	v_pk_add_f32 v[152:153], v[152:153], v[156:157] neg_lo:[0,1] neg_hi:[0,1]
	v_pk_add_f32 v[138:139], v[158:159], v[140:141]
	v_pk_add_f32 v[136:137], v[162:163], v[154:155]
	v_pk_add_f32 v[140:141], v[162:163], v[154:155] neg_lo:[0,1] neg_hi:[0,1]
	v_xor_b32_e32 v155, 0x80000000, v152
	v_mov_b32_e32 v154, v153
	v_pk_add_f32 v[152:153], v[136:137], v[142:143]
	v_pk_add_f32 v[162:163], v[140:141], v[154:155]
	v_pk_add_f32 v[168:169], v[136:137], v[142:143] neg_lo:[0,1] neg_hi:[0,1]
	v_pk_add_f32 v[170:171], v[140:141], v[154:155] neg_lo:[0,1] neg_hi:[0,1]
	v_pk_add_f32 v[136:137], v[144:145], v[148:149]
	v_pk_add_f32 v[140:141], v[144:145], v[148:149] neg_lo:[0,1] neg_hi:[0,1]
	v_pk_add_f32 v[142:143], v[146:147], v[150:151]
	v_pk_add_f32 v[144:145], v[146:147], v[150:151] neg_lo:[0,1] neg_hi:[0,1]
	v_pk_add_f32 v[172:173], v[136:137], v[142:143] neg_lo:[0,1] neg_hi:[0,1]
	v_xor_b32_e32 v147, 0x80000000, v144
	v_mov_b32_e32 v146, v145
	v_pk_add_f32 v[144:145], v[136:137], v[142:143]
	v_pk_add_f32 v[136:137], v[128:129], v[132:133]
	v_pk_add_f32 v[128:129], v[128:129], v[132:133] neg_lo:[0,1] neg_hi:[0,1]
	v_pk_add_f32 v[132:133], v[130:131], v[134:135]
	v_pk_add_f32 v[130:131], v[130:131], v[134:135] neg_lo:[0,1] neg_hi:[0,1]
	v_xor_b32_e32 v142, 0x80000000, v117
	v_xor_b32_e32 v135, 0x80000000, v130
	v_mov_b32_e32 v134, v131
	v_mov_b32_e32 v143, v116
	v_pk_add_f32 v[148:149], v[140:141], v[146:147]
	v_pk_add_f32 v[174:175], v[140:141], v[146:147] neg_lo:[0,1] neg_hi:[0,1]
	v_pk_add_f32 v[130:131], v[136:137], v[132:133]
	v_pk_add_f32 v[146:147], v[128:129], v[134:135]
	v_pk_add_f32 v[198:199], v[136:137], v[132:133] neg_lo:[0,1] neg_hi:[0,1]
	v_pk_add_f32 v[200:201], v[128:129], v[134:135] neg_lo:[0,1] neg_hi:[0,1]
	v_pk_mul_f32 v[128:129], v[142:143], v[138:139] op_sel:[0,1]
	v_pk_mul_f32 v[132:133], v[126:127], v[152:153] op_sel:[1,1] op_sel_hi:[0,1] neg_lo:[1,0]
	v_pk_fma_f32 v[128:129], v[116:117], v[138:139], v[128:129] op_sel_hi:[1,0,1]
	v_pk_fma_f32 v[132:133], v[126:127], v[152:153], v[132:133] op_sel_hi:[1,0,1]
	ds_write2_b64 v184, v[128:129], v[132:133] offset1:17
	v_pk_mul_f32 v[128:129], v[124:125], v[144:145] op_sel:[1,1] op_sel_hi:[0,1] neg_lo:[1,0]
	v_pk_mul_f32 v[132:133], v[122:123], v[130:131] op_sel:[1,1] op_sel_hi:[0,1] neg_lo:[1,0]
	v_pk_fma_f32 v[128:129], v[124:125], v[144:145], v[128:129] op_sel_hi:[1,0,1]
	v_pk_fma_f32 v[130:131], v[122:123], v[130:131], v[132:133] op_sel_hi:[1,0,1]
	ds_write2_b64 v184, v[128:129], v[130:131] offset0:34 offset1:51
	v_pk_mul_f32 v[128:129], v[120:121], v[160:161] op_sel:[1,1] op_sel_hi:[0,1] neg_lo:[1,0]
	v_pk_mul_f32 v[130:131], v[118:119], v[162:163] op_sel:[1,1] op_sel_hi:[0,1] neg_lo:[1,0]
	v_pk_fma_f32 v[128:129], v[120:121], v[160:161], v[128:129] op_sel_hi:[1,0,1]
	v_pk_fma_f32 v[130:131], v[118:119], v[162:163], v[130:131] op_sel_hi:[1,0,1]
	ds_write2_b64 v184, v[128:129], v[130:131] offset0:68 offset1:85
	v_pk_mul_f32 v[128:129], v[114:115], v[148:149] op_sel:[1,1] op_sel_hi:[0,1] neg_lo:[1,0]
	v_pk_mul_f32 v[130:131], v[112:113], v[146:147] op_sel:[1,1] op_sel_hi:[0,1] neg_lo:[1,0]
	v_pk_fma_f32 v[128:129], v[114:115], v[148:149], v[128:129] op_sel_hi:[1,0,1]
	v_pk_fma_f32 v[130:131], v[112:113], v[146:147], v[130:131] op_sel_hi:[1,0,1]
	ds_write2_b64 v184, v[128:129], v[130:131] offset0:102 offset1:119
	v_pk_mul_f32 v[128:129], v[110:111], v[164:165] op_sel:[1,1] op_sel_hi:[0,1] neg_lo:[1,0]
	v_pk_mul_f32 v[130:131], v[108:109], v[168:169] op_sel:[1,1] op_sel_hi:[0,1] neg_lo:[1,0]
	v_pk_fma_f32 v[128:129], v[110:111], v[164:165], v[128:129] op_sel_hi:[1,0,1]
	v_pk_fma_f32 v[130:131], v[108:109], v[168:169], v[130:131] op_sel_hi:[1,0,1]
	ds_write2_b64 v184, v[128:129], v[130:131] offset0:136 offset1:153
	v_pk_mul_f32 v[128:129], v[106:107], v[172:173] op_sel:[1,1] op_sel_hi:[0,1] neg_lo:[1,0]
	v_pk_mul_f32 v[130:131], v[104:105], v[198:199] op_sel:[1,1] op_sel_hi:[0,1] neg_lo:[1,0]
	v_pk_fma_f32 v[128:129], v[106:107], v[172:173], v[128:129] op_sel_hi:[1,0,1]
	v_pk_fma_f32 v[130:131], v[104:105], v[198:199], v[130:131] op_sel_hi:[1,0,1]
	ds_write2_b64 v184, v[128:129], v[130:131] offset0:170 offset1:187
	v_pk_mul_f32 v[128:129], v[6:7], v[166:167] op_sel:[1,1] op_sel_hi:[0,1] neg_lo:[1,0]
	v_pk_mul_f32 v[144:145], v[4:5], v[170:171] op_sel:[1,1] op_sel_hi:[0,1] neg_lo:[1,0]
	v_pk_fma_f32 v[128:129], v[6:7], v[166:167], v[128:129] op_sel_hi:[1,0,1]
	v_pk_fma_f32 v[144:145], v[4:5], v[170:171], v[144:145] op_sel_hi:[1,0,1]
	ds_write2_b64 v184, v[128:129], v[144:145] offset0:204 offset1:221
	v_pk_mul_f32 v[144:145], v[2:3], v[174:175] op_sel:[1,1] op_sel_hi:[0,1] neg_lo:[1,0]
	v_pk_fma_f32 v[160:161], v[2:3], v[174:175], v[144:145] op_sel_hi:[1,0,1]
	v_pk_mul_f32 v[162:163], v[0:1], v[200:201] op_sel:[1,1] op_sel_hi:[0,1] neg_lo:[1,0]
	v_pk_fma_f32 v[162:163], v[0:1], v[200:201], v[162:163] op_sel_hi:[1,0,1]
	ds_write2_b64 v184, v[160:161], v[162:163] offset0:238 offset1:255
	s_waitcnt lgkmcnt(0)
	s_barrier
	s_nop 0
	v_and_b32_e32 v129, 0xff, v206
	v_mad_u32_u24 v129, v129, s19, v207
	ds_read2_b64 v[160:163], v129 offset1:1
	ds_read2_b64 v[164:167], v129 offset0:2 offset1:3
	ds_read2_b64 v[168:171], v129 offset0:4 offset1:5
	ds_read2_b64 v[172:175], v129 offset0:6 offset1:7
	ds_read2_b64 v[198:201], v129 offset0:8 offset1:9
	ds_read2_b64 v[202:205], v129 offset0:10 offset1:11
	ds_read2_b64 v[236:239], v129 offset0:12 offset1:13
	ds_read2_b64 v[240:243], v129 offset0:14 offset1:15
	s_waitcnt lgkmcnt(3)
	v_pk_add_f32 v[244:245], v[160:161], v[198:199]
	v_pk_add_f32 v[160:161], v[160:161], v[198:199] neg_lo:[0,1] neg_hi:[0,1]
	s_waitcnt lgkmcnt(1)
	v_pk_add_f32 v[198:199], v[168:169], v[236:237]
	v_pk_add_f32 v[168:169], v[168:169], v[236:237] neg_lo:[0,1] neg_hi:[0,1]
	s_nop 0
	v_pk_add_f32 v[246:247], v[160:161], v[168:169] op_sel:[0,1] op_sel_hi:[1,0] neg_hi:[0,1]
	v_pk_add_f32 v[160:161], v[160:161], v[168:169] op_sel:[0,1] op_sel_hi:[1,0] neg_lo:[0,1]
	v_pk_add_f32 v[236:237], v[162:163], v[200:201]
	v_pk_add_f32 v[162:163], v[162:163], v[200:201] neg_lo:[0,1] neg_hi:[0,1]
	v_pk_add_f32 v[200:201], v[170:171], v[238:239]
	v_pk_add_f32 v[170:171], v[170:171], v[238:239] neg_lo:[0,1] neg_hi:[0,1]
	v_pk_add_f32 v[168:169], v[244:245], v[198:199]
	v_xor_b32_e32 v239, 0x80000000, v170
	v_mov_b32_e32 v238, v171
	v_pk_add_f32 v[170:171], v[236:237], v[200:201]
	v_pk_add_f32 v[200:201], v[236:237], v[200:201] neg_lo:[0,1] neg_hi:[0,1]
	v_pk_add_f32 v[236:237], v[164:165], v[202:203]
	v_pk_add_f32 v[164:165], v[164:165], v[202:203] neg_lo:[0,1] neg_hi:[0,1]
	s_waitcnt lgkmcnt(0)
	v_pk_add_f32 v[202:203], v[172:173], v[240:241]
	v_pk_add_f32 v[172:173], v[172:173], v[240:241] neg_lo:[0,1] neg_hi:[0,1]
	v_pk_add_f32 v[198:199], v[244:245], v[198:199] neg_lo:[0,1] neg_hi:[0,1]
	v_pk_add_f32 v[244:245], v[162:163], v[238:239]
	v_pk_add_f32 v[162:163], v[162:163], v[238:239] neg_lo:[0,1] neg_hi:[0,1]
	v_xor_b32_e32 v239, 0x80000000, v172
	v_mov_b32_e32 v238, v173
	v_pk_add_f32 v[172:173], v[236:237], v[202:203]
	v_pk_add_f32 v[202:203], v[236:237], v[202:203] neg_lo:[0,1] neg_hi:[0,1]
	v_pk_add_f32 v[236:237], v[166:167], v[204:205]
	v_pk_add_f32 v[166:167], v[166:167], v[204:205] neg_lo:[0,1] neg_hi:[0,1]
	v_pk_add_f32 v[204:205], v[174:175], v[242:243]
	v_pk_add_f32 v[174:175], v[174:175], v[242:243] neg_lo:[0,1] neg_hi:[0,1]
	v_pk_add_f32 v[240:241], v[164:165], v[238:239]
	v_pk_add_f32 v[164:165], v[164:165], v[238:239] neg_lo:[0,1] neg_hi:[0,1]
	v_pk_add_f32 v[242:243], v[166:167], v[174:175] op_sel:[0,1] op_sel_hi:[1,0] neg_hi:[0,1]
	v_pk_add_f32 v[166:167], v[166:167], v[174:175] op_sel:[0,1] op_sel_hi:[1,0] neg_lo:[0,1]
	v_pk_mul_f32 v[238:239], v[200:201], s[12:13] op_sel:[1,0] op_sel_hi:[0,0] neg_lo:[1,0]
	v_pk_add_f32 v[174:175], v[236:237], v[204:205]
	v_pk_fma_f32 v[200:201], v[200:201], s[12:13], v[238:239] op_sel_hi:[1,0,1] neg_lo:[0,0,1] neg_hi:[0,0,1]
	v_pk_mul_f32 v[238:239], v[162:163], s[36:37] op_sel:[1,0] op_sel_hi:[0,0] neg_lo:[1,0]
	v_pk_add_f32 v[204:205], v[236:237], v[204:205] neg_lo:[0,1] neg_hi:[0,1]
	v_pk_fma_f32 v[162:163], v[162:163], s[22:23], v[238:239] op_sel_hi:[1,0,1] neg_lo:[0,0,1] neg_hi:[0,0,1]
	v_pk_mul_f32 v[238:239], v[240:241], s[12:13] op_sel:[1,0] op_sel_hi:[0,0] neg_lo:[1,0]
	v_pk_fma_f32 v[238:239], v[240:241], s[12:13], v[238:239] op_sel_hi:[1,0,1] neg_lo:[0,0,1] neg_hi:[0,0,1]
	v_pk_fma_f32 v[202:203], v[202:203], 0, v[202:203] op_sel:[0,0,1] op_sel_hi:[1,0,0] neg_hi:[0,0,1]
	v_pk_mul_f32 v[240:241], v[164:165], s[12:13] op_sel:[1,0] op_sel_hi:[0,0] neg_lo:[1,0]
	v_pk_fma_f32 v[164:165], v[164:165], s[18:19], v[240:241] op_sel_hi:[1,0,1] neg_lo:[0,0,1] neg_hi:[0,0,1]
	v_pk_mul_f32 v[240:241], v[242:243], s[36:37] op_sel:[1,0] op_sel_hi:[0,0] neg_lo:[1,0]
	v_pk_mul_f32 v[236:237], v[244:245], s[22:23] op_sel:[1,0] op_sel_hi:[0,0] neg_lo:[1,0]
	v_pk_fma_f32 v[240:241], v[242:243], s[22:23], v[240:241] op_sel_hi:[1,0,1] neg_lo:[0,0,1] neg_hi:[0,0,1]
	v_pk_mul_f32 v[242:243], v[204:205], s[12:13] op_sel:[1,0] op_sel_hi:[0,0] neg_lo:[1,0]
	v_pk_fma_f32 v[236:237], v[244:245], s[36:37], v[236:237] op_sel_hi:[1,0,1] neg_lo:[0,0,1] neg_hi:[0,0,1]
	v_pk_fma_f32 v[204:205], v[204:205], s[18:19], v[242:243] op_sel_hi:[1,0,1] neg_lo:[0,0,1] neg_hi:[0,0,1]
	v_xor_b32_e32 v242, 0x80000000, v167
	v_mov_b32_e32 v243, v166
	v_pk_mul_f32 v[166:167], v[166:167], s[36:37] op_sel_hi:[1,0]
	s_nop 0
	v_pk_fma_f32 v[166:167], v[242:243], s[22:23], v[166:167] op_sel_hi:[1,0,1] neg_lo:[0,0,1] neg_hi:[0,0,1]
	v_pk_add_f32 v[242:243], v[168:169], v[172:173]
	v_pk_add_f32 v[168:169], v[168:169], v[172:173] neg_lo:[0,1] neg_hi:[0,1]
	v_pk_add_f32 v[172:173], v[170:171], v[174:175]
	v_pk_add_f32 v[170:171], v[170:171], v[174:175] neg_lo:[0,1] neg_hi:[0,1]
	v_pk_add_f32 v[244:245], v[242:243], v[172:173]
	v_pk_add_f32 v[248:249], v[168:169], v[170:171] op_sel:[0,1] op_sel_hi:[1,0] neg_hi:[0,1]
	v_pk_add_f32 v[250:251], v[168:169], v[170:171] op_sel:[0,1] op_sel_hi:[1,0] neg_lo:[0,1]
	v_pk_add_f32 v[174:175], v[236:237], v[240:241] neg_lo:[0,1] neg_hi:[0,1]
	v_pk_add_f32 v[242:243], v[242:243], v[172:173] neg_lo:[0,1] neg_hi:[0,1]
	v_pk_add_f32 v[168:169], v[246:247], v[238:239]
	v_pk_add_f32 v[172:173], v[236:237], v[240:241]
	v_xor_b32_e32 v237, 0x80000000, v174
	v_mov_b32_e32 v236, v175
	v_pk_add_f32 v[174:175], v[200:201], v[204:205] neg_lo:[0,1] neg_hi:[0,1]
	v_pk_add_f32 v[170:171], v[246:247], v[238:239] neg_lo:[0,1] neg_hi:[0,1]
	v_pk_add_f32 v[238:239], v[168:169], v[172:173]
	v_pk_add_f32 v[246:247], v[168:169], v[172:173] neg_lo:[0,1] neg_hi:[0,1]
	v_pk_add_f32 v[172:173], v[200:201], v[204:205]
	v_xor_b32_e32 v201, 0x80000000, v174
	v_mov_b32_e32 v200, v175
	v_pk_add_f32 v[174:175], v[160:161], v[164:165]
	v_pk_add_f32 v[160:161], v[160:161], v[164:165] neg_lo:[0,1] neg_hi:[0,1]
	v_pk_add_f32 v[164:165], v[162:163], v[166:167]
	v_pk_add_f32 v[162:163], v[162:163], v[166:167] neg_lo:[0,1] neg_hi:[0,1]
	v_pk_add_f32 v[240:241], v[170:171], v[236:237]
	v_pk_add_f32 v[192:193], v[170:171], v[236:237] neg_lo:[0,1] neg_hi:[0,1]
	v_pk_add_f32 v[168:169], v[198:199], v[202:203]
	v_pk_add_f32 v[170:171], v[198:199], v[202:203] neg_lo:[0,1] neg_hi:[0,1]
	v_xor_b32_e32 v167, 0x80000000, v162
	v_mov_b32_e32 v166, v163
	v_pk_add_f32 v[194:195], v[168:169], v[172:173]
	v_pk_add_f32 v[184:185], v[170:171], v[200:201]
	v_pk_add_f32 v[198:199], v[168:169], v[172:173] neg_lo:[0,1] neg_hi:[0,1]
	v_pk_add_f32 v[172:173], v[170:171], v[200:201] neg_lo:[0,1] neg_hi:[0,1]
	v_pk_add_f32 v[170:171], v[174:175], v[164:165]
	v_pk_add_f32 v[168:169], v[160:161], v[162:163] op_sel:[0,1] op_sel_hi:[1,0] neg_hi:[0,1]
	v_pk_add_f32 v[162:163], v[174:175], v[164:165] neg_lo:[0,1] neg_hi:[0,1]
	v_pk_add_f32 v[160:161], v[160:161], v[166:167] neg_lo:[0,1] neg_hi:[0,1]
	ds_read2st64_b64 v[164:167], v234 offset1:8
	ds_read2st64_b64 v[200:203], v234 offset0:16 offset1:24
	s_waitcnt lgkmcnt(1)
	v_pk_mul_f32 v[174:175], v[164:165], v[244:245] op_sel:[1,1] op_sel_hi:[0,1] neg_lo:[1,0]
	v_pk_fma_f32 v[164:165], v[164:165], v[244:245], v[174:175] op_sel_hi:[1,0,1]
	v_pk_mul_f32 v[174:175], v[166:167], v[248:249] op_sel:[1,1] op_sel_hi:[0,1] neg_lo:[1,0]
	v_pk_fma_f32 v[166:167], v[166:167], v[248:249], v[174:175] op_sel_hi:[1,0,1]
	s_waitcnt lgkmcnt(0)
	v_pk_mul_f32 v[174:175], v[242:243], v[200:201] op_sel:[1,1] op_sel_hi:[1,0] neg_lo:[0,1]
	s_nop 0
	v_pk_fma_f32 v[174:175], v[200:201], v[242:243], v[174:175] op_sel_hi:[1,0,1]
	v_pk_mul_f32 v[200:201], v[202:203], v[250:251] op_sel:[1,1] op_sel_hi:[0,1] neg_lo:[1,0]
	v_pk_fma_f32 v[200:201], v[202:203], v[250:251], v[200:201] op_sel_hi:[1,0,1]
	ds_read2st64_b64 v[202:205], v234 offset0:32 offset1:40
	s_waitcnt lgkmcnt(0)
	v_pk_mul_f32 v[236:237], v[202:203], v[238:239] op_sel:[1,1] op_sel_hi:[0,1] neg_lo:[1,0]
	v_pk_fma_f32 v[202:203], v[202:203], v[238:239], v[236:237] op_sel_hi:[1,0,1]
	v_pk_mul_f32 v[236:237], v[204:205], v[240:241] op_sel:[1,1] op_sel_hi:[0,1] neg_lo:[1,0]
	v_pk_fma_f32 v[204:205], v[204:205], v[240:241], v[236:237] op_sel_hi:[1,0,1]
	ds_read2st64_b64 v[236:239], v234 offset0:48 offset1:56
	s_waitcnt lgkmcnt(0)
	v_pk_mul_f32 v[240:241], v[236:237], v[246:247] op_sel:[1,1] op_sel_hi:[0,1] neg_lo:[1,0]
	v_pk_fma_f32 v[240:241], v[236:237], v[246:247], v[240:241] op_sel_hi:[1,0,1]
	v_pk_mul_f32 v[236:237], v[238:239], v[192:193] op_sel:[1,1] op_sel_hi:[0,1] neg_lo:[1,0]
	v_pk_fma_f32 v[192:193], v[238:239], v[192:193], v[236:237] op_sel_hi:[1,0,1]
	ds_read2st64_b64 v[236:239], v234 offset0:64 offset1:72
	s_waitcnt lgkmcnt(0)
	v_pk_mul_f32 v[242:243], v[194:195], v[236:237] op_sel:[1,1] op_sel_hi:[1,0] neg_lo:[0,1]
	s_nop 0
	v_pk_fma_f32 v[194:195], v[236:237], v[194:195], v[242:243] op_sel_hi:[1,0,1]
	v_pk_mul_f32 v[236:237], v[184:185], v[238:239] op_sel:[1,1] op_sel_hi:[1,0] neg_lo:[0,1]
	s_nop 0
	v_pk_fma_f32 v[184:185], v[238:239], v[184:185], v[236:237] op_sel_hi:[1,0,1]
	ds_read2st64_b64 v[236:239], v234 offset0:80 offset1:88
	s_waitcnt lgkmcnt(0)
	v_pk_mul_f32 v[242:243], v[198:199], v[236:237] op_sel:[1,1] op_sel_hi:[1,0] neg_lo:[0,1]
	s_nop 0
	v_pk_fma_f32 v[198:199], v[198:199], v[236:237], v[242:243] op_sel_hi:[0,1,1]
	v_pk_mul_f32 v[236:237], v[172:173], v[238:239] op_sel:[1,1] op_sel_hi:[1,0] neg_lo:[0,1]
	s_nop 0
	v_pk_fma_f32 v[172:173], v[238:239], v[172:173], v[236:237] op_sel_hi:[1,0,1]
	ds_read2st64_b64 v[236:239], v234 offset0:96 offset1:104
	s_waitcnt lgkmcnt(0)
	v_pk_mul_f32 v[242:243], v[170:171], v[236:237] op_sel:[1,1] op_sel_hi:[1,0] neg_lo:[0,1]
	s_nop 0
	v_pk_fma_f32 v[236:237], v[170:171], v[236:237], v[242:243] op_sel_hi:[0,1,1]
	v_pk_mul_f32 v[170:171], v[168:169], v[238:239] op_sel:[1,1] op_sel_hi:[1,0] neg_lo:[0,1]
	s_nop 0
	v_pk_fma_f32 v[238:239], v[238:239], v[168:169], v[170:171] op_sel_hi:[1,0,1]
	ds_read2st64_b64 v[168:171], v234 offset0:112 offset1:120
	s_waitcnt lgkmcnt(0)
	v_pk_mul_f32 v[234:235], v[162:163], v[168:169] op_sel:[1,1] op_sel_hi:[1,0] neg_lo:[0,1]
	s_nop 0
	v_pk_fma_f32 v[162:163], v[162:163], v[168:169], v[234:235] op_sel_hi:[0,1,1]
	v_pk_mul_f32 v[168:169], v[160:161], v[170:171] op_sel:[1,1] op_sel_hi:[1,0] neg_lo:[0,1]
	s_nop 0
	v_pk_fma_f32 v[160:161], v[160:161], v[170:171], v[168:169] op_sel_hi:[0,1,1]
	v_pk_add_f32 v[170:171], v[166:167], v[200:201]
	v_pk_add_f32 v[166:167], v[166:167], v[200:201] neg_lo:[0,1] neg_hi:[0,1]
	v_pk_add_f32 v[168:169], v[164:165], v[174:175]
	v_pk_add_f32 v[164:165], v[164:165], v[174:175] neg_lo:[0,1] neg_hi:[0,1]
	v_xor_b32_e32 v174, 0x80000000, v167
	v_mov_b32_e32 v175, v166
	v_pk_add_f32 v[166:167], v[168:169], v[170:171]
	v_pk_add_f32 v[200:201], v[164:165], v[174:175]
	v_pk_add_f32 v[168:169], v[168:169], v[170:171] neg_lo:[0,1] neg_hi:[0,1]
	v_pk_add_f32 v[164:165], v[164:165], v[174:175] neg_lo:[0,1] neg_hi:[0,1]
	v_pk_add_f32 v[170:171], v[202:203], v[240:241]
	v_pk_add_f32 v[174:175], v[202:203], v[240:241] neg_lo:[0,1] neg_hi:[0,1]
	v_pk_add_f32 v[202:203], v[204:205], v[192:193]
	v_pk_add_f32 v[192:193], v[204:205], v[192:193] neg_lo:[0,1] neg_hi:[0,1]
	s_nop 0
	v_xor_b32_e32 v204, 0x80000000, v193
	v_mov_b32_e32 v205, v192
	v_pk_add_f32 v[192:193], v[170:171], v[202:203]
	v_pk_add_f32 v[170:171], v[170:171], v[202:203] neg_lo:[0,1] neg_hi:[0,1]
	v_pk_add_f32 v[202:203], v[194:195], v[198:199]
	v_pk_add_f32 v[194:195], v[194:195], v[198:199] neg_lo:[0,1] neg_hi:[0,1]
	v_pk_add_f32 v[198:199], v[184:185], v[172:173]
	v_pk_add_f32 v[172:173], v[184:185], v[172:173] neg_lo:[0,1] neg_hi:[0,1]
	v_pk_add_f32 v[234:235], v[174:175], v[204:205]
	v_xor_b32_e32 v184, 0x80000000, v173
	v_mov_b32_e32 v185, v172
	v_pk_add_f32 v[174:175], v[174:175], v[204:205] neg_lo:[0,1] neg_hi:[0,1]
	v_pk_add_f32 v[172:173], v[202:203], v[198:199]
	v_pk_add_f32 v[204:205], v[194:195], v[184:185]
	v_pk_add_f32 v[198:199], v[202:203], v[198:199] neg_lo:[0,1] neg_hi:[0,1]
	v_pk_add_f32 v[184:185], v[194:195], v[184:185] neg_lo:[0,1] neg_hi:[0,1]
	v_pk_add_f32 v[194:195], v[236:237], v[162:163]
	v_pk_add_f32 v[202:203], v[238:239], v[160:161]
	v_pk_add_f32 v[160:161], v[238:239], v[160:161] neg_lo:[0,1] neg_hi:[0,1]
	v_pk_add_f32 v[162:163], v[236:237], v[162:163] neg_lo:[0,1] neg_hi:[0,1]
	v_xor_b32_e32 v236, 0x80000000, v161
	v_mov_b32_e32 v237, v160
	v_pk_add_f32 v[160:161], v[194:195], v[202:203]
	v_pk_add_f32 v[194:195], v[194:195], v[202:203] neg_lo:[0,1] neg_hi:[0,1]
	v_pk_mul_f32 v[202:203], v[234:235], s[22:23] op_sel:[1,0] op_sel_hi:[0,0] neg_lo:[1,0]
	v_pk_add_f32 v[238:239], v[162:163], v[236:237]
	v_pk_fma_f32 v[202:203], v[234:235], s[36:37], v[202:203] op_sel_hi:[1,0,1]
	v_pk_mul_f32 v[234:235], v[170:171], s[12:13] op_sel:[1,0] op_sel_hi:[0,0] neg_lo:[1,0]
	v_pk_add_f32 v[162:163], v[162:163], v[236:237] neg_lo:[0,1] neg_hi:[0,1]
	v_pk_fma_f32 v[170:171], v[170:171], s[12:13], v[234:235] op_sel_hi:[1,0,1]
	v_pk_mul_f32 v[234:235], v[174:175], s[36:37] op_sel:[1,0] op_sel_hi:[0,0] neg_lo:[1,0]
	v_xor_b32_e32 v236, 0x80000000, v195
	v_pk_fma_f32 v[174:175], v[174:175], s[22:23], v[234:235] op_sel_hi:[1,0,1]
	v_pk_mul_f32 v[234:235], v[204:205], s[12:13] op_sel:[1,0] op_sel_hi:[0,0] neg_lo:[1,0]
	v_mov_b32_e32 v237, v194
	v_pk_fma_f32 v[204:205], v[204:205], s[12:13], v[234:235] op_sel_hi:[1,0,1]
	v_pk_mul_f32 v[194:195], v[194:195], s[12:13] op_sel_hi:[1,0]
	v_pk_fma_f32 v[198:199], v[198:199], 0, v[198:199] op_sel:[0,0,1] op_sel_hi:[1,0,0] neg_lo:[0,0,1]
	v_xor_b32_e32 v234, 0x80000000, v185
	v_mov_b32_e32 v235, v184
	v_pk_mul_f32 v[184:185], v[184:185], s[12:13] op_sel_hi:[1,0]
	v_pk_fma_f32 v[194:195], v[236:237], s[12:13], v[194:195] op_sel_hi:[1,0,1] neg_lo:[0,0,1] neg_hi:[0,0,1]
	v_pk_fma_f32 v[184:185], v[234:235], s[12:13], v[184:185] op_sel_hi:[1,0,1] neg_lo:[0,0,1] neg_hi:[0,0,1]
	v_pk_mul_f32 v[236:237], v[162:163], s[22:23] op_sel:[1,0] op_sel_hi:[0,0] neg_lo:[1,0]
	v_pk_mul_f32 v[234:235], v[238:239], s[36:37] op_sel:[1,0] op_sel_hi:[0,0] neg_lo:[1,0]
	v_pk_fma_f32 v[162:163], v[162:163], s[26:27], v[236:237] op_sel_hi:[1,0,1] neg_lo:[0,0,1] neg_hi:[0,0,1]
	v_pk_add_f32 v[236:237], v[166:167], v[172:173]
	v_pk_add_f32 v[166:167], v[166:167], v[172:173] neg_lo:[0,1] neg_hi:[0,1]
	v_pk_add_f32 v[172:173], v[192:193], v[160:161]
	v_pk_add_f32 v[160:161], v[192:193], v[160:161] neg_lo:[0,1] neg_hi:[0,1]
	v_pk_fma_f32 v[234:235], v[238:239], s[22:23], v[234:235] op_sel_hi:[1,0,1]
	v_pk_add_f32 v[238:239], v[166:167], v[160:161] op_sel:[0,1] op_sel_hi:[1,0] neg_lo:[0,1]
	v_pk_add_f32 v[166:167], v[166:167], v[160:161] op_sel:[0,1] op_sel_hi:[1,0] neg_hi:[0,1]
	v_pk_add_f32 v[192:193], v[200:201], v[204:205]
	v_pk_add_f32 v[200:201], v[200:201], v[204:205] neg_lo:[0,1] neg_hi:[0,1]
	v_pk_add_f32 v[204:205], v[202:203], v[234:235]
	v_pk_add_f32 v[202:203], v[202:203], v[234:235] neg_lo:[0,1] neg_hi:[0,1]
	v_pk_add_f32 v[160:161], v[236:237], v[172:173]
	v_xor_b32_e32 v234, 0x80000000, v203
	v_mov_b32_e32 v235, v202
	v_pk_add_f32 v[202:203], v[192:193], v[204:205]
	v_pk_add_f32 v[192:193], v[192:193], v[204:205] neg_lo:[0,1] neg_hi:[0,1]
	v_pk_add_f32 v[204:205], v[168:169], v[198:199]
	v_pk_add_f32 v[168:169], v[168:169], v[198:199] neg_lo:[0,1] neg_hi:[0,1]
	v_pk_add_f32 v[198:199], v[170:171], v[194:195]
	v_pk_add_f32 v[170:171], v[170:171], v[194:195] neg_lo:[0,1] neg_hi:[0,1]
	v_pk_add_f32 v[172:173], v[236:237], v[172:173] neg_lo:[0,1] neg_hi:[0,1]
	v_pk_add_f32 v[236:237], v[200:201], v[234:235]
	v_pk_add_f32 v[200:201], v[200:201], v[234:235] neg_lo:[0,1] neg_hi:[0,1]
	v_pk_add_f32 v[234:235], v[168:169], v[170:171] op_sel:[0,1] op_sel_hi:[1,0] neg_lo:[0,1]
	v_pk_add_f32 v[168:169], v[168:169], v[170:171] op_sel:[0,1] op_sel_hi:[1,0] neg_hi:[0,1]
	v_pk_add_f32 v[194:195], v[164:165], v[184:185]
	v_pk_add_f32 v[164:165], v[164:165], v[184:185] neg_lo:[0,1] neg_hi:[0,1]
	v_pk_add_f32 v[184:185], v[174:175], v[162:163]
	v_pk_add_f32 v[162:163], v[174:175], v[162:163] neg_lo:[0,1] neg_hi:[0,1]
	v_pk_add_f32 v[170:171], v[204:205], v[198:199]
	v_pk_add_f32 v[198:199], v[204:205], v[198:199] neg_lo:[0,1] neg_hi:[0,1]
	v_pk_add_f32 v[204:205], v[164:165], v[162:163] op_sel:[0,1] op_sel_hi:[1,0] neg_lo:[0,1]
	v_pk_add_f32 v[164:165], v[164:165], v[162:163] op_sel:[0,1] op_sel_hi:[1,0] neg_hi:[0,1]
	v_mov_b32_e32 v174, v116
	v_mov_b32_e32 v175, v142
	v_pk_mul_f32 v[142:143], v[174:175], v[160:161] op_sel_hi:[1,0]
	v_pk_add_f32 v[162:163], v[194:195], v[184:185]
	v_pk_fma_f32 v[116:117], v[116:117], v[160:161], v[142:143] op_sel:[1,1,0] op_sel_hi:[0,1,1]
	v_pk_mul_f32 v[142:143], v[126:127], v[202:203] op_sel_hi:[1,0] neg_hi:[1,0]
	v_pk_add_f32 v[184:185], v[194:195], v[184:185] neg_lo:[0,1] neg_hi:[0,1]
	v_pk_fma_f32 v[126:127], v[126:127], v[202:203], v[142:143] op_sel:[1,1,0] op_sel_hi:[0,1,1]
	ds_write2_b64 v129, v[116:117], v[126:127] offset1:1
	v_pk_mul_f32 v[116:117], v[124:125], v[170:171] op_sel_hi:[1,0] neg_hi:[1,0]
	s_nop 0
	v_pk_fma_f32 v[116:117], v[124:125], v[170:171], v[116:117] op_sel:[1,1,0] op_sel_hi:[0,1,1]
	v_pk_mul_f32 v[124:125], v[122:123], v[162:163] op_sel_hi:[1,0] neg_hi:[1,0]
	s_nop 0
	v_pk_fma_f32 v[122:123], v[122:123], v[162:163], v[124:125] op_sel:[1,1,0] op_sel_hi:[0,1,1]
	ds_write2_b64 v129, v[116:117], v[122:123] offset0:2 offset1:3
	v_pk_mul_f32 v[116:117], v[120:121], v[238:239] op_sel_hi:[1,0] neg_hi:[1,0]
	s_nop 0
	v_pk_fma_f32 v[116:117], v[120:121], v[238:239], v[116:117] op_sel:[1,1,0] op_sel_hi:[0,1,1]
	v_pk_mul_f32 v[120:121], v[118:119], v[236:237] op_sel_hi:[1,0] neg_hi:[1,0]
	s_nop 0
	v_pk_fma_f32 v[118:119], v[118:119], v[236:237], v[120:121] op_sel:[1,1,0] op_sel_hi:[0,1,1]
	ds_write2_b64 v129, v[116:117], v[118:119] offset0:4 offset1:5
	v_pk_mul_f32 v[116:117], v[114:115], v[234:235] op_sel_hi:[1,0] neg_hi:[1,0]
	s_nop 0
	v_pk_fma_f32 v[114:115], v[114:115], v[234:235], v[116:117] op_sel:[1,1,0] op_sel_hi:[0,1,1]
	v_pk_mul_f32 v[116:117], v[112:113], v[204:205] op_sel_hi:[1,0] neg_hi:[1,0]
	s_nop 0
	v_pk_fma_f32 v[112:113], v[112:113], v[204:205], v[116:117] op_sel:[1,1,0] op_sel_hi:[0,1,1]
	ds_write2_b64 v129, v[114:115], v[112:113] offset0:6 offset1:7
	v_pk_mul_f32 v[112:113], v[110:111], v[172:173] op_sel_hi:[1,0] neg_hi:[1,0]
	s_nop 0
	v_pk_fma_f32 v[110:111], v[110:111], v[172:173], v[112:113] op_sel:[1,1,0] op_sel_hi:[0,1,1]
	v_pk_mul_f32 v[112:113], v[108:109], v[192:193] op_sel_hi:[1,0] neg_hi:[1,0]
	s_nop 0
	v_pk_fma_f32 v[108:109], v[108:109], v[192:193], v[112:113] op_sel:[1,1,0] op_sel_hi:[0,1,1]
	ds_write2_b64 v129, v[110:111], v[108:109] offset0:8 offset1:9
	v_pk_mul_f32 v[108:109], v[106:107], v[198:199] op_sel_hi:[1,0] neg_hi:[1,0]
	s_nop 0
	v_pk_fma_f32 v[106:107], v[106:107], v[198:199], v[108:109] op_sel:[1,1,0] op_sel_hi:[0,1,1]
	v_pk_mul_f32 v[108:109], v[104:105], v[184:185] op_sel_hi:[1,0] neg_hi:[1,0]
	s_nop 0
	v_pk_fma_f32 v[104:105], v[104:105], v[184:185], v[108:109] op_sel:[1,1,0] op_sel_hi:[0,1,1]
	ds_write2_b64 v129, v[106:107], v[104:105] offset0:10 offset1:11
	v_pk_mul_f32 v[104:105], v[6:7], v[166:167] op_sel_hi:[1,0] neg_hi:[1,0]
	s_nop 0
	v_pk_fma_f32 v[6:7], v[6:7], v[166:167], v[104:105] op_sel:[1,1,0] op_sel_hi:[0,1,1]
	v_pk_mul_f32 v[104:105], v[4:5], v[200:201] op_sel_hi:[1,0] neg_hi:[1,0]
	s_nop 0
	v_pk_fma_f32 v[4:5], v[4:5], v[200:201], v[104:105] op_sel:[1,1,0] op_sel_hi:[0,1,1]
	ds_write2_b64 v129, v[6:7], v[4:5] offset0:12 offset1:13
	v_pk_mul_f32 v[4:5], v[2:3], v[168:169] op_sel_hi:[1,0] neg_hi:[1,0]
	s_nop 0
	v_pk_fma_f32 v[2:3], v[2:3], v[168:169], v[4:5] op_sel:[1,1,0] op_sel_hi:[0,1,1]
	v_pk_mul_f32 v[4:5], v[0:1], v[164:165] op_sel_hi:[1,0] neg_hi:[1,0]
	s_nop 0
	v_pk_fma_f32 v[0:1], v[0:1], v[164:165], v[4:5] op_sel:[1,1,0] op_sel_hi:[0,1,1]
	ds_write2_b64 v129, v[2:3], v[0:1] offset0:14 offset1:15
	v_mov_b32_e32 v0, v217
	v_mov_b32_e32 v1, v218
	v_mov_b32_e32 v114, v215
	v_xor_b32_e32 v4, 0x80000000, v1
	v_mov_b32_e32 v5, v0
	v_pk_mul_f32 v[2:3], v[4:5], v[218:219] op_sel_hi:[1,0]
	v_mov_b32_e32 v115, v216
	v_pk_fma_f32 v[2:3], v[216:217], v[0:1], v[2:3] op_sel:[1,0,0]
	s_nop 0
	v_pk_mul_f32 v[104:105], v[2:3], v[2:3] op_sel:[1,1] op_sel_hi:[1,0] neg_lo:[0,1]
	v_pk_mul_f32 v[4:5], v[4:5], v[216:217] op_sel_hi:[1,0]
	v_pk_fma_f32 v[104:105], v[2:3], v[2:3], v[104:105] op_sel_hi:[1,0,1]
	v_pk_fma_f32 v[126:127], v[0:1], v[214:215], v[4:5] op_sel:[0,1,0]
	v_pk_mul_f32 v[0:1], v[216:217], v[2:3] op_sel:[0,1] op_sel_hi:[0,0] neg_lo:[0,1]
	v_pk_fma_f32 v[124:125], v[214:215], v[2:3], v[0:1] op_sel:[1,0,0]
	v_pk_mul_f32 v[0:1], v[126:127], v[2:3] op_sel:[1,1] op_sel_hi:[1,0] neg_lo:[0,1]
	v_pk_mul_f32 v[108:109], v[104:105], v[104:105] op_sel:[1,1] op_sel_hi:[1,0] neg_lo:[0,1]
	v_pk_fma_f32 v[122:123], v[2:3], v[126:127], v[0:1] op_sel_hi:[1,0,1]
	v_pk_mul_f32 v[0:1], v[216:217], v[104:105] op_sel:[0,1] op_sel_hi:[0,0] neg_lo:[0,1]
	v_pk_fma_f32 v[120:121], v[214:215], v[104:105], v[0:1] op_sel:[1,0,0]
	v_pk_mul_f32 v[0:1], v[126:127], v[104:105] op_sel:[1,1] op_sel_hi:[1,0] neg_lo:[0,1]
	s_waitcnt lgkmcnt(0)
	v_pk_fma_f32 v[118:119], v[126:127], v[104:105], v[0:1] op_sel_hi:[0,1,1]
	v_pk_mul_f32 v[0:1], v[124:125], v[104:105] op_sel:[1,1] op_sel_hi:[1,0] neg_lo:[0,1]
	s_barrier
	v_pk_fma_f32 v[116:117], v[104:105], v[124:125], v[0:1] op_sel_hi:[1,0,1]
	v_pk_mul_f32 v[0:1], v[122:123], v[104:105] op_sel:[1,1] op_sel_hi:[1,0] neg_lo:[0,1]
	s_nop 0
	v_pk_fma_f32 v[110:111], v[104:105], v[122:123], v[0:1] op_sel_hi:[1,0,1]
	v_pk_fma_f32 v[0:1], v[104:105], v[104:105], v[108:109] op_sel_hi:[1,0,1]
	s_cmpk_lg_u32 s42, 0xc000
	v_pk_mul_f32 v[2:3], v[216:217], v[0:1] op_sel:[0,1] op_sel_hi:[0,0] neg_lo:[0,1]
	v_pk_fma_f32 v[112:113], v[214:215], v[0:1], v[2:3] op_sel:[1,0,0]
	v_pk_mul_f32 v[2:3], v[126:127], v[0:1] op_sel:[1,1] op_sel_hi:[1,0] neg_lo:[0,1]
	s_cselect_b32 s34, s47, 0
	v_pk_fma_f32 v[108:109], v[126:127], v[0:1], v[2:3] op_sel_hi:[0,1,1]
	v_pk_mul_f32 v[2:3], v[124:125], v[0:1] op_sel:[1,1] op_sel_hi:[1,0] neg_lo:[0,1]
	s_lshl_b64 s[2:3], s[34:35], 1
	v_pk_fma_f32 v[106:107], v[124:125], v[0:1], v[2:3] op_sel_hi:[0,1,1]
	v_pk_mul_f32 v[2:3], v[122:123], v[0:1] op_sel:[1,1] op_sel_hi:[1,0] neg_lo:[0,1]
	s_add_u32 s2, s40, s2
	v_pk_fma_f32 v[104:105], v[122:123], v[0:1], v[2:3] op_sel_hi:[0,1,1]
	v_pk_mul_f32 v[2:3], v[120:121], v[0:1] op_sel:[1,1] op_sel_hi:[1,0] neg_lo:[0,1]
	s_addc_u32 s3, s41, s3
	v_pk_fma_f32 v[6:7], v[0:1], v[120:121], v[2:3] op_sel_hi:[1,0,1]
	v_pk_mul_f32 v[2:3], v[118:119], v[0:1] op_sel:[1,1] op_sel_hi:[1,0] neg_lo:[0,1]
	s_add_u32 s6, s2, 0x2000
	v_pk_fma_f32 v[4:5], v[0:1], v[118:119], v[2:3] op_sel_hi:[1,0,1]
	v_pk_mul_f32 v[2:3], v[116:117], v[0:1] op_sel:[1,1] op_sel_hi:[1,0] neg_lo:[0,1]
	v_pk_mul_f32 v[128:129], v[110:111], v[0:1] op_sel:[1,1] op_sel_hi:[1,0] neg_lo:[0,1]
	v_pk_fma_f32 v[2:3], v[0:1], v[116:117], v[2:3] op_sel_hi:[1,0,1]
	v_pk_fma_f32 v[0:1], v[0:1], v[110:111], v[128:129] op_sel_hi:[1,0,1]
	s_addc_u32 s7, s3, 0
	v_bfe_u32 v129, v206, 4, 4
	v_and_b32_e32 v128, 15, v206
	v_mul_u32_u24_e32 v129, 0x880, v129
	v_lshlrev_b32_e32 v128, 3, v128
	v_add3_u32 v164, v207, v129, v128
	ds_read2_b64 v[128:131], v164 offset1:17
	ds_read2_b64 v[132:135], v164 offset0:34 offset1:51
	ds_read2_b64 v[136:139], v164 offset0:68 offset1:85
	ds_read2_b64 v[140:143], v164 offset0:102 offset1:119
	ds_read2_b64 v[144:147], v164 offset0:136 offset1:153
	ds_read2_b64 v[148:151], v164 offset0:170 offset1:187
	ds_read2_b64 v[152:155], v164 offset0:204 offset1:221
	ds_read2_b64 v[156:159], v164 offset0:238 offset1:255
	s_add_u32 s42, s42, 0x4000
	s_waitcnt lgkmcnt(3)
	v_pk_add_f32 v[160:161], v[128:129], v[144:145]
	v_pk_add_f32 v[128:129], v[128:129], v[144:145] neg_lo:[0,1] neg_hi:[0,1]
	s_waitcnt lgkmcnt(1)
	v_pk_add_f32 v[144:145], v[136:137], v[152:153]
	v_pk_add_f32 v[136:137], v[136:137], v[152:153] neg_lo:[0,1] neg_hi:[0,1]
	s_addc_u32 s43, s43, 0
	v_pk_add_f32 v[162:163], v[128:129], v[136:137] op_sel:[0,1] op_sel_hi:[1,0] neg_lo:[0,1]
	v_pk_add_f32 v[128:129], v[128:129], v[136:137] op_sel:[0,1] op_sel_hi:[1,0] neg_hi:[0,1]
	v_pk_add_f32 v[152:153], v[130:131], v[146:147]
	v_pk_add_f32 v[130:131], v[130:131], v[146:147] neg_lo:[0,1] neg_hi:[0,1]
	v_pk_add_f32 v[146:147], v[138:139], v[154:155]
	v_pk_add_f32 v[138:139], v[138:139], v[154:155] neg_lo:[0,1] neg_hi:[0,1]
	v_pk_add_f32 v[136:137], v[160:161], v[144:145]
	v_xor_b32_e32 v154, 0x80000000, v139
	v_mov_b32_e32 v155, v138
	v_pk_add_f32 v[138:139], v[152:153], v[146:147]
	v_pk_add_f32 v[146:147], v[152:153], v[146:147] neg_lo:[0,1] neg_hi:[0,1]
	v_pk_add_f32 v[152:153], v[132:133], v[148:149]
	v_pk_add_f32 v[132:133], v[132:133], v[148:149] neg_lo:[0,1] neg_hi:[0,1]
	s_waitcnt lgkmcnt(0)
	v_pk_add_f32 v[148:149], v[140:141], v[156:157]
	v_pk_add_f32 v[140:141], v[140:141], v[156:157] neg_lo:[0,1] neg_hi:[0,1]
	v_pk_add_f32 v[144:145], v[160:161], v[144:145] neg_lo:[0,1] neg_hi:[0,1]
	v_pk_add_f32 v[160:161], v[130:131], v[154:155]
	v_pk_add_f32 v[130:131], v[130:131], v[154:155] neg_lo:[0,1] neg_hi:[0,1]
	v_xor_b32_e32 v154, 0x80000000, v141
	v_mov_b32_e32 v155, v140
	v_pk_add_f32 v[140:141], v[152:153], v[148:149]
	v_pk_add_f32 v[148:149], v[152:153], v[148:149] neg_lo:[0,1] neg_hi:[0,1]
	v_pk_add_f32 v[152:153], v[134:135], v[150:151]
	v_pk_add_f32 v[134:135], v[134:135], v[150:151] neg_lo:[0,1] neg_hi:[0,1]
	v_pk_add_f32 v[150:151], v[142:143], v[158:159]
	v_pk_add_f32 v[142:143], v[142:143], v[158:159] neg_lo:[0,1] neg_hi:[0,1]
	v_pk_add_f32 v[156:157], v[132:133], v[154:155]
	v_pk_add_f32 v[132:133], v[132:133], v[154:155] neg_lo:[0,1] neg_hi:[0,1]
	v_pk_add_f32 v[158:159], v[134:135], v[142:143] op_sel:[0,1] op_sel_hi:[1,0] neg_lo:[0,1]
	v_pk_add_f32 v[134:135], v[134:135], v[142:143] op_sel:[0,1] op_sel_hi:[1,0] neg_hi:[0,1]
	v_pk_mul_f32 v[154:155], v[146:147], s[12:13] op_sel:[1,0] op_sel_hi:[0,0] neg_lo:[1,0]
	v_pk_add_f32 v[142:143], v[152:153], v[150:151]
	v_pk_fma_f32 v[146:147], v[146:147], s[12:13], v[154:155] op_sel_hi:[1,0,1]
	v_pk_mul_f32 v[154:155], v[130:131], s[36:37] op_sel:[1,0] op_sel_hi:[0,0] neg_lo:[1,0]
	v_pk_add_f32 v[150:151], v[152:153], v[150:151] neg_lo:[0,1] neg_hi:[0,1]
	v_pk_fma_f32 v[130:131], v[130:131], s[22:23], v[154:155] op_sel_hi:[1,0,1]
	v_pk_mul_f32 v[154:155], v[156:157], s[12:13] op_sel:[1,0] op_sel_hi:[0,0] neg_lo:[1,0]
	v_pk_fma_f32 v[154:155], v[156:157], s[12:13], v[154:155] op_sel_hi:[1,0,1]
	v_pk_fma_f32 v[148:149], v[148:149], 0, v[148:149] op_sel:[0,0,1] op_sel_hi:[1,0,0] neg_lo:[0,0,1]
	v_xor_b32_e32 v156, 0x80000000, v133
	v_mov_b32_e32 v157, v132
	v_pk_mul_f32 v[132:133], v[132:133], s[12:13] op_sel_hi:[1,0]
	s_nop 0
	v_pk_fma_f32 v[132:133], v[156:157], s[12:13], v[132:133] op_sel_hi:[1,0,1] neg_lo:[0,0,1] neg_hi:[0,0,1]
	v_pk_mul_f32 v[156:157], v[158:159], s[36:37] op_sel:[1,0] op_sel_hi:[0,0] neg_lo:[1,0]
	v_pk_mul_f32 v[152:153], v[160:161], s[22:23] op_sel:[1,0] op_sel_hi:[0,0] neg_lo:[1,0]
	v_pk_fma_f32 v[156:157], v[158:159], s[22:23], v[156:157] op_sel_hi:[1,0,1]
	v_xor_b32_e32 v158, 0x80000000, v151
	v_mov_b32_e32 v159, v150
	v_pk_mul_f32 v[150:151], v[150:151], s[12:13] op_sel_hi:[1,0]
	v_pk_fma_f32 v[152:153], v[160:161], s[36:37], v[152:153] op_sel_hi:[1,0,1]
	v_pk_fma_f32 v[150:151], v[158:159], s[12:13], v[150:151] op_sel_hi:[1,0,1] neg_lo:[0,0,1] neg_hi:[0,0,1]
	v_pk_mul_f32 v[158:159], v[134:135], s[22:23] op_sel:[1,0] op_sel_hi:[0,0] neg_lo:[1,0]
	s_addk_i32 s47, 0x2000
	v_pk_fma_f32 v[134:135], v[134:135], s[26:27], v[158:159] op_sel_hi:[1,0,1] neg_lo:[0,0,1] neg_hi:[0,0,1]
	v_pk_add_f32 v[158:159], v[136:137], v[140:141]
	v_pk_add_f32 v[136:137], v[136:137], v[140:141] neg_lo:[0,1] neg_hi:[0,1]
	v_pk_add_f32 v[140:141], v[138:139], v[142:143]
	v_pk_add_f32 v[138:139], v[138:139], v[142:143] neg_lo:[0,1] neg_hi:[0,1]
	s_cmp_eq_u32 s42, 0x10000
	v_xor_b32_e32 v142, 0x80000000, v139
	v_mov_b32_e32 v143, v138
	v_pk_add_f32 v[138:139], v[158:159], v[140:141]
	v_pk_add_f32 v[140:141], v[158:159], v[140:141] neg_lo:[0,1] neg_hi:[0,1]
	v_pk_add_f32 v[158:159], v[152:153], v[156:157]
	v_pk_add_f32 v[152:153], v[152:153], v[156:157] neg_lo:[0,1] neg_hi:[0,1]
	v_pk_add_f32 v[160:161], v[136:137], v[142:143]
	v_pk_add_f32 v[136:137], v[136:137], v[142:143] neg_lo:[0,1] neg_hi:[0,1]
	v_pk_add_f32 v[142:143], v[162:163], v[154:155]
	v_pk_add_f32 v[154:155], v[162:163], v[154:155] neg_lo:[0,1] neg_hi:[0,1]
	s_nop 0
	v_pk_add_f32 v[162:163], v[154:155], v[152:153] op_sel:[0,1] op_sel_hi:[1,0] neg_lo:[0,1]
	v_pk_add_f32 v[154:155], v[154:155], v[152:153] op_sel:[0,1] op_sel_hi:[1,0] neg_hi:[0,1]
	v_pk_add_f32 v[156:157], v[144:145], v[148:149]
	v_pk_add_f32 v[144:145], v[144:145], v[148:149] neg_lo:[0,1] neg_hi:[0,1]
	v_pk_add_f32 v[148:149], v[146:147], v[150:151]
	v_pk_add_f32 v[146:147], v[146:147], v[150:151] neg_lo:[0,1] neg_hi:[0,1]
	v_pk_add_f32 v[152:153], v[142:143], v[158:159]
	v_pk_add_f32 v[142:143], v[142:143], v[158:159] neg_lo:[0,1] neg_hi:[0,1]
	v_pk_add_f32 v[158:159], v[144:145], v[146:147] op_sel:[0,1] op_sel_hi:[1,0] neg_lo:[0,1]
	v_pk_add_f32 v[144:145], v[144:145], v[146:147] op_sel:[0,1] op_sel_hi:[1,0] neg_hi:[0,1]
	v_pk_add_f32 v[150:151], v[128:129], v[132:133]
	v_pk_add_f32 v[128:129], v[128:129], v[132:133] neg_lo:[0,1] neg_hi:[0,1]
	v_pk_add_f32 v[132:133], v[130:131], v[134:135]
	v_pk_add_f32 v[130:131], v[130:131], v[134:135] neg_lo:[0,1] neg_hi:[0,1]
	v_pk_add_f32 v[146:147], v[156:157], v[148:149]
	v_pk_add_f32 v[148:149], v[156:157], v[148:149] neg_lo:[0,1] neg_hi:[0,1]
	v_pk_add_f32 v[156:157], v[128:129], v[130:131] op_sel:[0,1] op_sel_hi:[1,0] neg_lo:[0,1]
	v_pk_add_f32 v[128:129], v[128:129], v[130:131] op_sel:[0,1] op_sel_hi:[1,0] neg_hi:[0,1]
	v_xor_b32_e32 v134, 0x80000000, v115
	v_mov_b32_e32 v135, v114
	v_pk_mul_f32 v[134:135], v[134:135], v[138:139] op_sel:[0,1]
	v_pk_add_f32 v[130:131], v[150:151], v[132:133]
	v_pk_fma_f32 v[114:115], v[114:115], v[138:139], v[134:135] op_sel_hi:[1,0,1]
	v_pk_mul_f32 v[134:135], v[126:127], v[152:153] op_sel:[1,1] op_sel_hi:[0,1] neg_lo:[1,0]
	v_pk_add_f32 v[132:133], v[150:151], v[132:133] neg_lo:[0,1] neg_hi:[0,1]
	v_pk_fma_f32 v[126:127], v[126:127], v[152:153], v[134:135] op_sel_hi:[1,0,1]
	ds_write2_b64 v164, v[114:115], v[126:127] offset1:17
	v_pk_mul_f32 v[114:115], v[124:125], v[146:147] op_sel:[1,1] op_sel_hi:[0,1] neg_lo:[1,0]
	v_pk_fma_f32 v[114:115], v[124:125], v[146:147], v[114:115] op_sel_hi:[1,0,1]
	v_pk_mul_f32 v[124:125], v[122:123], v[130:131] op_sel:[1,1] op_sel_hi:[0,1] neg_lo:[1,0]
	v_pk_fma_f32 v[122:123], v[122:123], v[130:131], v[124:125] op_sel_hi:[1,0,1]
	ds_write2_b64 v164, v[114:115], v[122:123] offset0:34 offset1:51
	v_pk_mul_f32 v[114:115], v[120:121], v[160:161] op_sel:[1,1] op_sel_hi:[0,1] neg_lo:[1,0]
	v_pk_fma_f32 v[114:115], v[120:121], v[160:161], v[114:115] op_sel_hi:[1,0,1]
	v_pk_mul_f32 v[120:121], v[118:119], v[162:163] op_sel:[1,1] op_sel_hi:[0,1] neg_lo:[1,0]
	v_pk_fma_f32 v[118:119], v[118:119], v[162:163], v[120:121] op_sel_hi:[1,0,1]
	ds_write2_b64 v164, v[114:115], v[118:119] offset0:68 offset1:85
	v_pk_mul_f32 v[114:115], v[116:117], v[158:159] op_sel:[1,1] op_sel_hi:[0,1] neg_lo:[1,0]
	v_pk_fma_f32 v[114:115], v[116:117], v[158:159], v[114:115] op_sel_hi:[1,0,1]
	v_pk_mul_f32 v[116:117], v[110:111], v[156:157] op_sel:[1,1] op_sel_hi:[0,1] neg_lo:[1,0]
	v_pk_fma_f32 v[110:111], v[110:111], v[156:157], v[116:117] op_sel_hi:[1,0,1]
	ds_write2_b64 v164, v[114:115], v[110:111] offset0:102 offset1:119
	v_pk_mul_f32 v[110:111], v[112:113], v[140:141] op_sel:[1,1] op_sel_hi:[0,1] neg_lo:[1,0]
	v_pk_fma_f32 v[110:111], v[112:113], v[140:141], v[110:111] op_sel_hi:[1,0,1]
	v_pk_mul_f32 v[112:113], v[108:109], v[142:143] op_sel:[1,1] op_sel_hi:[0,1] neg_lo:[1,0]
	v_pk_fma_f32 v[108:109], v[108:109], v[142:143], v[112:113] op_sel_hi:[1,0,1]
	ds_write2_b64 v164, v[110:111], v[108:109] offset0:136 offset1:153
	v_pk_mul_f32 v[108:109], v[106:107], v[148:149] op_sel:[1,1] op_sel_hi:[0,1] neg_lo:[1,0]
	v_pk_fma_f32 v[106:107], v[106:107], v[148:149], v[108:109] op_sel_hi:[1,0,1]
	v_pk_mul_f32 v[108:109], v[104:105], v[132:133] op_sel:[1,1] op_sel_hi:[0,1] neg_lo:[1,0]
	v_pk_fma_f32 v[104:105], v[104:105], v[132:133], v[108:109] op_sel_hi:[1,0,1]
	ds_write2_b64 v164, v[106:107], v[104:105] offset0:170 offset1:187
	v_pk_mul_f32 v[104:105], v[6:7], v[136:137] op_sel:[1,1] op_sel_hi:[0,1] neg_lo:[1,0]
	s_waitcnt vmcnt(5)
	v_and_b32_e32 v133, 0xffff0000, v13
	v_pk_fma_f32 v[6:7], v[6:7], v[136:137], v[104:105] op_sel_hi:[1,0,1]
	v_pk_mul_f32 v[104:105], v[4:5], v[154:155] op_sel:[1,1] op_sel_hi:[0,1] neg_lo:[1,0]
	v_lshlrev_b32_e32 v136, 16, v12
	v_pk_fma_f32 v[4:5], v[4:5], v[154:155], v[104:105] op_sel_hi:[1,0,1]
	ds_write2_b64 v164, v[6:7], v[4:5] offset0:204 offset1:221
	v_pk_mul_f32 v[4:5], v[2:3], v[144:145] op_sel:[1,1] op_sel_hi:[0,1] neg_lo:[1,0]
	v_and_b32_e32 v137, 0xffff0000, v12
	v_pk_fma_f32 v[2:3], v[2:3], v[144:145], v[4:5] op_sel_hi:[1,0,1]
	v_pk_mul_f32 v[4:5], v[0:1], v[128:129] op_sel:[1,1] op_sel_hi:[0,1] neg_lo:[1,0]
	v_pk_fma_f32 v[0:1], v[0:1], v[128:129], v[4:5] op_sel_hi:[1,0,1]
	ds_write2_b64 v164, v[2:3], v[0:1] offset0:238 offset1:255
	v_mov_b32_e32 v0, v206
	s_waitcnt lgkmcnt(0)
	s_barrier
	s_nop 0
	v_lshlrev_b32_sdwa v1, v228, v0 dst_sel:DWORD dst_unused:UNUSED_PAD src0_sel:DWORD src1_sel:BYTE_0
	v_lshrrev_b32_e32 v0, 1, v206
	v_and_b32_e32 v0, 0x78, v0
	v_add3_u32 v132, v207, v1, v0
	ds_read_b64 v[0:1], v132
	ds_read_b64 v[2:3], v132 offset:2176
	ds_read_b64 v[4:5], v132 offset:4352
	ds_read_b64 v[6:7], v132 offset:6528
	ds_read_b64 v[104:105], v132 offset:8704
	ds_read_b64 v[106:107], v132 offset:10880
	ds_read_b64 v[108:109], v132 offset:13056
	ds_read_b64 v[110:111], v132 offset:15232
	ds_read_b64 v[112:113], v132 offset:17408
	ds_read_b64 v[114:115], v132 offset:19584
	ds_read_b64 v[116:117], v132 offset:21760
	ds_read_b64 v[118:119], v132 offset:23936
	ds_read_b64 v[120:121], v132 offset:26112
	ds_read_b64 v[122:123], v132 offset:28288
	ds_read_b64 v[124:125], v132 offset:30464
	ds_read_b64 v[126:127], v132 offset:32640
	s_waitcnt lgkmcnt(7)
	v_pk_add_f32 v[128:129], v[0:1], v[112:113]
	v_pk_add_f32 v[0:1], v[0:1], v[112:113] neg_lo:[0,1] neg_hi:[0,1]
	s_waitcnt lgkmcnt(3)
	v_pk_add_f32 v[112:113], v[104:105], v[120:121]
	v_pk_add_f32 v[104:105], v[104:105], v[120:121] neg_lo:[0,1] neg_hi:[0,1]
	s_nop 0
	v_pk_add_f32 v[130:131], v[0:1], v[104:105] op_sel:[0,1] op_sel_hi:[1,0] neg_lo:[0,1]
	v_pk_add_f32 v[0:1], v[0:1], v[104:105] op_sel:[0,1] op_sel_hi:[1,0] neg_hi:[0,1]
	v_pk_add_f32 v[120:121], v[2:3], v[114:115]
	v_pk_add_f32 v[2:3], v[2:3], v[114:115] neg_lo:[0,1] neg_hi:[0,1]
	s_waitcnt lgkmcnt(2)
	v_pk_add_f32 v[114:115], v[106:107], v[122:123]
	v_pk_add_f32 v[106:107], v[106:107], v[122:123] neg_lo:[0,1] neg_hi:[0,1]
	v_pk_add_f32 v[104:105], v[128:129], v[112:113]
	v_xor_b32_e32 v122, 0x80000000, v107
	v_mov_b32_e32 v123, v106
	v_pk_add_f32 v[106:107], v[120:121], v[114:115]
	v_pk_add_f32 v[114:115], v[120:121], v[114:115] neg_lo:[0,1] neg_hi:[0,1]
	v_pk_add_f32 v[120:121], v[4:5], v[116:117]
	v_pk_add_f32 v[4:5], v[4:5], v[116:117] neg_lo:[0,1] neg_hi:[0,1]
	s_waitcnt lgkmcnt(1)
	v_pk_add_f32 v[116:117], v[108:109], v[124:125]
	v_pk_add_f32 v[108:109], v[108:109], v[124:125] neg_lo:[0,1] neg_hi:[0,1]
	v_pk_add_f32 v[112:113], v[128:129], v[112:113] neg_lo:[0,1] neg_hi:[0,1]
	v_pk_add_f32 v[128:129], v[2:3], v[122:123]
	v_pk_add_f32 v[2:3], v[2:3], v[122:123] neg_lo:[0,1] neg_hi:[0,1]
	v_xor_b32_e32 v122, 0x80000000, v109
	v_mov_b32_e32 v123, v108
	v_pk_add_f32 v[108:109], v[120:121], v[116:117]
	v_pk_add_f32 v[116:117], v[120:121], v[116:117] neg_lo:[0,1] neg_hi:[0,1]
	v_pk_add_f32 v[120:121], v[6:7], v[118:119]
	v_pk_add_f32 v[6:7], v[6:7], v[118:119] neg_lo:[0,1] neg_hi:[0,1]
	s_waitcnt lgkmcnt(0)
	v_pk_add_f32 v[118:119], v[110:111], v[126:127]
	v_pk_add_f32 v[110:111], v[110:111], v[126:127] neg_lo:[0,1] neg_hi:[0,1]
	v_pk_add_f32 v[124:125], v[4:5], v[122:123]
	v_pk_add_f32 v[4:5], v[4:5], v[122:123] neg_lo:[0,1] neg_hi:[0,1]
	v_pk_add_f32 v[126:127], v[6:7], v[110:111] op_sel:[0,1] op_sel_hi:[1,0] neg_lo:[0,1]
	v_pk_add_f32 v[6:7], v[6:7], v[110:111] op_sel:[0,1] op_sel_hi:[1,0] neg_hi:[0,1]
	v_pk_mul_f32 v[122:123], v[114:115], s[12:13] op_sel:[1,0] op_sel_hi:[0,0] neg_lo:[1,0]
	v_pk_add_f32 v[110:111], v[120:121], v[118:119]
	v_pk_fma_f32 v[114:115], v[114:115], s[12:13], v[122:123] op_sel_hi:[1,0,1]
	v_pk_mul_f32 v[122:123], v[2:3], s[36:37] op_sel:[1,0] op_sel_hi:[0,0] neg_lo:[1,0]
	v_pk_add_f32 v[118:119], v[120:121], v[118:119] neg_lo:[0,1] neg_hi:[0,1]
	v_pk_fma_f32 v[2:3], v[2:3], s[22:23], v[122:123] op_sel_hi:[1,0,1]
	v_pk_mul_f32 v[122:123], v[124:125], s[12:13] op_sel:[1,0] op_sel_hi:[0,0] neg_lo:[1,0]
	v_pk_fma_f32 v[122:123], v[124:125], s[12:13], v[122:123] op_sel_hi:[1,0,1]
	v_pk_fma_f32 v[116:117], v[116:117], 0, v[116:117] op_sel:[0,0,1] op_sel_hi:[1,0,0] neg_lo:[0,0,1]
	v_xor_b32_e32 v124, 0x80000000, v5
	v_mov_b32_e32 v125, v4
	v_pk_mul_f32 v[4:5], v[4:5], s[12:13] op_sel_hi:[1,0]
	s_nop 0
	v_pk_fma_f32 v[4:5], v[124:125], s[12:13], v[4:5] op_sel_hi:[1,0,1] neg_lo:[0,0,1] neg_hi:[0,0,1]
	v_pk_mul_f32 v[124:125], v[126:127], s[36:37] op_sel:[1,0] op_sel_hi:[0,0] neg_lo:[1,0]
	v_pk_mul_f32 v[120:121], v[128:129], s[22:23] op_sel:[1,0] op_sel_hi:[0,0] neg_lo:[1,0]
	v_pk_fma_f32 v[124:125], v[126:127], s[22:23], v[124:125] op_sel_hi:[1,0,1]
	v_xor_b32_e32 v126, 0x80000000, v119
	v_mov_b32_e32 v127, v118
	v_pk_mul_f32 v[118:119], v[118:119], s[12:13] op_sel_hi:[1,0]
	v_pk_fma_f32 v[120:121], v[128:129], s[36:37], v[120:121] op_sel_hi:[1,0,1]
	v_pk_fma_f32 v[118:119], v[126:127], s[12:13], v[118:119] op_sel_hi:[1,0,1] neg_lo:[0,0,1] neg_hi:[0,0,1]
	v_pk_mul_f32 v[126:127], v[6:7], s[22:23] op_sel:[1,0] op_sel_hi:[0,0] neg_lo:[1,0]
	v_pk_fma_f32 v[6:7], v[6:7], s[26:27], v[126:127] op_sel_hi:[1,0,1] neg_lo:[0,0,1] neg_hi:[0,0,1]
	v_pk_add_f32 v[126:127], v[104:105], v[108:109]
	v_pk_add_f32 v[104:105], v[104:105], v[108:109] neg_lo:[0,1] neg_hi:[0,1]
	v_pk_add_f32 v[108:109], v[106:107], v[110:111]
	v_pk_add_f32 v[106:107], v[106:107], v[110:111] neg_lo:[0,1] neg_hi:[0,1]
	s_nop 0
	v_xor_b32_e32 v110, 0x80000000, v107
	v_mov_b32_e32 v111, v106
	v_pk_add_f32 v[106:107], v[126:127], v[108:109]
	v_pk_add_f32 v[108:109], v[126:127], v[108:109] neg_lo:[0,1] neg_hi:[0,1]
	v_pk_add_f32 v[126:127], v[120:121], v[124:125]
	v_pk_add_f32 v[120:121], v[120:121], v[124:125] neg_lo:[0,1] neg_hi:[0,1]
	v_pk_add_f32 v[128:129], v[104:105], v[110:111]
	v_pk_add_f32 v[104:105], v[104:105], v[110:111] neg_lo:[0,1] neg_hi:[0,1]
	v_pk_add_f32 v[110:111], v[130:131], v[122:123]
	v_pk_add_f32 v[122:123], v[130:131], v[122:123] neg_lo:[0,1] neg_hi:[0,1]
	s_nop 0
	v_pk_add_f32 v[130:131], v[122:123], v[120:121] op_sel:[0,1] op_sel_hi:[1,0] neg_lo:[0,1]
	v_pk_add_f32 v[122:123], v[122:123], v[120:121] op_sel:[0,1] op_sel_hi:[1,0] neg_hi:[0,1]
	v_pk_add_f32 v[124:125], v[112:113], v[116:117]
	v_pk_add_f32 v[112:113], v[112:113], v[116:117] neg_lo:[0,1] neg_hi:[0,1]
	v_pk_add_f32 v[116:117], v[114:115], v[118:119]
	v_pk_add_f32 v[114:115], v[114:115], v[118:119] neg_lo:[0,1] neg_hi:[0,1]
	v_pk_add_f32 v[120:121], v[110:111], v[126:127]
	v_pk_add_f32 v[110:111], v[110:111], v[126:127] neg_lo:[0,1] neg_hi:[0,1]
	v_pk_add_f32 v[126:127], v[112:113], v[114:115] op_sel:[0,1] op_sel_hi:[1,0] neg_lo:[0,1]
	v_pk_add_f32 v[112:113], v[112:113], v[114:115] op_sel:[0,1] op_sel_hi:[1,0] neg_hi:[0,1]
	v_pk_add_f32 v[118:119], v[0:1], v[4:5]
	v_pk_add_f32 v[0:1], v[0:1], v[4:5] neg_lo:[0,1] neg_hi:[0,1]
	v_pk_add_f32 v[4:5], v[2:3], v[6:7]
	v_pk_add_f32 v[2:3], v[2:3], v[6:7] neg_lo:[0,1] neg_hi:[0,1]
	v_pk_add_f32 v[114:115], v[124:125], v[116:117]
	v_pk_add_f32 v[116:117], v[124:125], v[116:117] neg_lo:[0,1] neg_hi:[0,1]
	v_pk_add_f32 v[124:125], v[0:1], v[2:3] op_sel:[0,1] op_sel_hi:[1,0] neg_lo:[0,1]
	v_pk_add_f32 v[0:1], v[0:1], v[2:3] op_sel:[0,1] op_sel_hi:[1,0] neg_hi:[0,1]
	v_pk_add_f32 v[2:3], v[118:119], v[4:5]
	v_pk_add_f32 v[4:5], v[118:119], v[4:5] neg_lo:[0,1] neg_hi:[0,1]
	ds_write_b64 v132, v[106:107]
	ds_write_b64 v132, v[128:129] offset:8704
	ds_write_b64 v132, v[108:109] offset:17408
	ds_write_b64 v132, v[104:105] offset:26112
	ds_write_b64 v132, v[120:121] offset:2176
	ds_write_b64 v132, v[130:131] offset:10880
	ds_write_b64 v132, v[110:111] offset:19584
	ds_write_b64 v132, v[122:123] offset:28288
	ds_write_b64 v132, v[114:115] offset:4352
	ds_write_b64 v132, v[126:127] offset:13056
	ds_write_b64 v132, v[116:117] offset:21760
	ds_write_b64 v132, v[112:113] offset:30464
	ds_write_b64 v132, v[2:3] offset:6528
	ds_write_b64 v132, v[124:125] offset:15232
	ds_write_b64 v132, v[4:5] offset:23936
	ds_write_b64 v132, v[0:1] offset:32640
	s_waitcnt lgkmcnt(0)
	s_barrier
	v_mov_b32_e32 v115, v214
	v_and_b32_e32 v1, 0x1ff, v212
	v_lshlrev_b32_e32 v2, 3, v1
	v_bfe_u32 v0, v212, 1, 8
	v_add_u32_e32 v104, v2, v0
	v_cmp_eq_u32_e32 vcc, 0, v1
	s_waitcnt vmcnt(3)
	v_lshlrev_b32_e32 v0, 16, v233
	v_cmp_eq_u32_e64 s[0:1], s37, v1
	v_cndmask_b32_e64 v139, v0, 0, vcc
	s_waitcnt vmcnt(2)
	v_lshlrev_b32_e32 v0, 16, v232
	v_cndmask_b32_e64 v135, v0, 0, s[0:1]
	s_waitcnt vmcnt(1)
	v_lshlrev_b32_e32 v0, 16, v231
	v_cndmask_b32_e64 v121, v0, 0, vcc
	s_waitcnt vmcnt(0)
	v_lshlrev_b32_e32 v0, 16, v176
	v_cndmask_b32_e64 v107, v0, 0, s[0:1]
	v_add_u32_e32 v0, -1, v2
	v_cndmask_b32_e64 v176, v0, 0, vcc
	v_add_u32_e32 v0, 8, v2
	v_cndmask_b32_e64 v12, v0, v229, s[0:1]
	v_lshlrev_b64 v[110:111], 1, v[176:177]
	v_mov_b32_e32 v114, v213
	v_lshlrev_b32_e32 v116, 16, v8
	v_and_b32_e32 v117, 0xffff0000, v8
	v_lshlrev_b32_e32 v8, 4, v1
	v_lshl_add_u64 v[112:113], s[2:3], 0, v[110:111]
	v_lshlrev_b32_e32 v12, 1, v12
	v_lshl_add_u64 v[110:111], s[6:7], 0, v[110:111]
	v_lshl_add_u32 v104, v104, 3, 0
	global_load_dwordx4 v[4:7], v8, s[2:3]
	global_load_dwordx4 v[0:3], v8, s[6:7]
	global_load_ushort v143, v[112:113], off
	global_load_ushort v142, v12, s[2:3]
	global_load_ushort v141, v[110:111], off
	global_load_ushort v140, v12, s[6:7]
	v_add_u32_e32 v12, 0x8800, v104
	ds_read2_b64 v[110:113], v104 offset1:1
	ds_read2_b64 v[122:125], v12 offset1:1
	v_xor_b32_e32 v119, 0x80000000, v115
	v_mov_b32_e32 v118, v114
	v_mov_b32_e32 v132, v137
	s_waitcnt lgkmcnt(0)
	v_pk_mul_f32 v[118:119], v[118:119], v[122:123] op_sel_hi:[1,0]
	v_lshlrev_b32_e32 v131, 16, v15
	v_pk_fma_f32 v[118:119], v[114:115], v[122:123], v[118:119] op_sel:[1,1,0] op_sel_hi:[0,1,1]
	v_pk_add_f32 v[122:123], v[110:111], v[118:119]
	v_pk_mul_f32 v[110:111], v[214:215], s[8:9] op_sel_hi:[0,1]
	v_pk_fma_f32 v[110:111], v[212:213], s[30:31], v[110:111] op_sel:[1,0,0]
	s_nop 0
	v_pk_add_f32 v[114:115], v[110:111], 0 neg_lo:[1,1] neg_hi:[1,1]
	s_nop 0
	v_mov_b32_e32 v114, v110
	v_pk_mul_f32 v[114:115], v[114:115], v[124:125] op_sel_hi:[1,0]
	v_and_b32_e32 v15, 0xffff0000, v15
	v_pk_fma_f32 v[114:115], v[110:111], v[124:125], v[114:115] op_sel:[1,1,0] op_sel_hi:[0,1,1]
	v_pk_add_f32 v[124:125], v[112:113], v[114:115]
	v_pk_mul_f32 v[112:113], v[110:111], s[8:9] op_sel:[1,0]
	v_add_u32_e32 v12, 0x8810, v104
	v_pk_fma_f32 v[114:115], v[110:111], s[30:31], v[112:113] op_sel_hi:[0,1,1]
	ds_read2_b64 v[110:113], v104 offset0:2 offset1:3
	ds_read2_b64 v[126:129], v12 offset1:1
	v_pk_add_f32 v[118:119], v[114:115], 0 neg_lo:[1,1] neg_hi:[1,1]
	v_mov_b32_e32 v134, v131
	v_mov_b32_e32 v118, v114
	v_and_b32_e32 v109, 0xffff0000, v9
	s_waitcnt lgkmcnt(0)
	v_pk_mul_f32 v[118:119], v[118:119], v[126:127] op_sel_hi:[1,0]
	s_nop 0
	v_pk_fma_f32 v[118:119], v[114:115], v[126:127], v[118:119] op_sel:[1,1,0] op_sel_hi:[0,1,1]
	v_pk_add_f32 v[126:127], v[110:111], v[118:119]
	v_pk_mul_f32 v[110:111], v[114:115], s[8:9] op_sel:[1,0]
	v_lshlrev_b32_e32 v105, 16, v11
	v_pk_fma_f32 v[110:111], v[114:115], s[30:31], v[110:111] op_sel_hi:[0,1,1]
	v_pk_add_f32 v[114:115], v[110:111], 0 neg_lo:[1,1] neg_hi:[1,1]
	v_and_b32_e32 v11, 0xffff0000, v11
	v_mov_b32_e32 v114, v110
	v_pk_mul_f32 v[114:115], v[114:115], v[128:129] op_sel_hi:[1,0]
	s_brev_b32 s0, 48
	v_pk_fma_f32 v[114:115], v[110:111], v[128:129], v[114:115] op_sel:[1,1,0] op_sel_hi:[0,1,1]
	v_pk_add_f32 v[128:129], v[112:113], v[114:115]
	v_pk_mul_f32 v[112:113], v[110:111], s[8:9] op_sel:[1,0]
	v_add_u32_e32 v12, 0x8820, v104
	v_pk_fma_f32 v[114:115], v[110:111], s[30:31], v[112:113] op_sel_hi:[0,1,1]
	ds_read2_b64 v[110:113], v104 offset0:4 offset1:5
	ds_read2_b64 v[144:147], v12 offset1:1
	v_pk_add_f32 v[118:119], v[114:115], 0 neg_lo:[1,1] neg_hi:[1,1]
	s_waitcnt lgkmcnt(0)
	v_mov_b32_e32 v12, v147
	v_mov_b32_e32 v118, v114
	v_pk_mul_f32 v[118:119], v[118:119], v[144:145] op_sel_hi:[1,0]
	s_nop 0
	v_pk_fma_f32 v[118:119], v[114:115], v[144:145], v[118:119] op_sel:[1,1,0] op_sel_hi:[0,1,1]
	v_pk_add_f32 v[110:111], v[110:111], v[118:119]
	v_pk_mul_f32 v[118:119], v[114:115], s[8:9] op_sel:[1,0]
	s_nop 0
	v_pk_fma_f32 v[114:115], v[114:115], s[30:31], v[118:119] op_sel_hi:[0,1,1]
	v_pk_add_f32 v[118:119], v[114:115], 0 neg_lo:[1,1] neg_hi:[1,1]
	s_nop 0
	v_mov_b32_e32 v118, v114
	v_pk_mul_f32 v[118:119], v[118:119], v[146:147] op_sel_hi:[1,0]
	ds_read2_b64 v[144:147], v104 offset0:6 offset1:7
	v_pk_fma_f32 v[118:119], v[114:115], v[12:13], v[118:119] op_sel:[1,0,0] op_sel_hi:[0,0,1]
	v_add_u32_e32 v12, 0x8830, v104
	ds_read2_b64 v[148:151], v12 offset1:1
	v_pk_add_f32 v[112:113], v[112:113], v[118:119]
	v_pk_mul_f32 v[118:119], v[114:115], s[8:9] op_sel:[1,0]
	s_waitcnt lgkmcnt(0)
	v_pk_fma_f32 v[118:119], v[114:115], s[30:31], v[118:119] op_sel_hi:[0,1,1]
	v_pk_add_f32 v[114:115], v[118:119], 0 neg_lo:[1,1] neg_hi:[1,1]
	s_nop 0
	v_mov_b32_e32 v114, v118
	v_pk_mul_f32 v[114:115], v[114:115], v[148:149] op_sel_hi:[1,0]
	s_nop 0
	v_pk_fma_f32 v[114:115], v[118:119], v[148:149], v[114:115] op_sel:[1,1,0] op_sel_hi:[0,1,1]
	v_pk_add_f32 v[114:115], v[144:145], v[114:115]
	v_pk_mul_f32 v[144:145], v[118:119], s[8:9] op_sel:[1,0]
	s_nop 0
	v_pk_fma_f32 v[118:119], v[118:119], s[30:31], v[144:145] op_sel_hi:[0,1,1]
	v_pk_add_f32 v[144:145], v[118:119], 0 neg_lo:[1,1] neg_hi:[1,1]
	s_nop 0
	v_mov_b32_e32 v144, v118
	v_pk_mul_f32 v[144:145], v[150:151], v[144:145] op_sel_hi:[0,1]
	v_pk_fma_f32 v[118:119], v[118:119], v[150:151], v[144:145] op_sel:[1,1,0] op_sel_hi:[0,1,1]
	v_lshlrev_b32_e32 v144, 16, v13
	v_mov_b32_e32 v138, v144
	v_pk_mul_f32 v[138:139], v[30:31], v[138:139]
	v_mov_b32_e32 v12, v136
	v_mov_b32_e32 v13, v144
	v_pk_fma_f32 v[136:137], v[30:31], v[136:137], v[138:139] op_sel:[0,0,1] op_sel_hi:[1,1,0]
	v_pk_mul_f32 v[138:139], v[102:103], v[132:133]
	v_lshlrev_b32_e32 v145, 16, v14
	v_pk_fma_f32 v[136:137], v[34:35], v[132:133], v[136:137]
	v_pk_fma_f32 v[12:13], v[100:101], v[12:13], v[138:139]
	v_pk_add_f32 v[136:137], v[36:37], v[136:137]
	v_pk_fma_f32 v[12:13], v[34:35], v[144:145], v[12:13]
	v_mov_b32_e32 v138, v122
	v_mov_b32_e32 v139, v126
	v_pk_add_f32 v[12:13], v[36:37], v[12:13]
	v_pk_mul_f32 v[136:137], v[136:137], v[138:139]
	v_mov_b32_e32 v138, v124
	v_mov_b32_e32 v139, v128
	v_pk_mul_f32 v[12:13], v[12:13], v[138:139]
	v_and_b32_e32 v14, 0xffff0000, v14
	v_mov_b32_e32 v138, v145
	v_mov_b32_e32 v139, v131
	v_pk_mov_b32 v[132:133], v[132:133], v[14:15] op_sel:[1,0]
	v_pk_mul_f32 v[138:139], v[102:103], v[138:139]
	v_mov_b32_e32 v144, v15
	v_pk_fma_f32 v[132:133], v[100:101], v[132:133], v[138:139]
	v_mov_b32_e32 v130, v14
	v_pk_fma_f32 v[132:133], v[34:35], v[14:15], v[132:133]
	v_pk_mul_f32 v[14:15], v[30:31], v[144:145]
	v_pk_add_f32 v[118:119], v[146:147], v[118:119]
	v_pk_fma_f32 v[14:15], v[30:31], v[130:131], v[14:15] op_sel:[0,0,1] op_sel_hi:[1,1,0]
	v_pk_add_f32 v[132:133], v[36:37], v[132:133]
	v_pk_fma_f32 v[14:15], v[34:35], v[134:135], v[14:15]
	v_mov_b32_e32 v130, v110
	v_mov_b32_e32 v131, v114
	v_pk_add_f32 v[14:15], v[36:37], v[14:15]
	v_pk_mul_f32 v[130:131], v[132:133], v[130:131]
	v_mov_b32_e32 v132, v112
	v_mov_b32_e32 v133, v118
	v_pk_mul_f32 v[14:15], v[14:15], v[132:133]
	v_bfe_u32 v108, v13, 16, 1
	v_bfe_u32 v104, v15, 16, 1
	v_add3_u32 v15, v15, v104, s13
	v_add3_u32 v13, v13, v108, s13
	v_bfe_u32 v104, v130, 16, 1
	v_bfe_u32 v108, v136, 16, 1
	v_bfe_u32 v106, v14, 16, 1
	v_bfe_u32 v110, v12, 16, 1
	v_add3_u32 v104, v130, v104, s13
	v_add3_u32 v108, v136, v108, s13
	v_lshlrev_b32_e32 v130, 16, v9
	v_add3_u32 v14, v14, v106, s13
	v_add3_u32 v12, v12, v110, s13
	v_bfe_u32 v106, v131, 16, 1
	v_lshrrev_b32_e32 v108, 16, v108
	v_mov_b32_e32 v120, v130
	v_add3_u32 v106, v131, v106, s13
	v_and_or_b32 v12, v12, s33, v108
	v_lshlrev_b32_e32 v131, 16, v10
	v_mov_b32_e32 v108, v117
	v_pk_mul_f32 v[120:121], v[30:31], v[120:121]
	v_mov_b32_e32 v132, v116
	v_mov_b32_e32 v133, v130
	v_pk_fma_f32 v[116:117], v[30:31], v[116:117], v[120:121] op_sel:[0,0,1] op_sel_hi:[1,1,0]
	v_pk_mul_f32 v[120:121], v[102:103], v[108:109]
	v_mov_b32_e32 v126, v123
	v_and_b32_e32 v10, 0xffff0000, v10
	v_mov_b32_e32 v122, v131
	v_mov_b32_e32 v123, v105
	v_pk_fma_f32 v[116:117], v[34:35], v[108:109], v[116:117]
	v_pk_fma_f32 v[120:121], v[100:101], v[132:133], v[120:121]
	v_pk_mov_b32 v[108:109], v[108:109], v[10:11] op_sel:[1,0]
	v_pk_mul_f32 v[122:123], v[102:103], v[122:123]
	v_lshrrev_b32_e32 v104, 16, v104
	v_pk_fma_f32 v[120:121], v[34:35], v[130:131], v[120:121]
	v_pk_fma_f32 v[108:109], v[100:101], v[108:109], v[122:123]
	v_mov_b32_e32 v130, v11
	v_lshrrev_b32_e32 v106, 16, v106
	v_and_or_b32 v14, v14, s33, v104
	v_mov_b32_e32 v104, v10
	v_pk_fma_f32 v[108:109], v[34:35], v[10:11], v[108:109]
	v_pk_mul_f32 v[10:11], v[30:31], v[130:131]
	v_and_or_b32 v15, v15, s33, v106
	v_mov_b32_e32 v106, v105
	v_pk_fma_f32 v[10:11], v[30:31], v[104:105], v[10:11] op_sel:[0,0,1] op_sel_hi:[1,1,0]
	v_pk_add_f32 v[120:121], v[36:37], v[120:121]
	v_pk_fma_f32 v[10:11], v[34:35], v[106:107], v[10:11]
	v_mov_b32_e32 v128, v125
	v_pk_add_f32 v[10:11], v[36:37], v[10:11]
	v_mov_b32_e32 v118, v113
	v_pk_mul_f32 v[120:121], v[120:121], v[128:129]
	v_pk_add_f32 v[108:109], v[36:37], v[108:109]
	v_mov_b32_e32 v114, v111
	v_pk_mul_f32 v[10:11], v[10:11], v[118:119]
	v_pk_add_f32 v[116:117], v[36:37], v[116:117]
	v_pk_mul_f32 v[104:105], v[108:109], v[114:115]
	v_bfe_u32 v9, v11, 16, 1
	v_bfe_u32 v107, v121, 16, 1
	v_bfe_u32 v108, v120, 16, 1
	v_bfe_u32 v110, v137, 16, 1
	v_pk_mul_f32 v[116:117], v[116:117], v[126:127]
	v_add3_u32 v9, v11, v9, s13
	v_add3_u32 v11, v120, v108, s13
	v_add3_u32 v108, v121, v107, s13
	v_bfe_u32 v107, v105, 16, 1
	v_add3_u32 v110, v137, v110, s13
	v_bfe_u32 v106, v10, 16, 1
	v_bfe_u32 v109, v116, 16, 1
	v_add3_u32 v105, v105, v107, s13
	v_lshrrev_b32_e32 v110, 16, v110
	v_add3_u32 v10, v10, v106, s13
	v_bfe_u32 v106, v104, 16, 1
	v_add3_u32 v107, v116, v109, s13
	v_lshrrev_b32_e32 v105, 16, v105
	v_and_or_b32 v13, v13, s33, v110
	v_bfe_u32 v110, v117, 16, 1
	v_add3_u32 v104, v104, v106, s13
	v_lshrrev_b32_e32 v109, 16, v107
	v_and_or_b32 v107, v9, s33, v105
	v_mov_b32_e32 v9, v177
	v_add3_u32 v106, v117, v110, s13
	v_lshrrev_b32_e32 v104, 16, v104
	v_lshl_add_u64 v[8:9], s[44:45], 0, v[8:9]
	v_lshrrev_b32_e32 v110, 16, v106
	v_and_or_b32 v106, v10, s33, v104
	v_add_co_u32_e32 v10, vcc, s0, v8
	v_and_or_b32 v104, v11, s33, v109
	s_nop 0
	v_addc_co_u32_e32 v11, vcc, 0, v9, vcc
	v_add_co_u32_e32 v8, vcc, 0xc002000, v8
	v_and_or_b32 v105, v108, s33, v110
	s_nop 0
	v_addc_co_u32_e32 v9, vcc, 0, v9, vcc
	global_store_dwordx4 v[10:11], v[12:15], off sc1
	global_store_dwordx4 v[8:9], v[104:107], off sc1
	s_cbranch_scc0 .LBB0_209
	s_load_dword s0, s[74:75], 0x0
	s_waitcnt lgkmcnt(0)
	s_add_i32 s38, s0, s38
	s_cmpk_gt_i32 s38, 0x1ff
	s_cbranch_scc0 .LBB0_204

.LBB0_213:
	s_or_b64 exec, exec, s[0:1]
	s_waitcnt lgkmcnt(0)
	v_bfe_u32 v0, v6, 16, 1
	v_lshlrev_b32_e32 v176, 1, v4
	v_add3_u32 v5, v6, v0, s13
	v_lshl_add_u64 v[0:1], v[2:3], 0, v[176:177]
	v_add_u32_e32 v49, s6, v49
	v_add_u32_e32 v52, s7, v52
	s_and_b64 vcc, exec, s[40:41]
	global_store_short_d16_hi v[0:1], v5, off sc1
	s_waitcnt vmcnt(63) expcnt(7) lgkmcnt(15)
	s_barrier
	s_cbranch_vccnz .LBB0_278
.LBB0_214:
	s_mov_b32 s0, s9
	s_add_i32 s9, s9, s3
	s_cmpk_gt_i32 s9, 0x7ff
	s_cselect_b64 s[40:41], -1, 0
	s_cmpk_lt_i32 s9, 0x800
	v_add_u32_e32 v69, s0, v34
	s_cselect_b32 s0, s9, s0
	v_add_u32_e32 v2, s0, v34
	v_and_b32_e32 v0, 31, v2
	v_lshlrev_b32_e32 v1, 1, v2
	s_movk_i32 s0, 0x1c0
	v_and_or_b32 v0, v1, s0, v0
	v_readlane_b32 s0, v254, 43
	v_lshlrev_b32_e32 v2, 4, v2
	v_lshlrev_b32_e32 v176, 16, v0
	v_readlane_b32 s1, v254, 44
	v_and_b32_e32 v2, 0xfffff000, v2
	v_ashrrev_i32_e32 v3, 31, v2
	v_lshl_add_u64 v[0:1], s[0:1], 0, v[176:177]
	v_lshlrev_b32_e32 v4, 1, v206
	v_lshl_add_u64 v[0:1], v[2:3], 1, v[0:1]
	s_mov_b64 s[0:1], 0x200000
	v_and_b32_e32 v176, 0x1fe, v4
	v_lshl_add_u64 v[2:3], v[0:1], 0, s[0:1]
	v_lshl_add_u64 v[4:5], v[0:1], 0, v[176:177]
	s_waitcnt vmcnt(0)
	v_lshlrev_b32_e32 v70, 16, v68
	v_lshlrev_b32_e32 v71, 16, v67
	v_lshlrev_b32_e32 v72, 16, v63
	v_lshlrev_b32_e32 v73, 16, v66
	v_lshlrev_b32_e32 v22, 16, v62
	v_lshlrev_b32_e32 v23, 16, v65
	v_lshlrev_b32_e32 v6, 16, v59
	v_lshlrev_b32_e32 v7, 16, v64
	v_lshlrev_b32_e32 v74, 16, v57
	v_lshlrev_b32_e32 v75, 16, v61
	v_lshlrev_b32_e32 v76, 16, v55
	v_lshlrev_b32_e32 v77, 16, v58
	v_lshlrev_b32_e32 v24, 16, v54
	v_lshlrev_b32_e32 v25, 16, v56
	v_lshlrev_b32_e32 v10, 16, v51
	v_lshlrev_b32_e32 v11, 16, v53
	v_lshl_add_u64 v[8:9], v[2:3], 0, v[176:177]
	global_load_ushort v68, v[4:5], off
	global_load_ushort v63, v[4:5], off offset:512
	global_load_ushort v62, v[4:5], off offset:1024
	global_load_ushort v59, v[4:5], off offset:1536
	global_load_ushort v57, v[4:5], off offset:2048
	global_load_ushort v55, v[4:5], off offset:2560
	global_load_ushort v54, v[4:5], off offset:3072
	global_load_ushort v51, v[4:5], off offset:3584
	global_load_ushort v67, v[8:9], off
	global_load_ushort v66, v[8:9], off offset:512
	global_load_ushort v65, v[8:9], off offset:1024
	global_load_ushort v64, v[8:9], off offset:1536
	global_load_ushort v61, v[8:9], off offset:2048
	global_load_ushort v58, v[8:9], off offset:2560
	global_load_ushort v56, v[8:9], off offset:3072
	global_load_ushort v53, v[8:9], off offset:3584
	v_or_b32_e32 v4, 0x1000, v176
	v_mov_b32_e32 v5, v177
	v_or_b32_e32 v12, 0x1200, v176
	v_mov_b32_e32 v13, v177
	v_or_b32_e32 v16, 0x1400, v176
	v_mov_b32_e32 v17, v177
	v_lshl_add_u64 v[8:9], v[0:1], 0, v[4:5]
	v_lshl_add_u64 v[4:5], v[2:3], 0, v[4:5]
	v_lshl_add_u64 v[14:15], v[0:1], 0, v[12:13]
	v_lshl_add_u64 v[12:13], v[2:3], 0, v[12:13]
	v_lshl_add_u64 v[26:27], v[0:1], 0, v[16:17]
	v_lshl_add_u64 v[16:17], v[2:3], 0, v[16:17]
	v_or_b32_e32 v28, 0x1600, v176
	v_mov_b32_e32 v29, v177
	v_lshlrev_b32_e32 v78, 16, v60
	v_lshlrev_b32_e32 v79, 16, v50
	v_lshlrev_b32_e32 v80, 16, v48
	v_lshlrev_b32_e32 v81, 16, v47
	v_lshlrev_b32_e32 v82, 16, v45
	v_lshlrev_b32_e32 v83, 16, v44
	v_lshlrev_b32_e32 v18, 16, v43
	v_lshlrev_b32_e32 v19, 16, v42
	v_lshl_add_u64 v[30:31], v[0:1], 0, v[28:29]
	v_lshl_add_u64 v[28:29], v[2:3], 0, v[28:29]
	global_load_ushort v60, v[8:9], off
	global_load_ushort v50, v[4:5], off
	global_load_ushort v48, v[14:15], off
	global_load_ushort v47, v[12:13], off
	global_load_ushort v45, v[26:27], off
	global_load_ushort v44, v[16:17], off
	global_load_ushort v43, v[30:31], off
	global_load_ushort v42, v[28:29], off
	v_or_b32_e32 v4, 0x1800, v176
	v_mov_b32_e32 v5, v177
	v_or_b32_e32 v12, 0x1a00, v176
	v_mov_b32_e32 v13, v177
	v_or_b32_e32 v16, 0x1c00, v176
	v_mov_b32_e32 v17, v177
	v_or_b32_e32 v176, 0x1e00, v176
	v_lshl_add_u64 v[8:9], v[0:1], 0, v[4:5]
	v_lshl_add_u64 v[14:15], v[0:1], 0, v[12:13]
	v_lshl_add_u64 v[26:27], v[0:1], 0, v[16:17]
	v_lshl_add_u64 v[0:1], v[0:1], 0, v[176:177]
	v_lshlrev_b32_e32 v84, 16, v46
	v_lshlrev_b32_e32 v85, 16, v41
	v_lshlrev_b32_e32 v86, 16, v40
	v_lshlrev_b32_e32 v87, 16, v39
	v_lshlrev_b32_e32 v88, 16, v38
	v_lshlrev_b32_e32 v89, 16, v37
	v_lshlrev_b32_e32 v20, 16, v36
	v_lshlrev_b32_e32 v21, 16, v35
	v_lshl_add_u64 v[4:5], v[2:3], 0, v[4:5]
	v_lshl_add_u64 v[12:13], v[2:3], 0, v[12:13]
	v_lshl_add_u64 v[16:17], v[2:3], 0, v[16:17]
	v_lshl_add_u64 v[2:3], v[2:3], 0, v[176:177]
	global_load_ushort v46, v[8:9], off
	global_load_ushort v41, v[4:5], off
	global_load_ushort v40, v[14:15], off
	global_load_ushort v39, v[12:13], off
	global_load_ushort v38, v[26:27], off
	global_load_ushort v37, v[16:17], off
	global_load_ushort v36, v[0:1], off
	global_load_ushort v35, v[2:3], off
	v_mov_b32_e32 v90, 1.0
	v_pk_mul_f32 v[2:3], v[208:209], v[208:209] op_sel:[1,1] op_sel_hi:[0,1] neg_lo:[1,0]
	v_mov_b32_e32 v91, v177
	v_pk_fma_f32 v[2:3], v[208:209], v[208:209], v[2:3] op_sel_hi:[0,1,1]
	v_pk_mul_f32 v[12:13], v[2:3], v[2:3] op_sel:[1,1] op_sel_hi:[1,0] neg_lo:[0,1]
	v_pk_mul_f32 v[4:5], v[208:209], v[176:177] op_sel:[1,1] op_sel_hi:[0,1] neg_lo:[1,0]
	v_pk_fma_f32 v[12:13], v[2:3], v[2:3], v[12:13] op_sel_hi:[1,0,1]
	v_pk_fma_f32 v[92:93], v[208:209], v[90:91], v[4:5] op_sel_hi:[1,0,1]
	v_pk_mul_f32 v[0:1], v[176:177], v[2:3] op_sel:[1,1] op_sel_hi:[1,0] neg_lo:[0,1]
	s_nop 0
	v_pk_fma_f32 v[94:95], v[90:91], v[2:3], v[0:1] op_sel_hi:[0,1,1]
	v_pk_mul_f32 v[0:1], v[92:93], v[2:3] op_sel:[1,1] op_sel_hi:[1,0] neg_lo:[0,1]
	v_pk_mul_f32 v[16:17], v[12:13], v[12:13] op_sel:[1,1] op_sel_hi:[1,0] neg_lo:[0,1]
	v_pk_fma_f32 v[96:97], v[2:3], v[92:93], v[0:1] op_sel_hi:[1,0,1]
	v_pk_mul_f32 v[0:1], v[176:177], v[12:13] op_sel:[1,1] op_sel_hi:[1,0] neg_lo:[0,1]
	s_nop 0
	v_pk_fma_f32 v[98:99], v[90:91], v[12:13], v[0:1] op_sel_hi:[0,1,1]
	v_pk_mul_f32 v[0:1], v[92:93], v[12:13] op_sel:[1,1] op_sel_hi:[1,0] neg_lo:[0,1]
	s_nop 0
	v_pk_fma_f32 v[32:33], v[92:93], v[12:13], v[0:1] op_sel_hi:[0,1,1]
	v_pk_mul_f32 v[0:1], v[94:95], v[12:13] op_sel:[1,1] op_sel_hi:[1,0] neg_lo:[0,1]
	s_nop 0
	v_pk_fma_f32 v[30:31], v[12:13], v[94:95], v[0:1] op_sel_hi:[1,0,1]
	v_pk_mul_f32 v[0:1], v[96:97], v[12:13] op_sel:[1,1] op_sel_hi:[1,0] neg_lo:[0,1]
	s_nop 0
	v_pk_fma_f32 v[26:27], v[12:13], v[96:97], v[0:1] op_sel_hi:[1,0,1]
	v_pk_fma_f32 v[0:1], v[12:13], v[12:13], v[16:17] op_sel_hi:[1,0,1]
	s_nop 0
	v_pk_mul_f32 v[2:3], v[176:177], v[0:1] op_sel:[1,1] op_sel_hi:[1,0] neg_lo:[0,1]
	s_nop 0
	v_pk_fma_f32 v[28:29], v[90:91], v[0:1], v[2:3] op_sel_hi:[0,1,1]
	v_pk_mul_f32 v[2:3], v[92:93], v[0:1] op_sel:[1,1] op_sel_hi:[1,0] neg_lo:[0,1]
	s_nop 0
	v_pk_fma_f32 v[16:17], v[92:93], v[0:1], v[2:3] op_sel_hi:[0,1,1]
	v_pk_mul_f32 v[2:3], v[94:95], v[0:1] op_sel:[1,1] op_sel_hi:[1,0] neg_lo:[0,1]
	s_nop 0
	v_pk_fma_f32 v[14:15], v[94:95], v[0:1], v[2:3] op_sel_hi:[0,1,1]
	v_pk_mul_f32 v[2:3], v[96:97], v[0:1] op_sel:[1,1] op_sel_hi:[1,0] neg_lo:[0,1]
	s_nop 0
	v_pk_fma_f32 v[12:13], v[96:97], v[0:1], v[2:3] op_sel_hi:[0,1,1]
	v_pk_mul_f32 v[2:3], v[98:99], v[0:1] op_sel:[1,1] op_sel_hi:[1,0] neg_lo:[0,1]
	s_nop 0
	v_pk_fma_f32 v[8:9], v[0:1], v[98:99], v[2:3] op_sel_hi:[1,0,1]
	v_pk_mul_f32 v[2:3], v[32:33], v[0:1] op_sel:[1,1] op_sel_hi:[1,0] neg_lo:[0,1]
	s_nop 0
	v_pk_fma_f32 v[4:5], v[0:1], v[32:33], v[2:3] op_sel_hi:[1,0,1]
	v_pk_mul_f32 v[2:3], v[30:31], v[0:1] op_sel:[1,1] op_sel_hi:[1,0] neg_lo:[0,1]
	v_pk_mul_f32 v[100:101], v[26:27], v[0:1] op_sel:[1,1] op_sel_hi:[1,0] neg_lo:[0,1]
	v_pk_fma_f32 v[2:3], v[0:1], v[30:31], v[2:3] op_sel_hi:[1,0,1]
	v_pk_fma_f32 v[0:1], v[0:1], v[26:27], v[100:101] op_sel_hi:[1,0,1]
	v_pk_add_f32 v[100:101], v[78:79], v[70:71]
	v_pk_add_f32 v[70:71], v[70:71], v[78:79] neg_lo:[0,1] neg_hi:[0,1]
	v_pk_add_f32 v[78:79], v[84:85], v[74:75]
	v_pk_add_f32 v[74:75], v[74:75], v[84:85] neg_lo:[0,1] neg_hi:[0,1]
	s_nop 0
	v_pk_add_f32 v[102:103], v[74:75], v[70:71] op_sel:[1,0] op_sel_hi:[0,1] neg_hi:[1,0]
	v_pk_add_f32 v[70:71], v[70:71], v[74:75] op_sel:[0,1] op_sel_hi:[1,0] neg_lo:[0,1]
	v_pk_add_f32 v[84:85], v[80:81], v[72:73]
	v_pk_add_f32 v[72:73], v[72:73], v[80:81] neg_lo:[0,1] neg_hi:[0,1]
	v_pk_add_f32 v[80:81], v[86:87], v[76:77]
	v_pk_add_f32 v[76:77], v[76:77], v[86:87] neg_lo:[0,1] neg_hi:[0,1]
	v_pk_add_f32 v[74:75], v[78:79], v[100:101]
	v_xor_b32_e32 v87, 0x80000000, v76
	v_mov_b32_e32 v86, v77
	v_pk_add_f32 v[76:77], v[80:81], v[84:85]
	v_pk_add_f32 v[80:81], v[84:85], v[80:81] neg_lo:[0,1] neg_hi:[0,1]
	v_pk_add_f32 v[84:85], v[82:83], v[22:23]
	v_pk_add_f32 v[22:23], v[22:23], v[82:83] neg_lo:[0,1] neg_hi:[0,1]
	v_pk_add_f32 v[82:83], v[88:89], v[24:25]
	v_pk_add_f32 v[24:25], v[24:25], v[88:89] neg_lo:[0,1] neg_hi:[0,1]
	v_pk_add_f32 v[78:79], v[100:101], v[78:79] neg_lo:[0,1] neg_hi:[0,1]
	v_pk_add_f32 v[100:101], v[86:87], v[72:73]
	v_pk_add_f32 v[72:73], v[72:73], v[86:87] neg_lo:[0,1] neg_hi:[0,1]
	v_xor_b32_e32 v87, 0x80000000, v24
	v_mov_b32_e32 v86, v25
	v_pk_add_f32 v[24:25], v[82:83], v[84:85]
	v_pk_add_f32 v[82:83], v[84:85], v[82:83] neg_lo:[0,1] neg_hi:[0,1]
	v_pk_add_f32 v[84:85], v[18:19], v[6:7]
	v_pk_add_f32 v[6:7], v[6:7], v[18:19] neg_lo:[0,1] neg_hi:[0,1]
	v_pk_add_f32 v[18:19], v[20:21], v[10:11]
	v_pk_add_f32 v[10:11], v[10:11], v[20:21] neg_lo:[0,1] neg_hi:[0,1]
	v_pk_add_f32 v[88:89], v[86:87], v[22:23]
	v_xor_b32_e32 v21, 0x80000000, v10
	v_mov_b32_e32 v20, v11
	v_pk_add_f32 v[10:11], v[18:19], v[84:85]
	v_pk_add_f32 v[18:19], v[84:85], v[18:19] neg_lo:[0,1] neg_hi:[0,1]
	v_pk_mul_f32 v[84:85], v[80:81], s[12:13] op_sel:[1,0] op_sel_hi:[0,0] neg_lo:[1,0]
	v_pk_add_f32 v[22:23], v[22:23], v[86:87] neg_lo:[0,1] neg_hi:[0,1]
	v_pk_fma_f32 v[80:81], v[80:81], s[12:13], v[84:85] op_sel_hi:[1,0,1] neg_lo:[0,0,1] neg_hi:[0,0,1]
	v_pk_mul_f32 v[84:85], v[72:73], s[36:37] op_sel:[1,0] op_sel_hi:[0,0] neg_lo:[1,0]
	v_pk_add_f32 v[86:87], v[20:21], v[6:7]
	v_pk_fma_f32 v[72:73], v[72:73], s[22:23], v[84:85] op_sel_hi:[1,0,1] neg_lo:[0,0,1] neg_hi:[0,0,1]
	v_pk_mul_f32 v[84:85], v[88:89], s[12:13] op_sel:[1,0] op_sel_hi:[0,0] neg_lo:[1,0]
	v_pk_add_f32 v[6:7], v[6:7], v[20:21] neg_lo:[0,1] neg_hi:[0,1]
	v_pk_fma_f32 v[84:85], v[88:89], s[12:13], v[84:85] op_sel_hi:[1,0,1] neg_lo:[0,0,1] neg_hi:[0,0,1]
	v_pk_fma_f32 v[82:83], v[82:83], 0, v[82:83] op_sel:[0,0,1] op_sel_hi:[1,0,0] neg_hi:[0,0,1]
	v_pk_mul_f32 v[88:89], v[22:23], s[12:13] op_sel:[1,0] op_sel_hi:[0,0] neg_lo:[1,0]
	v_pk_fma_f32 v[22:23], v[22:23], s[18:19], v[88:89] op_sel_hi:[1,0,1] neg_lo:[0,0,1] neg_hi:[0,0,1]
	v_pk_mul_f32 v[88:89], v[86:87], s[36:37] op_sel:[1,0] op_sel_hi:[0,0] neg_lo:[1,0]
	v_pk_fma_f32 v[86:87], v[86:87], s[22:23], v[88:89] op_sel_hi:[1,0,1] neg_lo:[0,0,1] neg_hi:[0,0,1]
	v_pk_mul_f32 v[88:89], v[18:19], s[12:13] op_sel:[1,0] op_sel_hi:[0,0] neg_lo:[1,0]
	v_pk_mul_f32 v[20:21], v[100:101], s[22:23] op_sel:[1,0] op_sel_hi:[0,0] neg_lo:[1,0]
	v_pk_fma_f32 v[18:19], v[18:19], s[18:19], v[88:89] op_sel_hi:[1,0,1] neg_lo:[0,0,1] neg_hi:[0,0,1]
	v_xor_b32_e32 v88, 0x80000000, v7
	v_mov_b32_e32 v89, v6
	v_pk_mul_f32 v[6:7], v[6:7], s[36:37] op_sel_hi:[1,0]
	v_pk_fma_f32 v[20:21], v[100:101], s[36:37], v[20:21] op_sel_hi:[1,0,1] neg_lo:[0,0,1] neg_hi:[0,0,1]
	v_pk_fma_f32 v[6:7], v[88:89], s[22:23], v[6:7] op_sel_hi:[1,0,1] neg_lo:[0,0,1] neg_hi:[0,0,1]
	v_pk_add_f32 v[88:89], v[24:25], v[74:75]
	v_pk_add_f32 v[24:25], v[74:75], v[24:25] neg_lo:[0,1] neg_hi:[0,1]
	v_pk_add_f32 v[74:75], v[10:11], v[76:77]
	v_pk_add_f32 v[10:11], v[76:77], v[10:11] neg_lo:[0,1] neg_hi:[0,1]
	s_nop 0
	v_xor_b32_e32 v77, 0x80000000, v10
	v_mov_b32_e32 v76, v11
	v_pk_add_f32 v[10:11], v[74:75], v[88:89]
	v_pk_add_f32 v[74:75], v[88:89], v[74:75] neg_lo:[0,1] neg_hi:[0,1]
	v_pk_add_f32 v[88:89], v[86:87], v[20:21]
	v_pk_add_f32 v[20:21], v[20:21], v[86:87] neg_lo:[0,1] neg_hi:[0,1]
	v_pk_add_f32 v[100:101], v[24:25], v[76:77]
	v_pk_add_f32 v[24:25], v[24:25], v[76:77] neg_lo:[0,1] neg_hi:[0,1]
	v_pk_add_f32 v[76:77], v[102:103], v[84:85]
	v_pk_add_f32 v[84:85], v[102:103], v[84:85] neg_lo:[0,1] neg_hi:[0,1]
	s_nop 0
	v_pk_add_f32 v[102:103], v[84:85], v[20:21] op_sel:[0,1] op_sel_hi:[1,0] neg_hi:[0,1]
	v_pk_add_f32 v[84:85], v[84:85], v[20:21] op_sel:[0,1] op_sel_hi:[1,0] neg_lo:[0,1]
	v_pk_add_f32 v[86:87], v[78:79], v[82:83]
	v_pk_add_f32 v[78:79], v[78:79], v[82:83] neg_lo:[0,1] neg_hi:[0,1]
	v_pk_add_f32 v[82:83], v[18:19], v[80:81]
	v_pk_add_f32 v[18:19], v[80:81], v[18:19] neg_lo:[0,1] neg_hi:[0,1]
	v_pk_add_f32 v[20:21], v[76:77], v[88:89]
	v_pk_add_f32 v[76:77], v[76:77], v[88:89] neg_lo:[0,1] neg_hi:[0,1]
	v_pk_add_f32 v[88:89], v[78:79], v[18:19] op_sel:[0,1] op_sel_hi:[1,0] neg_hi:[0,1]
	v_pk_add_f32 v[78:79], v[78:79], v[18:19] op_sel:[0,1] op_sel_hi:[1,0] neg_lo:[0,1]
	v_pk_add_f32 v[80:81], v[70:71], v[22:23]
	v_pk_add_f32 v[22:23], v[70:71], v[22:23] neg_lo:[0,1] neg_hi:[0,1]
	v_pk_add_f32 v[70:71], v[6:7], v[72:73]
	v_pk_add_f32 v[6:7], v[72:73], v[6:7] neg_lo:[0,1] neg_hi:[0,1]
	v_pk_add_f32 v[18:19], v[86:87], v[82:83]
	v_pk_add_f32 v[82:83], v[86:87], v[82:83] neg_lo:[0,1] neg_hi:[0,1]
	v_pk_add_f32 v[86:87], v[22:23], v[6:7] op_sel:[0,1] op_sel_hi:[1,0] neg_hi:[0,1]
	v_pk_add_f32 v[22:23], v[22:23], v[6:7] op_sel:[0,1] op_sel_hi:[1,0] neg_lo:[0,1]
	v_mov_b32_e32 v72, v206
	v_pk_add_f32 v[6:7], v[80:81], v[70:71]
	v_lshlrev_b32_sdwa v73, v228, v72 dst_sel:DWORD dst_unused:UNUSED_PAD src0_sel:DWORD src1_sel:BYTE_0
	v_lshrrev_b32_e32 v72, 1, v206
	v_and_b32_e32 v72, 0x78, v72
	v_pk_add_f32 v[70:71], v[80:81], v[70:71] neg_lo:[0,1] neg_hi:[0,1]
	v_add3_u32 v80, v207, v73, v72
	v_xor_b32_e32 v72, 0x80000000, v91
	v_mov_b32_e32 v73, v90
	v_pk_mul_f32 v[72:73], v[10:11], v[72:73] op_sel:[1,0]
	s_nop 0
	v_pk_fma_f32 v[10:11], v[10:11], v[90:91], v[72:73] op_sel_hi:[0,1,1]
	ds_write_b64 v80, v[10:11]
	v_pk_mul_f32 v[10:11], v[20:21], v[92:93] op_sel:[1,1] op_sel_hi:[1,0] neg_lo:[0,1]
	s_nop 0
	v_pk_fma_f32 v[10:11], v[20:21], v[92:93], v[10:11] op_sel_hi:[0,1,1]
	ds_write_b64 v80, v[10:11] offset:2176
	v_pk_mul_f32 v[10:11], v[18:19], v[94:95] op_sel:[1,1] op_sel_hi:[1,0] neg_lo:[0,1]
	s_nop 0
	v_pk_fma_f32 v[10:11], v[18:19], v[94:95], v[10:11] op_sel_hi:[0,1,1]
	ds_write_b64 v80, v[10:11] offset:4352
	v_pk_mul_f32 v[10:11], v[6:7], v[96:97] op_sel:[1,1] op_sel_hi:[1,0] neg_lo:[0,1]
	s_nop 0
	v_pk_fma_f32 v[6:7], v[6:7], v[96:97], v[10:11] op_sel_hi:[0,1,1]
	ds_write_b64 v80, v[6:7] offset:6528
	v_pk_mul_f32 v[6:7], v[100:101], v[98:99] op_sel:[1,1] op_sel_hi:[1,0] neg_lo:[0,1]
	s_nop 0
	v_pk_fma_f32 v[6:7], v[100:101], v[98:99], v[6:7] op_sel_hi:[0,1,1]
	ds_write_b64 v80, v[6:7] offset:8704
	v_pk_mul_f32 v[6:7], v[102:103], v[32:33] op_sel:[1,1] op_sel_hi:[1,0] neg_lo:[0,1]
	s_nop 0
	v_pk_fma_f32 v[6:7], v[102:103], v[32:33], v[6:7] op_sel_hi:[0,1,1]
	ds_write_b64 v80, v[6:7] offset:10880
	v_pk_mul_f32 v[6:7], v[88:89], v[30:31] op_sel:[1,1] op_sel_hi:[1,0] neg_lo:[0,1]
	s_nop 0
	v_pk_fma_f32 v[6:7], v[88:89], v[30:31], v[6:7] op_sel_hi:[0,1,1]
	ds_write_b64 v80, v[6:7] offset:13056
	v_pk_mul_f32 v[6:7], v[86:87], v[26:27] op_sel:[1,1] op_sel_hi:[1,0] neg_lo:[0,1]
	s_nop 0
	v_pk_fma_f32 v[6:7], v[86:87], v[26:27], v[6:7] op_sel_hi:[0,1,1]
	ds_write_b64 v80, v[6:7] offset:15232
	v_pk_mul_f32 v[6:7], v[74:75], v[28:29] op_sel:[1,1] op_sel_hi:[1,0] neg_lo:[0,1]
	s_nop 0
	v_pk_fma_f32 v[6:7], v[74:75], v[28:29], v[6:7] op_sel_hi:[0,1,1]
	ds_write_b64 v80, v[6:7] offset:17408
	v_pk_mul_f32 v[6:7], v[76:77], v[16:17] op_sel:[1,1] op_sel_hi:[1,0] neg_lo:[0,1]
	s_nop 0
	v_pk_fma_f32 v[6:7], v[76:77], v[16:17], v[6:7] op_sel_hi:[0,1,1]
	ds_write_b64 v80, v[6:7] offset:19584
	v_pk_mul_f32 v[6:7], v[82:83], v[14:15] op_sel:[1,1] op_sel_hi:[1,0] neg_lo:[0,1]
	s_nop 0
	v_pk_fma_f32 v[6:7], v[82:83], v[14:15], v[6:7] op_sel_hi:[0,1,1]
	ds_write_b64 v80, v[6:7] offset:21760
	v_pk_mul_f32 v[6:7], v[70:71], v[12:13] op_sel:[1,1] op_sel_hi:[1,0] neg_lo:[0,1]
	s_nop 0
	v_pk_fma_f32 v[6:7], v[70:71], v[12:13], v[6:7] op_sel_hi:[0,1,1]
	ds_write_b64 v80, v[6:7] offset:23936
	v_pk_mul_f32 v[6:7], v[24:25], v[8:9] op_sel:[1,1] op_sel_hi:[1,0] neg_lo:[0,1]
	s_nop 0
	v_pk_fma_f32 v[6:7], v[24:25], v[8:9], v[6:7] op_sel_hi:[0,1,1]
	ds_write_b64 v80, v[6:7] offset:26112
	v_pk_mul_f32 v[6:7], v[84:85], v[4:5] op_sel:[1,1] op_sel_hi:[1,0] neg_lo:[0,1]
	s_nop 0
	v_pk_fma_f32 v[4:5], v[84:85], v[4:5], v[6:7] op_sel_hi:[0,1,1]
	ds_write_b64 v80, v[4:5] offset:28288
	v_pk_mul_f32 v[4:5], v[78:79], v[2:3] op_sel:[1,1] op_sel_hi:[1,0] neg_lo:[0,1]
	s_nop 0
	v_pk_fma_f32 v[2:3], v[78:79], v[2:3], v[4:5] op_sel_hi:[0,1,1]
	ds_write_b64 v80, v[2:3] offset:30464
	v_pk_mul_f32 v[2:3], v[22:23], v[0:1] op_sel:[1,1] op_sel_hi:[1,0] neg_lo:[0,1]
	s_nop 0
	v_pk_fma_f32 v[0:1], v[22:23], v[0:1], v[2:3] op_sel_hi:[0,1,1]
	ds_write_b64 v80, v[0:1] offset:32640
	v_mov_b32_e32 v78, 1.0
	v_pk_mul_f32 v[2:3], v[210:211], v[210:211] op_sel:[1,1] op_sel_hi:[0,1] neg_lo:[1,0]
	v_mov_b32_e32 v79, v177
	v_pk_fma_f32 v[2:3], v[210:211], v[210:211], v[2:3] op_sel_hi:[0,1,1]
	v_pk_mul_f32 v[8:9], v[2:3], v[2:3] op_sel:[1,1] op_sel_hi:[1,0] neg_lo:[0,1]
	v_pk_mul_f32 v[4:5], v[210:211], v[176:177] op_sel:[1,1] op_sel_hi:[0,1] neg_lo:[1,0]
	v_pk_fma_f32 v[8:9], v[2:3], v[2:3], v[8:9] op_sel_hi:[1,0,1]
	v_pk_fma_f32 v[80:81], v[210:211], v[78:79], v[4:5] op_sel_hi:[1,0,1]
	v_pk_mul_f32 v[0:1], v[176:177], v[2:3] op_sel:[1,1] op_sel_hi:[1,0] neg_lo:[0,1]
	s_nop 0
	v_pk_fma_f32 v[82:83], v[78:79], v[2:3], v[0:1] op_sel_hi:[0,1,1]
	v_pk_mul_f32 v[0:1], v[80:81], v[2:3] op_sel:[1,1] op_sel_hi:[1,0] neg_lo:[0,1]
	v_pk_mul_f32 v[12:13], v[8:9], v[8:9] op_sel:[1,1] op_sel_hi:[1,0] neg_lo:[0,1]
	v_pk_fma_f32 v[84:85], v[2:3], v[80:81], v[0:1] op_sel_hi:[1,0,1]
	v_pk_mul_f32 v[0:1], v[176:177], v[8:9] op_sel:[1,1] op_sel_hi:[1,0] neg_lo:[0,1]
	s_nop 0
	v_pk_fma_f32 v[86:87], v[78:79], v[8:9], v[0:1] op_sel_hi:[0,1,1]
	v_pk_mul_f32 v[0:1], v[80:81], v[8:9] op_sel:[1,1] op_sel_hi:[1,0] neg_lo:[0,1]
	s_waitcnt lgkmcnt(0)
	v_pk_fma_f32 v[88:89], v[80:81], v[8:9], v[0:1] op_sel_hi:[0,1,1]
	v_pk_mul_f32 v[0:1], v[82:83], v[8:9] op_sel:[1,1] op_sel_hi:[1,0] neg_lo:[0,1]
	s_barrier
	v_pk_fma_f32 v[90:91], v[8:9], v[82:83], v[0:1] op_sel_hi:[1,0,1]
	v_pk_mul_f32 v[0:1], v[84:85], v[8:9] op_sel:[1,1] op_sel_hi:[1,0] neg_lo:[0,1]
	s_nop 0
	v_pk_fma_f32 v[92:93], v[8:9], v[84:85], v[0:1] op_sel_hi:[1,0,1]
	v_pk_fma_f32 v[0:1], v[8:9], v[8:9], v[12:13] op_sel_hi:[1,0,1]
	s_nop 0
	v_pk_mul_f32 v[2:3], v[176:177], v[0:1] op_sel:[1,1] op_sel_hi:[1,0] neg_lo:[0,1]
	s_nop 0
	v_pk_fma_f32 v[94:95], v[78:79], v[0:1], v[2:3] op_sel_hi:[0,1,1]
	v_pk_mul_f32 v[2:3], v[80:81], v[0:1] op_sel:[1,1] op_sel_hi:[1,0] neg_lo:[0,1]
	s_nop 0
	v_pk_fma_f32 v[96:97], v[80:81], v[0:1], v[2:3] op_sel_hi:[0,1,1]
	v_pk_mul_f32 v[2:3], v[82:83], v[0:1] op_sel:[1,1] op_sel_hi:[1,0] neg_lo:[0,1]
	s_nop 0
	v_pk_fma_f32 v[98:99], v[82:83], v[0:1], v[2:3] op_sel_hi:[0,1,1]
	v_pk_mul_f32 v[2:3], v[84:85], v[0:1] op_sel:[1,1] op_sel_hi:[1,0] neg_lo:[0,1]
	s_nop 0
	v_pk_fma_f32 v[8:9], v[84:85], v[0:1], v[2:3] op_sel_hi:[0,1,1]
	v_pk_mul_f32 v[2:3], v[86:87], v[0:1] op_sel:[1,1] op_sel_hi:[1,0] neg_lo:[0,1]
	s_nop 0
	v_pk_fma_f32 v[6:7], v[0:1], v[86:87], v[2:3] op_sel_hi:[1,0,1]
	v_pk_mul_f32 v[2:3], v[88:89], v[0:1] op_sel:[1,1] op_sel_hi:[1,0] neg_lo:[0,1]
	s_nop 0
	v_pk_fma_f32 v[4:5], v[0:1], v[88:89], v[2:3] op_sel_hi:[1,0,1]
	v_pk_mul_f32 v[2:3], v[90:91], v[0:1] op_sel:[1,1] op_sel_hi:[1,0] neg_lo:[0,1]
	v_pk_mul_f32 v[10:11], v[92:93], v[0:1] op_sel:[1,1] op_sel_hi:[1,0] neg_lo:[0,1]
	v_pk_fma_f32 v[2:3], v[0:1], v[90:91], v[2:3] op_sel_hi:[1,0,1]
	v_pk_fma_f32 v[0:1], v[0:1], v[92:93], v[10:11] op_sel_hi:[1,0,1]
	s_nop 0
	v_bfe_u32 v11, v206, 4, 4
	v_and_b32_e32 v10, 15, v206
	v_mul_u32_u24_e32 v11, 0x880, v11
	v_lshlrev_b32_e32 v10, 3, v10
	v_add3_u32 v104, v207, v11, v10
	ds_read2_b64 v[10:13], v104 offset1:17
	ds_read2_b64 v[14:17], v104 offset0:34 offset1:51
	ds_read2_b64 v[18:21], v104 offset0:68 offset1:85
	ds_read2_b64 v[22:25], v104 offset0:136 offset1:153
	ds_read2_b64 v[26:29], v104 offset0:102 offset1:119
	ds_read2_b64 v[30:33], v104 offset0:204 offset1:221
	ds_read2_b64 v[70:73], v104 offset0:170 offset1:187
	ds_read2_b64 v[74:77], v104 offset0:238 offset1:255
	s_waitcnt lgkmcnt(4)
	v_pk_add_f32 v[100:101], v[10:11], v[22:23]
	v_pk_add_f32 v[10:11], v[10:11], v[22:23] neg_lo:[0,1] neg_hi:[0,1]
	s_waitcnt lgkmcnt(2)
	v_pk_add_f32 v[22:23], v[18:19], v[30:31]
	v_pk_add_f32 v[18:19], v[18:19], v[30:31] neg_lo:[0,1] neg_hi:[0,1]
	s_nop 0
	v_pk_add_f32 v[102:103], v[10:11], v[18:19] op_sel:[0,1] op_sel_hi:[1,0] neg_hi:[0,1]
	v_pk_add_f32 v[10:11], v[10:11], v[18:19] op_sel:[0,1] op_sel_hi:[1,0] neg_lo:[0,1]
	v_pk_add_f32 v[30:31], v[12:13], v[24:25]
	v_pk_add_f32 v[12:13], v[12:13], v[24:25] neg_lo:[0,1] neg_hi:[0,1]
	v_pk_add_f32 v[24:25], v[20:21], v[32:33]
	v_pk_add_f32 v[20:21], v[20:21], v[32:33] neg_lo:[0,1] neg_hi:[0,1]
	v_pk_add_f32 v[18:19], v[100:101], v[22:23]
	v_pk_add_f32 v[22:23], v[100:101], v[22:23] neg_lo:[0,1] neg_hi:[0,1]
	v_pk_add_f32 v[100:101], v[12:13], v[20:21] op_sel:[0,1] op_sel_hi:[1,0] neg_hi:[0,1]
	v_pk_add_f32 v[12:13], v[12:13], v[20:21] op_sel:[0,1] op_sel_hi:[1,0] neg_lo:[0,1]
	s_waitcnt lgkmcnt(0)
	v_pk_add_f32 v[32:33], v[26:27], v[74:75]
	v_pk_add_f32 v[26:27], v[26:27], v[74:75] neg_lo:[0,1] neg_hi:[0,1]
	v_pk_add_f32 v[20:21], v[30:31], v[24:25]
	v_pk_add_f32 v[24:25], v[30:31], v[24:25] neg_lo:[0,1] neg_hi:[0,1]
	v_pk_add_f32 v[30:31], v[14:15], v[70:71]
	v_pk_add_f32 v[14:15], v[14:15], v[70:71] neg_lo:[0,1] neg_hi:[0,1]
	s_nop 0
	v_pk_add_f32 v[74:75], v[14:15], v[26:27] op_sel:[0,1] op_sel_hi:[1,0] neg_hi:[0,1]
	v_pk_add_f32 v[14:15], v[14:15], v[26:27] op_sel:[0,1] op_sel_hi:[1,0] neg_lo:[0,1]
	v_pk_add_f32 v[70:71], v[28:29], v[76:77]
	v_pk_add_f32 v[28:29], v[28:29], v[76:77] neg_lo:[0,1] neg_hi:[0,1]
	v_pk_add_f32 v[26:27], v[30:31], v[32:33]
	v_pk_add_f32 v[30:31], v[30:31], v[32:33] neg_lo:[0,1] neg_hi:[0,1]
	v_pk_add_f32 v[32:33], v[16:17], v[72:73]
	v_pk_add_f32 v[16:17], v[16:17], v[72:73] neg_lo:[0,1] neg_hi:[0,1]
	s_nop 0
	v_pk_add_f32 v[76:77], v[16:17], v[28:29] op_sel:[0,1] op_sel_hi:[1,0] neg_hi:[0,1]
	v_pk_add_f32 v[16:17], v[16:17], v[28:29] op_sel:[0,1] op_sel_hi:[1,0] neg_lo:[0,1]
	v_pk_mul_f32 v[72:73], v[24:25], s[12:13] op_sel:[1,0] op_sel_hi:[0,0] neg_lo:[1,0]
	v_pk_add_f32 v[28:29], v[32:33], v[70:71]
	v_pk_fma_f32 v[24:25], v[24:25], s[12:13], v[72:73] op_sel_hi:[1,0,1] neg_lo:[0,0,1] neg_hi:[0,0,1]
	v_pk_mul_f32 v[72:73], v[12:13], s[36:37] op_sel:[1,0] op_sel_hi:[0,0] neg_lo:[1,0]
	v_pk_add_f32 v[32:33], v[32:33], v[70:71] neg_lo:[0,1] neg_hi:[0,1]
	v_pk_fma_f32 v[12:13], v[12:13], s[22:23], v[72:73] op_sel_hi:[1,0,1] neg_lo:[0,0,1] neg_hi:[0,0,1]
	v_pk_mul_f32 v[72:73], v[74:75], s[12:13] op_sel:[1,0] op_sel_hi:[0,0] neg_lo:[1,0]
	v_pk_fma_f32 v[72:73], v[74:75], s[12:13], v[72:73] op_sel_hi:[1,0,1] neg_lo:[0,0,1] neg_hi:[0,0,1]
	v_pk_fma_f32 v[30:31], v[30:31], 0, v[30:31] op_sel:[0,0,1] op_sel_hi:[1,0,0] neg_hi:[0,0,1]
	v_pk_mul_f32 v[74:75], v[14:15], s[12:13] op_sel:[1,0] op_sel_hi:[0,0] neg_lo:[1,0]
	v_pk_fma_f32 v[14:15], v[14:15], s[18:19], v[74:75] op_sel_hi:[1,0,1] neg_lo:[0,0,1] neg_hi:[0,0,1]
	v_pk_mul_f32 v[74:75], v[76:77], s[36:37] op_sel:[1,0] op_sel_hi:[0,0] neg_lo:[1,0]
	v_pk_mul_f32 v[70:71], v[100:101], s[22:23] op_sel:[1,0] op_sel_hi:[0,0] neg_lo:[1,0]
	v_pk_fma_f32 v[74:75], v[76:77], s[22:23], v[74:75] op_sel_hi:[1,0,1] neg_lo:[0,0,1] neg_hi:[0,0,1]
	v_pk_mul_f32 v[76:77], v[32:33], s[12:13] op_sel:[1,0] op_sel_hi:[0,0] neg_lo:[1,0]
	v_pk_fma_f32 v[70:71], v[100:101], s[36:37], v[70:71] op_sel_hi:[1,0,1] neg_lo:[0,0,1] neg_hi:[0,0,1]
	v_pk_fma_f32 v[32:33], v[32:33], s[18:19], v[76:77] op_sel_hi:[1,0,1] neg_lo:[0,0,1] neg_hi:[0,0,1]
	v_xor_b32_e32 v76, 0x80000000, v17
	v_mov_b32_e32 v77, v16
	v_pk_mul_f32 v[16:17], v[16:17], s[36:37] op_sel_hi:[1,0]
	s_nop 0
	v_pk_fma_f32 v[16:17], v[76:77], s[22:23], v[16:17] op_sel_hi:[1,0,1] neg_lo:[0,0,1] neg_hi:[0,0,1]
	v_pk_add_f32 v[76:77], v[18:19], v[26:27]
	v_pk_add_f32 v[18:19], v[18:19], v[26:27] neg_lo:[0,1] neg_hi:[0,1]
	v_pk_add_f32 v[26:27], v[20:21], v[28:29]
	v_pk_add_f32 v[20:21], v[20:21], v[28:29] neg_lo:[0,1] neg_hi:[0,1]
	s_nop 0
	v_xor_b32_e32 v29, 0x80000000, v20
	v_mov_b32_e32 v28, v21
	v_pk_add_f32 v[20:21], v[76:77], v[26:27]
	v_pk_add_f32 v[26:27], v[76:77], v[26:27] neg_lo:[0,1] neg_hi:[0,1]
	v_pk_add_f32 v[76:77], v[70:71], v[74:75]
	v_pk_add_f32 v[70:71], v[70:71], v[74:75] neg_lo:[0,1] neg_hi:[0,1]
	v_pk_add_f32 v[100:101], v[18:19], v[28:29]
	v_pk_add_f32 v[18:19], v[18:19], v[28:29] neg_lo:[0,1] neg_hi:[0,1]
	v_pk_add_f32 v[28:29], v[102:103], v[72:73]
	v_pk_add_f32 v[72:73], v[102:103], v[72:73] neg_lo:[0,1] neg_hi:[0,1]
	s_nop 0
	v_pk_add_f32 v[102:103], v[72:73], v[70:71] op_sel:[0,1] op_sel_hi:[1,0] neg_hi:[0,1]
	v_pk_add_f32 v[72:73], v[72:73], v[70:71] op_sel:[0,1] op_sel_hi:[1,0] neg_lo:[0,1]
	v_pk_add_f32 v[74:75], v[22:23], v[30:31]
	v_pk_add_f32 v[22:23], v[22:23], v[30:31] neg_lo:[0,1] neg_hi:[0,1]
	v_pk_add_f32 v[30:31], v[24:25], v[32:33]
	v_pk_add_f32 v[24:25], v[24:25], v[32:33] neg_lo:[0,1] neg_hi:[0,1]
	v_pk_add_f32 v[70:71], v[28:29], v[76:77]
	v_pk_add_f32 v[28:29], v[28:29], v[76:77] neg_lo:[0,1] neg_hi:[0,1]
	v_pk_add_f32 v[76:77], v[22:23], v[24:25] op_sel:[0,1] op_sel_hi:[1,0] neg_hi:[0,1]
	v_pk_add_f32 v[22:23], v[22:23], v[24:25] op_sel:[0,1] op_sel_hi:[1,0] neg_lo:[0,1]
	v_pk_add_f32 v[32:33], v[10:11], v[14:15]
	v_pk_add_f32 v[10:11], v[10:11], v[14:15] neg_lo:[0,1] neg_hi:[0,1]
	v_pk_add_f32 v[14:15], v[12:13], v[16:17]
	v_pk_add_f32 v[12:13], v[12:13], v[16:17] neg_lo:[0,1] neg_hi:[0,1]
	v_pk_add_f32 v[24:25], v[74:75], v[30:31]
	v_pk_add_f32 v[30:31], v[74:75], v[30:31] neg_lo:[0,1] neg_hi:[0,1]
	v_pk_add_f32 v[74:75], v[10:11], v[12:13] op_sel:[0,1] op_sel_hi:[1,0] neg_hi:[0,1]
	v_pk_add_f32 v[10:11], v[10:11], v[12:13] op_sel:[0,1] op_sel_hi:[1,0] neg_lo:[0,1]
	v_xor_b32_e32 v16, 0x80000000, v79
	v_mov_b32_e32 v17, v78
	v_pk_mul_f32 v[16:17], v[16:17], v[20:21] op_sel:[0,1]
	v_pk_add_f32 v[12:13], v[32:33], v[14:15]
	v_pk_fma_f32 v[16:17], v[78:79], v[20:21], v[16:17] op_sel_hi:[1,0,1]
	v_pk_mul_f32 v[20:21], v[80:81], v[70:71] op_sel:[1,1] op_sel_hi:[0,1] neg_lo:[1,0]
	v_pk_add_f32 v[14:15], v[32:33], v[14:15] neg_lo:[0,1] neg_hi:[0,1]
	v_pk_fma_f32 v[20:21], v[80:81], v[70:71], v[20:21] op_sel_hi:[1,0,1]
	ds_write2_b64 v104, v[16:17], v[20:21] offset1:17
	v_pk_mul_f32 v[16:17], v[82:83], v[24:25] op_sel:[1,1] op_sel_hi:[0,1] neg_lo:[1,0]
	v_pk_mul_f32 v[20:21], v[84:85], v[12:13] op_sel:[1,1] op_sel_hi:[0,1] neg_lo:[1,0]
	v_pk_fma_f32 v[16:17], v[82:83], v[24:25], v[16:17] op_sel_hi:[1,0,1]
	v_pk_fma_f32 v[12:13], v[84:85], v[12:13], v[20:21] op_sel_hi:[1,0,1]
	ds_write2_b64 v104, v[16:17], v[12:13] offset0:34 offset1:51
	v_pk_mul_f32 v[12:13], v[86:87], v[100:101] op_sel:[1,1] op_sel_hi:[0,1] neg_lo:[1,0]
	v_pk_mul_f32 v[16:17], v[88:89], v[102:103] op_sel:[1,1] op_sel_hi:[0,1] neg_lo:[1,0]
	v_pk_fma_f32 v[12:13], v[86:87], v[100:101], v[12:13] op_sel_hi:[1,0,1]
	v_pk_fma_f32 v[16:17], v[88:89], v[102:103], v[16:17] op_sel_hi:[1,0,1]
	ds_write2_b64 v104, v[12:13], v[16:17] offset0:68 offset1:85
	v_pk_mul_f32 v[12:13], v[90:91], v[76:77] op_sel:[1,1] op_sel_hi:[0,1] neg_lo:[1,0]
	v_pk_mul_f32 v[16:17], v[92:93], v[74:75] op_sel:[1,1] op_sel_hi:[0,1] neg_lo:[1,0]
	v_pk_fma_f32 v[12:13], v[90:91], v[76:77], v[12:13] op_sel_hi:[1,0,1]
	v_pk_fma_f32 v[16:17], v[92:93], v[74:75], v[16:17] op_sel_hi:[1,0,1]
	ds_write2_b64 v104, v[12:13], v[16:17] offset0:102 offset1:119
	v_pk_mul_f32 v[12:13], v[94:95], v[26:27] op_sel:[1,1] op_sel_hi:[0,1] neg_lo:[1,0]
	v_pk_mul_f32 v[16:17], v[96:97], v[28:29] op_sel:[1,1] op_sel_hi:[0,1] neg_lo:[1,0]
	v_pk_fma_f32 v[12:13], v[94:95], v[26:27], v[12:13] op_sel_hi:[1,0,1]
	v_pk_fma_f32 v[16:17], v[96:97], v[28:29], v[16:17] op_sel_hi:[1,0,1]
	ds_write2_b64 v104, v[12:13], v[16:17] offset0:136 offset1:153
	v_pk_mul_f32 v[12:13], v[98:99], v[30:31] op_sel:[1,1] op_sel_hi:[0,1] neg_lo:[1,0]
	v_pk_mul_f32 v[16:17], v[8:9], v[14:15] op_sel:[1,1] op_sel_hi:[0,1] neg_lo:[1,0]
	v_pk_fma_f32 v[12:13], v[98:99], v[30:31], v[12:13] op_sel_hi:[1,0,1]
	v_pk_fma_f32 v[8:9], v[8:9], v[14:15], v[16:17] op_sel_hi:[1,0,1]
	ds_write2_b64 v104, v[12:13], v[8:9] offset0:170 offset1:187
	v_pk_mul_f32 v[8:9], v[6:7], v[18:19] op_sel:[1,1] op_sel_hi:[0,1] neg_lo:[1,0]
	v_pk_fma_f32 v[6:7], v[6:7], v[18:19], v[8:9] op_sel_hi:[1,0,1]
	v_pk_mul_f32 v[8:9], v[4:5], v[72:73] op_sel:[1,1] op_sel_hi:[0,1] neg_lo:[1,0]
	v_pk_fma_f32 v[4:5], v[4:5], v[72:73], v[8:9] op_sel_hi:[1,0,1]
	ds_write2_b64 v104, v[6:7], v[4:5] offset0:204 offset1:221
	v_pk_mul_f32 v[4:5], v[2:3], v[22:23] op_sel:[1,1] op_sel_hi:[0,1] neg_lo:[1,0]
	v_pk_fma_f32 v[2:3], v[2:3], v[22:23], v[4:5] op_sel_hi:[1,0,1]
	v_pk_mul_f32 v[4:5], v[0:1], v[10:11] op_sel:[1,1] op_sel_hi:[0,1] neg_lo:[1,0]
	v_pk_fma_f32 v[0:1], v[0:1], v[10:11], v[4:5] op_sel_hi:[1,0,1]
	ds_write2_b64 v104, v[2:3], v[0:1] offset0:238 offset1:255
	s_waitcnt lgkmcnt(0)
	s_barrier
	s_nop 0
	v_and_b32_e32 v0, 0xff, v206
	v_mad_u32_u24 v28, v0, s19, v207
	ds_read2_b64 v[0:3], v28 offset1:1
	ds_read2_b64 v[4:7], v28 offset0:2 offset1:3
	ds_read2_b64 v[8:11], v28 offset0:8 offset1:9
	ds_read2_b64 v[12:15], v28 offset0:4 offset1:5
	ds_read2_b64 v[16:19], v28 offset0:6 offset1:7
	ds_read2_b64 v[20:23], v28 offset0:12 offset1:13
	ds_read2_b64 v[24:27], v28 offset0:10 offset1:11
	ds_read2_b64 v[28:31], v28 offset0:14 offset1:15
	s_waitcnt lgkmcnt(5)
	v_pk_add_f32 v[32:33], v[0:1], v[8:9]
	v_pk_add_f32 v[0:1], v[0:1], v[8:9] neg_lo:[0,1] neg_hi:[0,1]
	s_waitcnt lgkmcnt(2)
	v_pk_add_f32 v[8:9], v[12:13], v[20:21]
	v_pk_add_f32 v[12:13], v[12:13], v[20:21] neg_lo:[0,1] neg_hi:[0,1]
	s_waitcnt lgkmcnt(0)
	v_pk_add_f32 v[70:71], v[0:1], v[12:13] op_sel:[0,1] op_sel_hi:[1,0] neg_hi:[0,1]
	v_pk_add_f32 v[0:1], v[0:1], v[12:13] op_sel:[0,1] op_sel_hi:[1,0] neg_lo:[0,1]
	v_pk_add_f32 v[20:21], v[2:3], v[10:11]
	v_pk_add_f32 v[2:3], v[2:3], v[10:11] neg_lo:[0,1] neg_hi:[0,1]
	v_pk_add_f32 v[10:11], v[14:15], v[22:23]
	v_pk_add_f32 v[14:15], v[14:15], v[22:23] neg_lo:[0,1] neg_hi:[0,1]
	v_pk_add_f32 v[12:13], v[32:33], v[8:9]
	v_pk_add_f32 v[8:9], v[32:33], v[8:9] neg_lo:[0,1] neg_hi:[0,1]
	v_pk_add_f32 v[32:33], v[2:3], v[14:15] op_sel:[0,1] op_sel_hi:[1,0] neg_hi:[0,1]
	v_pk_add_f32 v[2:3], v[2:3], v[14:15] op_sel:[0,1] op_sel_hi:[1,0] neg_lo:[0,1]
	v_pk_add_f32 v[22:23], v[16:17], v[28:29]
	v_pk_add_f32 v[16:17], v[16:17], v[28:29] neg_lo:[0,1] neg_hi:[0,1]
	v_pk_add_f32 v[14:15], v[20:21], v[10:11]
	v_pk_add_f32 v[10:11], v[20:21], v[10:11] neg_lo:[0,1] neg_hi:[0,1]
	v_pk_add_f32 v[20:21], v[4:5], v[24:25]
	v_pk_add_f32 v[4:5], v[4:5], v[24:25] neg_lo:[0,1] neg_hi:[0,1]
	s_nop 0
	v_pk_add_f32 v[28:29], v[4:5], v[16:17] op_sel:[0,1] op_sel_hi:[1,0] neg_hi:[0,1]
	v_pk_add_f32 v[4:5], v[4:5], v[16:17] op_sel:[0,1] op_sel_hi:[1,0] neg_lo:[0,1]
	v_pk_add_f32 v[24:25], v[18:19], v[30:31]
	v_pk_add_f32 v[18:19], v[18:19], v[30:31] neg_lo:[0,1] neg_hi:[0,1]
	v_pk_add_f32 v[16:17], v[20:21], v[22:23]
	v_pk_add_f32 v[20:21], v[20:21], v[22:23] neg_lo:[0,1] neg_hi:[0,1]
	v_pk_add_f32 v[22:23], v[6:7], v[26:27]
	v_pk_add_f32 v[6:7], v[6:7], v[26:27] neg_lo:[0,1] neg_hi:[0,1]
	s_nop 0
	v_pk_add_f32 v[30:31], v[6:7], v[18:19] op_sel:[0,1] op_sel_hi:[1,0] neg_hi:[0,1]
	v_pk_add_f32 v[6:7], v[6:7], v[18:19] op_sel:[0,1] op_sel_hi:[1,0] neg_lo:[0,1]
	v_pk_mul_f32 v[26:27], v[10:11], s[12:13] op_sel:[1,0] op_sel_hi:[0,0] neg_lo:[1,0]
	v_pk_add_f32 v[18:19], v[22:23], v[24:25]
	v_pk_fma_f32 v[10:11], v[10:11], s[12:13], v[26:27] op_sel_hi:[1,0,1] neg_lo:[0,0,1] neg_hi:[0,0,1]
	v_pk_mul_f32 v[26:27], v[2:3], s[36:37] op_sel:[1,0] op_sel_hi:[0,0] neg_lo:[1,0]
	v_pk_add_f32 v[22:23], v[22:23], v[24:25] neg_lo:[0,1] neg_hi:[0,1]
	v_pk_fma_f32 v[2:3], v[2:3], s[22:23], v[26:27] op_sel_hi:[1,0,1] neg_lo:[0,0,1] neg_hi:[0,0,1]
	v_pk_mul_f32 v[26:27], v[28:29], s[12:13] op_sel:[1,0] op_sel_hi:[0,0] neg_lo:[1,0]
	v_pk_fma_f32 v[26:27], v[28:29], s[12:13], v[26:27] op_sel_hi:[1,0,1] neg_lo:[0,0,1] neg_hi:[0,0,1]
	v_pk_fma_f32 v[20:21], v[20:21], 0, v[20:21] op_sel:[0,0,1] op_sel_hi:[1,0,0] neg_hi:[0,0,1]
	v_pk_mul_f32 v[28:29], v[4:5], s[12:13] op_sel:[1,0] op_sel_hi:[0,0] neg_lo:[1,0]
	v_pk_fma_f32 v[4:5], v[4:5], s[18:19], v[28:29] op_sel_hi:[1,0,1] neg_lo:[0,0,1] neg_hi:[0,0,1]
	v_pk_mul_f32 v[28:29], v[30:31], s[36:37] op_sel:[1,0] op_sel_hi:[0,0] neg_lo:[1,0]
	v_pk_mul_f32 v[24:25], v[32:33], s[22:23] op_sel:[1,0] op_sel_hi:[0,0] neg_lo:[1,0]
	v_pk_fma_f32 v[28:29], v[30:31], s[22:23], v[28:29] op_sel_hi:[1,0,1] neg_lo:[0,0,1] neg_hi:[0,0,1]
	v_pk_mul_f32 v[30:31], v[22:23], s[12:13] op_sel:[1,0] op_sel_hi:[0,0] neg_lo:[1,0]
	v_pk_fma_f32 v[24:25], v[32:33], s[36:37], v[24:25] op_sel_hi:[1,0,1] neg_lo:[0,0,1] neg_hi:[0,0,1]
	v_pk_fma_f32 v[22:23], v[22:23], s[18:19], v[30:31] op_sel_hi:[1,0,1] neg_lo:[0,0,1] neg_hi:[0,0,1]
	v_xor_b32_e32 v30, 0x80000000, v7
	v_mov_b32_e32 v31, v6
	v_pk_mul_f32 v[6:7], v[6:7], s[36:37] op_sel_hi:[1,0]
	s_barrier
	v_pk_fma_f32 v[6:7], v[30:31], s[22:23], v[6:7] op_sel_hi:[1,0,1] neg_lo:[0,0,1] neg_hi:[0,0,1]
	v_pk_add_f32 v[30:31], v[12:13], v[16:17]
	v_pk_add_f32 v[12:13], v[12:13], v[16:17] neg_lo:[0,1] neg_hi:[0,1]
	v_pk_add_f32 v[16:17], v[14:15], v[18:19]
	v_pk_add_f32 v[14:15], v[14:15], v[18:19] neg_lo:[0,1] neg_hi:[0,1]
	s_nop 0
	v_xor_b32_e32 v19, 0x80000000, v14
	v_mov_b32_e32 v18, v15
	v_pk_add_f32 v[14:15], v[30:31], v[16:17]
	v_pk_add_f32 v[16:17], v[30:31], v[16:17] neg_lo:[0,1] neg_hi:[0,1]
	v_pk_add_f32 v[30:31], v[24:25], v[28:29]
	v_pk_add_f32 v[24:25], v[24:25], v[28:29] neg_lo:[0,1] neg_hi:[0,1]
	v_pk_add_f32 v[32:33], v[12:13], v[18:19]
	v_pk_add_f32 v[12:13], v[12:13], v[18:19] neg_lo:[0,1] neg_hi:[0,1]
	v_pk_add_f32 v[18:19], v[70:71], v[26:27]
	v_pk_add_f32 v[26:27], v[70:71], v[26:27] neg_lo:[0,1] neg_hi:[0,1]
	s_nop 0
	v_pk_add_f32 v[70:71], v[26:27], v[24:25] op_sel:[0,1] op_sel_hi:[1,0] neg_hi:[0,1]
	v_pk_add_f32 v[26:27], v[26:27], v[24:25] op_sel:[0,1] op_sel_hi:[1,0] neg_lo:[0,1]
	v_pk_add_f32 v[28:29], v[8:9], v[20:21]
	v_pk_add_f32 v[8:9], v[8:9], v[20:21] neg_lo:[0,1] neg_hi:[0,1]
	v_pk_add_f32 v[20:21], v[10:11], v[22:23]
	v_pk_add_f32 v[10:11], v[10:11], v[22:23] neg_lo:[0,1] neg_hi:[0,1]
	v_pk_add_f32 v[24:25], v[18:19], v[30:31]
	v_pk_add_f32 v[18:19], v[18:19], v[30:31] neg_lo:[0,1] neg_hi:[0,1]
	v_pk_add_f32 v[30:31], v[8:9], v[10:11] op_sel:[0,1] op_sel_hi:[1,0] neg_hi:[0,1]
	v_pk_add_f32 v[8:9], v[8:9], v[10:11] op_sel:[0,1] op_sel_hi:[1,0] neg_lo:[0,1]
	v_pk_add_f32 v[22:23], v[0:1], v[4:5]
	v_pk_add_f32 v[0:1], v[0:1], v[4:5] neg_lo:[0,1] neg_hi:[0,1]
	v_pk_add_f32 v[4:5], v[2:3], v[6:7]
	v_pk_add_f32 v[2:3], v[2:3], v[6:7] neg_lo:[0,1] neg_hi:[0,1]
	v_pk_add_f32 v[10:11], v[28:29], v[20:21]
	v_pk_add_f32 v[20:21], v[28:29], v[20:21] neg_lo:[0,1] neg_hi:[0,1]
	v_pk_add_f32 v[28:29], v[0:1], v[2:3] op_sel:[0,1] op_sel_hi:[1,0] neg_hi:[0,1]
	v_pk_add_f32 v[0:1], v[0:1], v[2:3] op_sel:[0,1] op_sel_hi:[1,0] neg_lo:[0,1]
	v_pk_add_f32 v[2:3], v[22:23], v[4:5]
	v_and_b32_e32 v7, 15, v206
	v_lshrrev_b32_e32 v6, 1, v206
	v_and_b32_e32 v6, 0x78, v6
	v_mul_u32_u24_e32 v7, 0x88, v7
	v_pk_add_f32 v[4:5], v[22:23], v[4:5] neg_lo:[0,1] neg_hi:[0,1]
	v_add3_u32 v6, v207, v6, v7
	ds_write_b64 v6, v[14:15]
	ds_write_b64 v6, v[32:33] offset:8704
	ds_write_b64 v6, v[16:17] offset:17408
	ds_write_b64 v6, v[12:13] offset:26112
	ds_write_b64 v6, v[24:25] offset:2176
	ds_write_b64 v6, v[70:71] offset:10880
	ds_write_b64 v6, v[18:19] offset:19584
	ds_write_b64 v6, v[26:27] offset:28288
	ds_write_b64 v6, v[10:11] offset:4352
	ds_write_b64 v6, v[30:31] offset:13056
	ds_write_b64 v6, v[20:21] offset:21760
	ds_write_b64 v6, v[8:9] offset:30464
	ds_write_b64 v6, v[2:3] offset:6528
	ds_write_b64 v6, v[28:29] offset:15232
	ds_write_b64 v6, v[4:5] offset:23936
	ds_write_b64 v6, v[0:1] offset:32640
	s_waitcnt lgkmcnt(0)
	s_barrier
	v_and_b32_e32 v12, 31, v69
	v_and_b32_e32 v4, 0xff, v206
	v_sub_u32_e32 v6, 0x100, v4
	v_lshrrev_b32_e32 v5, 1, v206
	v_lshlrev_b32_e32 v7, 3, v4
	v_and_b32_e32 v5, 0x78, v5
	v_lshrrev_b32_e32 v6, 1, v6
	v_add3_u32 v5, v207, v7, v5
	v_sub_u32_e32 v7, v207, v7
	v_and_b32_e32 v6, 0xf8, v6
	v_add_u32_e32 v14, v7, v6
	ds_read_b64 v[10:11], v5
	ds_read_b64 v[6:7], v14 offset:34688
	v_and_b32_e32 v13, 0x1c0, v52
	v_or_b32_sdwa v176, v13, v12 dst_sel:WORD_1 dst_unused:UNUSED_PAD src0_sel:DWORD src1_sel:DWORD
	v_and_b32_e32 v2, 0xfffff000, v49
	v_lshl_add_u64 v[0:1], s[48:49], 0, v[176:177]
	v_ashrrev_i32_e32 v3, 31, v2
	v_cmp_eq_u32_e64 s[38:39], 0, v4
	v_lshl_add_u64 v[0:1], v[2:3], 1, v[0:1]
	v_cmp_eq_u32_e64 s[0:1], 0, v12
	v_cmp_ne_u32_e32 vcc, 0, v12
	s_waitcnt lgkmcnt(0)
	v_cndmask_b32_e64 v9, v7, v11, s[38:39]
	v_cndmask_b32_e64 v8, v6, v10, s[38:39]
	v_lshlrev_b32_e32 v6, 1, v4
	s_and_saveexec_b64 s[20:21], vcc
	s_xor_b64 s[28:29], exec, s[20:21]
	s_cbranch_execz .LBB0_216
	v_bfe_u32 v7, v10, 16, 1
	v_add3_u32 v9, v10, v7, s13
	v_mov_b32_e32 v7, v177
	v_lshl_add_u64 v[10:11], v[0:1], 0, v[6:7]
	global_store_short_d16_hi v[10:11], v9, off sc1
.LBB0_216:
	s_andn2_saveexec_b64 s[28:29], s[28:29]
	s_cbranch_execz .LBB0_218
	v_pk_add_f32 v[8:9], v[10:11], v[8:9]
	v_lshlrev_b32_e32 v176, 1, v4
	v_mul_f32_e32 v7, 0.5, v8
	v_bfe_u32 v8, v7, 16, 1
	v_add3_u32 v7, v7, v8, s13
	v_lshl_add_u64 v[10:11], v[0:1], 0, v[176:177]
	v_mul_f32_e32 v8, 0.5, v9
	global_store_short_d16_hi v[10:11], v7, off sc1
.LBB0_218:
	s_or_b64 exec, exec, s[28:29]
	v_sub_u32_e32 v7, 64, v12
	v_cndmask_b32_e64 v7, v7, 32, s[0:1]
	v_add_lshl_u32 v176, v7, v13, 16
	v_lshl_add_u64 v[10:11], s[48:49], 0, v[176:177]
	v_lshl_add_u64 v[2:3], v[2:3], 1, v[10:11]
	v_bfe_u32 v7, v8, 16, 1
	v_lshlrev_b32_e32 v176, 1, v4
	v_add3_u32 v7, v8, v7, s13
	v_lshl_add_u64 v[8:9], v[2:3], 0, v[176:177]
	global_store_short_d16_hi v[8:9], v7, off sc1
	ds_read_b64 v[12:13], v5 offset:2176
	ds_read_b64 v[10:11], v14 offset:32512
	v_or_b32_e32 v8, 0x100, v4
	s_and_saveexec_b64 s[0:1], vcc
	s_xor_b64 s[0:1], exec, s[0:1]
	s_cbranch_execz .LBB0_220
	s_waitcnt lgkmcnt(1)
	v_bfe_u32 v7, v12, 16, 1
	v_add3_u32 v9, v12, v7, s13
	v_mov_b32_e32 v7, v177
	v_lshl_add_u64 v[12:13], v[0:1], 0, v[6:7]
	global_store_short_d16_hi v[12:13], v9, off offset:512 sc1
.LBB0_220:
	s_andn2_saveexec_b64 s[0:1], s[0:1]
	s_cbranch_execz .LBB0_222
	s_waitcnt lgkmcnt(0)
	v_pk_add_f32 v[10:11], v[12:13], v[10:11]
	s_nop 0
	v_mul_f32_e32 v7, 0.5, v10
	v_bfe_u32 v9, v7, 16, 1
	v_add3_u32 v9, v7, v9, s13
	v_mov_b32_e32 v7, v177
	v_lshl_add_u64 v[12:13], v[0:1], 0, v[6:7]
	v_mul_f32_e32 v10, 0.5, v11
	global_store_short_d16_hi v[12:13], v9, off offset:512 sc1
.LBB0_222:
	s_or_b64 exec, exec, s[0:1]
	s_waitcnt lgkmcnt(0)
	v_bfe_u32 v7, v10, 16, 1
	v_lshlrev_b32_e32 v176, 1, v8
	v_add3_u32 v7, v10, v7, s13
	v_lshl_add_u64 v[8:9], v[2:3], 0, v[176:177]
	global_store_short_d16_hi v[8:9], v7, off sc1
	ds_read_b64 v[12:13], v5 offset:4352
	ds_read_b64 v[10:11], v14 offset:30336
	v_or_b32_e32 v8, 0x200, v4
	s_and_saveexec_b64 s[0:1], vcc
	s_xor_b64 s[0:1], exec, s[0:1]
	s_cbranch_execz .LBB0_224
	s_waitcnt lgkmcnt(1)
	v_bfe_u32 v7, v12, 16, 1
	v_add3_u32 v9, v12, v7, s13
	v_mov_b32_e32 v7, v177
	v_lshl_add_u64 v[12:13], v[0:1], 0, v[6:7]
	global_store_short_d16_hi v[12:13], v9, off offset:1024 sc1
.LBB0_224:
	s_andn2_saveexec_b64 s[0:1], s[0:1]
	s_cbranch_execz .LBB0_226
	s_waitcnt lgkmcnt(0)
	v_pk_add_f32 v[10:11], v[12:13], v[10:11]
	s_nop 0
	v_mul_f32_e32 v7, 0.5, v10
	v_bfe_u32 v9, v7, 16, 1
	v_add3_u32 v9, v7, v9, s13
	v_mov_b32_e32 v7, v177
	v_lshl_add_u64 v[12:13], v[0:1], 0, v[6:7]
	v_mul_f32_e32 v10, 0.5, v11
	global_store_short_d16_hi v[12:13], v9, off offset:1024 sc1
.LBB0_226:
	s_or_b64 exec, exec, s[0:1]
	s_waitcnt lgkmcnt(0)
	v_bfe_u32 v7, v10, 16, 1
	v_lshlrev_b32_e32 v176, 1, v8
	v_add3_u32 v7, v10, v7, s13
	v_lshl_add_u64 v[8:9], v[2:3], 0, v[176:177]
	global_store_short_d16_hi v[8:9], v7, off sc1
	ds_read_b64 v[12:13], v5 offset:6528
	ds_read_b64 v[10:11], v14 offset:28160
	v_or_b32_e32 v8, 0x300, v4
	s_and_saveexec_b64 s[0:1], vcc
	s_xor_b64 s[0:1], exec, s[0:1]
	s_cbranch_execz .LBB0_228
	s_waitcnt lgkmcnt(1)
	v_bfe_u32 v7, v12, 16, 1
	v_add3_u32 v9, v12, v7, s13
	v_mov_b32_e32 v7, v177
	v_lshl_add_u64 v[12:13], v[0:1], 0, v[6:7]
	global_store_short_d16_hi v[12:13], v9, off offset:1536 sc1
.LBB0_228:
	s_andn2_saveexec_b64 s[0:1], s[0:1]
	s_cbranch_execz .LBB0_230
	s_waitcnt lgkmcnt(0)
	v_pk_add_f32 v[10:11], v[12:13], v[10:11]
	s_nop 0
	v_mul_f32_e32 v7, 0.5, v10
	v_bfe_u32 v9, v7, 16, 1
	v_add3_u32 v9, v7, v9, s13
	v_mov_b32_e32 v7, v177
	v_lshl_add_u64 v[12:13], v[0:1], 0, v[6:7]
	v_mul_f32_e32 v10, 0.5, v11
	global_store_short_d16_hi v[12:13], v9, off offset:1536 sc1
.LBB0_230:
	s_or_b64 exec, exec, s[0:1]
	s_waitcnt lgkmcnt(0)
	v_bfe_u32 v7, v10, 16, 1
	v_lshlrev_b32_e32 v176, 1, v8
	v_add3_u32 v7, v10, v7, s13
	v_lshl_add_u64 v[8:9], v[2:3], 0, v[176:177]
	global_store_short_d16_hi v[8:9], v7, off sc1
	ds_read_b64 v[12:13], v5 offset:8704
	ds_read_b64 v[10:11], v14 offset:25984
	v_or_b32_e32 v8, 0x400, v4
	s_and_saveexec_b64 s[0:1], vcc
	s_xor_b64 s[0:1], exec, s[0:1]
	s_cbranch_execz .LBB0_232
	s_waitcnt lgkmcnt(1)
	v_bfe_u32 v7, v12, 16, 1
	v_add3_u32 v9, v12, v7, s13
	v_mov_b32_e32 v7, v177
	v_lshl_add_u64 v[12:13], v[0:1], 0, v[6:7]
	global_store_short_d16_hi v[12:13], v9, off offset:2048 sc1
.LBB0_232:
	s_andn2_saveexec_b64 s[0:1], s[0:1]
	s_cbranch_execz .LBB0_234
	s_waitcnt lgkmcnt(0)
	v_pk_add_f32 v[10:11], v[12:13], v[10:11]
	s_nop 0
	v_mul_f32_e32 v7, 0.5, v10
	v_bfe_u32 v9, v7, 16, 1
	v_add3_u32 v9, v7, v9, s13
	v_mov_b32_e32 v7, v177
	v_lshl_add_u64 v[12:13], v[0:1], 0, v[6:7]
	v_mul_f32_e32 v10, 0.5, v11
	global_store_short_d16_hi v[12:13], v9, off offset:2048 sc1
.LBB0_234:
	s_or_b64 exec, exec, s[0:1]
	s_waitcnt lgkmcnt(0)
	v_bfe_u32 v7, v10, 16, 1
	v_lshlrev_b32_e32 v176, 1, v8
	v_add3_u32 v7, v10, v7, s13
	v_lshl_add_u64 v[8:9], v[2:3], 0, v[176:177]
	global_store_short_d16_hi v[8:9], v7, off sc1
	ds_read_b64 v[12:13], v5 offset:10880
	ds_read_b64 v[10:11], v14 offset:23808
	v_or_b32_e32 v8, 0x500, v4
	s_and_saveexec_b64 s[0:1], vcc
	s_xor_b64 s[0:1], exec, s[0:1]
	s_cbranch_execz .LBB0_236
	s_waitcnt lgkmcnt(1)
	v_bfe_u32 v7, v12, 16, 1
	v_add3_u32 v9, v12, v7, s13
	v_mov_b32_e32 v7, v177
	v_lshl_add_u64 v[12:13], v[0:1], 0, v[6:7]
	global_store_short_d16_hi v[12:13], v9, off offset:2560 sc1
.LBB0_236:
	s_andn2_saveexec_b64 s[0:1], s[0:1]
	s_cbranch_execz .LBB0_238
	s_waitcnt lgkmcnt(0)
	v_pk_add_f32 v[10:11], v[12:13], v[10:11]
	s_nop 0
	v_mul_f32_e32 v7, 0.5, v10
	v_bfe_u32 v9, v7, 16, 1
	v_add3_u32 v9, v7, v9, s13
	v_mov_b32_e32 v7, v177
	v_lshl_add_u64 v[12:13], v[0:1], 0, v[6:7]
	v_mul_f32_e32 v10, 0.5, v11
	global_store_short_d16_hi v[12:13], v9, off offset:2560 sc1
.LBB0_238:
	s_or_b64 exec, exec, s[0:1]
	s_waitcnt lgkmcnt(0)
	v_bfe_u32 v7, v10, 16, 1
	v_lshlrev_b32_e32 v176, 1, v8
	v_add3_u32 v7, v10, v7, s13
	v_lshl_add_u64 v[8:9], v[2:3], 0, v[176:177]
	global_store_short_d16_hi v[8:9], v7, off sc1
	ds_read_b64 v[12:13], v5 offset:13056
	ds_read_b64 v[10:11], v14 offset:21632
	v_or_b32_e32 v8, 0x600, v4
	s_and_saveexec_b64 s[0:1], vcc
	s_xor_b64 s[0:1], exec, s[0:1]
	s_cbranch_execz .LBB0_240
	s_waitcnt lgkmcnt(1)
	v_bfe_u32 v7, v12, 16, 1
	v_add3_u32 v9, v12, v7, s13
	v_mov_b32_e32 v7, v177
	v_lshl_add_u64 v[12:13], v[0:1], 0, v[6:7]
	global_store_short_d16_hi v[12:13], v9, off offset:3072 sc1
.LBB0_240:
	s_andn2_saveexec_b64 s[0:1], s[0:1]
	s_cbranch_execz .LBB0_242
	s_waitcnt lgkmcnt(0)
	v_pk_add_f32 v[10:11], v[12:13], v[10:11]
	s_nop 0
	v_mul_f32_e32 v7, 0.5, v10
	v_bfe_u32 v9, v7, 16, 1
	v_add3_u32 v9, v7, v9, s13
	v_mov_b32_e32 v7, v177
	v_lshl_add_u64 v[12:13], v[0:1], 0, v[6:7]
	v_mul_f32_e32 v10, 0.5, v11
	global_store_short_d16_hi v[12:13], v9, off offset:3072 sc1
.LBB0_242:
	s_or_b64 exec, exec, s[0:1]
	s_waitcnt lgkmcnt(0)
	v_bfe_u32 v7, v10, 16, 1
	v_lshlrev_b32_e32 v176, 1, v8
	v_add3_u32 v7, v10, v7, s13
	v_lshl_add_u64 v[8:9], v[2:3], 0, v[176:177]
	global_store_short_d16_hi v[8:9], v7, off sc1
	ds_read_b64 v[12:13], v5 offset:15232
	ds_read_b64 v[10:11], v14 offset:19456
	v_or_b32_e32 v8, 0x700, v4
	s_and_saveexec_b64 s[0:1], vcc
	s_xor_b64 s[0:1], exec, s[0:1]
	s_cbranch_execz .LBB0_244
	s_waitcnt lgkmcnt(1)
	v_bfe_u32 v7, v12, 16, 1
	v_add3_u32 v9, v12, v7, s13
	v_mov_b32_e32 v7, v177
	v_lshl_add_u64 v[6:7], v[0:1], 0, v[6:7]
	global_store_short_d16_hi v[6:7], v9, off offset:3584 sc1
.LBB0_244:
	s_andn2_saveexec_b64 s[0:1], s[0:1]
	s_cbranch_execz .LBB0_246
	s_waitcnt lgkmcnt(0)
	v_pk_add_f32 v[10:11], v[12:13], v[10:11]
	s_nop 0
	v_mul_f32_e32 v7, 0.5, v10
	v_bfe_u32 v9, v7, 16, 1
	v_add3_u32 v9, v7, v9, s13
	v_mov_b32_e32 v7, v177
	v_lshl_add_u64 v[6:7], v[0:1], 0, v[6:7]
	v_mul_f32_e32 v10, 0.5, v11
	global_store_short_d16_hi v[6:7], v9, off offset:3584 sc1
.LBB0_246:
	s_or_b64 exec, exec, s[0:1]
	s_waitcnt lgkmcnt(0)
	v_bfe_u32 v6, v10, 16, 1
	v_lshlrev_b32_e32 v176, 1, v8
	v_add3_u32 v9, v10, v6, s13
	v_lshl_add_u64 v[6:7], v[2:3], 0, v[176:177]
	global_store_short_d16_hi v[6:7], v9, off sc1
	ds_read_b64 v[10:11], v5 offset:17408
	ds_read_b64 v[8:9], v14 offset:17280
	v_or_b32_e32 v6, 0x800, v4
	s_and_saveexec_b64 s[0:1], vcc
	s_xor_b64 s[0:1], exec, s[0:1]
	s_cbranch_execz .LBB0_248
	s_waitcnt lgkmcnt(1)
	v_bfe_u32 v7, v10, 16, 1
	v_lshlrev_b32_e32 v176, 1, v6
	v_add3_u32 v7, v10, v7, s13
	v_lshl_add_u64 v[10:11], v[0:1], 0, v[176:177]
	global_store_short_d16_hi v[10:11], v7, off sc1
.LBB0_248:
	s_andn2_saveexec_b64 s[0:1], s[0:1]
	s_cbranch_execz .LBB0_250
	s_waitcnt lgkmcnt(0)
	v_pk_add_f32 v[8:9], v[10:11], v[8:9]
	v_lshlrev_b32_e32 v176, 1, v6
	v_mul_f32_e32 v7, 0.5, v8
	v_bfe_u32 v8, v7, 16, 1
	v_add3_u32 v7, v7, v8, s13
	v_lshl_add_u64 v[10:11], v[0:1], 0, v[176:177]
	v_mul_f32_e32 v8, 0.5, v9
	global_store_short_d16_hi v[10:11], v7, off sc1
.LBB0_250:
	s_or_b64 exec, exec, s[0:1]
	s_waitcnt lgkmcnt(0)
	v_bfe_u32 v7, v8, 16, 1
	v_lshlrev_b32_e32 v176, 1, v6
	v_add3_u32 v8, v8, v7, s13
	v_lshl_add_u64 v[6:7], v[2:3], 0, v[176:177]
	global_store_short_d16_hi v[6:7], v8, off sc1
	ds_read_b64 v[10:11], v5 offset:19584
	ds_read_b64 v[8:9], v14 offset:15104
	v_or_b32_e32 v6, 0x900, v4
	s_and_saveexec_b64 s[0:1], vcc
	s_xor_b64 s[0:1], exec, s[0:1]
	s_cbranch_execz .LBB0_252
	s_waitcnt lgkmcnt(1)
	v_bfe_u32 v7, v10, 16, 1
	v_lshlrev_b32_e32 v176, 1, v6
	v_add3_u32 v7, v10, v7, s13
	v_lshl_add_u64 v[10:11], v[0:1], 0, v[176:177]
	global_store_short_d16_hi v[10:11], v7, off sc1

.LBB0_254:
	s_or_b64 exec, exec, s[0:1]
	s_waitcnt lgkmcnt(0)
	v_bfe_u32 v7, v8, 16, 1
	v_lshlrev_b32_e32 v176, 1, v6
	v_add3_u32 v8, v8, v7, s13
	v_lshl_add_u64 v[6:7], v[2:3], 0, v[176:177]
	global_store_short_d16_hi v[6:7], v8, off sc1
	ds_read_b64 v[10:11], v5 offset:21760
	ds_read_b64 v[8:9], v14 offset:12928
	v_or_b32_e32 v6, 0xa00, v4
	s_and_saveexec_b64 s[0:1], vcc
	s_xor_b64 s[0:1], exec, s[0:1]
	s_cbranch_execz .LBB0_256
	s_waitcnt lgkmcnt(1)
	v_bfe_u32 v7, v10, 16, 1
	v_lshlrev_b32_e32 v176, 1, v6
	v_add3_u32 v7, v10, v7, s13
	v_lshl_add_u64 v[10:11], v[0:1], 0, v[176:177]
	global_store_short_d16_hi v[10:11], v7, off sc1

.LBB0_258:
	s_or_b64 exec, exec, s[0:1]
	s_waitcnt lgkmcnt(0)
	v_bfe_u32 v7, v8, 16, 1
	v_lshlrev_b32_e32 v176, 1, v6
	v_add3_u32 v8, v8, v7, s13
	v_lshl_add_u64 v[6:7], v[2:3], 0, v[176:177]
	global_store_short_d16_hi v[6:7], v8, off sc1
	ds_read_b64 v[10:11], v5 offset:23936
	ds_read_b64 v[8:9], v14 offset:10752
	v_or_b32_e32 v6, 0xb00, v4
	s_and_saveexec_b64 s[0:1], vcc
	s_xor_b64 s[0:1], exec, s[0:1]
	s_cbranch_execz .LBB0_260
	s_waitcnt lgkmcnt(1)
	v_bfe_u32 v7, v10, 16, 1
	v_lshlrev_b32_e32 v176, 1, v6
	v_add3_u32 v7, v10, v7, s13
	v_lshl_add_u64 v[10:11], v[0:1], 0, v[176:177]
	global_store_short_d16_hi v[10:11], v7, off sc1

.LBB0_262:
	s_or_b64 exec, exec, s[0:1]
	s_waitcnt lgkmcnt(0)
	v_bfe_u32 v7, v8, 16, 1
	v_lshlrev_b32_e32 v176, 1, v6
	v_add3_u32 v8, v8, v7, s13
	v_lshl_add_u64 v[6:7], v[2:3], 0, v[176:177]
	global_store_short_d16_hi v[6:7], v8, off sc1
	ds_read_b64 v[10:11], v5 offset:26112
	ds_read_b64 v[8:9], v14 offset:8576
	v_or_b32_e32 v6, 0xc00, v4
	s_and_saveexec_b64 s[0:1], vcc
	s_xor_b64 s[0:1], exec, s[0:1]
	s_cbranch_execz .LBB0_264
	s_waitcnt lgkmcnt(1)
	v_bfe_u32 v7, v10, 16, 1
	v_lshlrev_b32_e32 v176, 1, v6
	v_add3_u32 v7, v10, v7, s13
	v_lshl_add_u64 v[10:11], v[0:1], 0, v[176:177]
	global_store_short_d16_hi v[10:11], v7, off sc1

.LBB0_266:
	s_or_b64 exec, exec, s[0:1]
	s_waitcnt lgkmcnt(0)
	v_bfe_u32 v7, v8, 16, 1
	v_lshlrev_b32_e32 v176, 1, v6
	v_add3_u32 v8, v8, v7, s13
	v_lshl_add_u64 v[6:7], v[2:3], 0, v[176:177]
	global_store_short_d16_hi v[6:7], v8, off sc1
	ds_read_b64 v[10:11], v5 offset:28288
	ds_read_b64 v[8:9], v14 offset:6400
	v_or_b32_e32 v6, 0xd00, v4
	s_and_saveexec_b64 s[0:1], vcc
	s_xor_b64 s[0:1], exec, s[0:1]
	s_cbranch_execz .LBB0_268
	s_waitcnt lgkmcnt(1)
	v_bfe_u32 v7, v10, 16, 1
	v_lshlrev_b32_e32 v176, 1, v6
	v_add3_u32 v7, v10, v7, s13
	v_lshl_add_u64 v[10:11], v[0:1], 0, v[176:177]
	global_store_short_d16_hi v[10:11], v7, off sc1

.LBB0_270:
	s_or_b64 exec, exec, s[0:1]
	s_waitcnt lgkmcnt(0)
	v_bfe_u32 v7, v8, 16, 1
	v_lshlrev_b32_e32 v176, 1, v6
	v_add3_u32 v8, v8, v7, s13
	v_lshl_add_u64 v[6:7], v[2:3], 0, v[176:177]
	global_store_short_d16_hi v[6:7], v8, off sc1
	ds_read_b64 v[10:11], v5 offset:30464
	ds_read_b64 v[8:9], v14 offset:4224
	v_or_b32_e32 v6, 0xe00, v4
	s_and_saveexec_b64 s[0:1], vcc
	s_xor_b64 s[0:1], exec, s[0:1]
	s_cbranch_execz .LBB0_272
	s_waitcnt lgkmcnt(1)
	v_bfe_u32 v7, v10, 16, 1
	v_lshlrev_b32_e32 v176, 1, v6
	v_add3_u32 v7, v10, v7, s13
	v_lshl_add_u64 v[10:11], v[0:1], 0, v[176:177]
	global_store_short_d16_hi v[10:11], v7, off sc1

.LBB0_274:
	s_or_b64 exec, exec, s[0:1]
	s_waitcnt lgkmcnt(0)
	v_bfe_u32 v7, v8, 16, 1
	v_lshlrev_b32_e32 v176, 1, v6
	v_add3_u32 v8, v8, v7, s13
	v_lshl_add_u64 v[6:7], v[2:3], 0, v[176:177]
	global_store_short_d16_hi v[6:7], v8, off sc1
	ds_read_b64 v[8:9], v5 offset:32640
	ds_read_b64 v[6:7], v14 offset:2048
	v_or_b32_e32 v4, 0xf00, v4
	s_and_saveexec_b64 s[0:1], vcc
	s_xor_b64 s[0:1], exec, s[0:1]
	s_cbranch_execz .LBB0_276
	s_waitcnt lgkmcnt(1)
	v_bfe_u32 v5, v8, 16, 1
	v_lshlrev_b32_e32 v176, 1, v4
	v_add3_u32 v5, v8, v5, s13
	v_lshl_add_u64 v[0:1], v[0:1], 0, v[176:177]
	global_store_short_d16_hi v[0:1], v5, off sc1
.LBB0_276:
	s_andn2_saveexec_b64 s[0:1], s[0:1]
	s_cbranch_execz .LBB0_213
	s_waitcnt lgkmcnt(0)
	v_pk_add_f32 v[6:7], v[8:9], v[6:7]
	v_lshlrev_b32_e32 v176, 1, v4
	v_mul_f32_e32 v5, 0.5, v6
	v_bfe_u32 v6, v5, 16, 1
	v_add3_u32 v5, v5, v6, s13
	v_lshl_add_u64 v[0:1], v[0:1], 0, v[176:177]
	v_mul_f32_e32 v6, 0.5, v7
	global_store_short_d16_hi v[0:1], v5, off sc1
	s_branch .LBB0_213

.LBB0_305:
	s_waitcnt lgkmcnt(3)
	v_bfe_u32 v17, v0, 16, 1
	v_add3_u32 v0, v0, v17, s13
	v_bfe_u32 v17, v1, 16, 1
	v_lshrrev_b32_e32 v0, 16, v0
	v_add3_u32 v1, v1, v17, s13
	v_and_or_b32 v0, v1, s33, v0
	s_waitcnt lgkmcnt(2)
	v_bfe_u32 v1, v2, 16, 1
	v_add3_u32 v1, v2, v1, s13
	v_bfe_u32 v2, v3, 16, 1
	s_ashr_i32 s6, s3, 31
	v_lshrrev_b32_e32 v1, 16, v1
	v_add3_u32 v2, v3, v2, s13
	s_lshr_b32 s6, s6, 28
	v_and_or_b32 v1, v2, s33, v1
	s_waitcnt lgkmcnt(1)
	v_bfe_u32 v2, v4, 16, 1
	s_add_i32 s7, s3, s6
	v_add3_u32 v2, v4, v2, s13
	v_bfe_u32 v3, v5, 16, 1
	s_and_b32 s6, s7, 0x3fffff0
	v_lshrrev_b32_e32 v2, 16, v2
	v_add3_u32 v3, v5, v3, s13
	s_sub_i32 s3, s3, s6
	v_and_or_b32 v2, v3, s33, v2
	s_waitcnt lgkmcnt(0)
	v_bfe_u32 v3, v6, 16, 1
	s_lshl_b32 s6, s3, 6
	s_lshl_b32 s3, s7, 2
	v_add3_u32 v3, v6, v3, s13
	v_bfe_u32 v4, v7, 16, 1
	s_andn2_b32 s3, s3, 63
	v_lshrrev_b32_e32 v3, 16, v3
	v_add3_u32 v4, v7, v4, s13
	v_and_or_b32 v3, v4, s33, v3
	v_add_u32_e32 v4, s3, v31
	v_ashrrev_i32_e32 v5, 31, v4
	v_readlane_b32 s20, v254, 15
	v_lshlrev_b64 v[4:5], 11, v[4:5]
	v_readlane_b32 s21, v254, 16
	s_ashr_i32 s7, s6, 31
	s_andn2_b64 vcc, exec, s[0:1]
	v_lshl_add_u64 v[4:5], s[20:21], 0, v[4:5]
	v_lshl_add_u64 v[4:5], s[6:7], 1, v[4:5]
	v_lshl_add_u64 v[4:5], v[4:5], 0, v[176:177]
	s_mov_b32 s3, s2
	global_store_dwordx4 v[4:5], v[0:3], off sc1
	s_cbranch_vccz .LBB0_321

.LBB0_324:
	s_waitcnt lgkmcnt(3)
	v_bfe_u32 v17, v0, 16, 1
	v_add3_u32 v0, v0, v17, s13
	v_bfe_u32 v17, v1, 16, 1
	v_lshrrev_b32_e32 v0, 16, v0
	v_add3_u32 v1, v1, v17, s13
	v_and_or_b32 v0, v1, s33, v0
	s_waitcnt lgkmcnt(2)
	v_bfe_u32 v1, v2, 16, 1
	v_add3_u32 v1, v2, v1, s13
	v_bfe_u32 v2, v3, 16, 1
	s_ashr_i32 s6, s3, 31
	v_lshrrev_b32_e32 v1, 16, v1
	v_add3_u32 v2, v3, v2, s13
	s_lshr_b32 s6, s6, 28
	v_and_or_b32 v1, v2, s33, v1
	s_waitcnt lgkmcnt(1)
	v_bfe_u32 v2, v4, 16, 1
	s_add_i32 s7, s3, s6
	v_add3_u32 v2, v4, v2, s13
	v_bfe_u32 v3, v5, 16, 1
	s_and_b32 s6, s7, 0x3fffff0
	v_lshrrev_b32_e32 v2, 16, v2
	v_add3_u32 v3, v5, v3, s13
	s_sub_i32 s3, s3, s6
	v_and_or_b32 v2, v3, s33, v2
	s_waitcnt lgkmcnt(0)
	v_bfe_u32 v3, v6, 16, 1
	s_lshl_b32 s6, s3, 6
	s_lshl_b32 s3, s7, 2
	v_add3_u32 v3, v6, v3, s13
	v_bfe_u32 v4, v7, 16, 1
	s_andn2_b32 s3, s3, 63
	v_lshrrev_b32_e32 v3, 16, v3
	v_add3_u32 v4, v7, v4, s13
	v_and_or_b32 v3, v4, s33, v3
	v_add_u32_e32 v4, s3, v31
	v_ashrrev_i32_e32 v5, 31, v4
	v_readlane_b32 s20, v254, 41
	v_lshlrev_b64 v[4:5], 11, v[4:5]
	v_readlane_b32 s21, v254, 42
	s_ashr_i32 s7, s6, 31
	s_andn2_b64 vcc, exec, s[0:1]
	v_lshl_add_u64 v[4:5], s[20:21], 0, v[4:5]
	v_lshl_add_u64 v[4:5], s[6:7], 1, v[4:5]
	v_lshl_add_u64 v[4:5], v[4:5], 0, v[176:177]
	s_mov_b32 s3, s2
	global_store_dwordx4 v[4:5], v[0:3], off sc1
	s_cbranch_vccz .LBB0_340

.LBB0_342:
	s_waitcnt lgkmcnt(3)
	v_bfe_u32 v19, v0, 16, 1
	v_add3_u32 v0, v0, v19, s13
	v_bfe_u32 v19, v1, 16, 1
	v_lshrrev_b32_e32 v0, 16, v0
	v_add3_u32 v1, v1, v19, s13
	v_and_or_b32 v0, v1, s33, v0
	s_waitcnt lgkmcnt(2)
	v_bfe_u32 v1, v2, 16, 1
	v_add3_u32 v1, v2, v1, s13
	v_bfe_u32 v2, v3, 16, 1
	v_lshrrev_b32_e32 v1, 16, v1
	v_add3_u32 v2, v3, v2, s13
	v_and_or_b32 v1, v2, s33, v1
	s_waitcnt lgkmcnt(1)
	v_bfe_u32 v2, v4, 16, 1
	v_add3_u32 v2, v4, v2, s13
	v_bfe_u32 v3, v5, 16, 1
	v_lshrrev_b32_e32 v2, 16, v2
	v_add3_u32 v3, v5, v3, s13
	v_and_or_b32 v2, v3, s33, v2
	s_waitcnt lgkmcnt(0)
	v_bfe_u32 v3, v6, 16, 1
	v_add3_u32 v3, v6, v3, s13
	v_bfe_u32 v4, v7, 16, 1
	s_ashr_i32 s3, s6, 4
	v_lshrrev_b32_e32 v3, 16, v3
	v_add3_u32 v4, v7, v4, s13
	v_and_or_b32 v3, v4, s33, v3
	v_lshl_add_u32 v4, s3, 6, v32
	v_ashrrev_i32_e32 v5, 31, v4
	v_readlane_b32 s6, v253, 62
	v_lshlrev_b64 v[4:5], 11, v[4:5]
	v_readlane_b32 s7, v253, 63
	s_ashr_i32 s29, s28, 31
	v_lshlrev_b32_e32 v176, 1, v16
	v_lshl_add_u64 v[4:5], s[6:7], 0, v[4:5]
	v_lshl_add_u64 v[4:5], s[28:29], 1, v[4:5]
	v_lshl_add_u64 v[4:5], v[4:5], 0, v[176:177]
	s_andn2_b64 vcc, exec, s[0:1]
	s_mov_b32 s3, s2
	global_store_dwordx4 v[4:5], v[0:3], off sc1
	s_cbranch_vccz .LBB0_361

.LBB0_364:
	s_waitcnt lgkmcnt(3)
	v_bfe_u32 v17, v0, 16, 1
	v_add3_u32 v0, v0, v17, s13
	v_bfe_u32 v17, v1, 16, 1
	v_lshrrev_b32_e32 v0, 16, v0
	v_add3_u32 v1, v1, v17, s13
	v_and_or_b32 v0, v1, s33, v0
	s_waitcnt lgkmcnt(2)
	v_bfe_u32 v1, v2, 16, 1
	v_add3_u32 v1, v2, v1, s13
	v_bfe_u32 v2, v3, 16, 1
	v_lshrrev_b32_e32 v1, 16, v1
	v_add3_u32 v2, v3, v2, s13
	v_and_or_b32 v1, v2, s33, v1
	s_waitcnt lgkmcnt(1)
	v_bfe_u32 v2, v4, 16, 1
	v_add3_u32 v2, v4, v2, s13
	v_bfe_u32 v3, v5, 16, 1
	s_ashr_i32 s6, s3, 31
	v_lshrrev_b32_e32 v2, 16, v2
	v_add3_u32 v3, v5, v3, s13
	s_lshr_b32 s6, s6, 26
	v_and_or_b32 v2, v3, s33, v2
	s_waitcnt lgkmcnt(0)
	v_bfe_u32 v3, v6, 16, 1
	s_add_i32 s6, s3, s6
	v_add3_u32 v3, v6, v3, s13
	v_bfe_u32 v4, v7, 16, 1
	s_and_b32 s7, s6, 0xffffffc0
	v_lshrrev_b32_e32 v3, 16, v3
	v_add3_u32 v4, v7, v4, s13
	v_and_or_b32 v3, v4, s33, v3
	v_add_u32_e32 v4, s7, v31
	s_sub_i32 s3, s3, s7
	v_ashrrev_i32_e32 v5, 31, v4
	v_readlane_b32 s20, v254, 27
	s_lshl_b32 s6, s3, 6
	v_lshlrev_b64 v[4:5], 13, v[4:5]
	v_readlane_b32 s21, v254, 28
	s_ashr_i32 s7, s6, 31
	s_andn2_b64 vcc, exec, s[0:1]
	v_lshl_add_u64 v[4:5], s[20:21], 0, v[4:5]
	v_lshl_add_u64 v[4:5], s[6:7], 1, v[4:5]
	v_lshl_add_u64 v[4:5], v[4:5], 0, v[176:177]
	s_mov_b32 s3, s2
	global_store_dwordx4 v[4:5], v[0:3], off sc1
	s_cbranch_vccz .LBB0_380

.LBB0_441:
	s_nop 0
	v_add_u32_e32 v24, v44, v22
	v_ashrrev_i32_e32 v25, 31, v24
	v_lshl_add_u64 v[92:93], v[24:25], 2, s[80:81]
	v_add_u32_e32 v76, 16, v24
	v_add_u32_e32 v78, 0x2010, v24
	global_load_dword v25, v[92:93], off
	v_add_u32_e32 v62, 0x2000, v24
	v_add_u32_e32 v64, 0x4000, v24
	v_add_u32_e32 v66, 0x6000, v24
	v_add_u32_e32 v68, 0x8000, v24
	v_add_u32_e32 v70, 0xa000, v24
	v_add_u32_e32 v72, 0xc000, v24
	v_add_u32_e32 v74, 0xe000, v24
	v_add_u32_e32 v80, 0x4010, v24
	v_add_u32_e32 v82, 0x6010, v24
	v_ashrrev_i32_e32 v77, 31, v76
	v_ashrrev_i32_e32 v79, 31, v78
	v_ashrrev_i32_e32 v63, 31, v62
	v_ashrrev_i32_e32 v65, 31, v64
	v_ashrrev_i32_e32 v67, 31, v66
	v_ashrrev_i32_e32 v69, 31, v68
	v_ashrrev_i32_e32 v71, 31, v70
	v_ashrrev_i32_e32 v73, 31, v72
	v_ashrrev_i32_e32 v75, 31, v74
	v_ashrrev_i32_e32 v81, 31, v80
	v_ashrrev_i32_e32 v83, 31, v82
	v_lshl_add_u64 v[76:77], v[76:77], 2, s[80:81]
	v_lshl_add_u64 v[78:79], v[78:79], 2, s[80:81]
	v_lshl_add_u64 v[62:63], v[62:63], 2, s[80:81]
	v_lshl_add_u64 v[64:65], v[64:65], 2, s[80:81]
	v_lshl_add_u64 v[66:67], v[66:67], 2, s[80:81]
	v_lshl_add_u64 v[68:69], v[68:69], 2, s[80:81]
	v_lshl_add_u64 v[70:71], v[70:71], 2, s[80:81]
	v_lshl_add_u64 v[72:73], v[72:73], 2, s[80:81]
	v_lshl_add_u64 v[74:75], v[74:75], 2, s[80:81]
	v_lshl_add_u64 v[80:81], v[80:81], 2, s[80:81]
	v_lshl_add_u64 v[82:83], v[82:83], 2, s[80:81]
	global_load_dword v29, v[76:77], off
	global_load_dword v31, v[62:63], off
	global_load_dword v33, v[78:79], off
	s_nop 0
	global_load_dword v79, v[64:65], off
	global_load_dword v92, v[80:81], off
	global_load_dword v94, v[66:67], off
	global_load_dword v95, v[82:83], off
	global_load_dword v96, v[68:69], off
	global_load_dword v97, v[70:71], off
	global_load_dword v98, v[72:73], off
	global_load_dword v99, v[74:75], off
	v_add_u32_e32 v84, 0x8010, v24
	v_add_u32_e32 v86, 0xa010, v24
	v_add_u32_e32 v88, 0xc010, v24
	v_add_u32_e32 v90, 0xe010, v24
	v_ashrrev_i32_e32 v85, 31, v84
	v_ashrrev_i32_e32 v87, 31, v86
	v_ashrrev_i32_e32 v89, 31, v88
	v_ashrrev_i32_e32 v91, 31, v90
	v_lshl_add_u64 v[84:85], v[84:85], 2, s[80:81]
	v_lshl_add_u64 v[86:87], v[86:87], 2, s[80:81]
	v_lshl_add_u64 v[88:89], v[88:89], 2, s[80:81]
	v_lshl_add_u64 v[90:91], v[90:91], 2, s[80:81]
	global_load_dword v100, v[84:85], off
	global_load_dword v101, v[86:87], off
	global_load_dword v102, v[88:89], off
	global_load_dword v103, v[90:91], off
	v_add_u32_e32 v38, 0x10000, v24
	v_add_u32_e32 v40, 0x12000, v24
	v_ashrrev_i32_e32 v39, 31, v38
	v_ashrrev_i32_e32 v41, 31, v40
	v_lshl_add_u64 v[86:87], v[38:39], 2, s[80:81]
	v_lshl_add_u64 v[88:89], v[40:41], 2, s[80:81]
	v_add_u32_e32 v72, 0x10010, v24
	v_add_u32_e32 v32, 0x18000, v24
	v_add_u32_e32 v34, 0x1a000, v24
	v_ashrrev_i32_e32 v73, 31, v72
	v_and_b32_e32 v27, 0x1ef, v22
	v_ashrrev_i32_e32 v35, 31, v34
	v_lshl_add_u64 v[72:73], v[72:73], 2, s[80:81]
	v_cvt_f32_u32_e32 v104, v27
	global_load_dword v27, v[86:87], off
	v_add_u32_e32 v28, 0x14000, v24
	v_add_u32_e32 v30, 0x16000, v24
	v_add_u32_e32 v74, 0x12010, v24
	v_ashrrev_i32_e32 v75, 31, v74
	v_add_u32_e32 v76, 0x14010, v24
	v_ashrrev_i32_e32 v77, 31, v76
	v_add_u32_e32 v78, 0x16010, v24
	v_add_u32_e32 v70, 0x1e000, v24
	s_waitcnt vmcnt(15) lgkmcnt(7)
	v_mfma_f32_16x16x4_f32 v[66:69], v4, v29, 0
	v_ashrrev_i32_e32 v29, 31, v28
	v_add_u32_e32 v80, 0x18010, v24
	v_add_u32_e32 v36, 0x1c000, v24
	v_add_u32_e32 v82, 0x1a010, v24
	v_add_u32_e32 v84, 0x1c010, v24
	v_add_u32_e32 v24, 0x1e010, v24
	v_ashrrev_i32_e32 v71, 31, v70
	v_mfma_f32_16x16x4_f32 v[62:65], v4, v25, 0
	v_ashrrev_i32_e32 v81, 31, v80
	v_ashrrev_i32_e32 v37, 31, v36
	v_ashrrev_i32_e32 v83, 31, v82
	v_ashrrev_i32_e32 v85, 31, v84
	v_ashrrev_i32_e32 v25, 31, v24
	v_lshl_add_u64 v[70:71], v[70:71], 2, s[80:81]
	v_lshl_add_u64 v[36:37], v[36:37], 2, s[80:81]
	s_waitcnt vmcnt(13)
	v_mfma_f32_16x16x4_f32 v[66:69], v5, v33, v[66:69]
	v_ashrrev_i32_e32 v33, 31, v32
	v_lshl_add_u64 v[90:91], v[32:33], 2, s[80:81]
	v_lshl_add_u64 v[24:25], v[24:25], 2, s[80:81]
	v_ashrrev_i32_e32 v23, 31, v22
	v_add_u32_e32 v26, 16, v22
	s_add_i32 s3, s3, 2
	s_cmp_gt_u32 s3, 13
	v_mfma_f32_16x16x4_f32 v[62:65], v5, v31, v[62:65]
	v_ashrrev_i32_e32 v31, 31, v30
	s_waitcnt vmcnt(11) lgkmcnt(6)
	v_mfma_f32_16x16x4_f32 v[38:41], v6, v92, v[66:69]
	v_lshl_add_u64 v[92:93], v[34:35], 2, s[80:81]
	v_lshl_add_u64 v[66:67], v[28:29], 2, s[80:81]
	v_lshl_add_u64 v[68:69], v[30:31], 2, s[80:81]
	v_mfma_f32_16x16x4_f32 v[62:65], v6, v79, v[62:65]
	v_ashrrev_i32_e32 v79, 31, v78
	s_waitcnt vmcnt(9)
	v_mfma_f32_16x16x4_f32 v[32:35], v7, v95, v[38:41]
	s_nop 2
	global_load_dword v38, v[72:73], off
	global_load_dword v39, v[88:89], off
	global_load_dword v41, v[66:67], off
	v_fmamk_f32 v73, v104, 0xbcc4df2d, v224
	v_mfma_f32_16x16x4_f32 v[28:31], v7, v94, v[62:65]
	v_lshl_add_u64 v[62:63], v[74:75], 2, s[80:81]
	global_load_dword v40, v[62:63], off
	v_lshl_add_u64 v[64:65], v[76:77], 2, s[80:81]
	global_load_dword v62, v[64:65], off
	global_load_dword v63, v[68:69], off
	v_lshl_add_u64 v[74:75], v[78:79], 2, s[80:81]
	global_load_dword v64, v[74:75], off
	v_lshl_add_u64 v[76:77], v[80:81], 2, s[80:81]
	v_lshl_add_u64 v[78:79], v[82:83], 2, s[80:81]
	v_lshl_add_u64 v[80:81], v[84:85], 2, s[80:81]
	global_load_dword v65, v[90:91], off
	global_load_dword v66, v[92:93], off
	global_load_dword v67, v[36:37], off
	global_load_dword v68, v[70:71], off
	global_load_dword v69, v[76:77], off
	s_nop 0
	global_load_dword v70, v[78:79], off
	global_load_dword v71, v[80:81], off
	global_load_dword v72, v[24:25], off
	s_waitcnt vmcnt(23) lgkmcnt(5)
	v_mfma_f32_16x16x4_f32 v[28:31], v8, v96, v[28:31]
	v_lshlrev_b64 v[24:25], 14, v[22:23]
	v_lshl_add_u64 v[36:37], v[20:21], 0, v[24:25]
	v_and_b32_e32 v23, 0x1ff, v26
	v_cvt_f32_u32_e32 v23, v23
	v_and_b32_e32 v74, 0x7fffffff, v73
	v_mul_f32_e64 v75, v61, |v73|
	v_mul_f32_e32 v76, 0x3fb8aa3b, v75
	s_waitcnt vmcnt(19)
	v_mfma_f32_16x16x4_f32 v[32:35], v8, v100, v[32:35]
	v_fmamk_f32 v23, v23, 0xbcc4df2d, v224
	v_cmp_ngt_f32_e64 s[44:45], s17, v75
	v_add_u32_e32 v22, 32, v22
	v_mfma_f32_16x16x4_f32 v[28:31], v9, v97, v[28:31]
	s_waitcnt vmcnt(18)
	v_mfma_f32_16x16x4_f32 v[32:35], v9, v101, v[32:35]
	s_waitcnt lgkmcnt(4)
	v_mfma_f32_16x16x4_f32 v[28:31], v10, v98, v[28:31]
	s_waitcnt vmcnt(17)
	v_mfma_f32_16x16x4_f32 v[32:35], v10, v102, v[32:35]
	v_mfma_f32_16x16x4_f32 v[28:31], v11, v99, v[28:31]
	s_waitcnt vmcnt(16)
	v_mfma_f32_16x16x4_f32 v[32:35], v11, v103, v[32:35]
	s_waitcnt vmcnt(15) lgkmcnt(3)
	v_mfma_f32_16x16x4_f32 v[28:31], v12, v27, v[28:31]
	v_ashrrev_i32_e32 v27, 31, v26
	v_lshlrev_b64 v[24:25], 14, v[26:27]
	s_waitcnt vmcnt(14)
	v_mfma_f32_16x16x4_f32 v[32:35], v12, v38, v[32:35]
	s_waitcnt vmcnt(13)
	v_mfma_f32_16x16x4_f32 v[28:31], v13, v39, v[28:31]
	v_lshl_add_u64 v[38:39], v[20:21], 0, v[24:25]
	s_waitcnt vmcnt(11)
	v_mfma_f32_16x16x4_f32 v[24:27], v13, v40, v[32:35]
	s_nop 4
	v_div_scale_f32 v33, s[0:1], s11, s11, v74
	v_and_b32_e32 v32, 0x7fffffff, v23
	v_div_scale_f32 v34, vcc, v74, s11, v74
	v_mul_f32_e64 v35, v61, |v23|
	v_fma_f32 v40, v75, s16, -v76
	s_waitcnt lgkmcnt(2)
	v_mfma_f32_16x16x4_f32 v[28:31], v14, v41, v[28:31]
	v_rndne_f32_e32 v41, v76
	v_rcp_f32_e32 v74, v33
	v_div_scale_f32 v78, s[0:1], s11, s11, v32
	v_mul_f32_e32 v77, 0x3fb8aa3b, v35
	v_div_scale_f32 v79, s[0:1], v32, s11, v32
	s_waitcnt vmcnt(10)
	v_mfma_f32_16x16x4_f32 v[24:27], v14, v62, v[24:27]
	v_fmac_f32_e32 v40, 0x32a5705f, v75
	v_sub_f32_e32 v32, v76, v41
	v_rcp_f32_e32 v80, v78
	v_fma_f32 v62, v35, s16, -v77
	v_rndne_f32_e32 v76, v77
	v_add_f32_e32 v32, v32, v40
	v_cvt_i32_f32_e32 v41, v41
	s_waitcnt vmcnt(9)
	v_mfma_f32_16x16x4_f32 v[28:31], v15, v63, v[28:31]
	v_fmac_f32_e32 v62, 0x32a5705f, v35
	v_sub_f32_e32 v40, v77, v76
	v_exp_f32_e32 v32, v32
	v_add_f32_e32 v40, v40, v62
	v_fma_f32 v62, -v33, v74, 1.0
	v_cvt_i32_f32_e32 v63, v76
	v_exp_f32_e32 v40, v40
	s_waitcnt vmcnt(8)
	v_mfma_f32_16x16x4_f32 v[24:27], v15, v64, v[24:27]
	v_fmac_f32_e32 v74, v62, v74
	v_fma_f32 v62, -v78, v80, 1.0
	v_mul_f32_e32 v64, v34, v74
	v_fmac_f32_e32 v80, v62, v80
	v_ldexp_f32 v32, v32, v41
	v_fma_f32 v41, -v33, v64, v34
	v_mul_f32_e32 v62, v79, v80
	s_waitcnt vmcnt(7) lgkmcnt(1)
	v_mfma_f32_16x16x4_f32 v[28:31], v16, v65, v[28:31]
	v_fmac_f32_e32 v64, v41, v74
	v_fma_f32 v41, -v78, v62, v79
	v_ldexp_f32 v40, v40, v63
	v_cmp_ngt_f32_e64 s[46:47], s17, v35
	v_fma_f32 v33, -v33, v64, v34
	v_fmac_f32_e32 v62, v41, v80
	v_cndmask_b32_e64 v40, 0, v40, s[46:47]
	s_waitcnt vmcnt(3)
	v_mfma_f32_16x16x4_f32 v[24:27], v16, v69, v[24:27]
	v_cmp_nlt_f32_e64 s[46:47], s14, v35
	v_div_fmas_f32 v33, v33, v74, v64
	v_fma_f32 v35, -v78, v62, v79
	s_mov_b64 vcc, s[0:1]
	v_div_fixup_f32 v33, v33, s11, |v73|
	v_div_fmas_f32 v35, v35, v80, v62
	v_cndmask_b32_e64 v34, v230, v40, s[46:47]
	v_mfma_f32_16x16x4_f32 v[28:31], v17, v66, v[28:31]
	v_mul_f32_e32 v40, 0x3fb8aa3b, v33
	v_div_fixup_f32 v23, v35, s11, |v23|
	v_fma_f32 v35, v33, s16, -v40
	v_rndne_f32_e32 v41, v40
	v_mul_f32_e32 v62, 0x3fb8aa3b, v23
	v_fmac_f32_e32 v35, 0x32a5705f, v33
	v_sub_f32_e32 v40, v40, v41
	s_waitcnt vmcnt(2)
	v_mfma_f32_16x16x4_f32 v[24:27], v17, v70, v[24:27]
	v_fma_f32 v63, v23, s16, -v62
	v_rndne_f32_e32 v64, v62
	v_add_f32_e32 v35, v40, v35
	v_fmac_f32_e32 v63, 0x32a5705f, v23
	v_sub_f32_e32 v40, v62, v64
	v_cvt_i32_f32_e32 v41, v41
	v_exp_f32_e32 v35, v35
	s_waitcnt lgkmcnt(0)
	v_mfma_f32_16x16x4_f32 v[28:31], v18, v67, v[28:31]
	v_add_f32_e32 v40, v40, v63
	v_cvt_i32_f32_e32 v62, v64
	v_exp_f32_e32 v40, v40
	v_ldexp_f32 v35, v35, v41
	v_cmp_ngt_f32_e32 vcc, s17, v33
	v_cmp_ngt_f32_e64 s[0:1], s17, v23
	v_cndmask_b32_e64 v32, 0, v32, s[44:45]
	s_waitcnt vmcnt(1)
	v_mfma_f32_16x16x4_f32 v[24:27], v18, v71, v[24:27]
	v_cndmask_b32_e32 v35, 0, v35, vcc
	v_cmp_nlt_f32_e32 vcc, s14, v33
	v_ldexp_f32 v33, v40, v62
	v_cmp_nlt_f32_e64 s[44:45], s14, v75
	v_cndmask_b32_e64 v40, 0, v33, s[0:1]
	v_cmp_nlt_f32_e64 s[0:1], s14, v23
	v_cndmask_b32_e64 v32, v230, v32, s[44:45]
	v_mfma_f32_16x16x4_f32 v[28:31], v19, v68, v[28:31]
	v_cndmask_b32_e32 v23, v230, v35, vcc
	v_cndmask_b32_e64 v63, v230, v40, s[0:1]
	v_mul_f32_e32 v33, v32, v23
	v_mul_f32_e32 v35, v34, v63
	v_mul_f32_e32 v40, v23, v33
	v_mul_f32_e32 v62, v63, v35
	v_mul_f32_e32 v41, v23, v40
	s_waitcnt vmcnt(0)
	v_mfma_f32_16x16x4_f32 v[24:27], v19, v72, v[24:27]
	v_mul_f32_e32 v63, v63, v62
	v_mul_f32_e64 v30, v40, v30
	v_mul_f32_e64 v31, v41, v31
	v_mul_f32_e64 v28, v32, v28
	v_mul_f32_e64 v29, v33, v29
	global_store_dwordx4 v[36:37], v[28:31], off sc1
	s_nop 3
	v_pk_mul_f32 v[26:27], v[62:63], v[26:27]
	v_pk_mul_f32 v[24:25], v[34:35], v[24:25]
	global_store_dwordx4 v[38:39], v[24:27], off sc1
	s_cbranch_scc0 .LBB0_441
	s_load_dword s0, s[74:75], 0x0
	s_waitcnt lgkmcnt(0)
	s_add_i32 s6, s6, s0
	s_cmpk_gt_i32 s6, 0xff
	s_cbranch_scc0 .LBB0_412
	v_writelane_b32 v255, s24, 2
	s_nop 1
	v_writelane_b32 v255, s25, 3

.LBB0_446:
	v_ashrrev_i32_e32 v81, 31, v80
	v_lshlrev_b64 v[16:17], 12, v[80:81]
	v_lshl_add_u64 v[16:17], v[82:83], 0, v[16:17]
	v_add_u32_e32 v94, 1, v80
	global_load_dwordx4 v[76:79], v[16:17], off nt
	global_load_dwordx4 v[72:75], v[16:17], off offset:1024 nt
	global_load_dwordx4 v[68:71], v[16:17], off offset:2048 nt
	global_load_dwordx4 v[64:67], v[16:17], off offset:3072 nt
	v_ashrrev_i32_e32 v95, 31, v94
	v_lshlrev_b64 v[16:17], 12, v[94:95]
	v_lshl_add_u64 v[16:17], v[82:83], 0, v[16:17]
	global_load_dwordx4 v[60:63], v[16:17], off nt
	global_load_dwordx4 v[56:59], v[16:17], off offset:1024 nt
	global_load_dwordx4 v[52:55], v[16:17], off offset:2048 nt
	global_load_dwordx4 v[48:51], v[16:17], off offset:3072 nt
	v_add_u32_e32 v92, 2, v80
	v_ashrrev_i32_e32 v93, 31, v92
	v_lshlrev_b64 v[16:17], 12, v[92:93]
	v_lshl_add_u64 v[16:17], v[82:83], 0, v[16:17]
	global_load_dwordx4 v[44:47], v[16:17], off nt
	global_load_dwordx4 v[40:43], v[16:17], off offset:1024 nt
	global_load_dwordx4 v[36:39], v[16:17], off offset:2048 nt
	global_load_dwordx4 v[32:35], v[16:17], off offset:3072 nt
	v_add_u32_e32 v90, 3, v80
	v_ashrrev_i32_e32 v91, 31, v90
	v_lshlrev_b64 v[16:17], 12, v[90:91]
	v_lshl_add_u64 v[16:17], v[82:83], 0, v[16:17]
	global_load_dwordx4 v[28:31], v[16:17], off nt
	global_load_dwordx4 v[24:27], v[16:17], off offset:1024 nt
	global_load_dwordx4 v[20:23], v[16:17], off offset:2048 nt
	s_nop 0
	global_load_dwordx4 v[16:19], v[16:17], off offset:3072 nt
	v_mov_b32_e32 v85, v177
	s_waitcnt vmcnt(15)
	v_mov_b32_e32 v98, v77
	s_waitcnt vmcnt(14)
	v_mov_b32_e32 v99, v73
	s_waitcnt vmcnt(13)
	v_mov_b32_e32 v112, v69
	s_waitcnt vmcnt(12)
	v_mov_b32_e32 v113, v65
	v_mov_b32_e32 v110, v68
	v_mov_b32_e32 v111, v64
	v_pk_mul_f32 v[112:113], v[112:113], v[112:113]
	v_mov_b32_e32 v96, v76
	v_mov_b32_e32 v97, v72
	v_mov_b32_e32 v114, v70
	v_mov_b32_e32 v115, v66
	v_pk_mul_f32 v[98:99], v[98:99], v[98:99]
	v_pk_fma_f32 v[110:111], v[110:111], v[110:111], v[112:113]
	v_mov_b32_e32 v100, v78
	v_mov_b32_e32 v101, v74
	v_pk_fma_f32 v[96:97], v[96:97], v[96:97], v[98:99]
	v_pk_fma_f32 v[110:111], v[114:115], v[114:115], v[110:111]
	s_waitcnt vmcnt(9)
	v_mov_b32_e32 v114, v53
	s_waitcnt vmcnt(8)
	v_mov_b32_e32 v115, v49
	v_mov_b32_e32 v120, v61
	v_mov_b32_e32 v121, v57
	v_pk_fma_f32 v[96:97], v[100:101], v[100:101], v[96:97]
	v_mov_b32_e32 v100, v52
	v_mov_b32_e32 v101, v48
	v_pk_mul_f32 v[114:115], v[114:115], v[114:115]
	v_mov_b32_e32 v118, v60
	v_mov_b32_e32 v119, v56
	v_pk_mul_f32 v[120:121], v[120:121], v[120:121]
	v_pk_fma_f32 v[100:101], v[100:101], v[100:101], v[114:115]
	s_waitcnt vmcnt(7)
	v_mov_b32_e32 v114, v45
	s_waitcnt vmcnt(6)
	v_mov_b32_e32 v115, v41
	v_mov_b32_e32 v98, v62
	v_mov_b32_e32 v99, v58
	v_pk_fma_f32 v[118:119], v[118:119], v[118:119], v[120:121]
	v_mov_b32_e32 v120, v44
	v_mov_b32_e32 v121, v40
	v_pk_mul_f32 v[114:115], v[114:115], v[114:115]
	v_mov_b32_e32 v108, v79
	v_mov_b32_e32 v109, v75
	v_mov_b32_e32 v116, v71
	v_mov_b32_e32 v117, v67
	v_mov_b32_e32 v112, v63
	v_mov_b32_e32 v113, v59
	v_pk_fma_f32 v[114:115], v[120:121], v[120:121], v[114:115]
	v_mov_b32_e32 v120, v54
	v_mov_b32_e32 v121, v50
	v_pk_fma_f32 v[98:99], v[98:99], v[98:99], v[118:119]
	v_pk_fma_f32 v[108:109], v[108:109], v[108:109], v[96:97]
	v_mov_b32_e32 v96, v55
	v_mov_b32_e32 v97, v51
	v_pk_fma_f32 v[110:111], v[116:117], v[116:117], v[110:111]
	v_mov_b32_e32 v116, v46
	v_mov_b32_e32 v117, v42
	v_pk_fma_f32 v[100:101], v[120:121], v[120:121], v[100:101]
	v_pk_fma_f32 v[112:113], v[112:113], v[112:113], v[98:99]
	v_pk_fma_f32 v[114:115], v[116:117], v[116:117], v[114:115]
	v_pk_fma_f32 v[100:101], v[96:97], v[96:97], v[100:101]
	v_mov_b32_e32 v116, v112
	v_mov_b32_e32 v117, v108
	v_mov_b32_e32 v108, v113
	v_pk_add_f32 v[108:109], v[116:117], v[108:109]
	v_mov_b32_e32 v112, v100
	v_mov_b32_e32 v113, v110
	v_pk_add_f32 v[108:109], v[108:109], v[112:113]
	v_mov_b32_e32 v110, v101
	v_pk_add_f32 v[100:101], v[108:109], v[110:111]
	ds_bpermute_b32 v109, v102, v101
	ds_bpermute_b32 v108, v102, v100
	v_mov_b32_e32 v118, v47
	v_mov_b32_e32 v119, v43
	v_pk_fma_f32 v[96:97], v[118:119], v[118:119], v[114:115]
	s_waitcnt vmcnt(5)
	v_mov_b32_e32 v114, v37
	s_waitcnt lgkmcnt(0)
	v_pk_add_f32 v[100:101], v[100:101], v[108:109]
	ds_bpermute_b32 v109, v103, v101
	ds_bpermute_b32 v108, v103, v100
	s_waitcnt vmcnt(4)
	v_mov_b32_e32 v115, v33
	v_mov_b32_e32 v98, v36
	v_mov_b32_e32 v99, v32
	v_pk_mul_f32 v[114:115], v[114:115], v[114:115]
	s_waitcnt lgkmcnt(0)
	v_pk_add_f32 v[100:101], v[100:101], v[108:109]
	ds_bpermute_b32 v109, v104, v101
	ds_bpermute_b32 v108, v104, v100
	v_pk_fma_f32 v[98:99], v[98:99], v[98:99], v[114:115]
	v_mov_b32_e32 v114, v38
	v_mov_b32_e32 v115, v34
	v_pk_fma_f32 v[98:99], v[114:115], v[114:115], v[98:99]
	s_waitcnt lgkmcnt(0)
	v_pk_add_f32 v[100:101], v[100:101], v[108:109]
	ds_bpermute_b32 v109, v105, v101
	ds_bpermute_b32 v108, v105, v100
	v_mov_b32_e32 v114, v39
	v_mov_b32_e32 v115, v35
	s_waitcnt vmcnt(3)
	v_mov_b32_e32 v110, v29
	s_waitcnt vmcnt(2)
	v_mov_b32_e32 v111, v25
	s_waitcnt lgkmcnt(0)
	v_pk_add_f32 v[100:101], v[100:101], v[108:109]
	ds_bpermute_b32 v109, v106, v101
	ds_bpermute_b32 v108, v106, v100
	v_pk_fma_f32 v[98:99], v[114:115], v[114:115], v[98:99]
	v_mov_b32_e32 v114, v28
	v_mov_b32_e32 v115, v24
	v_pk_mul_f32 v[110:111], v[110:111], v[110:111]
	s_waitcnt lgkmcnt(0)
	v_pk_add_f32 v[100:101], v[100:101], v[108:109]
	ds_bpermute_b32 v109, v107, v101
	ds_bpermute_b32 v108, v107, v100
	v_pk_fma_f32 v[110:111], v[114:115], v[114:115], v[110:111]
	v_mov_b32_e32 v112, v30
	v_mov_b32_e32 v113, v26
	v_pk_fma_f32 v[110:111], v[112:113], v[112:113], v[110:111]
	v_mov_b32_e32 v112, v31
	v_mov_b32_e32 v113, v27
	s_waitcnt vmcnt(1)
	v_mov_b32_e32 v114, v21
	s_waitcnt vmcnt(0)
	v_mov_b32_e32 v115, v17
	v_pk_fma_f32 v[110:111], v[112:113], v[112:113], v[110:111]
	v_mov_b32_e32 v112, v20
	v_mov_b32_e32 v113, v16
	v_pk_mul_f32 v[114:115], v[114:115], v[114:115]
	s_waitcnt lgkmcnt(0)
	v_pk_add_f32 v[108:109], v[100:101], v[108:109]
	v_pk_fma_f32 v[112:113], v[112:113], v[112:113], v[114:115]
	v_mov_b32_e32 v114, v22
	v_mov_b32_e32 v115, v18
	v_mov_b64_e32 v[100:101], s[20:21]
	v_pk_fma_f32 v[112:113], v[114:115], v[114:115], v[112:113]
	v_mov_b32_e32 v114, v23
	v_mov_b32_e32 v115, v19
	v_pk_fma_f32 v[108:109], v[108:109], s[6:7], v[100:101] op_sel_hi:[1,0,0]
	v_pk_fma_f32 v[112:113], v[114:115], v[114:115], v[112:113]
	v_lshlrev_b64 v[114:115], 11, v[80:81]
	v_mul_f32_e32 v81, 0x4b800000, v109
	v_cmp_gt_f32_e32 vcc, s23, v109
	v_lshl_add_u64 v[114:115], s[50:51], 0, v[114:115]
	v_lshl_add_u64 v[116:117], v[114:115], 0, v[176:177]
	v_cndmask_b32_e32 v81, v109, v81, vcc
	v_rsq_f32_e32 v81, v81
	v_add_u32_e32 v80, s2, v80
	v_mul_f32_e32 v87, 0x45800000, v81
	v_cndmask_b32_e32 v118, v81, v87, vcc
	v_pk_mul_f32 v[76:77], v[76:77], v[118:119] op_sel_hi:[1,0]
	v_pk_mul_f32 v[78:79], v[78:79], v[118:119] op_sel_hi:[1,0]
	v_pk_mul_f32 v[76:77], v[0:1], v[76:77]
	v_pk_mul_f32 v[78:79], v[2:3], v[78:79]
	v_bfe_u32 v81, v76, 16, 1
	v_add3_u32 v81, v76, v81, s13
	v_bfe_u32 v76, v77, 16, 1
	v_add3_u32 v89, v77, v76, s13
	v_bfe_u32 v76, v78, 16, 1
	v_add3_u32 v109, v78, v76, s13
	v_bfe_u32 v76, v79, 16, 1
	v_add3_u32 v79, v79, v76, s13
	v_lshrrev_b32_e32 v78, 16, v81
	v_lshrrev_b32_e32 v81, 16, v109
	v_pk_mul_f32 v[72:73], v[72:73], v[118:119] op_sel_hi:[1,0]
	v_and_or_b32 v78, v89, s33, v78
	v_and_or_b32 v79, v79, s33, v81
	v_pk_mul_f32 v[72:73], v[4:5], v[72:73]
	global_store_dwordx2 v[116:117], v[78:79], off sc1
	v_bfe_u32 v78, v72, 16, 1
	v_pk_mul_f32 v[74:75], v[74:75], v[118:119] op_sel_hi:[1,0]
	v_add3_u32 v72, v72, v78, s13
	v_bfe_u32 v78, v73, 16, 1
	v_pk_mul_f32 v[74:75], v[6:7], v[74:75]
	v_lshrrev_b32_e32 v72, 16, v72
	v_add3_u32 v73, v73, v78, s13
	v_and_or_b32 v72, v73, s33, v72
	v_bfe_u32 v73, v74, 16, 1
	v_add3_u32 v73, v74, v73, s13
	v_bfe_u32 v74, v75, 16, 1
	v_lshrrev_b32_e32 v73, 16, v73
	v_add3_u32 v74, v75, v74, s13
	v_pk_mul_f32 v[68:69], v[68:69], v[118:119] op_sel_hi:[1,0]
	v_lshl_add_u64 v[76:77], v[114:115], 0, v[84:85]
	v_and_or_b32 v73, v74, s33, v73
	v_pk_mul_f32 v[68:69], v[8:9], v[68:69]
	global_store_dwordx2 v[76:77], v[72:73], off sc1
	v_bfe_u32 v72, v68, 16, 1
	v_pk_mul_f32 v[70:71], v[70:71], v[118:119] op_sel_hi:[1,0]
	v_add3_u32 v68, v68, v72, s13
	v_bfe_u32 v72, v69, 16, 1
	v_pk_mul_f32 v[70:71], v[10:11], v[70:71]
	v_lshrrev_b32_e32 v68, 16, v68
	v_add3_u32 v69, v69, v72, s13
	v_and_or_b32 v68, v69, s33, v68
	v_bfe_u32 v69, v70, 16, 1
	v_add3_u32 v69, v70, v69, s13
	v_bfe_u32 v70, v71, 16, 1
	v_mov_b32_e32 v87, v177
	v_lshrrev_b32_e32 v69, 16, v69
	v_add3_u32 v70, v71, v70, s13
	v_pk_mul_f32 v[64:65], v[64:65], v[118:119] op_sel_hi:[1,0]
	v_lshl_add_u64 v[120:121], v[114:115], 0, v[86:87]
	v_and_or_b32 v69, v70, s33, v69
	v_pk_mul_f32 v[64:65], v[12:13], v[64:65]
	global_store_dwordx2 v[120:121], v[68:69], off sc1
	v_bfe_u32 v68, v64, 16, 1
	v_add3_u32 v64, v64, v68, s13
	v_bfe_u32 v68, v65, 16, 1
	v_pk_mul_f32 v[66:67], v[66:67], v[118:119] op_sel_hi:[1,0]
	v_add3_u32 v65, v65, v68, s13
	v_mul_f32_e32 v68, 0x4b800000, v108
	v_cmp_gt_f32_e32 vcc, s23, v108
	v_pk_mul_f32 v[66:67], v[14:15], v[66:67]
	v_lshrrev_b32_e32 v64, 16, v64
	v_cndmask_b32_e32 v68, v108, v68, vcc
	v_and_or_b32 v64, v65, s33, v64
	v_bfe_u32 v65, v66, 16, 1
	v_rsq_f32_e32 v68, v68
	v_add3_u32 v65, v66, v65, s13
	v_bfe_u32 v66, v67, 16, 1
	v_mov_b32_e32 v89, v177
	v_lshrrev_b32_e32 v65, 16, v65
	v_add3_u32 v66, v67, v66, s13
	v_lshl_add_u64 v[114:115], v[114:115], 0, v[88:89]
	v_and_or_b32 v65, v66, s33, v65
	global_store_dwordx2 v[114:115], v[64:65], off sc1
	v_mul_f32_e32 v64, 0x45800000, v68
	v_cndmask_b32_e32 v64, v68, v64, vcc
	v_pk_mul_f32 v[60:61], v[60:61], v[64:65] op_sel_hi:[1,0]
	v_pk_mul_f32 v[62:63], v[62:63], v[64:65] op_sel_hi:[1,0]
	v_pk_mul_f32 v[60:61], v[0:1], v[60:61]
	v_pk_mul_f32 v[62:63], v[2:3], v[62:63]
	v_bfe_u32 v65, v60, 16, 1
	v_add3_u32 v60, v60, v65, s13
	v_bfe_u32 v65, v61, 16, 1
	v_lshrrev_b32_e32 v60, 16, v60
	v_add3_u32 v61, v61, v65, s13
	v_and_or_b32 v60, v61, s33, v60
	v_bfe_u32 v61, v62, 16, 1
	v_lshlrev_b64 v[66:67], 11, v[94:95]
	v_add3_u32 v61, v62, v61, s13
	v_bfe_u32 v62, v63, 16, 1
	v_lshl_add_u64 v[66:67], s[50:51], 0, v[66:67]
	v_lshrrev_b32_e32 v61, 16, v61
	v_add3_u32 v62, v63, v62, s13
	v_pk_mul_f32 v[56:57], v[56:57], v[64:65] op_sel_hi:[1,0]
	v_and_or_b32 v61, v62, s33, v61
	v_lshl_add_u64 v[62:63], v[66:67], 0, v[176:177]
	v_pk_mul_f32 v[56:57], v[4:5], v[56:57]
	global_store_dwordx2 v[62:63], v[60:61], off sc1
	v_bfe_u32 v60, v56, 16, 1
	v_pk_mul_f32 v[58:59], v[58:59], v[64:65] op_sel_hi:[1,0]
	v_add3_u32 v56, v56, v60, s13
	v_bfe_u32 v60, v57, 16, 1
	v_pk_mul_f32 v[58:59], v[6:7], v[58:59]
	v_lshrrev_b32_e32 v56, 16, v56
	v_add3_u32 v57, v57, v60, s13
	v_and_or_b32 v56, v57, s33, v56
	v_bfe_u32 v57, v58, 16, 1
	v_add3_u32 v57, v58, v57, s13
	v_bfe_u32 v58, v59, 16, 1
	v_lshrrev_b32_e32 v57, 16, v57
	v_add3_u32 v58, v59, v58, s13
	v_pk_mul_f32 v[52:53], v[52:53], v[64:65] op_sel_hi:[1,0]
	v_and_or_b32 v57, v58, s33, v57
	v_lshl_add_u64 v[58:59], v[66:67], 0, v[84:85]
	v_pk_mul_f32 v[52:53], v[8:9], v[52:53]
	global_store_dwordx2 v[58:59], v[56:57], off sc1
	v_bfe_u32 v56, v52, 16, 1
	v_pk_mul_f32 v[54:55], v[54:55], v[64:65] op_sel_hi:[1,0]
	v_add3_u32 v52, v52, v56, s13
	v_bfe_u32 v56, v53, 16, 1
	v_pk_mul_f32 v[54:55], v[10:11], v[54:55]
	v_lshrrev_b32_e32 v52, 16, v52
	v_add3_u32 v53, v53, v56, s13
	v_and_or_b32 v52, v53, s33, v52
	v_bfe_u32 v53, v54, 16, 1
	v_add3_u32 v53, v54, v53, s13
	v_bfe_u32 v54, v55, 16, 1
	v_add3_u32 v58, v55, v54, s13
	v_mov_b32_e32 v54, v110
	v_mov_b32_e32 v55, v96
	v_mov_b32_e32 v96, v111
	v_pk_add_f32 v[54:55], v[54:55], v[96:97]
	v_mov_b32_e32 v56, v112
	v_mov_b32_e32 v57, v98
	v_pk_add_f32 v[54:55], v[54:55], v[56:57]
	v_mov_b32_e32 v98, v113
	v_pk_add_f32 v[54:55], v[54:55], v[98:99]
	ds_bpermute_b32 v57, v102, v55
	ds_bpermute_b32 v56, v102, v54
	v_lshrrev_b32_e32 v53, 16, v53
	v_and_or_b32 v53, v58, s33, v53
	v_lshl_add_u64 v[58:59], v[66:67], 0, v[86:87]
	global_store_dwordx2 v[58:59], v[52:53], off sc1
	s_waitcnt lgkmcnt(0)
	v_pk_add_f32 v[52:53], v[54:55], v[56:57]
	ds_bpermute_b32 v55, v103, v53
	ds_bpermute_b32 v54, v103, v52
	v_pk_mul_f32 v[48:49], v[48:49], v[64:65] op_sel_hi:[1,0]
	v_pk_mul_f32 v[50:51], v[50:51], v[64:65] op_sel_hi:[1,0]
	v_pk_mul_f32 v[48:49], v[12:13], v[48:49]
	v_pk_mul_f32 v[50:51], v[14:15], v[50:51]
	s_waitcnt lgkmcnt(0)
	v_pk_add_f32 v[52:53], v[52:53], v[54:55]
	ds_bpermute_b32 v55, v104, v53
	ds_bpermute_b32 v54, v104, v52
	v_bfe_u32 v56, v48, 16, 1
	v_add3_u32 v48, v48, v56, s13
	v_lshrrev_b32_e32 v56, 16, v48
	v_bfe_u32 v48, v49, 16, 1
	v_add3_u32 v57, v49, v48, s13
	s_waitcnt lgkmcnt(0)
	v_pk_add_f32 v[48:49], v[52:53], v[54:55]
	ds_bpermute_b32 v53, v105, v49
	ds_bpermute_b32 v52, v105, v48
	v_bfe_u32 v55, v50, 16, 1
	v_add3_u32 v50, v50, v55, s13
	v_bfe_u32 v55, v51, 16, 1
	v_lshrrev_b32_e32 v50, 16, v50
	s_waitcnt lgkmcnt(0)
	v_pk_add_f32 v[48:49], v[48:49], v[52:53]
	ds_bpermute_b32 v53, v106, v49
	ds_bpermute_b32 v52, v106, v48
	v_add3_u32 v51, v51, v55, s13
	v_and_or_b32 v54, v57, s33, v56
	v_and_or_b32 v55, v51, s33, v50
	v_lshl_add_u64 v[50:51], v[66:67], 0, v[88:89]
	s_waitcnt lgkmcnt(0)
	v_pk_add_f32 v[48:49], v[48:49], v[52:53]
	ds_bpermute_b32 v53, v107, v49
	ds_bpermute_b32 v52, v107, v48
	global_store_dwordx2 v[50:51], v[54:55], off sc1
	v_lshlrev_b64 v[50:51], 11, v[92:93]
	v_lshl_add_u64 v[50:51], s[50:51], 0, v[50:51]
	v_lshl_add_u64 v[54:55], v[50:51], 0, v[176:177]
	s_waitcnt lgkmcnt(0)
	v_pk_add_f32 v[48:49], v[48:49], v[52:53]
	v_lshl_add_u64 v[56:57], v[50:51], 0, v[86:87]
	v_pk_fma_f32 v[48:49], v[48:49], s[6:7], v[100:101] op_sel_hi:[1,0,0]
	s_nop 0
	v_mul_f32_e32 v52, 0x4b800000, v49
	v_cmp_gt_f32_e32 vcc, s23, v49
	s_nop 1
	v_cndmask_b32_e32 v49, v49, v52, vcc
	v_rsq_f32_e32 v49, v49
	v_lshl_add_u64 v[52:53], v[50:51], 0, v[84:85]
	v_lshl_add_u64 v[50:51], v[50:51], 0, v[88:89]
	v_mul_f32_e32 v58, 0x45800000, v49
	v_cndmask_b32_e32 v58, v49, v58, vcc
	v_pk_mul_f32 v[44:45], v[44:45], v[58:59] op_sel_hi:[1,0]
	v_pk_mul_f32 v[46:47], v[46:47], v[58:59] op_sel_hi:[1,0]
	v_pk_mul_f32 v[44:45], v[0:1], v[44:45]
	v_pk_mul_f32 v[46:47], v[2:3], v[46:47]
	v_bfe_u32 v49, v44, 16, 1
	v_add3_u32 v44, v44, v49, s13
	v_bfe_u32 v49, v45, 16, 1
	v_lshrrev_b32_e32 v44, 16, v44
	v_add3_u32 v45, v45, v49, s13
	v_and_or_b32 v44, v45, s33, v44
	v_bfe_u32 v45, v46, 16, 1
	v_add3_u32 v45, v46, v45, s13
	v_bfe_u32 v46, v47, 16, 1
	v_lshrrev_b32_e32 v45, 16, v45
	v_add3_u32 v46, v47, v46, s13
	v_pk_mul_f32 v[40:41], v[40:41], v[58:59] op_sel_hi:[1,0]
	v_and_or_b32 v45, v46, s33, v45
	v_pk_mul_f32 v[40:41], v[4:5], v[40:41]
	global_store_dwordx2 v[54:55], v[44:45], off sc1
	v_bfe_u32 v44, v40, 16, 1
	v_pk_mul_f32 v[42:43], v[42:43], v[58:59] op_sel_hi:[1,0]
	v_add3_u32 v40, v40, v44, s13
	v_bfe_u32 v44, v41, 16, 1
	v_pk_mul_f32 v[42:43], v[6:7], v[42:43]
	v_lshrrev_b32_e32 v40, 16, v40
	v_add3_u32 v41, v41, v44, s13
	v_and_or_b32 v40, v41, s33, v40
	v_bfe_u32 v41, v42, 16, 1
	v_add3_u32 v41, v42, v41, s13
	v_bfe_u32 v42, v43, 16, 1
	v_lshrrev_b32_e32 v41, 16, v41
	v_add3_u32 v42, v43, v42, s13
	v_pk_mul_f32 v[36:37], v[36:37], v[58:59] op_sel_hi:[1,0]
	v_and_or_b32 v41, v42, s33, v41
	v_pk_mul_f32 v[36:37], v[8:9], v[36:37]
	global_store_dwordx2 v[52:53], v[40:41], off sc1
	v_bfe_u32 v40, v36, 16, 1
	v_pk_mul_f32 v[38:39], v[38:39], v[58:59] op_sel_hi:[1,0]
	v_add3_u32 v36, v36, v40, s13
	v_bfe_u32 v40, v37, 16, 1
	v_pk_mul_f32 v[38:39], v[10:11], v[38:39]
	v_lshrrev_b32_e32 v36, 16, v36
	v_add3_u32 v37, v37, v40, s13
	v_and_or_b32 v36, v37, s33, v36
	v_bfe_u32 v37, v38, 16, 1
	v_add3_u32 v37, v38, v37, s13
	v_bfe_u32 v38, v39, 16, 1
	v_lshrrev_b32_e32 v37, 16, v37
	v_add3_u32 v38, v39, v38, s13
	v_pk_mul_f32 v[32:33], v[32:33], v[58:59] op_sel_hi:[1,0]
	v_and_or_b32 v37, v38, s33, v37
	v_pk_mul_f32 v[32:33], v[12:13], v[32:33]
	global_store_dwordx2 v[56:57], v[36:37], off sc1
	v_bfe_u32 v36, v32, 16, 1
	v_add3_u32 v32, v32, v36, s13
	v_bfe_u32 v36, v33, 16, 1
	v_pk_mul_f32 v[34:35], v[34:35], v[58:59] op_sel_hi:[1,0]
	v_add3_u32 v33, v33, v36, s13
	v_mul_f32_e32 v36, 0x4b800000, v48
	v_cmp_gt_f32_e32 vcc, s23, v48
	v_pk_mul_f32 v[34:35], v[14:15], v[34:35]
	v_lshrrev_b32_e32 v32, 16, v32
	v_cndmask_b32_e32 v36, v48, v36, vcc
	v_and_or_b32 v32, v33, s33, v32
	v_bfe_u32 v33, v34, 16, 1
	v_rsq_f32_e32 v36, v36
	v_add3_u32 v33, v34, v33, s13
	v_bfe_u32 v34, v35, 16, 1
	v_lshrrev_b32_e32 v33, 16, v33
	v_add3_u32 v34, v35, v34, s13
	v_and_or_b32 v33, v34, s33, v33
	global_store_dwordx2 v[50:51], v[32:33], off sc1
	v_mul_f32_e32 v32, 0x45800000, v36
	v_cndmask_b32_e32 v32, v36, v32, vcc
	v_pk_mul_f32 v[28:29], v[28:29], v[32:33] op_sel_hi:[1,0]
	v_pk_mul_f32 v[30:31], v[30:31], v[32:33] op_sel_hi:[1,0]
	v_pk_mul_f32 v[28:29], v[0:1], v[28:29]
	v_pk_mul_f32 v[30:31], v[2:3], v[30:31]
	v_bfe_u32 v33, v28, 16, 1
	v_add3_u32 v28, v28, v33, s13
	v_bfe_u32 v33, v29, 16, 1
	v_lshrrev_b32_e32 v28, 16, v28
	v_add3_u32 v29, v29, v33, s13
	v_and_or_b32 v28, v29, s33, v28
	v_bfe_u32 v29, v30, 16, 1
	v_lshlrev_b64 v[34:35], 11, v[90:91]
	v_add3_u32 v29, v30, v29, s13
	v_bfe_u32 v30, v31, 16, 1
	v_lshl_add_u64 v[34:35], s[50:51], 0, v[34:35]
	v_lshrrev_b32_e32 v29, 16, v29
	v_add3_u32 v30, v31, v30, s13
	v_pk_mul_f32 v[24:25], v[24:25], v[32:33] op_sel_hi:[1,0]
	v_and_or_b32 v29, v30, s33, v29
	v_lshl_add_u64 v[30:31], v[34:35], 0, v[176:177]
	v_pk_mul_f32 v[24:25], v[4:5], v[24:25]
	global_store_dwordx2 v[30:31], v[28:29], off sc1
	v_bfe_u32 v28, v24, 16, 1
	v_pk_mul_f32 v[26:27], v[26:27], v[32:33] op_sel_hi:[1,0]
	v_add3_u32 v24, v24, v28, s13
	v_bfe_u32 v28, v25, 16, 1
	v_pk_mul_f32 v[26:27], v[6:7], v[26:27]
	v_lshrrev_b32_e32 v24, 16, v24
	v_add3_u32 v25, v25, v28, s13
	v_and_or_b32 v24, v25, s33, v24
	v_bfe_u32 v25, v26, 16, 1
	v_add3_u32 v25, v26, v25, s13
	v_bfe_u32 v26, v27, 16, 1
	v_lshrrev_b32_e32 v25, 16, v25
	v_add3_u32 v26, v27, v26, s13
	v_pk_mul_f32 v[20:21], v[20:21], v[32:33] op_sel_hi:[1,0]
	v_and_or_b32 v25, v26, s33, v25
	v_lshl_add_u64 v[26:27], v[34:35], 0, v[84:85]
	v_pk_mul_f32 v[20:21], v[8:9], v[20:21]
	global_store_dwordx2 v[26:27], v[24:25], off sc1
	v_bfe_u32 v24, v20, 16, 1
	v_pk_mul_f32 v[22:23], v[22:23], v[32:33] op_sel_hi:[1,0]
	v_add3_u32 v20, v20, v24, s13
	v_bfe_u32 v24, v21, 16, 1
	v_pk_mul_f32 v[22:23], v[10:11], v[22:23]
	v_lshrrev_b32_e32 v20, 16, v20
	v_add3_u32 v21, v21, v24, s13
	v_and_or_b32 v20, v21, s33, v20
	v_bfe_u32 v21, v22, 16, 1
	v_add3_u32 v21, v22, v21, s13
	v_bfe_u32 v22, v23, 16, 1
	v_lshrrev_b32_e32 v21, 16, v21
	v_add3_u32 v22, v23, v22, s13
	v_pk_mul_f32 v[16:17], v[16:17], v[32:33] op_sel_hi:[1,0]
	v_and_or_b32 v21, v22, s33, v21
	v_lshl_add_u64 v[22:23], v[34:35], 0, v[86:87]
	v_pk_mul_f32 v[16:17], v[12:13], v[16:17]
	global_store_dwordx2 v[22:23], v[20:21], off sc1
	v_bfe_u32 v20, v16, 16, 1
	v_pk_mul_f32 v[18:19], v[18:19], v[32:33] op_sel_hi:[1,0]
	v_add3_u32 v16, v16, v20, s13
	v_bfe_u32 v20, v17, 16, 1
	v_pk_mul_f32 v[18:19], v[14:15], v[18:19]
	v_lshrrev_b32_e32 v16, 16, v16
	v_add3_u32 v17, v17, v20, s13
	v_and_or_b32 v16, v17, s33, v16
	v_bfe_u32 v17, v18, 16, 1
	v_add3_u32 v17, v18, v17, s13
	v_bfe_u32 v18, v19, 16, 1
	v_lshrrev_b32_e32 v17, 16, v17
	v_add3_u32 v18, v19, v18, s13
	v_cmp_lt_i32_e32 vcc, s13, v80
	v_and_or_b32 v17, v18, s33, v17
	v_lshl_add_u64 v[18:19], v[34:35], 0, v[88:89]
	s_or_b64 s[38:39], vcc, s[38:39]
	global_store_dwordx2 v[18:19], v[16:17], off sc1
	s_andn2_b64 exec, exec, s[38:39]
	s_cbranch_execnz .LBB0_446
	s_branch .LBB0_21
